# manager-wave grid-barrier arrivals for streamers + IEEE-div to v_rcp in in-projection gates + bf16 pack via v_cvt_pk + code placement pads
# speedup vs baseline: 1.0220x; 1.0220x over previous
.LBB0_93:
	s_and_b32 s18, s22, 0xff
	s_mov_b64 s[16:17], -1
	s_cmp_lg_u32 s18, 0
	s_mov_b64 s[20:21], -1
	s_sleep 2
	s_cbranch_scc1 .LBB0_96
	global_load_dword v3, v1, s[8:9] sc1
	s_waitcnt vmcnt(0)
	v_cmp_eq_u32_e32 vcc, 0, v3
	s_cbranch_vccnz .LBB0_98
	s_mov_b64 s[20:21], 0
	s_mov_b64 s[18:19], -1

.LBB0_110:
	s_and_b32 s16, s22, 0xff
	s_cmp_lg_u32 s16, 0
	s_mov_b64 s[18:19], -1
	s_sleep 2
	s_cbranch_scc1 .LBB0_113
	global_load_dword v2, v1, s[8:9] sc1
	s_waitcnt vmcnt(0)
	v_cmp_eq_u32_e32 vcc, 0, v2
	s_cbranch_vccnz .LBB0_115
	s_mov_b64 s[18:19], 0
	s_mov_b64 s[16:17], -1

.LBB0_143:
	s_ashr_i32 s23, s40, 1
	s_lshl_b32 s0, s40, 8
	s_and_b32 s0, s0, 0x100
	s_mul_i32 s1, s23, 0x1100000
	v_or_b32_e32 v192, s0, v184
	s_mul_hi_i32 s0, s23, 0x1100000
	s_add_u32 s30, s8, s1
	s_addc_u32 s31, s9, s0
	s_cmp_lt_u32 s40, 2
	s_cselect_b64 s[0:1], -1, 0
	s_cmp_gt_u32 s40, 1
	s_cselect_b64 s[34:35], -1, 0
	s_cmp_lg_u32 s23, 6
	s_cselect_b64 s[38:39], -1, 0
	s_and_b64 s[38:39], s[34:35], s[38:39]
	v_lshl_add_u32 v148, s36, 8, v1
	s_and_b64 vcc, exec, s[38:39]
	v_cndmask_b32_e64 v150, 1.0, v188, s[0:1]
	s_cbranch_vccnz .LBB0_145
	v_lshlrev_b32_e32 v138, 1, v192
	v_pk_mul_f32 v[154:155], v[150:151], v[126:127] op_sel_hi:[0,1]
	v_lshl_add_u64 v[158:159], s[30:31], 0, v[138:139]
	v_ashrrev_i32_e32 v149, 31, v148
	v_lshlrev_b64 v[152:153], 10, v[148:149]
	v_cvt_pk_bf16_f32 v149, v154, v155
	v_pk_mul_f32 v[156:157], v[150:151], v[128:129] op_sel_hi:[0,1]
	v_mov_b32_e32 v154, v149
	v_pk_mul_f32 v[162:163], v[150:151], v[122:123] op_sel_hi:[0,1]
	v_cvt_pk_bf16_f32 v155, v156, v157
	v_pk_mul_f32 v[160:161], v[150:151], v[124:125] op_sel_hi:[0,1]
	v_cvt_pk_bf16_f32 v156, v162, v163
	v_lshl_add_u64 v[152:153], v[158:159], 0, v[152:153]
	v_cvt_pk_bf16_f32 v157, v160, v161
	global_store_dwordx4 v[152:153], v[154:157], off
	v_pk_mul_f32 v[162:163], v[150:151], v[114:115] op_sel_hi:[0,1]
	v_pk_mul_f32 v[160:161], v[150:151], v[116:117] op_sel_hi:[0,1]
	v_pk_mul_f32 v[154:155], v[150:151], v[118:119] op_sel_hi:[0,1]
	v_pk_mul_f32 v[156:157], v[150:151], v[120:121] op_sel_hi:[0,1]
	v_cvt_pk_bf16_f32 v154, v154, v155
	v_cvt_pk_bf16_f32 v155, v156, v157
	v_cvt_pk_bf16_f32 v156, v162, v163
	v_cvt_pk_bf16_f32 v157, v160, v161
	global_store_dwordx4 v[152:153], v[154:157], off offset:256
	v_pk_mul_f32 v[164:165], v[150:151], v[106:107] op_sel_hi:[0,1]
	v_pk_mul_f32 v[162:163], v[150:151], v[108:109] op_sel_hi:[0,1]
	v_or_b32_e32 v154, 16, v148
	v_ashrrev_i32_e32 v155, 31, v154
	v_lshlrev_b64 v[154:155], 10, v[154:155]
	v_lshl_add_u64 v[160:161], v[158:159], 0, v[154:155]
	v_pk_mul_f32 v[154:155], v[150:151], v[110:111] op_sel_hi:[0,1]
	v_pk_mul_f32 v[156:157], v[150:151], v[112:113] op_sel_hi:[0,1]
	v_cvt_pk_bf16_f32 v154, v154, v155
	v_cvt_pk_bf16_f32 v155, v156, v157
	v_cvt_pk_bf16_f32 v156, v164, v165
	v_cvt_pk_bf16_f32 v157, v162, v163
	global_store_dwordx4 v[160:161], v[154:157], off
	v_pk_mul_f32 v[164:165], v[150:151], v[98:99] op_sel_hi:[0,1]
	v_pk_mul_f32 v[162:163], v[150:151], v[100:101] op_sel_hi:[0,1]
	v_pk_mul_f32 v[154:155], v[150:151], v[102:103] op_sel_hi:[0,1]
	v_pk_mul_f32 v[156:157], v[150:151], v[104:105] op_sel_hi:[0,1]
	v_cvt_pk_bf16_f32 v154, v154, v155
	v_cvt_pk_bf16_f32 v155, v156, v157
	v_cvt_pk_bf16_f32 v156, v164, v165
	v_cvt_pk_bf16_f32 v157, v162, v163
	global_store_dwordx4 v[160:161], v[154:157], off offset:256
	v_pk_mul_f32 v[164:165], v[150:151], v[90:91] op_sel_hi:[0,1]
	v_pk_mul_f32 v[162:163], v[150:151], v[92:93] op_sel_hi:[0,1]
	v_or_b32_e32 v154, 32, v148
	v_ashrrev_i32_e32 v155, 31, v154
	v_lshlrev_b64 v[154:155], 10, v[154:155]
	v_lshl_add_u64 v[160:161], v[158:159], 0, v[154:155]
	v_pk_mul_f32 v[154:155], v[150:151], v[94:95] op_sel_hi:[0,1]
	v_pk_mul_f32 v[156:157], v[150:151], v[96:97] op_sel_hi:[0,1]
	v_cvt_pk_bf16_f32 v154, v154, v155
	v_cvt_pk_bf16_f32 v155, v156, v157
	v_cvt_pk_bf16_f32 v156, v164, v165
	v_cvt_pk_bf16_f32 v157, v162, v163
	global_store_dwordx4 v[160:161], v[154:157], off
	v_pk_mul_f32 v[164:165], v[150:151], v[82:83] op_sel_hi:[0,1]
	v_pk_mul_f32 v[162:163], v[150:151], v[84:85] op_sel_hi:[0,1]
	v_pk_mul_f32 v[154:155], v[150:151], v[86:87] op_sel_hi:[0,1]
	v_pk_mul_f32 v[156:157], v[150:151], v[88:89] op_sel_hi:[0,1]
	v_cvt_pk_bf16_f32 v154, v154, v155
	v_cvt_pk_bf16_f32 v155, v156, v157
	v_cvt_pk_bf16_f32 v156, v164, v165
	v_cvt_pk_bf16_f32 v157, v162, v163
	global_store_dwordx4 v[160:161], v[154:157], off offset:256
	v_pk_mul_f32 v[162:163], v[150:151], v[74:75] op_sel_hi:[0,1]
	v_pk_mul_f32 v[160:161], v[150:151], v[76:77] op_sel_hi:[0,1]
	v_or_b32_e32 v154, 48, v148
	v_ashrrev_i32_e32 v155, 31, v154
	v_lshlrev_b64 v[154:155], 10, v[154:155]
	v_lshl_add_u64 v[158:159], v[158:159], 0, v[154:155]
	v_pk_mul_f32 v[154:155], v[150:151], v[78:79] op_sel_hi:[0,1]
	v_pk_mul_f32 v[156:157], v[150:151], v[80:81] op_sel_hi:[0,1]
	v_cvt_pk_bf16_f32 v154, v154, v155
	v_cvt_pk_bf16_f32 v155, v156, v157
	v_cvt_pk_bf16_f32 v156, v162, v163
	v_cvt_pk_bf16_f32 v157, v160, v161
	global_store_dwordx4 v[158:159], v[154:157], off
	v_pk_mul_f32 v[162:163], v[150:151], v[66:67] op_sel_hi:[0,1]
	v_pk_mul_f32 v[160:161], v[150:151], v[68:69] op_sel_hi:[0,1]
	v_pk_mul_f32 v[154:155], v[150:151], v[70:71] op_sel_hi:[0,1]
	v_pk_mul_f32 v[156:157], v[150:151], v[72:73] op_sel_hi:[0,1]
	v_cvt_pk_bf16_f32 v154, v154, v155
	v_cvt_pk_bf16_f32 v155, v156, v157
	v_cvt_pk_bf16_f32 v156, v162, v163
	v_cvt_pk_bf16_f32 v157, v160, v161
	global_store_dwordx4 v[158:159], v[154:157], off offset:256
	v_pk_mul_f32 v[162:163], v[150:151], v[58:59] op_sel_hi:[0,1]
	v_pk_mul_f32 v[160:161], v[150:151], v[60:61] op_sel_hi:[0,1]
	v_pk_mul_f32 v[154:155], v[150:151], v[62:63] op_sel_hi:[0,1]
	v_pk_mul_f32 v[156:157], v[150:151], v[64:65] op_sel_hi:[0,1]
	v_cvt_pk_bf16_f32 v154, v154, v155
	v_cvt_pk_bf16_f32 v155, v156, v157
	v_cvt_pk_bf16_f32 v156, v162, v163
	v_bfe_u32 v138, v160, 16, 1
	v_add3_u32 v138, v160, v138, s87
	v_bfe_u32 v149, v161, 16, 1
	v_lshrrev_b32_e32 v138, 16, v138
	v_add3_u32 v149, v161, v149, s87
	v_add_co_u32_e32 v160, vcc, s89, v152
	v_and_or_b32 v157, v149, s88, v138
	s_nop 0
	v_addc_co_u32_e32 v161, vcc, 0, v153, vcc
	global_store_dwordx4 v[160:161], v[154:157], off
	v_pk_mul_f32 v[162:163], v[150:151], v[50:51] op_sel_hi:[0,1]
	v_pk_mul_f32 v[160:161], v[150:151], v[52:53] op_sel_hi:[0,1]
	v_pk_mul_f32 v[154:155], v[150:151], v[54:55] op_sel_hi:[0,1]
	v_pk_mul_f32 v[156:157], v[150:151], v[56:57] op_sel_hi:[0,1]
	v_cvt_pk_bf16_f32 v154, v154, v155
	v_cvt_pk_bf16_f32 v155, v156, v157
	v_cvt_pk_bf16_f32 v156, v162, v163
	v_lshl_add_u64 v[158:159], v[152:153], 0, s[14:15]
	v_cvt_pk_bf16_f32 v157, v160, v161
	global_store_dwordx4 v[158:159], v[154:157], off offset:256
	v_pk_mul_f32 v[162:163], v[150:151], v[42:43] op_sel_hi:[0,1]
	v_pk_mul_f32 v[160:161], v[150:151], v[44:45] op_sel_hi:[0,1]
	v_pk_mul_f32 v[154:155], v[150:151], v[46:47] op_sel_hi:[0,1]
	v_pk_mul_f32 v[156:157], v[150:151], v[48:49] op_sel_hi:[0,1]
	v_cvt_pk_bf16_f32 v154, v154, v155
	v_cvt_pk_bf16_f32 v155, v156, v157
	v_cvt_pk_bf16_f32 v156, v162, v163
	v_bfe_u32 v138, v160, 16, 1
	v_add3_u32 v138, v160, v138, s87
	v_bfe_u32 v149, v161, 16, 1
	v_lshrrev_b32_e32 v138, 16, v138
	v_add3_u32 v149, v161, v149, s87
	v_add_co_u32_e32 v160, vcc, s90, v152
	v_and_or_b32 v157, v149, s88, v138
	s_nop 0
	v_addc_co_u32_e32 v161, vcc, 0, v153, vcc
	global_store_dwordx4 v[160:161], v[154:157], off
	v_pk_mul_f32 v[162:163], v[150:151], v[34:35] op_sel_hi:[0,1]
	v_pk_mul_f32 v[160:161], v[150:151], v[36:37] op_sel_hi:[0,1]
	v_pk_mul_f32 v[154:155], v[150:151], v[38:39] op_sel_hi:[0,1]
	v_pk_mul_f32 v[156:157], v[150:151], v[40:41] op_sel_hi:[0,1]
	v_cvt_pk_bf16_f32 v154, v154, v155
	v_cvt_pk_bf16_f32 v155, v156, v157
	v_cvt_pk_bf16_f32 v156, v162, v163
	v_lshl_add_u64 v[158:159], v[152:153], 0, s[16:17]
	v_cvt_pk_bf16_f32 v157, v160, v161
	global_store_dwordx4 v[158:159], v[154:157], off offset:256
	v_pk_mul_f32 v[162:163], v[150:151], v[26:27] op_sel_hi:[0,1]
	v_pk_mul_f32 v[160:161], v[150:151], v[28:29] op_sel_hi:[0,1]
	v_pk_mul_f32 v[154:155], v[150:151], v[30:31] op_sel_hi:[0,1]
	v_pk_mul_f32 v[156:157], v[150:151], v[32:33] op_sel_hi:[0,1]
	v_cvt_pk_bf16_f32 v154, v154, v155
	v_cvt_pk_bf16_f32 v155, v156, v157
	v_cvt_pk_bf16_f32 v156, v162, v163
	v_bfe_u32 v138, v160, 16, 1
	v_add3_u32 v138, v160, v138, s87
	v_bfe_u32 v149, v161, 16, 1
	v_lshrrev_b32_e32 v138, 16, v138
	v_add3_u32 v149, v161, v149, s87
	v_add_co_u32_e32 v160, vcc, s91, v152
	v_and_or_b32 v157, v149, s88, v138
	s_nop 0
	v_addc_co_u32_e32 v161, vcc, 0, v153, vcc
	global_store_dwordx4 v[160:161], v[154:157], off
	v_pk_mul_f32 v[162:163], v[150:151], v[18:19] op_sel_hi:[0,1]
	v_pk_mul_f32 v[160:161], v[150:151], v[20:21] op_sel_hi:[0,1]
	v_pk_mul_f32 v[154:155], v[150:151], v[22:23] op_sel_hi:[0,1]
	v_pk_mul_f32 v[156:157], v[150:151], v[24:25] op_sel_hi:[0,1]
	v_cvt_pk_bf16_f32 v154, v154, v155
	v_cvt_pk_bf16_f32 v155, v156, v157
	v_cvt_pk_bf16_f32 v156, v162, v163
	v_lshl_add_u64 v[158:159], v[152:153], 0, s[18:19]
	v_cvt_pk_bf16_f32 v157, v160, v161
	global_store_dwordx4 v[158:159], v[154:157], off offset:256
	v_pk_mul_f32 v[162:163], v[150:151], v[10:11] op_sel_hi:[0,1]
	v_pk_mul_f32 v[160:161], v[150:151], v[12:13] op_sel_hi:[0,1]
	v_pk_mul_f32 v[154:155], v[150:151], v[14:15] op_sel_hi:[0,1]
	v_pk_mul_f32 v[156:157], v[150:151], v[16:17] op_sel_hi:[0,1]
	v_cvt_pk_bf16_f32 v154, v154, v155
	v_cvt_pk_bf16_f32 v155, v156, v157
	v_cvt_pk_bf16_f32 v156, v162, v163
	v_lshl_add_u64 v[158:159], v[152:153], 0, s[20:21]
	v_add_co_u32_e32 v152, vcc, s92, v152
	v_cvt_pk_bf16_f32 v157, v160, v161
	s_nop 0
	v_addc_co_u32_e32 v153, vcc, 0, v153, vcc
	global_store_dwordx4 v[152:153], v[154:157], off
	v_pk_mul_f32 v[152:153], v[150:151], v[6:7] op_sel_hi:[0,1]
	s_nop 0
	v_pk_mul_f32 v[154:155], v[150:151], v[8:9] op_sel_hi:[0,1]
	v_cvt_pk_bf16_f32 v152, v152, v153
	v_pk_mul_f32 v[160:161], v[150:151], v[2:3] op_sel_hi:[0,1]
	v_cvt_pk_bf16_f32 v153, v154, v155
	v_pk_mul_f32 v[156:157], v[150:151], v[4:5] op_sel_hi:[0,1]
	v_cvt_pk_bf16_f32 v154, v160, v161
	v_cvt_pk_bf16_f32 v155, v156, v157
	global_store_dwordx4 v[158:159], v[152:155], off offset:256

.LBB0_173:
	s_andn2_b64 vcc, exec, s[38:39]
	s_cbranch_vccnz .LBB0_246
	s_add_i32 s0, s23, -1
	s_cmp_gt_u32 s0, 1
	s_mov_b64 s[0:1], -1
	s_cbranch_scc0 .LBB0_180
	s_cmp_eq_u32 s23, 5
	s_cbranch_scc1 .LBB0_177
	v_lshlrev_b32_e32 v138, 1, v192
	s_waitcnt lgkmcnt(0)
	v_lshl_add_u64 v[152:153], s[30:31], 0, v[138:139]
	v_mul_f32_e32 v138, 0xbfb8aa3b, v126
	v_exp_f32_e32 v154, v138
	v_mul_f32_e32 v138, 0xbfb8aa3b, v127
	v_exp_f32_e32 v156, v138
	v_mul_f32_e32 v138, 0xbfb8aa3b, v128
	v_exp_f32_e32 v155, v138
	v_mul_f32_e32 v138, 0xbfb8aa3b, v129
	v_ashrrev_i32_e32 v149, 31, v148
	v_exp_f32_e32 v157, v138
	v_pk_add_f32 v[154:155], v[154:155], 1.0 op_sel_hi:[1,0]
	v_lshlrev_b64 v[150:151], 10, v[148:149]
	v_rcp_f32_e32 v149, v155
	v_lshl_add_u64 v[150:151], v[152:153], 0, v[150:151]
	v_mul_f32_e32 v138, v128, v149
	v_rcp_f32_e32 v155, v154
	s_nop 0
	v_mul_f32_e32 v149, v126, v155
	v_pk_add_f32 v[154:155], v[156:157], 1.0 op_sel_hi:[1,0]
	s_nop 0
	v_rcp_f32_e32 v157, v154
	s_nop 0
	v_mul_f32_e32 v158, v127, v157
	v_rcp_f32_e32 v156, v155
	s_nop 0
	v_mul_f32_e32 v159, v129, v156
	v_mul_f32_e32 v155, 0xbfb8aa3b, v123
	v_mul_f32_e32 v154, 0xbfb8aa3b, v122
	v_exp_f32_e32 v156, v155
	v_mul_f32_e32 v155, 0xbfb8aa3b, v124
	v_exp_f32_e32 v154, v154
	v_exp_f32_e32 v155, v155
	v_mul_f32_e32 v157, 0xbfb8aa3b, v125
	v_exp_f32_e32 v157, v157
	v_pk_add_f32 v[154:155], v[154:155], 1.0 op_sel_hi:[1,0]
	s_nop 0
	v_rcp_f32_e32 v161, v155
	s_nop 0
	v_mul_f32_e32 v160, v124, v161
	v_rcp_f32_e32 v161, v154
	s_nop 0
	v_mul_f32_e32 v161, v122, v161
	v_pk_add_f32 v[154:155], v[156:157], 1.0 op_sel_hi:[1,0]
	s_nop 0
	v_rcp_f32_e32 v157, v154
	s_nop 0
	v_mul_f32_e32 v154, v123, v157
	v_rcp_f32_e32 v157, v155
	s_nop 0
	v_mul_f32_e32 v155, v125, v157
	v_cvt_pk_bf16_f32 v158, v149, v158
	v_cvt_pk_bf16_f32 v159, v138, v159
	v_cvt_pk_bf16_f32 v154, v161, v154
	v_cvt_pk_bf16_f32 v155, v160, v155
	v_mov_b32_e32 v157, v155
	v_mov_b32_e32 v156, v154
	v_mov_b32_e32 v155, v159
	v_mov_b32_e32 v154, v158
	v_mul_f32_e32 v138, 0xbfb8aa3b, v118
	global_store_dwordx4 v[150:151], v[154:157], off
	s_nop 1
	v_exp_f32_e32 v154, v138
	v_mul_f32_e32 v138, 0xbfb8aa3b, v119
	v_exp_f32_e32 v156, v138
	v_mul_f32_e32 v138, 0xbfb8aa3b, v120
	v_exp_f32_e32 v155, v138
	v_mul_f32_e32 v138, 0xbfb8aa3b, v121
	v_exp_f32_e32 v157, v138
	v_pk_add_f32 v[154:155], v[154:155], 1.0 op_sel_hi:[1,0]
	s_nop 0
	v_rcp_f32_e32 v149, v155
	s_nop 0
	v_mul_f32_e32 v138, v120, v149
	v_rcp_f32_e32 v155, v154
	s_nop 0
	v_mul_f32_e32 v149, v118, v155
	v_pk_add_f32 v[154:155], v[156:157], 1.0 op_sel_hi:[1,0]
	s_nop 0
	v_rcp_f32_e32 v157, v154
	s_nop 0
	v_mul_f32_e32 v158, v119, v157
	v_rcp_f32_e32 v156, v155
	s_nop 0
	v_mul_f32_e32 v159, v121, v156
	v_mul_f32_e32 v155, 0xbfb8aa3b, v115
	v_mul_f32_e32 v154, 0xbfb8aa3b, v114
	v_exp_f32_e32 v156, v155
	v_mul_f32_e32 v155, 0xbfb8aa3b, v116
	v_exp_f32_e32 v154, v154
	v_exp_f32_e32 v155, v155
	v_mul_f32_e32 v157, 0xbfb8aa3b, v117
	v_exp_f32_e32 v157, v157
	v_pk_add_f32 v[154:155], v[154:155], 1.0 op_sel_hi:[1,0]
	s_nop 0
	v_rcp_f32_e32 v161, v155
	s_nop 0
	v_mul_f32_e32 v160, v116, v161
	v_rcp_f32_e32 v161, v154
	s_nop 0
	v_mul_f32_e32 v161, v114, v161
	v_pk_add_f32 v[154:155], v[156:157], 1.0 op_sel_hi:[1,0]
	s_nop 0
	v_rcp_f32_e32 v157, v154
	s_nop 0
	v_mul_f32_e32 v154, v115, v157
	v_rcp_f32_e32 v157, v155
	s_nop 0
	v_mul_f32_e32 v155, v117, v157
	v_cvt_pk_bf16_f32 v158, v149, v158
	v_cvt_pk_bf16_f32 v159, v138, v159
	v_cvt_pk_bf16_f32 v154, v161, v154
	v_cvt_pk_bf16_f32 v155, v160, v155
	v_mov_b32_e32 v157, v155
	v_mov_b32_e32 v156, v154
	v_mov_b32_e32 v155, v159
	v_mov_b32_e32 v154, v158
	v_mul_f32_e32 v138, 0xbfb8aa3b, v110
	global_store_dwordx4 v[150:151], v[154:157], off offset:256
	s_nop 1
	v_exp_f32_e32 v156, v138
	v_mul_f32_e32 v138, 0xbfb8aa3b, v111
	v_exp_f32_e32 v158, v138
	v_mul_f32_e32 v138, 0xbfb8aa3b, v112
	v_exp_f32_e32 v157, v138
	v_mul_f32_e32 v138, 0xbfb8aa3b, v113
	v_exp_f32_e32 v159, v138
	v_or_b32_e32 v154, 16, v148
	v_pk_add_f32 v[156:157], v[156:157], 1.0 op_sel_hi:[1,0]
	v_ashrrev_i32_e32 v155, 31, v154
	v_rcp_f32_e32 v149, v157
	v_lshlrev_b64 v[154:155], 10, v[154:155]
	v_lshl_add_u64 v[154:155], v[152:153], 0, v[154:155]
	v_mul_f32_e32 v138, v112, v149
	v_rcp_f32_e32 v157, v156
	s_nop 0
	v_mul_f32_e32 v149, v110, v157
	v_pk_add_f32 v[156:157], v[158:159], 1.0 op_sel_hi:[1,0]
	s_nop 0
	v_rcp_f32_e32 v159, v156
	s_nop 0
	v_mul_f32_e32 v160, v111, v159
	v_rcp_f32_e32 v158, v157
	s_nop 0
	v_mul_f32_e32 v161, v113, v158
	v_mul_f32_e32 v157, 0xbfb8aa3b, v107
	v_mul_f32_e32 v156, 0xbfb8aa3b, v106
	v_exp_f32_e32 v158, v157
	v_mul_f32_e32 v157, 0xbfb8aa3b, v108
	v_exp_f32_e32 v156, v156
	v_exp_f32_e32 v157, v157
	v_mul_f32_e32 v159, 0xbfb8aa3b, v109
	v_exp_f32_e32 v159, v159
	v_pk_add_f32 v[156:157], v[156:157], 1.0 op_sel_hi:[1,0]
	s_nop 0
	v_rcp_f32_e32 v163, v157
	s_nop 0
	v_mul_f32_e32 v162, v108, v163
	v_rcp_f32_e32 v163, v156
	s_nop 0
	v_mul_f32_e32 v163, v106, v163
	v_pk_add_f32 v[156:157], v[158:159], 1.0 op_sel_hi:[1,0]
	s_nop 0
	v_rcp_f32_e32 v159, v156
	s_nop 0
	v_mul_f32_e32 v156, v107, v159
	v_rcp_f32_e32 v159, v157
	s_nop 0
	v_mul_f32_e32 v157, v109, v159
	v_cvt_pk_bf16_f32 v160, v149, v160
	v_cvt_pk_bf16_f32 v161, v138, v161
	v_cvt_pk_bf16_f32 v156, v163, v156
	v_cvt_pk_bf16_f32 v157, v162, v157
	v_mov_b32_e32 v159, v157
	v_mov_b32_e32 v158, v156
	v_mov_b32_e32 v157, v161
	v_mov_b32_e32 v156, v160
	v_mul_f32_e32 v138, 0xbfb8aa3b, v102
	global_store_dwordx4 v[154:155], v[156:159], off
	s_nop 1
	v_exp_f32_e32 v156, v138
	v_mul_f32_e32 v138, 0xbfb8aa3b, v103
	v_exp_f32_e32 v158, v138
	v_mul_f32_e32 v138, 0xbfb8aa3b, v104
	v_exp_f32_e32 v157, v138
	v_mul_f32_e32 v138, 0xbfb8aa3b, v105
	v_exp_f32_e32 v159, v138
	v_pk_add_f32 v[156:157], v[156:157], 1.0 op_sel_hi:[1,0]
	s_nop 0
	v_rcp_f32_e32 v149, v157
	s_nop 0
	v_mul_f32_e32 v138, v104, v149
	v_rcp_f32_e32 v157, v156
	s_nop 0
	v_mul_f32_e32 v149, v102, v157
	v_pk_add_f32 v[156:157], v[158:159], 1.0 op_sel_hi:[1,0]
	s_nop 0
	v_rcp_f32_e32 v159, v156
	s_nop 0
	v_mul_f32_e32 v160, v103, v159
	v_rcp_f32_e32 v158, v157
	s_nop 0
	v_mul_f32_e32 v161, v105, v158
	v_mul_f32_e32 v157, 0xbfb8aa3b, v99
	v_mul_f32_e32 v156, 0xbfb8aa3b, v98
	v_exp_f32_e32 v158, v157
	v_mul_f32_e32 v157, 0xbfb8aa3b, v100
	v_exp_f32_e32 v156, v156
	v_exp_f32_e32 v157, v157
	v_mul_f32_e32 v159, 0xbfb8aa3b, v101
	v_exp_f32_e32 v159, v159
	v_pk_add_f32 v[156:157], v[156:157], 1.0 op_sel_hi:[1,0]
	s_nop 0
	v_rcp_f32_e32 v163, v157
	s_nop 0
	v_mul_f32_e32 v162, v100, v163
	v_rcp_f32_e32 v163, v156
	s_nop 0
	v_mul_f32_e32 v163, v98, v163
	v_pk_add_f32 v[156:157], v[158:159], 1.0 op_sel_hi:[1,0]
	s_nop 0
	v_rcp_f32_e32 v159, v156
	s_nop 0
	v_mul_f32_e32 v156, v99, v159
	v_rcp_f32_e32 v159, v157
	s_nop 0
	v_mul_f32_e32 v157, v101, v159
	v_cvt_pk_bf16_f32 v160, v149, v160
	v_cvt_pk_bf16_f32 v161, v138, v161
	v_cvt_pk_bf16_f32 v156, v163, v156
	v_cvt_pk_bf16_f32 v157, v162, v157
	v_mov_b32_e32 v159, v157
	v_mov_b32_e32 v158, v156
	v_mov_b32_e32 v157, v161
	v_mov_b32_e32 v156, v160
	v_mul_f32_e32 v138, 0xbfb8aa3b, v94
	global_store_dwordx4 v[154:155], v[156:159], off offset:256
	v_or_b32_e32 v154, 32, v148
	v_ashrrev_i32_e32 v155, 31, v154
	v_exp_f32_e32 v156, v138
	v_mul_f32_e32 v138, 0xbfb8aa3b, v95
	v_exp_f32_e32 v158, v138
	v_mul_f32_e32 v138, 0xbfb8aa3b, v96
	v_exp_f32_e32 v157, v138
	v_mul_f32_e32 v138, 0xbfb8aa3b, v97
	v_exp_f32_e32 v159, v138
	v_lshlrev_b64 v[154:155], 10, v[154:155]
	v_pk_add_f32 v[156:157], v[156:157], 1.0 op_sel_hi:[1,0]
	v_lshl_add_u64 v[154:155], v[152:153], 0, v[154:155]
	v_rcp_f32_e32 v149, v157
	s_nop 0
	v_mul_f32_e32 v138, v96, v149
	v_rcp_f32_e32 v157, v156
	s_nop 0
	v_mul_f32_e32 v149, v94, v157
	v_pk_add_f32 v[156:157], v[158:159], 1.0 op_sel_hi:[1,0]
	s_nop 0
	v_rcp_f32_e32 v159, v156
	s_nop 0
	v_mul_f32_e32 v160, v95, v159
	v_rcp_f32_e32 v158, v157
	s_nop 0
	v_mul_f32_e32 v161, v97, v158
	v_mul_f32_e32 v157, 0xbfb8aa3b, v91
	v_mul_f32_e32 v156, 0xbfb8aa3b, v90
	v_exp_f32_e32 v158, v157
	v_mul_f32_e32 v157, 0xbfb8aa3b, v92
	v_exp_f32_e32 v156, v156
	v_exp_f32_e32 v157, v157
	v_mul_f32_e32 v159, 0xbfb8aa3b, v93
	v_exp_f32_e32 v159, v159
	v_pk_add_f32 v[156:157], v[156:157], 1.0 op_sel_hi:[1,0]
	s_nop 0
	v_rcp_f32_e32 v163, v157
	s_nop 0
	v_mul_f32_e32 v162, v92, v163
	v_rcp_f32_e32 v163, v156
	s_nop 0
	v_mul_f32_e32 v163, v90, v163
	v_pk_add_f32 v[156:157], v[158:159], 1.0 op_sel_hi:[1,0]
	s_nop 0
	v_rcp_f32_e32 v159, v156
	s_nop 0
	v_mul_f32_e32 v156, v91, v159
	v_rcp_f32_e32 v159, v157
	s_nop 0
	v_mul_f32_e32 v157, v93, v159
	v_cvt_pk_bf16_f32 v160, v149, v160
	v_cvt_pk_bf16_f32 v161, v138, v161
	v_cvt_pk_bf16_f32 v156, v163, v156
	v_cvt_pk_bf16_f32 v157, v162, v157
	v_mov_b32_e32 v159, v157
	v_mov_b32_e32 v158, v156
	v_mov_b32_e32 v157, v161
	v_mov_b32_e32 v156, v160
	v_mul_f32_e32 v138, 0xbfb8aa3b, v86
	global_store_dwordx4 v[154:155], v[156:159], off
	s_nop 1
	v_exp_f32_e32 v156, v138
	v_mul_f32_e32 v138, 0xbfb8aa3b, v87
	v_exp_f32_e32 v158, v138
	v_mul_f32_e32 v138, 0xbfb8aa3b, v88
	v_exp_f32_e32 v157, v138
	v_mul_f32_e32 v138, 0xbfb8aa3b, v89
	v_exp_f32_e32 v159, v138
	v_pk_add_f32 v[156:157], v[156:157], 1.0 op_sel_hi:[1,0]
	s_nop 0
	v_rcp_f32_e32 v149, v157
	s_nop 0
	v_mul_f32_e32 v138, v88, v149
	v_rcp_f32_e32 v157, v156
	s_nop 0
	v_mul_f32_e32 v149, v86, v157
	v_pk_add_f32 v[156:157], v[158:159], 1.0 op_sel_hi:[1,0]
	s_nop 0
	v_rcp_f32_e32 v159, v156
	s_nop 0
	v_mul_f32_e32 v160, v87, v159
	v_rcp_f32_e32 v158, v157
	s_nop 0
	v_mul_f32_e32 v161, v89, v158
	v_mul_f32_e32 v157, 0xbfb8aa3b, v83
	v_mul_f32_e32 v156, 0xbfb8aa3b, v82
	v_exp_f32_e32 v158, v157
	v_mul_f32_e32 v157, 0xbfb8aa3b, v84
	v_exp_f32_e32 v156, v156
	v_exp_f32_e32 v157, v157
	v_mul_f32_e32 v159, 0xbfb8aa3b, v85
	v_exp_f32_e32 v159, v159
	v_pk_add_f32 v[156:157], v[156:157], 1.0 op_sel_hi:[1,0]
	s_nop 0
	v_rcp_f32_e32 v163, v157
	s_nop 0
	v_mul_f32_e32 v162, v84, v163
	v_rcp_f32_e32 v163, v156
	s_nop 0
	v_mul_f32_e32 v163, v82, v163
	v_pk_add_f32 v[156:157], v[158:159], 1.0 op_sel_hi:[1,0]
	s_nop 0
	v_rcp_f32_e32 v159, v156
	s_nop 0
	v_mul_f32_e32 v156, v83, v159
	v_rcp_f32_e32 v159, v157
	s_nop 0
	v_mul_f32_e32 v157, v85, v159
	v_cvt_pk_bf16_f32 v160, v149, v160
	v_cvt_pk_bf16_f32 v161, v138, v161
	v_cvt_pk_bf16_f32 v156, v163, v156
	v_cvt_pk_bf16_f32 v157, v162, v157
	v_mov_b32_e32 v159, v157
	v_mov_b32_e32 v158, v156
	v_mov_b32_e32 v157, v161
	v_mov_b32_e32 v156, v160
	global_store_dwordx4 v[154:155], v[156:159], off offset:256
	v_or_b32_e32 v154, 48, v148
	v_ashrrev_i32_e32 v155, 31, v154
	v_lshlrev_b64 v[154:155], 10, v[154:155]
	v_mul_f32_e32 v138, 0xbfb8aa3b, v78
	v_lshl_add_u64 v[152:153], v[152:153], 0, v[154:155]
	v_exp_f32_e32 v154, v138
	v_mul_f32_e32 v138, 0xbfb8aa3b, v79
	v_exp_f32_e32 v156, v138
	v_mul_f32_e32 v138, 0xbfb8aa3b, v80
	v_exp_f32_e32 v155, v138
	v_mul_f32_e32 v138, 0xbfb8aa3b, v81
	v_exp_f32_e32 v157, v138
	v_pk_add_f32 v[154:155], v[154:155], 1.0 op_sel_hi:[1,0]
	s_nop 0
	v_rcp_f32_e32 v149, v155
	s_nop 0
	v_mul_f32_e32 v138, v80, v149
	v_rcp_f32_e32 v155, v154
	s_nop 0
	v_mul_f32_e32 v149, v78, v155
	v_pk_add_f32 v[154:155], v[156:157], 1.0 op_sel_hi:[1,0]
	s_nop 0
	v_rcp_f32_e32 v157, v154
	s_nop 0
	v_mul_f32_e32 v158, v79, v157
	v_rcp_f32_e32 v156, v155
	s_nop 0
	v_mul_f32_e32 v159, v81, v156
	v_mul_f32_e32 v155, 0xbfb8aa3b, v75
	v_mul_f32_e32 v154, 0xbfb8aa3b, v74
	v_exp_f32_e32 v156, v155
	v_mul_f32_e32 v155, 0xbfb8aa3b, v76
	v_exp_f32_e32 v154, v154
	v_exp_f32_e32 v155, v155
	v_mul_f32_e32 v157, 0xbfb8aa3b, v77
	v_exp_f32_e32 v157, v157
	v_pk_add_f32 v[154:155], v[154:155], 1.0 op_sel_hi:[1,0]
	s_nop 0
	v_rcp_f32_e32 v161, v155
	s_nop 0
	v_mul_f32_e32 v160, v76, v161
	v_rcp_f32_e32 v161, v154
	s_nop 0
	v_mul_f32_e32 v161, v74, v161
	v_pk_add_f32 v[154:155], v[156:157], 1.0 op_sel_hi:[1,0]
	s_nop 0
	v_rcp_f32_e32 v157, v154
	s_nop 0
	v_mul_f32_e32 v154, v75, v157
	v_rcp_f32_e32 v157, v155
	s_nop 0
	v_mul_f32_e32 v155, v77, v157
	v_cvt_pk_bf16_f32 v158, v149, v158
	v_cvt_pk_bf16_f32 v159, v138, v159
	v_cvt_pk_bf16_f32 v154, v161, v154
	v_cvt_pk_bf16_f32 v155, v160, v155
	v_mov_b32_e32 v157, v155
	v_mov_b32_e32 v156, v154
	v_mov_b32_e32 v155, v159
	v_mov_b32_e32 v154, v158
	v_mul_f32_e32 v138, 0xbfb8aa3b, v70
	global_store_dwordx4 v[152:153], v[154:157], off
	s_nop 1
	v_exp_f32_e32 v154, v138
	v_mul_f32_e32 v138, 0xbfb8aa3b, v71
	v_exp_f32_e32 v156, v138
	v_mul_f32_e32 v138, 0xbfb8aa3b, v72
	v_exp_f32_e32 v155, v138
	v_mul_f32_e32 v138, 0xbfb8aa3b, v73
	v_exp_f32_e32 v157, v138
	v_pk_add_f32 v[154:155], v[154:155], 1.0 op_sel_hi:[1,0]
	s_nop 0
	v_rcp_f32_e32 v149, v155
	s_nop 0
	v_mul_f32_e32 v138, v72, v149
	v_rcp_f32_e32 v155, v154
	s_nop 0
	v_mul_f32_e32 v149, v70, v155
	v_pk_add_f32 v[154:155], v[156:157], 1.0 op_sel_hi:[1,0]
	s_nop 0
	v_rcp_f32_e32 v157, v154
	s_nop 0
	v_mul_f32_e32 v158, v71, v157
	v_rcp_f32_e32 v156, v155
	s_nop 0
	v_mul_f32_e32 v159, v73, v156
	v_mul_f32_e32 v155, 0xbfb8aa3b, v67
	v_mul_f32_e32 v154, 0xbfb8aa3b, v66
	v_exp_f32_e32 v156, v155
	v_mul_f32_e32 v155, 0xbfb8aa3b, v68
	v_exp_f32_e32 v154, v154
	v_exp_f32_e32 v155, v155
	v_mul_f32_e32 v157, 0xbfb8aa3b, v69
	v_exp_f32_e32 v157, v157
	v_pk_add_f32 v[154:155], v[154:155], 1.0 op_sel_hi:[1,0]
	s_nop 0
	v_rcp_f32_e32 v161, v155
	s_nop 0
	v_mul_f32_e32 v160, v68, v161
	v_rcp_f32_e32 v161, v154
	s_nop 0
	v_mul_f32_e32 v161, v66, v161
	v_pk_add_f32 v[154:155], v[156:157], 1.0 op_sel_hi:[1,0]
	s_nop 0
	v_rcp_f32_e32 v157, v154
	s_nop 0
	v_mul_f32_e32 v154, v67, v157
	v_rcp_f32_e32 v157, v155
	s_nop 0
	v_mul_f32_e32 v155, v69, v157
	v_cvt_pk_bf16_f32 v158, v149, v158
	v_cvt_pk_bf16_f32 v159, v138, v159
	v_cvt_pk_bf16_f32 v154, v161, v154
	v_cvt_pk_bf16_f32 v155, v160, v155
	v_mov_b32_e32 v157, v155
	v_mov_b32_e32 v156, v154
	v_mov_b32_e32 v155, v159
	v_mov_b32_e32 v154, v158
	v_mul_f32_e32 v138, 0xbfb8aa3b, v62
	global_store_dwordx4 v[152:153], v[154:157], off offset:256
	v_lshl_add_u64 v[152:153], v[150:151], 0, s[14:15]
	s_nop 0
	v_exp_f32_e32 v154, v138
	v_mul_f32_e32 v138, 0xbfb8aa3b, v63
	v_exp_f32_e32 v156, v138
	v_mul_f32_e32 v138, 0xbfb8aa3b, v64
	v_exp_f32_e32 v155, v138
	v_mul_f32_e32 v138, 0xbfb8aa3b, v65
	v_exp_f32_e32 v157, v138
	v_pk_add_f32 v[154:155], v[154:155], 1.0 op_sel_hi:[1,0]
	s_nop 0
	v_rcp_f32_e32 v149, v155
	s_nop 0
	v_mul_f32_e32 v138, v64, v149
	v_rcp_f32_e32 v155, v154
	s_nop 0
	v_mul_f32_e32 v149, v62, v155
	v_pk_add_f32 v[154:155], v[156:157], 1.0 op_sel_hi:[1,0]
	s_nop 0
	v_rcp_f32_e32 v157, v154
	s_nop 0
	v_mul_f32_e32 v158, v63, v157
	v_rcp_f32_e32 v156, v155
	s_nop 0
	v_mul_f32_e32 v159, v65, v156
	v_mul_f32_e32 v155, 0xbfb8aa3b, v59
	v_mul_f32_e32 v154, 0xbfb8aa3b, v58
	v_exp_f32_e32 v156, v155
	v_mul_f32_e32 v155, 0xbfb8aa3b, v60
	v_exp_f32_e32 v154, v154
	v_exp_f32_e32 v155, v155
	v_mul_f32_e32 v157, 0xbfb8aa3b, v61
	v_exp_f32_e32 v157, v157
	v_pk_add_f32 v[154:155], v[154:155], 1.0 op_sel_hi:[1,0]
	s_nop 0
	v_rcp_f32_e32 v161, v155
	s_nop 0
	v_mul_f32_e32 v160, v60, v161
	v_rcp_f32_e32 v161, v154
	s_nop 0
	v_mul_f32_e32 v161, v58, v161
	v_pk_add_f32 v[154:155], v[156:157], 1.0 op_sel_hi:[1,0]
	s_nop 0
	v_rcp_f32_e32 v157, v154
	s_nop 0
	v_mul_f32_e32 v154, v59, v157
	v_rcp_f32_e32 v157, v155
	s_nop 0
	v_mul_f32_e32 v155, v61, v157
	v_cvt_pk_bf16_f32 v159, v138, v159
	v_cvt_pk_bf16_f32 v155, v160, v155
	v_cvt_pk_bf16_f32 v158, v149, v158
	v_cvt_pk_bf16_f32 v154, v161, v154
	v_mov_b32_e32 v156, v154
	v_mov_b32_e32 v154, v158
	v_add_co_u32_e32 v158, vcc, s89, v150
	v_mov_b32_e32 v157, v155
	v_mov_b32_e32 v155, v159
	v_addc_co_u32_e32 v159, vcc, 0, v151, vcc
	v_mul_f32_e32 v138, 0xbfb8aa3b, v54
	global_store_dwordx4 v[158:159], v[154:157], off
	s_nop 1
	v_exp_f32_e32 v154, v138
	v_mul_f32_e32 v138, 0xbfb8aa3b, v55
	v_exp_f32_e32 v156, v138
	v_mul_f32_e32 v138, 0xbfb8aa3b, v56
	v_exp_f32_e32 v155, v138
	v_mul_f32_e32 v138, 0xbfb8aa3b, v57
	v_exp_f32_e32 v157, v138
	v_pk_add_f32 v[154:155], v[154:155], 1.0 op_sel_hi:[1,0]
	s_nop 0
	v_rcp_f32_e32 v149, v155
	s_nop 0
	v_mul_f32_e32 v138, v56, v149
	v_rcp_f32_e32 v155, v154
	s_nop 0
	v_mul_f32_e32 v149, v54, v155
	v_pk_add_f32 v[154:155], v[156:157], 1.0 op_sel_hi:[1,0]
	s_nop 0
	v_rcp_f32_e32 v157, v154
	s_nop 0
	v_mul_f32_e32 v158, v55, v157
	v_rcp_f32_e32 v156, v155
	s_nop 0
	v_mul_f32_e32 v159, v57, v156
	v_mul_f32_e32 v155, 0xbfb8aa3b, v51
	v_mul_f32_e32 v154, 0xbfb8aa3b, v50
	v_exp_f32_e32 v156, v155
	v_mul_f32_e32 v155, 0xbfb8aa3b, v52
	v_exp_f32_e32 v154, v154
	v_exp_f32_e32 v155, v155
	v_mul_f32_e32 v157, 0xbfb8aa3b, v53
	v_exp_f32_e32 v157, v157
	v_pk_add_f32 v[154:155], v[154:155], 1.0 op_sel_hi:[1,0]
	s_nop 0
	v_rcp_f32_e32 v161, v155
	s_nop 0
	v_mul_f32_e32 v160, v52, v161
	v_rcp_f32_e32 v161, v154
	s_nop 0
	v_mul_f32_e32 v161, v50, v161
	v_pk_add_f32 v[154:155], v[156:157], 1.0 op_sel_hi:[1,0]
	s_nop 0
	v_rcp_f32_e32 v157, v154
	s_nop 0
	v_mul_f32_e32 v154, v51, v157
	v_rcp_f32_e32 v157, v155
	s_nop 0
	v_mul_f32_e32 v155, v53, v157
	v_cvt_pk_bf16_f32 v158, v149, v158
	v_cvt_pk_bf16_f32 v159, v138, v159
	v_cvt_pk_bf16_f32 v154, v161, v154
	v_cvt_pk_bf16_f32 v155, v160, v155
	v_mov_b32_e32 v157, v155
	v_mov_b32_e32 v156, v154
	v_mov_b32_e32 v155, v159
	v_mov_b32_e32 v154, v158
	v_mul_f32_e32 v138, 0xbfb8aa3b, v46
	global_store_dwordx4 v[152:153], v[154:157], off offset:256
	v_lshl_add_u64 v[152:153], v[150:151], 0, s[16:17]
	s_nop 0
	v_exp_f32_e32 v154, v138
	v_mul_f32_e32 v138, 0xbfb8aa3b, v47
	v_exp_f32_e32 v156, v138
	v_mul_f32_e32 v138, 0xbfb8aa3b, v48
	v_exp_f32_e32 v155, v138
	v_mul_f32_e32 v138, 0xbfb8aa3b, v49
	v_exp_f32_e32 v157, v138
	v_pk_add_f32 v[154:155], v[154:155], 1.0 op_sel_hi:[1,0]
	s_nop 0
	v_rcp_f32_e32 v149, v155
	s_nop 0
	v_mul_f32_e32 v138, v48, v149
	v_rcp_f32_e32 v155, v154
	s_nop 0
	v_mul_f32_e32 v149, v46, v155
	v_pk_add_f32 v[154:155], v[156:157], 1.0 op_sel_hi:[1,0]
	s_nop 0
	v_rcp_f32_e32 v157, v154
	s_nop 0
	v_mul_f32_e32 v158, v47, v157
	v_rcp_f32_e32 v156, v155
	s_nop 0
	v_mul_f32_e32 v159, v49, v156
	v_mul_f32_e32 v155, 0xbfb8aa3b, v43
	v_mul_f32_e32 v154, 0xbfb8aa3b, v42
	v_exp_f32_e32 v156, v155
	v_mul_f32_e32 v155, 0xbfb8aa3b, v44
	v_exp_f32_e32 v154, v154
	v_exp_f32_e32 v155, v155
	v_mul_f32_e32 v157, 0xbfb8aa3b, v45
	v_exp_f32_e32 v157, v157
	v_pk_add_f32 v[154:155], v[154:155], 1.0 op_sel_hi:[1,0]
	s_nop 0
	v_rcp_f32_e32 v161, v155
	s_nop 0
	v_mul_f32_e32 v160, v44, v161
	v_rcp_f32_e32 v161, v154
	s_nop 0
	v_mul_f32_e32 v161, v42, v161
	v_pk_add_f32 v[154:155], v[156:157], 1.0 op_sel_hi:[1,0]
	s_nop 0
	v_rcp_f32_e32 v157, v154
	s_nop 0
	v_mul_f32_e32 v154, v43, v157
	v_rcp_f32_e32 v157, v155
	s_nop 0
	v_mul_f32_e32 v155, v45, v157
	v_cvt_pk_bf16_f32 v159, v138, v159
	v_cvt_pk_bf16_f32 v155, v160, v155
	v_cvt_pk_bf16_f32 v158, v149, v158
	v_cvt_pk_bf16_f32 v154, v161, v154
	v_mov_b32_e32 v156, v154
	v_mov_b32_e32 v154, v158
	v_add_co_u32_e32 v158, vcc, s90, v150
	v_mov_b32_e32 v157, v155
	v_mov_b32_e32 v155, v159
	v_addc_co_u32_e32 v159, vcc, 0, v151, vcc
	v_mul_f32_e32 v138, 0xbfb8aa3b, v38
	global_store_dwordx4 v[158:159], v[154:157], off
	s_nop 1
	v_exp_f32_e32 v154, v138
	v_mul_f32_e32 v138, 0xbfb8aa3b, v39
	v_exp_f32_e32 v156, v138
	v_mul_f32_e32 v138, 0xbfb8aa3b, v40
	v_exp_f32_e32 v155, v138
	v_mul_f32_e32 v138, 0xbfb8aa3b, v41
	v_exp_f32_e32 v157, v138
	v_pk_add_f32 v[154:155], v[154:155], 1.0 op_sel_hi:[1,0]
	s_nop 0
	v_rcp_f32_e32 v149, v155
	s_nop 0
	v_mul_f32_e32 v138, v40, v149
	v_rcp_f32_e32 v155, v154
	s_nop 0
	v_mul_f32_e32 v149, v38, v155
	v_pk_add_f32 v[154:155], v[156:157], 1.0 op_sel_hi:[1,0]
	s_nop 0
	v_rcp_f32_e32 v157, v154
	s_nop 0
	v_mul_f32_e32 v158, v39, v157
	v_rcp_f32_e32 v156, v155
	s_nop 0
	v_mul_f32_e32 v159, v41, v156
	v_mul_f32_e32 v155, 0xbfb8aa3b, v35
	v_mul_f32_e32 v154, 0xbfb8aa3b, v34
	v_exp_f32_e32 v156, v155
	v_mul_f32_e32 v155, 0xbfb8aa3b, v36
	v_exp_f32_e32 v154, v154
	v_exp_f32_e32 v155, v155
	v_mul_f32_e32 v157, 0xbfb8aa3b, v37
	v_exp_f32_e32 v157, v157
	v_pk_add_f32 v[154:155], v[154:155], 1.0 op_sel_hi:[1,0]
	s_nop 0
	v_rcp_f32_e32 v161, v155
	s_nop 0
	v_mul_f32_e32 v160, v36, v161
	v_rcp_f32_e32 v161, v154
	s_nop 0
	v_mul_f32_e32 v161, v34, v161
	v_pk_add_f32 v[154:155], v[156:157], 1.0 op_sel_hi:[1,0]
	s_nop 0
	v_rcp_f32_e32 v157, v154
	s_nop 0
	v_mul_f32_e32 v154, v35, v157
	v_rcp_f32_e32 v157, v155
	s_nop 0
	v_mul_f32_e32 v155, v37, v157
	v_cvt_pk_bf16_f32 v158, v149, v158
	v_cvt_pk_bf16_f32 v159, v138, v159
	v_cvt_pk_bf16_f32 v154, v161, v154
	v_cvt_pk_bf16_f32 v155, v160, v155
	v_mov_b32_e32 v157, v155
	v_mov_b32_e32 v156, v154
	v_mov_b32_e32 v155, v159
	v_mov_b32_e32 v154, v158
	v_mul_f32_e32 v138, 0xbfb8aa3b, v30
	global_store_dwordx4 v[152:153], v[154:157], off offset:256
	v_lshl_add_u64 v[152:153], v[150:151], 0, s[18:19]
	s_nop 0
	v_exp_f32_e32 v154, v138
	v_mul_f32_e32 v138, 0xbfb8aa3b, v31
	v_exp_f32_e32 v156, v138
	v_mul_f32_e32 v138, 0xbfb8aa3b, v32
	v_exp_f32_e32 v155, v138
	v_mul_f32_e32 v138, 0xbfb8aa3b, v33
	v_exp_f32_e32 v157, v138
	v_pk_add_f32 v[154:155], v[154:155], 1.0 op_sel_hi:[1,0]
	s_nop 0
	v_rcp_f32_e32 v149, v155
	s_nop 0
	v_mul_f32_e32 v138, v32, v149
	v_rcp_f32_e32 v155, v154
	s_nop 0
	v_mul_f32_e32 v149, v30, v155
	v_pk_add_f32 v[154:155], v[156:157], 1.0 op_sel_hi:[1,0]
	s_nop 0
	v_rcp_f32_e32 v157, v154
	s_nop 0
	v_mul_f32_e32 v158, v31, v157
	v_rcp_f32_e32 v156, v155
	s_nop 0
	v_mul_f32_e32 v159, v33, v156
	v_mul_f32_e32 v155, 0xbfb8aa3b, v27
	v_mul_f32_e32 v154, 0xbfb8aa3b, v26
	v_exp_f32_e32 v156, v155
	v_mul_f32_e32 v155, 0xbfb8aa3b, v28
	v_exp_f32_e32 v154, v154
	v_exp_f32_e32 v155, v155
	v_mul_f32_e32 v157, 0xbfb8aa3b, v29
	v_exp_f32_e32 v157, v157
	v_pk_add_f32 v[154:155], v[154:155], 1.0 op_sel_hi:[1,0]
	s_nop 0
	v_rcp_f32_e32 v161, v155
	s_nop 0
	v_mul_f32_e32 v160, v28, v161
	v_rcp_f32_e32 v161, v154
	s_nop 0
	v_mul_f32_e32 v161, v26, v161
	v_pk_add_f32 v[154:155], v[156:157], 1.0 op_sel_hi:[1,0]
	s_nop 0
	v_rcp_f32_e32 v157, v154
	s_nop 0
	v_mul_f32_e32 v154, v27, v157
	v_rcp_f32_e32 v157, v155
	s_nop 0
	v_mul_f32_e32 v155, v29, v157
	v_cvt_pk_bf16_f32 v159, v138, v159
	v_cvt_pk_bf16_f32 v155, v160, v155
	v_cvt_pk_bf16_f32 v158, v149, v158
	v_cvt_pk_bf16_f32 v154, v161, v154
	v_mov_b32_e32 v156, v154
	v_mov_b32_e32 v154, v158
	v_add_co_u32_e32 v158, vcc, s91, v150
	v_mov_b32_e32 v157, v155
	v_mov_b32_e32 v155, v159
	v_addc_co_u32_e32 v159, vcc, 0, v151, vcc
	v_mul_f32_e32 v138, 0xbfb8aa3b, v22
	global_store_dwordx4 v[158:159], v[154:157], off
	s_nop 1
	v_exp_f32_e32 v154, v138
	v_mul_f32_e32 v138, 0xbfb8aa3b, v23
	v_exp_f32_e32 v156, v138
	v_mul_f32_e32 v138, 0xbfb8aa3b, v24
	v_exp_f32_e32 v155, v138
	v_mul_f32_e32 v138, 0xbfb8aa3b, v25
	v_exp_f32_e32 v157, v138
	v_pk_add_f32 v[154:155], v[154:155], 1.0 op_sel_hi:[1,0]
	s_nop 0
	v_rcp_f32_e32 v149, v155
	s_nop 0
	v_mul_f32_e32 v138, v24, v149
	v_rcp_f32_e32 v155, v154
	s_nop 0
	v_mul_f32_e32 v149, v22, v155
	v_pk_add_f32 v[154:155], v[156:157], 1.0 op_sel_hi:[1,0]
	s_nop 0
	v_rcp_f32_e32 v157, v154
	s_nop 0
	v_mul_f32_e32 v158, v23, v157
	v_rcp_f32_e32 v156, v155
	s_nop 0
	v_mul_f32_e32 v159, v25, v156
	v_mul_f32_e32 v155, 0xbfb8aa3b, v19
	v_mul_f32_e32 v154, 0xbfb8aa3b, v18
	v_exp_f32_e32 v156, v155
	v_mul_f32_e32 v155, 0xbfb8aa3b, v20
	v_exp_f32_e32 v154, v154
	v_exp_f32_e32 v155, v155
	v_mul_f32_e32 v157, 0xbfb8aa3b, v21
	v_exp_f32_e32 v157, v157
	v_pk_add_f32 v[154:155], v[154:155], 1.0 op_sel_hi:[1,0]
	s_nop 0
	v_rcp_f32_e32 v161, v155
	s_nop 0
	v_mul_f32_e32 v160, v20, v161
	v_rcp_f32_e32 v161, v154
	s_nop 0
	v_mul_f32_e32 v161, v18, v161
	v_pk_add_f32 v[154:155], v[156:157], 1.0 op_sel_hi:[1,0]
	s_nop 0
	v_rcp_f32_e32 v157, v154
	s_nop 0
	v_mul_f32_e32 v154, v19, v157
	v_rcp_f32_e32 v157, v155
	s_nop 0
	v_mul_f32_e32 v155, v21, v157
	v_cvt_pk_bf16_f32 v158, v149, v158
	v_cvt_pk_bf16_f32 v159, v138, v159
	v_cvt_pk_bf16_f32 v154, v161, v154
	v_cvt_pk_bf16_f32 v155, v160, v155
	v_mov_b32_e32 v157, v155
	v_mov_b32_e32 v156, v154
	v_mov_b32_e32 v155, v159
	v_mov_b32_e32 v154, v158
	v_mul_f32_e32 v138, 0xbfb8aa3b, v14
	global_store_dwordx4 v[152:153], v[154:157], off offset:256
	v_lshl_add_u64 v[152:153], v[150:151], 0, s[20:21]
	s_nop 0
	v_exp_f32_e32 v154, v138
	v_mul_f32_e32 v138, 0xbfb8aa3b, v15
	v_exp_f32_e32 v156, v138
	v_mul_f32_e32 v138, 0xbfb8aa3b, v16
	v_exp_f32_e32 v155, v138
	v_mul_f32_e32 v138, 0xbfb8aa3b, v17
	v_exp_f32_e32 v157, v138
	v_pk_add_f32 v[154:155], v[154:155], 1.0 op_sel_hi:[1,0]
	s_nop 0
	v_rcp_f32_e32 v149, v155
	s_nop 0
	v_mul_f32_e32 v138, v16, v149
	v_rcp_f32_e32 v155, v154
	s_nop 0
	v_mul_f32_e32 v149, v14, v155
	v_pk_add_f32 v[154:155], v[156:157], 1.0 op_sel_hi:[1,0]
	s_nop 0
	v_rcp_f32_e32 v157, v154
	s_nop 0
	v_mul_f32_e32 v158, v15, v157
	v_rcp_f32_e32 v156, v155
	s_nop 0
	v_mul_f32_e32 v159, v17, v156
	v_mul_f32_e32 v155, 0xbfb8aa3b, v11
	v_mul_f32_e32 v154, 0xbfb8aa3b, v10
	v_exp_f32_e32 v156, v155
	v_mul_f32_e32 v155, 0xbfb8aa3b, v12
	v_exp_f32_e32 v154, v154
	v_exp_f32_e32 v155, v155
	v_mul_f32_e32 v157, 0xbfb8aa3b, v13
	v_exp_f32_e32 v157, v157
	v_pk_add_f32 v[154:155], v[154:155], 1.0 op_sel_hi:[1,0]
	s_nop 0
	v_rcp_f32_e32 v161, v155
	s_nop 0
	v_mul_f32_e32 v160, v12, v161
	v_rcp_f32_e32 v161, v154
	s_nop 0
	v_mul_f32_e32 v161, v10, v161
	v_pk_add_f32 v[154:155], v[156:157], 1.0 op_sel_hi:[1,0]
	s_nop 0
	v_rcp_f32_e32 v157, v154
	s_nop 0
	v_mul_f32_e32 v154, v11, v157
	v_rcp_f32_e32 v157, v155
	s_nop 0
	v_mul_f32_e32 v155, v13, v157
	v_cvt_pk_bf16_f32 v158, v149, v158
	v_cvt_pk_bf16_f32 v159, v138, v159
	v_cvt_pk_bf16_f32 v154, v161, v154
	v_cvt_pk_bf16_f32 v155, v160, v155
	v_add_co_u32_e32 v150, vcc, s92, v150
	v_mov_b32_e32 v157, v155
	v_mov_b32_e32 v156, v154
	v_mov_b32_e32 v155, v159
	v_mov_b32_e32 v154, v158
	v_addc_co_u32_e32 v151, vcc, 0, v151, vcc
	v_mul_f32_e32 v138, 0xbfb8aa3b, v6
	global_store_dwordx4 v[150:151], v[154:157], off
	v_exp_f32_e32 v150, v138
	v_mul_f32_e32 v138, 0xbfb8aa3b, v7
	v_exp_f32_e32 v154, v138
	v_mul_f32_e32 v138, 0xbfb8aa3b, v8
	v_exp_f32_e32 v151, v138
	v_mul_f32_e32 v138, 0xbfb8aa3b, v9
	v_exp_f32_e32 v155, v138
	v_pk_add_f32 v[150:151], v[150:151], 1.0 op_sel_hi:[1,0]
	s_nop 0
	v_rcp_f32_e32 v149, v151
	s_nop 0
	v_mul_f32_e32 v138, v8, v149
	v_rcp_f32_e32 v151, v150
	s_nop 0
	v_mul_f32_e32 v149, v6, v151
	v_pk_add_f32 v[150:151], v[154:155], 1.0 op_sel_hi:[1,0]
	s_nop 0
	v_rcp_f32_e32 v155, v150
	s_nop 0
	v_mul_f32_e32 v156, v7, v155
	v_rcp_f32_e32 v154, v151
	s_nop 0
	v_mul_f32_e32 v157, v9, v154
	v_mul_f32_e32 v151, 0xbfb8aa3b, v3
	v_mul_f32_e32 v150, 0xbfb8aa3b, v2
	v_exp_f32_e32 v154, v151
	v_mul_f32_e32 v151, 0xbfb8aa3b, v4
	v_exp_f32_e32 v150, v150
	v_exp_f32_e32 v151, v151
	v_mul_f32_e32 v155, 0xbfb8aa3b, v5
	v_exp_f32_e32 v155, v155
	v_pk_add_f32 v[150:151], v[150:151], 1.0 op_sel_hi:[1,0]
	s_nop 0
	v_rcp_f32_e32 v159, v151
	s_nop 0
	v_mul_f32_e32 v158, v4, v159
	v_rcp_f32_e32 v159, v150
	s_nop 0
	v_mul_f32_e32 v159, v2, v159
	v_pk_add_f32 v[150:151], v[154:155], 1.0 op_sel_hi:[1,0]
	s_nop 0
	v_rcp_f32_e32 v155, v150
	s_nop 0
	v_mul_f32_e32 v150, v3, v155
	v_rcp_f32_e32 v155, v151
	s_mov_b64 s[0:1], 0
	v_mul_f32_e32 v151, v5, v155
	v_bfe_u32 v160, v157, 16, 1
	v_bfe_u32 v161, v156, 16, 1
	v_add3_u32 v161, v156, v161, s87
	v_add3_u32 v160, v157, v160, s87
	v_cvt_pk_bf16_f32 v150, v159, v150
	v_cvt_pk_bf16_f32 v151, v158, v151
	v_bfe_u32 v154, v149, 16, 1
	v_bfe_u32 v155, v138, 16, 1
	v_add3_u32 v138, v138, v155, s87
	v_add3_u32 v149, v149, v154, s87
	v_lshrrev_b32_e32 v149, 16, v149
	v_lshrrev_b32_e32 v138, 16, v138
	v_mov_b32_e32 v157, v151
	v_mov_b32_e32 v156, v150
	v_and_or_b32 v155, v160, s88, v138
	v_and_or_b32 v154, v161, s88, v149
	global_store_dwordx4 v[152:153], v[154:157], off offset:256
.LBB0_177:
	s_andn2_b64 vcc, exec, s[0:1]
	s_cbranch_vccnz .LBB0_179
	v_readlane_b32 s36, v254, 4
	v_lshlrev_b32_e32 v138, 2, v192
	v_readlane_b32 s40, v254, 8
	v_readlane_b32 s41, v254, 9
	s_waitcnt lgkmcnt(0)
	s_nop 3
	global_load_dwordx4 v[150:153], v138, s[40:41] offset:16
	global_load_dwordx4 v[154:157], v138, s[40:41]
	global_load_dwordx4 v[158:161], v138, s[40:41] offset:2064
	global_load_dwordx4 v[162:165], v138, s[40:41] offset:2048
	v_readlane_b32 s0, v254, 31
	v_readlane_b32 s1, v254, 32
	s_movk_i32 s23, 0x2080
	v_readlane_b32 s37, v254, 5
	v_cmp_gt_i32_e32 vcc, s93, v148
	v_readlane_b32 s38, v254, 6
	v_readlane_b32 s39, v254, 7
	v_readlane_b32 s42, v254, 10
	v_readlane_b32 s43, v254, 11
	v_readlane_b32 s44, v254, 12
	v_readlane_b32 s45, v254, 13
	v_readlane_b32 s46, v254, 14
	v_readlane_b32 s47, v254, 15
	v_readlane_b32 s48, v254, 16
	v_readlane_b32 s49, v254, 17
	v_readlane_b32 s50, v254, 18
	v_readlane_b32 s51, v254, 19
	s_waitcnt vmcnt(0)
	v_sub_f32_e32 v149, v154, v162
	v_mul_f32_e32 v149, 0x3fb8aa3b, v149
	v_exp_f32_e32 v176, v149
	v_sub_f32_e32 v149, v155, v163
	v_mul_f32_e32 v149, 0x3fb8aa3b, v149
	v_exp_f32_e32 v174, v149
	v_sub_f32_e32 v149, v156, v164
	v_mul_f32_e32 v149, 0x3fb8aa3b, v149
	v_exp_f32_e32 v177, v149
	v_sub_f32_e32 v149, v157, v165
	v_mul_f32_e32 v149, 0x3fb8aa3b, v149
	v_exp_f32_e32 v175, v149
	v_sub_f32_e32 v149, v150, v158
	v_mul_f32_e32 v149, 0x3fb8aa3b, v149
	v_exp_f32_e32 v168, v149
	v_sub_f32_e32 v149, v151, v159
	v_mul_f32_e32 v149, 0x3fb8aa3b, v149
	v_exp_f32_e32 v166, v149
	v_sub_f32_e32 v149, v152, v160
	v_mul_f32_e32 v149, 0x3fb8aa3b, v149
	v_exp_f32_e32 v169, v149
	v_sub_f32_e32 v149, v153, v161
	global_load_dwordx4 v[150:153], v138, s[40:41] offset:528
	global_load_dwordx4 v[154:157], v138, s[40:41] offset:512
	global_load_dwordx4 v[170:173], v138, s[40:41] offset:2576
	global_load_dwordx4 v[158:161], v138, s[40:41] offset:2560
	v_mul_f32_e32 v149, 0x3fb8aa3b, v149
	v_pk_add_f32 v[176:177], v[176:177], 1.0 op_sel_hi:[1,0]
	v_exp_f32_e32 v167, v149
	v_ashrrev_i32_e32 v149, 31, v148
	v_pk_add_f32 v[174:175], v[174:175], 1.0 op_sel_hi:[1,0]
	v_pk_add_f32 v[168:169], v[168:169], 1.0 op_sel_hi:[1,0]
	v_pk_add_f32 v[166:167], v[166:167], 1.0 op_sel_hi:[1,0]
	s_waitcnt vmcnt(0)
	v_sub_f32_e32 v138, v154, v158
	v_mul_f32_e32 v138, 0x3fb8aa3b, v138
	v_exp_f32_e32 v164, v138
	v_sub_f32_e32 v138, v155, v159
	v_mul_f32_e32 v138, 0x3fb8aa3b, v138
	v_exp_f32_e32 v162, v138
	v_sub_f32_e32 v138, v156, v160
	v_mul_f32_e32 v138, 0x3fb8aa3b, v138
	v_exp_f32_e32 v165, v138
	v_sub_f32_e32 v138, v157, v161
	v_mul_f32_e32 v138, 0x3fb8aa3b, v138
	v_exp_f32_e32 v163, v138
	v_sub_f32_e32 v138, v150, v170
	v_mul_f32_e32 v138, 0x3fb8aa3b, v138
	v_exp_f32_e32 v160, v138
	v_sub_f32_e32 v138, v151, v171
	v_mul_f32_e32 v138, 0x3fb8aa3b, v138
	v_exp_f32_e32 v158, v138
	v_sub_f32_e32 v138, v152, v172
	v_mul_f32_e32 v138, 0x3fb8aa3b, v138
	v_exp_f32_e32 v161, v138
	v_sub_f32_e32 v138, v153, v173
	v_mul_f32_e32 v138, 0x3fb8aa3b, v138
	v_exp_f32_e32 v159, v138
	v_lshlrev_b32_e32 v138, 1, v192
	v_lshl_add_u64 v[152:153], s[0:1], 0, v[138:139]
	v_cmp_gt_i32_e64 s[0:1], s23, v148
	v_lshl_add_u64 v[150:151], s[30:31], 0, v[138:139]
	v_lshlrev_b64 v[154:155], 10, v[148:149]
	v_cndmask_b32_e64 v138, v189, 0, s[0:1]
	v_add_u32_e32 v138, v138, v148
	v_cmp_gt_i32_e64 s[0:1], s95, v138
	v_mul_f32_e32 v138, 0x3fb8aa3b, v126
	v_exp_f32_e32 v180, v138
	v_mul_f32_e32 v138, 0x3fb8aa3b, v127
	v_exp_f32_e32 v178, v138
	v_mul_f32_e32 v138, 0x3fb8aa3b, v128
	v_exp_f32_e32 v181, v138
	v_mul_f32_e32 v138, 0x3fb8aa3b, v129
	v_exp_f32_e32 v179, v138
	v_mul_f32_e32 v138, 0x3fb8aa3b, v122
	v_exp_f32_e32 v172, v138
	v_mul_f32_e32 v138, 0x3fb8aa3b, v123
	v_exp_f32_e32 v170, v138
	v_mul_f32_e32 v138, 0x3fb8aa3b, v124
	v_exp_f32_e32 v173, v138
	v_mul_f32_e32 v138, 0x3fb8aa3b, v125
	s_and_b64 s[36:37], vcc, s[0:1]
	v_exp_f32_e32 v171, v138
	v_rcp_f32_e32 v149, v176
	v_pk_add_f32 v[180:181], v[180:181], 1.0 op_sel_hi:[1,0]
	v_pk_add_f32 v[178:179], v[178:179], 1.0 op_sel_hi:[1,0]
	v_lshl_add_u64 v[156:157], v[150:151], 0, v[154:155]
	v_rcp_f32_e32 v176, v177
	v_pk_add_f32 v[164:165], v[164:165], 1.0 op_sel_hi:[1,0]
	v_pk_add_f32 v[162:163], v[162:163], 1.0 op_sel_hi:[1,0]
	v_lshl_add_u64 v[154:155], v[152:153], 0, v[154:155]
	v_rcp_f32_e32 v177, v174
	v_pk_add_f32 v[160:161], v[160:161], 1.0 op_sel_hi:[1,0]
	v_pk_add_f32 v[158:159], v[158:159], 1.0 op_sel_hi:[1,0]
	v_mov_b32_e32 v138, v177
	v_rcp_f32_e32 v177, v175
	s_nop 0
	v_mov_b32_e32 v174, v177
	v_rcp_f32_e32 v177, v181
	s_nop 0
	v_mul_f32_e32 v175, v176, v177
	v_rcp_f32_e32 v181, v180
	s_nop 0
	v_mul_f32_e32 v177, v149, v181
	v_sub_f32_e32 v180, 1.0, v177
	v_cmp_gt_f32_e32 vcc, s96, v180
	s_nop 1
	v_cndmask_b32_e64 v181, 0, 32, vcc
	v_ldexp_f32 v180, v180, v181
	v_log_f32_e32 v180, v180
	s_nop 0
	v_mul_f32_e32 v181, 0x3f317217, v180
	v_fma_f32 v181, v180, s97, -v181
	v_fmac_f32_e32 v181, 0x3377d1cf, v180
	v_fmac_f32_e32 v181, 0x3f317217, v180
	v_cmp_lt_f32_e64 s[0:1], |v180|, s94
	s_nop 1
	v_cndmask_b32_e64 v180, v180, v181, s[0:1]
	v_cndmask_b32_e32 v181, 0, v190, vcc
	v_sub_f32_e32 v180, v180, v181
	v_rcp_f32_e32 v193, v179
	s_nop 0
	v_mul_f32_e32 v179, v174, v193
	v_rcp_f32_e32 v193, v178
	v_cndmask_b32_e64 v198, v179, 0, s[36:37]
	v_bfe_u32 v201, v198, 16, 1
	v_add3_u32 v198, v198, v201, s87
	v_mul_f32_e32 v178, v138, v193
	v_sub_f32_e32 v181, 1.0, v178
	v_cmp_gt_f32_e32 vcc, s96, v181
	v_cndmask_b32_e64 v196, v177, 0, s[36:37]
	v_cndmask_b32_e64 v197, v178, 0, s[36:37]
	v_cndmask_b32_e64 v193, 0, 32, vcc
	v_ldexp_f32 v181, v181, v193
	v_log_f32_e32 v181, v181
	v_cvt_pk_bf16_f32 v197, v196, v197
	v_mul_f32_e32 v193, 0x3f317217, v181
	v_fma_f32 v193, v181, s97, -v193
	v_fmac_f32_e32 v193, 0x3377d1cf, v181
	v_fmac_f32_e32 v193, 0x3f317217, v181
	v_cmp_lt_f32_e64 s[0:1], |v181|, s94
	s_nop 1
	v_cndmask_b32_e64 v181, v181, v193, s[0:1]
	v_cndmask_b32_e32 v193, 0, v190, vcc
	v_sub_f32_e32 v181, v181, v193
	v_sub_f32_e32 v193, 1.0, v175
	v_cmp_gt_f32_e32 vcc, s96, v193
	s_nop 1
	v_cndmask_b32_e64 v194, 0, 32, vcc
	v_ldexp_f32 v193, v193, v194
	v_log_f32_e32 v193, v193
	s_nop 0
	v_mul_f32_e32 v194, 0x3f317217, v193
	v_fma_f32 v194, v193, s97, -v194
	v_fmac_f32_e32 v194, 0x3377d1cf, v193
	v_fmac_f32_e32 v194, 0x3f317217, v193
	v_cmp_lt_f32_e64 s[0:1], |v193|, s94
	s_nop 1
	v_cndmask_b32_e64 v193, v193, v194, s[0:1]
	v_cndmask_b32_e32 v194, 0, v190, vcc
	v_sub_f32_e32 v193, v193, v194
	v_sub_f32_e32 v194, 1.0, v179
	v_cmp_gt_f32_e32 vcc, s96, v194
	s_nop 1
	v_cndmask_b32_e64 v195, 0, 32, vcc
	v_ldexp_f32 v194, v194, v195
	v_log_f32_e32 v194, v194
	s_nop 0
	v_mul_f32_e32 v195, 0x3f317217, v194
	v_fma_f32 v195, v194, s97, -v195
	v_fmac_f32_e32 v195, 0x3377d1cf, v194
	v_fmac_f32_e32 v195, 0x3f317217, v194
	v_cmp_lt_f32_e64 s[0:1], |v194|, s94
	s_nop 1
	v_cndmask_b32_e64 v194, v194, v195, s[0:1]
	v_cndmask_b32_e32 v195, 0, v190, vcc
	v_sub_f32_e32 v194, v194, v195
	v_cndmask_b32_e64 v195, v175, 0, s[36:37]
	v_rcp_f32_e32 v177, v168
	s_nop 0
	v_rcp_f32_e32 v175, v169
	s_nop 0
	v_mov_b32_e32 v179, v175
	v_rcp_f32_e32 v169, v166
	s_nop 0
	v_mov_b32_e32 v175, v169
	v_rcp_f32_e32 v168, v167
	s_nop 0
	v_mov_b32_e32 v178, v168
	v_pk_add_f32 v[166:167], v[172:173], 1.0 op_sel_hi:[1,0]
	s_nop 0
	v_rcp_f32_e32 v169, v167
	s_nop 0
	v_mul_f32_e32 v168, v179, v169
	v_rcp_f32_e32 v169, v166
	s_nop 0
	v_mul_f32_e32 v169, v177, v169
	v_sub_f32_e32 v166, 1.0, v169
	v_cmp_gt_f32_e32 vcc, s96, v166
	v_cndmask_b32_e64 v169, v169, 0, s[36:37]
	v_bfe_u32 v201, v169, 16, 1
	v_cndmask_b32_e64 v167, 0, 32, vcc
	v_ldexp_f32 v166, v166, v167
	v_log_f32_e32 v166, v166
	v_add3_u32 v169, v169, v201, s87
	v_mul_f32_e32 v167, 0x3f317217, v166
	v_fma_f32 v167, v166, s97, -v167
	v_fmac_f32_e32 v167, 0x3377d1cf, v166
	v_fmac_f32_e32 v167, 0x3f317217, v166
	v_cmp_lt_f32_e64 s[0:1], |v166|, s94
	s_nop 1
	v_cndmask_b32_e64 v166, v166, v167, s[0:1]
	v_cndmask_b32_e32 v167, 0, v190, vcc
	v_sub_f32_e32 v172, v166, v167
	v_pk_add_f32 v[166:167], v[170:171], 1.0 op_sel_hi:[1,0]
	s_nop 0
	v_rcp_f32_e32 v171, v167
	s_nop 0
	v_mul_f32_e32 v167, v178, v171
	v_rcp_f32_e32 v171, v166
	s_nop 0
	v_mul_f32_e32 v166, v175, v171
	v_sub_f32_e32 v170, 1.0, v166
	v_cmp_gt_f32_e32 vcc, s96, v170
	v_cndmask_b32_e64 v166, v166, 0, s[36:37]
	v_bfe_u32 v200, v166, 16, 1
	v_cndmask_b32_e64 v171, 0, 32, vcc
	v_ldexp_f32 v170, v170, v171
	v_log_f32_e32 v170, v170
	v_add3_u32 v166, v166, v200, s87
	v_bfe_u32 v200, v195, 16, 1
	v_add3_u32 v195, v195, v200, s87
	v_mul_f32_e32 v171, 0x3f317217, v170
	v_fma_f32 v171, v170, s97, -v171
	v_fmac_f32_e32 v171, 0x3377d1cf, v170
	v_fmac_f32_e32 v171, 0x3f317217, v170
	v_cmp_lt_f32_e64 s[0:1], |v170|, s94
	v_lshrrev_b32_e32 v195, 16, v195
	s_nop 0
	v_cndmask_b32_e64 v170, v170, v171, s[0:1]
	v_cndmask_b32_e32 v171, 0, v190, vcc
	v_sub_f32_e32 v170, v170, v171
	v_sub_f32_e32 v171, 1.0, v168
	v_cmp_gt_f32_e32 vcc, s96, v171
	v_cndmask_b32_e64 v168, v168, 0, s[36:37]
	v_bfe_u32 v202, v168, 16, 1
	v_cndmask_b32_e64 v173, 0, 32, vcc
	v_ldexp_f32 v171, v171, v173
	v_log_f32_e32 v171, v171
	v_add3_u32 v168, v168, v202, s87
	v_lshrrev_b32_e32 v168, 16, v168
	v_mul_f32_e32 v173, 0x3f317217, v171
	v_fma_f32 v173, v171, s97, -v173
	v_fmac_f32_e32 v173, 0x3377d1cf, v171
	v_fmac_f32_e32 v173, 0x3f317217, v171
	v_cmp_lt_f32_e64 s[0:1], |v171|, s94
	s_nop 1
	v_cndmask_b32_e64 v171, v171, v173, s[0:1]
	v_cndmask_b32_e32 v173, 0, v190, vcc
	v_sub_f32_e32 v171, v171, v173
	v_sub_f32_e32 v173, 1.0, v167
	v_cmp_gt_f32_e32 vcc, s96, v173
	v_cndmask_b32_e64 v167, v167, 0, s[36:37]
	s_nop 0
	v_cndmask_b32_e64 v199, 0, 32, vcc
	v_ldexp_f32 v173, v173, v199
	v_log_f32_e32 v173, v173
	s_nop 0
	v_mul_f32_e32 v199, 0x3f317217, v173
	v_fma_f32 v199, v173, s97, -v199
	v_fmac_f32_e32 v199, 0x3377d1cf, v173
	v_fmac_f32_e32 v199, 0x3f317217, v173
	v_cmp_lt_f32_e64 s[0:1], |v173|, s94
	s_nop 1
	v_cndmask_b32_e64 v173, v173, v199, s[0:1]
	v_cndmask_b32_e32 v199, 0, v190, vcc
	v_sub_f32_e32 v173, v173, v199
	v_bfe_u32 v199, v167, 16, 1
	v_add3_u32 v167, v167, v199, s87
	v_lshrrev_b32_e32 v199, 16, v169
	v_and_or_b32 v169, v167, s88, v168
	v_and_or_b32 v168, v166, s88, v199
	v_and_or_b32 v167, v198, s88, v195
	v_mov_b32_e32 v166, v197
	global_store_dwordx4 v[156:157], v[166:169], off
	s_nop 1
	v_cndmask_b32_e64 v166, v180, 0, s[36:37]
	v_bfe_u32 v167, v166, 16, 1
	v_add3_u32 v166, v166, v167, s87
	v_cndmask_b32_e64 v167, v181, 0, s[36:37]
	v_rcp_f32_e32 v181, v164
	v_bfe_u32 v168, v167, 16, 1
	v_lshrrev_b32_e32 v166, 16, v166
	v_add3_u32 v167, v167, v168, s87
	v_and_or_b32 v166, v167, s88, v166
	v_cndmask_b32_e64 v167, v193, 0, s[36:37]
	v_bfe_u32 v168, v167, 16, 1
	v_add3_u32 v167, v167, v168, s87
	v_cndmask_b32_e64 v168, v194, 0, s[36:37]
	v_mov_b32_e32 v164, v181
	v_rcp_f32_e32 v181, v165
	v_bfe_u32 v169, v168, 16, 1
	v_lshrrev_b32_e32 v167, 16, v167
	v_add3_u32 v168, v168, v169, s87
	v_mov_b32_e32 v165, v181
	v_rcp_f32_e32 v181, v162
	v_and_or_b32 v167, v168, s88, v167
	v_cndmask_b32_e64 v168, v172, 0, s[36:37]
	v_bfe_u32 v169, v168, 16, 1
	v_add3_u32 v168, v168, v169, s87
	v_cndmask_b32_e64 v169, v170, 0, s[36:37]
	v_bfe_u32 v170, v169, 16, 1
	v_lshrrev_b32_e32 v168, 16, v168
	v_add3_u32 v169, v169, v170, s87
	v_and_or_b32 v168, v169, s88, v168
	v_cndmask_b32_e64 v169, v171, 0, s[36:37]
	v_bfe_u32 v170, v169, 16, 1
	v_add3_u32 v169, v169, v170, s87
	v_cndmask_b32_e64 v170, v173, 0, s[36:37]
	v_mov_b32_e32 v162, v181
	v_bfe_u32 v171, v170, 16, 1
	v_rcp_f32_e32 v181, v163
	v_lshrrev_b32_e32 v169, 16, v169
	v_add3_u32 v170, v170, v171, s87
	v_and_or_b32 v169, v170, s88, v169
	global_store_dwordx4 v[154:155], v[166:169], off
	s_nop 1
	v_mul_f32_e32 v166, 0x3fb8aa3b, v118
	v_exp_f32_e32 v172, v166
	v_mul_f32_e32 v166, 0x3fb8aa3b, v119
	v_exp_f32_e32 v170, v166
	v_mul_f32_e32 v166, 0x3fb8aa3b, v120
	v_exp_f32_e32 v173, v166
	s_nop 0
	v_pk_add_f32 v[172:173], v[172:173], 1.0 op_sel_hi:[1,0]
	v_mov_b32_e32 v163, v181
	v_rcp_f32_e32 v181, v173
	v_mul_f32_e32 v166, 0x3fb8aa3b, v121
	v_exp_f32_e32 v171, v166
	v_mul_f32_e32 v166, 0x3fb8aa3b, v114
	v_mul_f32_e32 v173, v165, v181
	v_rcp_f32_e32 v181, v172
	v_pk_add_f32 v[170:171], v[170:171], 1.0 op_sel_hi:[1,0]
	v_mul_f32_e32 v167, 0x3fb8aa3b, v116
	v_exp_f32_e32 v168, v166
	v_mul_f32_e32 v172, v164, v181
	v_sub_f32_e32 v180, 1.0, v172
	v_cmp_gt_f32_e32 vcc, s96, v180
	v_exp_f32_e32 v169, v167
	v_mul_f32_e32 v166, 0x3fb8aa3b, v115
	v_cndmask_b32_e64 v181, 0, 32, vcc
	v_ldexp_f32 v180, v180, v181
	v_log_f32_e32 v180, v180
	v_mul_f32_e32 v167, 0x3fb8aa3b, v117
	v_exp_f32_e32 v166, v166
	v_exp_f32_e32 v167, v167
	v_mul_f32_e32 v181, 0x3f317217, v180
	v_fma_f32 v181, v180, s97, -v181
	v_fmac_f32_e32 v181, 0x3377d1cf, v180
	v_fmac_f32_e32 v181, 0x3f317217, v180
	v_cmp_lt_f32_e64 s[0:1], |v180|, s94
	s_nop 1
	v_cndmask_b32_e64 v180, v180, v181, s[0:1]
	v_cndmask_b32_e32 v181, 0, v190, vcc
	v_sub_f32_e32 v180, v180, v181
	v_rcp_f32_e32 v193, v171
	s_nop 0
	v_mul_f32_e32 v171, v163, v193
	v_rcp_f32_e32 v193, v170
	v_cndmask_b32_e64 v198, v171, 0, s[36:37]
	v_bfe_u32 v201, v198, 16, 1
	v_add3_u32 v198, v198, v201, s87
	v_mul_f32_e32 v170, v162, v193
	v_sub_f32_e32 v181, 1.0, v170
	v_cmp_gt_f32_e32 vcc, s96, v181
	v_cndmask_b32_e64 v197, v170, 0, s[36:37]
	v_cndmask_b32_e64 v196, v172, 0, s[36:37]
	v_cndmask_b32_e64 v193, 0, 32, vcc
	v_ldexp_f32 v181, v181, v193
	v_log_f32_e32 v181, v181
	v_cvt_pk_bf16_f32 v197, v196, v197
	v_mul_f32_e32 v193, 0x3f317217, v181
	v_fma_f32 v193, v181, s97, -v193
	v_fmac_f32_e32 v193, 0x3377d1cf, v181
	v_fmac_f32_e32 v193, 0x3f317217, v181
	v_cmp_lt_f32_e64 s[0:1], |v181|, s94
	s_nop 1
	v_cndmask_b32_e64 v181, v181, v193, s[0:1]
	v_cndmask_b32_e32 v193, 0, v190, vcc
	v_sub_f32_e32 v181, v181, v193
	v_sub_f32_e32 v193, 1.0, v173
	v_cmp_gt_f32_e32 vcc, s96, v193
	s_nop 1
	v_cndmask_b32_e64 v194, 0, 32, vcc
	v_ldexp_f32 v193, v193, v194
	v_log_f32_e32 v193, v193
	s_nop 0
	v_mul_f32_e32 v194, 0x3f317217, v193
	v_fma_f32 v194, v193, s97, -v194
	v_fmac_f32_e32 v194, 0x3377d1cf, v193
	v_fmac_f32_e32 v194, 0x3f317217, v193
	v_cmp_lt_f32_e64 s[0:1], |v193|, s94
	s_nop 1
	v_cndmask_b32_e64 v193, v193, v194, s[0:1]
	v_cndmask_b32_e32 v194, 0, v190, vcc
	v_sub_f32_e32 v193, v193, v194
	v_sub_f32_e32 v194, 1.0, v171
	v_cmp_gt_f32_e32 vcc, s96, v194
	s_nop 1
	v_cndmask_b32_e64 v195, 0, 32, vcc
	v_ldexp_f32 v194, v194, v195
	v_log_f32_e32 v194, v194
	s_nop 0
	v_mul_f32_e32 v195, 0x3f317217, v194
	v_fma_f32 v195, v194, s97, -v195
	v_fmac_f32_e32 v195, 0x3377d1cf, v194
	v_fmac_f32_e32 v195, 0x3f317217, v194
	v_cmp_lt_f32_e64 s[0:1], |v194|, s94
	s_nop 1
	v_cndmask_b32_e64 v194, v194, v195, s[0:1]
	v_rcp_f32_e32 v171, v160
	v_cndmask_b32_e32 v195, 0, v190, vcc
	v_sub_f32_e32 v194, v194, v195
	v_cndmask_b32_e64 v195, v173, 0, s[36:37]
	v_rcp_f32_e32 v170, v161
	s_nop 0
	v_mov_b32_e32 v173, v170
	v_rcp_f32_e32 v161, v158
	s_nop 0
	v_mov_b32_e32 v170, v161
	v_rcp_f32_e32 v160, v159
	s_nop 0
	v_mov_b32_e32 v172, v160
	v_pk_add_f32 v[158:159], v[168:169], 1.0 op_sel_hi:[1,0]
	s_nop 0
	v_rcp_f32_e32 v161, v159
	s_nop 0
	v_mul_f32_e32 v160, v173, v161
	v_rcp_f32_e32 v161, v158
	s_nop 0
	v_mul_f32_e32 v161, v171, v161
	v_sub_f32_e32 v158, 1.0, v161
	v_cmp_gt_f32_e32 vcc, s96, v158
	v_cndmask_b32_e64 v161, v161, 0, s[36:37]
	v_bfe_u32 v201, v161, 16, 1
	v_cndmask_b32_e64 v159, 0, 32, vcc
	v_ldexp_f32 v158, v158, v159
	v_log_f32_e32 v158, v158
	v_add3_u32 v161, v161, v201, s87
	v_mul_f32_e32 v159, 0x3f317217, v158
	v_fma_f32 v159, v158, s97, -v159
	v_fmac_f32_e32 v159, 0x3377d1cf, v158
	v_fmac_f32_e32 v159, 0x3f317217, v158
	v_cmp_lt_f32_e64 s[0:1], |v158|, s94
	s_nop 1
	v_cndmask_b32_e64 v158, v158, v159, s[0:1]
	v_cndmask_b32_e32 v159, 0, v190, vcc
	v_sub_f32_e32 v168, v158, v159
	v_pk_add_f32 v[158:159], v[166:167], 1.0 op_sel_hi:[1,0]
	s_nop 0
	v_rcp_f32_e32 v167, v159
	s_nop 0
	v_mul_f32_e32 v159, v172, v167
	v_rcp_f32_e32 v167, v158
	s_nop 0
	v_mul_f32_e32 v158, v170, v167
	v_sub_f32_e32 v166, 1.0, v158
	v_cmp_gt_f32_e32 vcc, s96, v166
	v_cndmask_b32_e64 v158, v158, 0, s[36:37]
	v_bfe_u32 v200, v158, 16, 1
	v_cndmask_b32_e64 v167, 0, 32, vcc
	v_ldexp_f32 v166, v166, v167
	v_log_f32_e32 v166, v166
	v_add3_u32 v158, v158, v200, s87
	v_bfe_u32 v200, v195, 16, 1
	v_add3_u32 v195, v195, v200, s87
	v_mul_f32_e32 v167, 0x3f317217, v166
	v_fma_f32 v167, v166, s97, -v167
	v_fmac_f32_e32 v167, 0x3377d1cf, v166
	v_fmac_f32_e32 v167, 0x3f317217, v166
	v_cmp_lt_f32_e64 s[0:1], |v166|, s94
	v_lshrrev_b32_e32 v195, 16, v195
	s_nop 0
	v_cndmask_b32_e64 v166, v166, v167, s[0:1]
	v_cndmask_b32_e32 v167, 0, v190, vcc
	v_sub_f32_e32 v166, v166, v167
	v_sub_f32_e32 v167, 1.0, v160
	v_cmp_gt_f32_e32 vcc, s96, v167
	v_cndmask_b32_e64 v160, v160, 0, s[36:37]
	v_bfe_u32 v202, v160, 16, 1
	v_cndmask_b32_e64 v169, 0, 32, vcc
	v_ldexp_f32 v167, v167, v169
	v_log_f32_e32 v167, v167
	v_add3_u32 v160, v160, v202, s87
	v_lshrrev_b32_e32 v160, 16, v160
	v_mul_f32_e32 v169, 0x3f317217, v167
	v_fma_f32 v169, v167, s97, -v169
	v_fmac_f32_e32 v169, 0x3377d1cf, v167
	v_fmac_f32_e32 v169, 0x3f317217, v167
	v_cmp_lt_f32_e64 s[0:1], |v167|, s94
	s_nop 1
	v_cndmask_b32_e64 v167, v167, v169, s[0:1]
	v_cndmask_b32_e32 v169, 0, v190, vcc
	v_sub_f32_e32 v167, v167, v169
	v_sub_f32_e32 v169, 1.0, v159
	v_cmp_gt_f32_e32 vcc, s96, v169
	v_cndmask_b32_e64 v159, v159, 0, s[36:37]
	s_nop 0
	v_cndmask_b32_e64 v199, 0, 32, vcc
	v_ldexp_f32 v169, v169, v199
	v_log_f32_e32 v169, v169
	s_nop 0
	v_mul_f32_e32 v199, 0x3f317217, v169
	v_fma_f32 v199, v169, s97, -v199
	v_fmac_f32_e32 v199, 0x3377d1cf, v169
	v_fmac_f32_e32 v199, 0x3f317217, v169
	v_cmp_lt_f32_e64 s[0:1], |v169|, s94
	s_nop 1
	v_cndmask_b32_e64 v169, v169, v199, s[0:1]
	v_cndmask_b32_e32 v199, 0, v190, vcc
	v_sub_f32_e32 v169, v169, v199
	v_bfe_u32 v199, v159, 16, 1
	v_add3_u32 v159, v159, v199, s87
	v_lshrrev_b32_e32 v199, 16, v161
	v_and_or_b32 v161, v159, s88, v160
	v_and_or_b32 v160, v158, s88, v199
	v_and_or_b32 v159, v198, s88, v195
	v_mov_b32_e32 v158, v197
	global_store_dwordx4 v[156:157], v[158:161], off offset:256
	v_cndmask_b32_e64 v156, v180, 0, s[36:37]
	v_bfe_u32 v157, v156, 16, 1
	v_add3_u32 v156, v156, v157, s87
	v_cndmask_b32_e64 v157, v181, 0, s[36:37]
	v_bfe_u32 v158, v157, 16, 1
	v_lshrrev_b32_e32 v156, 16, v156
	v_add3_u32 v157, v157, v158, s87
	v_and_or_b32 v156, v157, s88, v156
	v_cndmask_b32_e64 v157, v193, 0, s[36:37]
	v_bfe_u32 v158, v157, 16, 1
	v_add3_u32 v157, v157, v158, s87
	v_cndmask_b32_e64 v158, v194, 0, s[36:37]
	v_bfe_u32 v159, v158, 16, 1
	v_lshrrev_b32_e32 v157, 16, v157
	v_add3_u32 v158, v158, v159, s87
	v_and_or_b32 v157, v158, s88, v157
	v_cndmask_b32_e64 v158, v168, 0, s[36:37]
	v_bfe_u32 v159, v158, 16, 1
	v_add3_u32 v158, v158, v159, s87
	v_cndmask_b32_e64 v159, v166, 0, s[36:37]
	v_bfe_u32 v160, v159, 16, 1
	v_lshrrev_b32_e32 v158, 16, v158
	v_add3_u32 v159, v159, v160, s87
	v_and_or_b32 v158, v159, s88, v158
	v_cndmask_b32_e64 v159, v167, 0, s[36:37]
	v_bfe_u32 v160, v159, 16, 1
	v_add3_u32 v159, v159, v160, s87
	v_cndmask_b32_e64 v160, v169, 0, s[36:37]
	v_bfe_u32 v161, v160, 16, 1
	v_lshrrev_b32_e32 v159, 16, v159
	v_add3_u32 v160, v160, v161, s87
	v_and_or_b32 v159, v160, s88, v159
	global_store_dwordx4 v[154:155], v[156:159], off offset:256
	v_or_b32_e32 v154, 16, v148
	v_cmp_gt_i32_e64 s[0:1], s23, v154
	v_mul_f32_e32 v158, 0x3fb8aa3b, v110
	v_exp_f32_e32 v166, v158
	v_mul_f32_e32 v158, 0x3fb8aa3b, v111
	v_exp_f32_e32 v168, v158
	v_mul_f32_e32 v158, 0x3fb8aa3b, v112
	v_exp_f32_e32 v167, v158
	v_cndmask_b32_e64 v155, v189, 0, s[0:1]
	v_add_u32_e32 v155, v155, v154
	v_cmp_gt_i32_e32 vcc, s93, v154
	v_cmp_gt_i32_e64 s[0:1], s95, v155
	v_pk_add_f32 v[166:167], v[166:167], 1.0 op_sel_hi:[1,0]
	s_and_b64 s[36:37], vcc, s[0:1]
	v_rcp_f32_e32 v181, v167
	v_mul_f32_e32 v158, 0x3fb8aa3b, v113
	v_exp_f32_e32 v169, v158
	v_mul_f32_e32 v158, 0x3fb8aa3b, v106
	v_mul_f32_e32 v167, v176, v181
	v_rcp_f32_e32 v181, v166
	v_pk_add_f32 v[168:169], v[168:169], 1.0 op_sel_hi:[1,0]
	v_mul_f32_e32 v159, 0x3fb8aa3b, v108
	v_exp_f32_e32 v160, v158
	v_mul_f32_e32 v180, v149, v181
	v_sub_f32_e32 v166, 1.0, v180
	v_cmp_gt_f32_e32 vcc, s96, v166
	v_exp_f32_e32 v161, v159
	v_mul_f32_e32 v158, 0x3fb8aa3b, v107
	v_cndmask_b32_e64 v181, 0, 32, vcc
	v_ldexp_f32 v166, v166, v181
	v_log_f32_e32 v166, v166
	v_pk_add_f32 v[160:161], v[160:161], 1.0 op_sel_hi:[1,0]
	v_mul_f32_e32 v159, 0x3fb8aa3b, v109
	v_exp_f32_e32 v158, v158
	v_mul_f32_e32 v181, 0x3f317217, v166
	v_fma_f32 v181, v166, s97, -v181
	v_fmac_f32_e32 v181, 0x3377d1cf, v166
	v_fmac_f32_e32 v181, 0x3f317217, v166
	v_cmp_lt_f32_e64 s[0:1], |v166|, s94
	v_exp_f32_e32 v159, v159
	v_cndmask_b32_e64 v180, v180, 0, s[36:37]
	v_cndmask_b32_e64 v166, v166, v181, s[0:1]
	v_cndmask_b32_e32 v181, 0, v190, vcc
	v_sub_f32_e32 v166, v166, v181
	v_rcp_f32_e32 v193, v169
	v_pk_add_f32 v[158:159], v[158:159], 1.0 op_sel_hi:[1,0]
	v_ashrrev_i32_e32 v155, 31, v154
	v_lshlrev_b64 v[154:155], 10, v[154:155]
	v_mul_f32_e32 v169, v174, v193
	v_rcp_f32_e32 v193, v168
	v_lshl_add_u64 v[156:157], v[150:151], 0, v[154:155]
	v_lshl_add_u64 v[154:155], v[152:153], 0, v[154:155]
	v_mul_f32_e32 v168, v138, v193
	v_sub_f32_e32 v181, 1.0, v168
	v_cmp_gt_f32_e32 vcc, s96, v181
	v_cndmask_b32_e64 v168, v168, 0, s[36:37]
	s_nop 0
	v_cndmask_b32_e64 v193, 0, 32, vcc
	v_ldexp_f32 v181, v181, v193
	v_log_f32_e32 v181, v181
	v_cvt_pk_bf16_f32 v168, v180, v168
	v_mul_f32_e32 v193, 0x3f317217, v181
	v_fma_f32 v193, v181, s97, -v193
	v_fmac_f32_e32 v193, 0x3377d1cf, v181
	v_fmac_f32_e32 v193, 0x3f317217, v181
	v_cmp_lt_f32_e64 s[0:1], |v181|, s94
	s_nop 1
	v_cndmask_b32_e64 v181, v181, v193, s[0:1]
	v_cndmask_b32_e32 v193, 0, v190, vcc
	v_sub_f32_e32 v181, v181, v193
	v_sub_f32_e32 v193, 1.0, v167
	v_cmp_gt_f32_e32 vcc, s96, v193
	v_cndmask_b32_e64 v167, v167, 0, s[36:37]
	s_nop 0
	v_cndmask_b32_e64 v194, 0, 32, vcc
	v_ldexp_f32 v193, v193, v194
	v_log_f32_e32 v193, v193
	s_nop 0
	v_mul_f32_e32 v194, 0x3f317217, v193
	v_fma_f32 v194, v193, s97, -v194
	v_fmac_f32_e32 v194, 0x3377d1cf, v193
	v_fmac_f32_e32 v194, 0x3f317217, v193
	v_cmp_lt_f32_e64 s[0:1], |v193|, s94
	s_nop 1
	v_cndmask_b32_e64 v193, v193, v194, s[0:1]
	v_cndmask_b32_e32 v194, 0, v190, vcc
	v_sub_f32_e32 v193, v193, v194
	v_sub_f32_e32 v194, 1.0, v169
	v_cmp_gt_f32_e32 vcc, s96, v194
	v_cndmask_b32_e64 v169, v169, 0, s[36:37]
	s_nop 0
	v_cndmask_b32_e64 v195, 0, 32, vcc
	v_ldexp_f32 v194, v194, v195
	v_log_f32_e32 v194, v194
	v_cvt_pk_bf16_f32 v169, v167, v169
	v_mul_f32_e32 v195, 0x3f317217, v194
	v_fma_f32 v195, v194, s97, -v195
	v_fmac_f32_e32 v195, 0x3377d1cf, v194
	v_fmac_f32_e32 v195, 0x3f317217, v194
	v_cmp_lt_f32_e64 s[0:1], |v194|, s94
	s_nop 1
	v_cndmask_b32_e64 v194, v194, v195, s[0:1]
	v_cndmask_b32_e32 v195, 0, v190, vcc
	v_sub_f32_e32 v194, v194, v195
	v_rcp_f32_e32 v196, v161
	s_nop 0
	v_mul_f32_e32 v161, v179, v196
	v_rcp_f32_e32 v196, v160
	s_nop 0
	v_mul_f32_e32 v160, v177, v196
	v_sub_f32_e32 v195, 1.0, v160
	v_cmp_gt_f32_e32 vcc, s96, v195
	v_cndmask_b32_e64 v160, v160, 0, s[36:37]
	v_bfe_u32 v201, v160, 16, 1
	v_cndmask_b32_e64 v196, 0, 32, vcc
	v_ldexp_f32 v195, v195, v196
	v_log_f32_e32 v195, v195
	v_add3_u32 v160, v160, v201, s87
	v_lshrrev_b32_e32 v160, 16, v160
	v_mul_f32_e32 v196, 0x3f317217, v195
	v_fma_f32 v196, v195, s97, -v196
	v_fmac_f32_e32 v196, 0x3377d1cf, v195
	v_fmac_f32_e32 v196, 0x3f317217, v195
	v_cmp_lt_f32_e64 s[0:1], |v195|, s94
	s_nop 1
	v_cndmask_b32_e64 v195, v195, v196, s[0:1]
	v_cndmask_b32_e32 v196, 0, v190, vcc
	v_sub_f32_e32 v195, v195, v196
	v_rcp_f32_e32 v197, v159
	s_nop 0
	v_mul_f32_e32 v159, v178, v197
	v_rcp_f32_e32 v197, v158
	s_nop 0
	v_mul_f32_e32 v158, v175, v197
	v_sub_f32_e32 v196, 1.0, v158
	v_cmp_gt_f32_e32 vcc, s96, v196
	v_cndmask_b32_e64 v158, v158, 0, s[36:37]
	v_bfe_u32 v200, v158, 16, 1
	v_cndmask_b32_e64 v197, 0, 32, vcc
	v_ldexp_f32 v196, v196, v197
	v_log_f32_e32 v196, v196
	v_add3_u32 v158, v158, v200, s87
	v_mul_f32_e32 v197, 0x3f317217, v196
	v_fma_f32 v197, v196, s97, -v197
	v_fmac_f32_e32 v197, 0x3377d1cf, v196
	v_fmac_f32_e32 v197, 0x3f317217, v196
	v_cmp_lt_f32_e64 s[0:1], |v196|, s94
	v_and_or_b32 v160, v158, s88, v160
	s_nop 0
	v_cndmask_b32_e64 v196, v196, v197, s[0:1]
	v_cndmask_b32_e32 v197, 0, v190, vcc
	v_sub_f32_e32 v196, v196, v197
	v_sub_f32_e32 v197, 1.0, v161
	v_cmp_gt_f32_e32 vcc, s96, v197
	v_cndmask_b32_e64 v161, v161, 0, s[36:37]
	v_bfe_u32 v202, v161, 16, 1
	v_cndmask_b32_e64 v198, 0, 32, vcc
	v_ldexp_f32 v197, v197, v198
	v_log_f32_e32 v197, v197
	v_add3_u32 v161, v161, v202, s87
	v_lshrrev_b32_e32 v161, 16, v161
	v_mul_f32_e32 v198, 0x3f317217, v197
	v_fma_f32 v198, v197, s97, -v198
	v_fmac_f32_e32 v198, 0x3377d1cf, v197
	v_fmac_f32_e32 v198, 0x3f317217, v197
	v_cmp_lt_f32_e64 s[0:1], |v197|, s94
	s_nop 1
	v_cndmask_b32_e64 v197, v197, v198, s[0:1]
	v_cndmask_b32_e32 v198, 0, v190, vcc
	v_sub_f32_e32 v197, v197, v198
	v_sub_f32_e32 v198, 1.0, v159
	v_cmp_gt_f32_e32 vcc, s96, v198
	v_cndmask_b32_e64 v159, v159, 0, s[36:37]
	s_nop 0
	v_cndmask_b32_e64 v199, 0, 32, vcc
	v_ldexp_f32 v198, v198, v199
	v_log_f32_e32 v198, v198
	s_nop 0
	v_mul_f32_e32 v199, 0x3f317217, v198
	v_fma_f32 v199, v198, s97, -v199
	v_fmac_f32_e32 v199, 0x3377d1cf, v198
	v_fmac_f32_e32 v199, 0x3f317217, v198
	v_cmp_lt_f32_e64 s[0:1], |v198|, s94
	s_nop 1
	v_cndmask_b32_e64 v198, v198, v199, s[0:1]
	v_cndmask_b32_e32 v199, 0, v190, vcc
	v_sub_f32_e32 v198, v198, v199
	v_bfe_u32 v199, v159, 16, 1
	v_add3_u32 v159, v159, v199, s87
	v_and_or_b32 v161, v159, s88, v161
	v_mov_b32_e32 v159, v169
	v_mov_b32_e32 v158, v168
	global_store_dwordx4 v[156:157], v[158:161], off
	s_nop 1
	v_cndmask_b32_e64 v158, v166, 0, s[36:37]
	v_bfe_u32 v159, v158, 16, 1
	v_add3_u32 v158, v158, v159, s87
	v_cndmask_b32_e64 v159, v181, 0, s[36:37]
	v_bfe_u32 v160, v159, 16, 1
	v_lshrrev_b32_e32 v158, 16, v158
	v_add3_u32 v159, v159, v160, s87
	v_and_or_b32 v158, v159, s88, v158
	v_cndmask_b32_e64 v159, v193, 0, s[36:37]
	v_bfe_u32 v160, v159, 16, 1
	v_add3_u32 v159, v159, v160, s87
	v_cndmask_b32_e64 v160, v194, 0, s[36:37]
	v_bfe_u32 v161, v160, 16, 1
	v_lshrrev_b32_e32 v159, 16, v159
	v_add3_u32 v160, v160, v161, s87
	v_and_or_b32 v159, v160, s88, v159
	v_cndmask_b32_e64 v160, v195, 0, s[36:37]
	v_bfe_u32 v161, v160, 16, 1
	v_add3_u32 v160, v160, v161, s87
	v_cndmask_b32_e64 v161, v196, 0, s[36:37]
	v_bfe_u32 v166, v161, 16, 1
	v_lshrrev_b32_e32 v160, 16, v160
	v_add3_u32 v161, v161, v166, s87
	v_and_or_b32 v160, v161, s88, v160
	v_cndmask_b32_e64 v161, v197, 0, s[36:37]
	v_bfe_u32 v166, v161, 16, 1
	v_add3_u32 v161, v161, v166, s87
	v_cndmask_b32_e64 v166, v198, 0, s[36:37]
	v_bfe_u32 v167, v166, 16, 1
	v_lshrrev_b32_e32 v161, 16, v161
	v_add3_u32 v166, v166, v167, s87
	v_and_or_b32 v161, v166, s88, v161
	global_store_dwordx4 v[154:155], v[158:161], off
	s_nop 1
	v_mul_f32_e32 v158, 0x3fb8aa3b, v102
	v_exp_f32_e32 v166, v158
	v_mul_f32_e32 v158, 0x3fb8aa3b, v103
	v_exp_f32_e32 v168, v158
	v_mul_f32_e32 v158, 0x3fb8aa3b, v104
	v_exp_f32_e32 v167, v158
	v_mul_f32_e32 v158, 0x3fb8aa3b, v105
	v_exp_f32_e32 v169, v158
	v_mul_f32_e32 v158, 0x3fb8aa3b, v98
	v_pk_add_f32 v[166:167], v[166:167], 1.0 op_sel_hi:[1,0]
	v_mul_f32_e32 v159, 0x3fb8aa3b, v100
	v_rcp_f32_e32 v181, v167
	v_pk_add_f32 v[168:169], v[168:169], 1.0 op_sel_hi:[1,0]
	v_exp_f32_e32 v160, v158
	v_exp_f32_e32 v161, v159
	v_mul_f32_e32 v167, v165, v181
	v_rcp_f32_e32 v181, v166
	v_pk_add_f32 v[160:161], v[160:161], 1.0 op_sel_hi:[1,0]
	v_mul_f32_e32 v158, 0x3fb8aa3b, v99
	v_mul_f32_e32 v159, 0x3fb8aa3b, v101
	v_mul_f32_e32 v180, v164, v181
	v_sub_f32_e32 v166, 1.0, v180
	v_cmp_gt_f32_e32 vcc, s96, v166
	v_exp_f32_e32 v158, v158
	v_exp_f32_e32 v159, v159
	v_cndmask_b32_e64 v181, 0, 32, vcc
	v_ldexp_f32 v166, v166, v181
	v_log_f32_e32 v166, v166
	v_pk_add_f32 v[158:159], v[158:159], 1.0 op_sel_hi:[1,0]
	v_cndmask_b32_e64 v180, v180, 0, s[36:37]
	v_mul_f32_e32 v181, 0x3f317217, v166
	v_fma_f32 v181, v166, s97, -v181
	v_fmac_f32_e32 v181, 0x3377d1cf, v166
	v_fmac_f32_e32 v181, 0x3f317217, v166
	v_cmp_lt_f32_e64 s[0:1], |v166|, s94
	s_nop 1
	v_cndmask_b32_e64 v166, v166, v181, s[0:1]
	v_cndmask_b32_e32 v181, 0, v190, vcc
	v_sub_f32_e32 v166, v166, v181
	v_rcp_f32_e32 v193, v169
	s_nop 0
	v_mul_f32_e32 v169, v163, v193
	v_rcp_f32_e32 v193, v168
	s_nop 0
	v_mul_f32_e32 v168, v162, v193
	v_sub_f32_e32 v181, 1.0, v168
	v_cmp_gt_f32_e32 vcc, s96, v181
	v_cndmask_b32_e64 v168, v168, 0, s[36:37]
	s_nop 0
	v_cndmask_b32_e64 v193, 0, 32, vcc
	v_ldexp_f32 v181, v181, v193
	v_log_f32_e32 v181, v181
	v_cvt_pk_bf16_f32 v168, v180, v168
	v_mul_f32_e32 v193, 0x3f317217, v181
	v_fma_f32 v193, v181, s97, -v193
	v_fmac_f32_e32 v193, 0x3377d1cf, v181
	v_fmac_f32_e32 v193, 0x3f317217, v181
	v_cmp_lt_f32_e64 s[0:1], |v181|, s94
	s_nop 1
	v_cndmask_b32_e64 v181, v181, v193, s[0:1]
	v_cndmask_b32_e32 v193, 0, v190, vcc
	v_sub_f32_e32 v181, v181, v193
	v_sub_f32_e32 v193, 1.0, v167
	v_cmp_gt_f32_e32 vcc, s96, v193
	v_cndmask_b32_e64 v167, v167, 0, s[36:37]
	s_nop 0
	v_cndmask_b32_e64 v194, 0, 32, vcc
	v_ldexp_f32 v193, v193, v194
	v_log_f32_e32 v193, v193
	s_nop 0
	v_mul_f32_e32 v194, 0x3f317217, v193
	v_fma_f32 v194, v193, s97, -v194
	v_fmac_f32_e32 v194, 0x3377d1cf, v193
	v_fmac_f32_e32 v194, 0x3f317217, v193
	v_cmp_lt_f32_e64 s[0:1], |v193|, s94
	s_nop 1
	v_cndmask_b32_e64 v193, v193, v194, s[0:1]
	v_cndmask_b32_e32 v194, 0, v190, vcc
	v_sub_f32_e32 v193, v193, v194
	v_sub_f32_e32 v194, 1.0, v169
	v_cmp_gt_f32_e32 vcc, s96, v194
	v_cndmask_b32_e64 v169, v169, 0, s[36:37]
	s_nop 0
	v_cndmask_b32_e64 v195, 0, 32, vcc
	v_ldexp_f32 v194, v194, v195
	v_log_f32_e32 v194, v194
	v_cvt_pk_bf16_f32 v169, v167, v169
	v_mul_f32_e32 v195, 0x3f317217, v194
	v_fma_f32 v195, v194, s97, -v195
	v_fmac_f32_e32 v195, 0x3377d1cf, v194
	v_fmac_f32_e32 v195, 0x3f317217, v194
	v_cmp_lt_f32_e64 s[0:1], |v194|, s94
	s_nop 1
	v_cndmask_b32_e64 v194, v194, v195, s[0:1]
	v_cndmask_b32_e32 v195, 0, v190, vcc
	v_sub_f32_e32 v194, v194, v195
	v_rcp_f32_e32 v196, v161
	s_nop 0
	v_mul_f32_e32 v161, v173, v196
	v_rcp_f32_e32 v196, v160
	s_nop 0
	v_mul_f32_e32 v160, v171, v196
	v_sub_f32_e32 v195, 1.0, v160
	v_cmp_gt_f32_e32 vcc, s96, v195
	v_cndmask_b32_e64 v160, v160, 0, s[36:37]
	v_bfe_u32 v201, v160, 16, 1
	v_cndmask_b32_e64 v196, 0, 32, vcc
	v_ldexp_f32 v195, v195, v196
	v_log_f32_e32 v195, v195
	v_add3_u32 v160, v160, v201, s87
	v_lshrrev_b32_e32 v160, 16, v160
	v_mul_f32_e32 v196, 0x3f317217, v195
	v_fma_f32 v196, v195, s97, -v196
	v_fmac_f32_e32 v196, 0x3377d1cf, v195
	v_fmac_f32_e32 v196, 0x3f317217, v195
	v_cmp_lt_f32_e64 s[0:1], |v195|, s94
	s_nop 1
	v_cndmask_b32_e64 v195, v195, v196, s[0:1]
	v_cndmask_b32_e32 v196, 0, v190, vcc
	v_sub_f32_e32 v195, v195, v196
	v_rcp_f32_e32 v197, v159
	s_nop 0
	v_mul_f32_e32 v159, v172, v197
	v_rcp_f32_e32 v197, v158
	s_nop 0
	v_mul_f32_e32 v158, v170, v197
	v_sub_f32_e32 v196, 1.0, v158
	v_cmp_gt_f32_e32 vcc, s96, v196
	v_cndmask_b32_e64 v158, v158, 0, s[36:37]
	v_bfe_u32 v200, v158, 16, 1
	v_cndmask_b32_e64 v197, 0, 32, vcc
	v_ldexp_f32 v196, v196, v197
	v_log_f32_e32 v196, v196
	v_add3_u32 v158, v158, v200, s87
	v_mul_f32_e32 v197, 0x3f317217, v196
	v_fma_f32 v197, v196, s97, -v197
	v_fmac_f32_e32 v197, 0x3377d1cf, v196
	v_fmac_f32_e32 v197, 0x3f317217, v196
	v_cmp_lt_f32_e64 s[0:1], |v196|, s94
	v_and_or_b32 v160, v158, s88, v160
	s_nop 0
	v_cndmask_b32_e64 v196, v196, v197, s[0:1]
	v_cndmask_b32_e32 v197, 0, v190, vcc
	v_sub_f32_e32 v196, v196, v197
	v_sub_f32_e32 v197, 1.0, v161
	v_cmp_gt_f32_e32 vcc, s96, v197
	v_cndmask_b32_e64 v161, v161, 0, s[36:37]
	v_bfe_u32 v202, v161, 16, 1
	v_cndmask_b32_e64 v198, 0, 32, vcc
	v_ldexp_f32 v197, v197, v198
	v_log_f32_e32 v197, v197
	v_add3_u32 v161, v161, v202, s87
	v_lshrrev_b32_e32 v161, 16, v161
	v_mul_f32_e32 v198, 0x3f317217, v197
	v_fma_f32 v198, v197, s97, -v198
	v_fmac_f32_e32 v198, 0x3377d1cf, v197
	v_fmac_f32_e32 v198, 0x3f317217, v197
	v_cmp_lt_f32_e64 s[0:1], |v197|, s94
	s_nop 1
	v_cndmask_b32_e64 v197, v197, v198, s[0:1]
	v_cndmask_b32_e32 v198, 0, v190, vcc
	v_sub_f32_e32 v197, v197, v198
	v_sub_f32_e32 v198, 1.0, v159
	v_cmp_gt_f32_e32 vcc, s96, v198
	v_cndmask_b32_e64 v159, v159, 0, s[36:37]
	s_nop 0
	v_cndmask_b32_e64 v199, 0, 32, vcc
	v_ldexp_f32 v198, v198, v199
	v_log_f32_e32 v198, v198
	s_nop 0
	v_mul_f32_e32 v199, 0x3f317217, v198
	v_fma_f32 v199, v198, s97, -v199
	v_fmac_f32_e32 v199, 0x3377d1cf, v198
	v_fmac_f32_e32 v199, 0x3f317217, v198
	v_cmp_lt_f32_e64 s[0:1], |v198|, s94
	s_nop 1
	v_cndmask_b32_e64 v198, v198, v199, s[0:1]
	v_cndmask_b32_e32 v199, 0, v190, vcc
	v_sub_f32_e32 v198, v198, v199
	v_bfe_u32 v199, v159, 16, 1
	v_add3_u32 v159, v159, v199, s87
	v_and_or_b32 v161, v159, s88, v161
	v_mov_b32_e32 v159, v169
	v_mov_b32_e32 v158, v168
	global_store_dwordx4 v[156:157], v[158:161], off offset:256
	v_cndmask_b32_e64 v156, v166, 0, s[36:37]
	v_bfe_u32 v157, v156, 16, 1
	v_add3_u32 v156, v156, v157, s87
	v_cndmask_b32_e64 v157, v181, 0, s[36:37]
	v_bfe_u32 v158, v157, 16, 1
	v_lshrrev_b32_e32 v156, 16, v156
	v_add3_u32 v157, v157, v158, s87
	v_and_or_b32 v156, v157, s88, v156
	v_cndmask_b32_e64 v157, v193, 0, s[36:37]
	v_bfe_u32 v158, v157, 16, 1
	v_add3_u32 v157, v157, v158, s87
	v_cndmask_b32_e64 v158, v194, 0, s[36:37]
	v_bfe_u32 v159, v158, 16, 1
	v_lshrrev_b32_e32 v157, 16, v157
	v_add3_u32 v158, v158, v159, s87
	v_and_or_b32 v157, v158, s88, v157
	v_cndmask_b32_e64 v158, v195, 0, s[36:37]
	v_bfe_u32 v159, v158, 16, 1
	v_add3_u32 v158, v158, v159, s87
	v_cndmask_b32_e64 v159, v196, 0, s[36:37]
	v_bfe_u32 v160, v159, 16, 1
	v_lshrrev_b32_e32 v158, 16, v158
	v_add3_u32 v159, v159, v160, s87
	v_and_or_b32 v158, v159, s88, v158
	v_cndmask_b32_e64 v159, v197, 0, s[36:37]
	v_bfe_u32 v160, v159, 16, 1
	v_add3_u32 v159, v159, v160, s87
	v_cndmask_b32_e64 v160, v198, 0, s[36:37]
	v_bfe_u32 v161, v160, 16, 1
	v_lshrrev_b32_e32 v159, 16, v159
	v_add3_u32 v160, v160, v161, s87
	v_and_or_b32 v159, v160, s88, v159
	global_store_dwordx4 v[154:155], v[156:159], off offset:256
	v_or_b32_e32 v154, 32, v148
	v_cmp_gt_i32_e64 s[0:1], s23, v154
	v_mul_f32_e32 v158, 0x3fb8aa3b, v94
	v_exp_f32_e32 v166, v158
	v_mul_f32_e32 v158, 0x3fb8aa3b, v95
	v_exp_f32_e32 v168, v158
	v_mul_f32_e32 v158, 0x3fb8aa3b, v96
	v_exp_f32_e32 v167, v158
	v_cndmask_b32_e64 v155, v189, 0, s[0:1]
	v_add_u32_e32 v155, v155, v154
	v_cmp_gt_i32_e32 vcc, s93, v154
	v_cmp_gt_i32_e64 s[0:1], s95, v155
	v_pk_add_f32 v[166:167], v[166:167], 1.0 op_sel_hi:[1,0]
	s_and_b64 s[36:37], vcc, s[0:1]
	v_rcp_f32_e32 v181, v167
	v_mul_f32_e32 v158, 0x3fb8aa3b, v97
	v_exp_f32_e32 v169, v158
	v_mul_f32_e32 v158, 0x3fb8aa3b, v90
	v_mul_f32_e32 v167, v176, v181
	v_rcp_f32_e32 v181, v166
	v_pk_add_f32 v[168:169], v[168:169], 1.0 op_sel_hi:[1,0]
	v_mul_f32_e32 v159, 0x3fb8aa3b, v92
	v_exp_f32_e32 v160, v158
	v_mul_f32_e32 v180, v149, v181
	v_sub_f32_e32 v166, 1.0, v180
	v_cmp_gt_f32_e32 vcc, s96, v166
	v_exp_f32_e32 v161, v159
	v_mul_f32_e32 v158, 0x3fb8aa3b, v91
	v_cndmask_b32_e64 v181, 0, 32, vcc
	v_ldexp_f32 v166, v166, v181
	v_log_f32_e32 v166, v166
	v_pk_add_f32 v[160:161], v[160:161], 1.0 op_sel_hi:[1,0]
	v_mul_f32_e32 v159, 0x3fb8aa3b, v93
	v_exp_f32_e32 v158, v158
	v_mul_f32_e32 v181, 0x3f317217, v166
	v_fma_f32 v181, v166, s97, -v181
	v_fmac_f32_e32 v181, 0x3377d1cf, v166
	v_fmac_f32_e32 v181, 0x3f317217, v166
	v_cmp_lt_f32_e64 s[0:1], |v166|, s94
	v_exp_f32_e32 v159, v159
	v_cndmask_b32_e64 v180, v180, 0, s[36:37]
	v_cndmask_b32_e64 v166, v166, v181, s[0:1]
	v_cndmask_b32_e32 v181, 0, v190, vcc
	v_sub_f32_e32 v166, v166, v181
	v_rcp_f32_e32 v193, v169
	v_pk_add_f32 v[158:159], v[158:159], 1.0 op_sel_hi:[1,0]
	v_ashrrev_i32_e32 v155, 31, v154
	v_lshlrev_b64 v[154:155], 10, v[154:155]
	v_mul_f32_e32 v169, v174, v193
	v_rcp_f32_e32 v193, v168
	v_lshl_add_u64 v[156:157], v[150:151], 0, v[154:155]
	v_lshl_add_u64 v[154:155], v[152:153], 0, v[154:155]
	v_mul_f32_e32 v168, v138, v193
	v_sub_f32_e32 v181, 1.0, v168
	v_cmp_gt_f32_e32 vcc, s96, v181
	v_cndmask_b32_e64 v168, v168, 0, s[36:37]
	s_nop 0
	v_cndmask_b32_e64 v193, 0, 32, vcc
	v_ldexp_f32 v181, v181, v193
	v_log_f32_e32 v181, v181
	v_cvt_pk_bf16_f32 v168, v180, v168
	v_mul_f32_e32 v193, 0x3f317217, v181
	v_fma_f32 v193, v181, s97, -v193
	v_fmac_f32_e32 v193, 0x3377d1cf, v181
	v_fmac_f32_e32 v193, 0x3f317217, v181
	v_cmp_lt_f32_e64 s[0:1], |v181|, s94
	s_nop 1
	v_cndmask_b32_e64 v181, v181, v193, s[0:1]
	v_cndmask_b32_e32 v193, 0, v190, vcc
	v_sub_f32_e32 v181, v181, v193
	v_sub_f32_e32 v193, 1.0, v167
	v_cmp_gt_f32_e32 vcc, s96, v193
	v_cndmask_b32_e64 v167, v167, 0, s[36:37]
	s_nop 0
	v_cndmask_b32_e64 v194, 0, 32, vcc
	v_ldexp_f32 v193, v193, v194
	v_log_f32_e32 v193, v193
	s_nop 0
	v_mul_f32_e32 v194, 0x3f317217, v193
	v_fma_f32 v194, v193, s97, -v194
	v_fmac_f32_e32 v194, 0x3377d1cf, v193
	v_fmac_f32_e32 v194, 0x3f317217, v193
	v_cmp_lt_f32_e64 s[0:1], |v193|, s94
	s_nop 1
	v_cndmask_b32_e64 v193, v193, v194, s[0:1]
	v_cndmask_b32_e32 v194, 0, v190, vcc
	v_sub_f32_e32 v193, v193, v194
	v_sub_f32_e32 v194, 1.0, v169
	v_cmp_gt_f32_e32 vcc, s96, v194
	v_cndmask_b32_e64 v169, v169, 0, s[36:37]
	s_nop 0
	v_cndmask_b32_e64 v195, 0, 32, vcc
	v_ldexp_f32 v194, v194, v195
	v_log_f32_e32 v194, v194
	v_cvt_pk_bf16_f32 v169, v167, v169
	v_mul_f32_e32 v195, 0x3f317217, v194
	v_fma_f32 v195, v194, s97, -v195
	v_fmac_f32_e32 v195, 0x3377d1cf, v194
	v_fmac_f32_e32 v195, 0x3f317217, v194
	v_cmp_lt_f32_e64 s[0:1], |v194|, s94
	s_nop 1
	v_cndmask_b32_e64 v194, v194, v195, s[0:1]
	v_cndmask_b32_e32 v195, 0, v190, vcc
	v_sub_f32_e32 v194, v194, v195
	v_rcp_f32_e32 v196, v161
	s_nop 0
	v_mul_f32_e32 v161, v179, v196
	v_rcp_f32_e32 v196, v160
	s_nop 0
	v_mul_f32_e32 v160, v177, v196
	v_sub_f32_e32 v195, 1.0, v160
	v_cmp_gt_f32_e32 vcc, s96, v195
	v_cndmask_b32_e64 v160, v160, 0, s[36:37]
	v_bfe_u32 v201, v160, 16, 1
	v_cndmask_b32_e64 v196, 0, 32, vcc
	v_ldexp_f32 v195, v195, v196
	v_log_f32_e32 v195, v195
	v_add3_u32 v160, v160, v201, s87
	v_lshrrev_b32_e32 v160, 16, v160
	v_mul_f32_e32 v196, 0x3f317217, v195
	v_fma_f32 v196, v195, s97, -v196
	v_fmac_f32_e32 v196, 0x3377d1cf, v195
	v_fmac_f32_e32 v196, 0x3f317217, v195
	v_cmp_lt_f32_e64 s[0:1], |v195|, s94
	s_nop 1
	v_cndmask_b32_e64 v195, v195, v196, s[0:1]
	v_cndmask_b32_e32 v196, 0, v190, vcc
	v_sub_f32_e32 v195, v195, v196
	v_rcp_f32_e32 v197, v159
	s_nop 0
	v_mul_f32_e32 v159, v178, v197
	v_rcp_f32_e32 v197, v158
	s_nop 0
	v_mul_f32_e32 v158, v175, v197
	v_sub_f32_e32 v196, 1.0, v158
	v_cmp_gt_f32_e32 vcc, s96, v196
	v_cndmask_b32_e64 v158, v158, 0, s[36:37]
	v_bfe_u32 v200, v158, 16, 1
	v_cndmask_b32_e64 v197, 0, 32, vcc
	v_ldexp_f32 v196, v196, v197
	v_log_f32_e32 v196, v196
	v_add3_u32 v158, v158, v200, s87
	v_mul_f32_e32 v197, 0x3f317217, v196
	v_fma_f32 v197, v196, s97, -v197
	v_fmac_f32_e32 v197, 0x3377d1cf, v196
	v_fmac_f32_e32 v197, 0x3f317217, v196
	v_cmp_lt_f32_e64 s[0:1], |v196|, s94
	v_and_or_b32 v160, v158, s88, v160
	s_nop 0
	v_cndmask_b32_e64 v196, v196, v197, s[0:1]
	v_cndmask_b32_e32 v197, 0, v190, vcc
	v_sub_f32_e32 v196, v196, v197
	v_sub_f32_e32 v197, 1.0, v161
	v_cmp_gt_f32_e32 vcc, s96, v197
	v_cndmask_b32_e64 v161, v161, 0, s[36:37]
	v_bfe_u32 v202, v161, 16, 1
	v_cndmask_b32_e64 v198, 0, 32, vcc
	v_ldexp_f32 v197, v197, v198
	v_log_f32_e32 v197, v197
	v_add3_u32 v161, v161, v202, s87
	v_lshrrev_b32_e32 v161, 16, v161
	v_mul_f32_e32 v198, 0x3f317217, v197
	v_fma_f32 v198, v197, s97, -v198
	v_fmac_f32_e32 v198, 0x3377d1cf, v197
	v_fmac_f32_e32 v198, 0x3f317217, v197
	v_cmp_lt_f32_e64 s[0:1], |v197|, s94
	s_nop 1
	v_cndmask_b32_e64 v197, v197, v198, s[0:1]
	v_cndmask_b32_e32 v198, 0, v190, vcc
	v_sub_f32_e32 v197, v197, v198
	v_sub_f32_e32 v198, 1.0, v159
	v_cmp_gt_f32_e32 vcc, s96, v198
	v_cndmask_b32_e64 v159, v159, 0, s[36:37]
	s_nop 0
	v_cndmask_b32_e64 v199, 0, 32, vcc
	v_ldexp_f32 v198, v198, v199
	v_log_f32_e32 v198, v198
	s_nop 0
	v_mul_f32_e32 v199, 0x3f317217, v198
	v_fma_f32 v199, v198, s97, -v199
	v_fmac_f32_e32 v199, 0x3377d1cf, v198
	v_fmac_f32_e32 v199, 0x3f317217, v198
	v_cmp_lt_f32_e64 s[0:1], |v198|, s94
	s_nop 1
	v_cndmask_b32_e64 v198, v198, v199, s[0:1]
	v_cndmask_b32_e32 v199, 0, v190, vcc
	v_sub_f32_e32 v198, v198, v199
	v_bfe_u32 v199, v159, 16, 1
	v_add3_u32 v159, v159, v199, s87
	v_and_or_b32 v161, v159, s88, v161
	v_mov_b32_e32 v159, v169
	v_mov_b32_e32 v158, v168
	global_store_dwordx4 v[156:157], v[158:161], off
	s_nop 1
	v_cndmask_b32_e64 v158, v166, 0, s[36:37]
	v_bfe_u32 v159, v158, 16, 1
	v_add3_u32 v158, v158, v159, s87
	v_cndmask_b32_e64 v159, v181, 0, s[36:37]
	v_bfe_u32 v160, v159, 16, 1
	v_lshrrev_b32_e32 v158, 16, v158
	v_add3_u32 v159, v159, v160, s87
	v_and_or_b32 v158, v159, s88, v158
	v_cndmask_b32_e64 v159, v193, 0, s[36:37]
	v_bfe_u32 v160, v159, 16, 1
	v_add3_u32 v159, v159, v160, s87
	v_cndmask_b32_e64 v160, v194, 0, s[36:37]
	v_bfe_u32 v161, v160, 16, 1
	v_lshrrev_b32_e32 v159, 16, v159
	v_add3_u32 v160, v160, v161, s87
	v_and_or_b32 v159, v160, s88, v159
	v_cndmask_b32_e64 v160, v195, 0, s[36:37]
	v_bfe_u32 v161, v160, 16, 1
	v_add3_u32 v160, v160, v161, s87
	v_cndmask_b32_e64 v161, v196, 0, s[36:37]
	v_bfe_u32 v166, v161, 16, 1
	v_lshrrev_b32_e32 v160, 16, v160
	v_add3_u32 v161, v161, v166, s87
	v_and_or_b32 v160, v161, s88, v160
	v_cndmask_b32_e64 v161, v197, 0, s[36:37]
	v_bfe_u32 v166, v161, 16, 1
	v_add3_u32 v161, v161, v166, s87
	v_cndmask_b32_e64 v166, v198, 0, s[36:37]
	v_bfe_u32 v167, v166, 16, 1
	v_lshrrev_b32_e32 v161, 16, v161
	v_add3_u32 v166, v166, v167, s87
	v_and_or_b32 v161, v166, s88, v161
	global_store_dwordx4 v[154:155], v[158:161], off
	s_nop 1
	v_mul_f32_e32 v158, 0x3fb8aa3b, v86
	v_exp_f32_e32 v166, v158
	v_mul_f32_e32 v158, 0x3fb8aa3b, v87
	v_exp_f32_e32 v168, v158
	v_mul_f32_e32 v158, 0x3fb8aa3b, v88
	v_exp_f32_e32 v167, v158
	v_mul_f32_e32 v158, 0x3fb8aa3b, v89
	v_exp_f32_e32 v169, v158
	v_mul_f32_e32 v158, 0x3fb8aa3b, v82
	v_pk_add_f32 v[166:167], v[166:167], 1.0 op_sel_hi:[1,0]
	v_mul_f32_e32 v159, 0x3fb8aa3b, v84
	v_rcp_f32_e32 v181, v167
	v_pk_add_f32 v[168:169], v[168:169], 1.0 op_sel_hi:[1,0]
	v_exp_f32_e32 v160, v158
	v_exp_f32_e32 v161, v159
	v_mul_f32_e32 v167, v165, v181
	v_rcp_f32_e32 v181, v166
	v_pk_add_f32 v[160:161], v[160:161], 1.0 op_sel_hi:[1,0]
	v_mul_f32_e32 v158, 0x3fb8aa3b, v83
	v_mul_f32_e32 v159, 0x3fb8aa3b, v85
	v_mul_f32_e32 v180, v164, v181
	v_sub_f32_e32 v166, 1.0, v180
	v_cmp_gt_f32_e32 vcc, s96, v166
	v_exp_f32_e32 v158, v158
	v_exp_f32_e32 v159, v159
	v_cndmask_b32_e64 v181, 0, 32, vcc
	v_ldexp_f32 v166, v166, v181
	v_log_f32_e32 v166, v166
	v_pk_add_f32 v[158:159], v[158:159], 1.0 op_sel_hi:[1,0]
	v_cndmask_b32_e64 v180, v180, 0, s[36:37]
	v_mul_f32_e32 v181, 0x3f317217, v166
	v_fma_f32 v181, v166, s97, -v181
	v_fmac_f32_e32 v181, 0x3377d1cf, v166
	v_fmac_f32_e32 v181, 0x3f317217, v166
	v_cmp_lt_f32_e64 s[0:1], |v166|, s94
	s_nop 1
	v_cndmask_b32_e64 v166, v166, v181, s[0:1]
	v_cndmask_b32_e32 v181, 0, v190, vcc
	v_sub_f32_e32 v166, v166, v181
	v_rcp_f32_e32 v193, v169
	s_nop 0
	v_mul_f32_e32 v169, v163, v193
	v_rcp_f32_e32 v193, v168
	s_nop 0
	v_mul_f32_e32 v168, v162, v193
	v_sub_f32_e32 v181, 1.0, v168
	v_cmp_gt_f32_e32 vcc, s96, v181
	v_cndmask_b32_e64 v168, v168, 0, s[36:37]
	s_nop 0
	v_cndmask_b32_e64 v193, 0, 32, vcc
	v_ldexp_f32 v181, v181, v193
	v_log_f32_e32 v181, v181
	v_cvt_pk_bf16_f32 v168, v180, v168
	v_mul_f32_e32 v193, 0x3f317217, v181
	v_fma_f32 v193, v181, s97, -v193
	v_fmac_f32_e32 v193, 0x3377d1cf, v181
	v_fmac_f32_e32 v193, 0x3f317217, v181
	v_cmp_lt_f32_e64 s[0:1], |v181|, s94
	s_nop 1
	v_cndmask_b32_e64 v181, v181, v193, s[0:1]
	v_cndmask_b32_e32 v193, 0, v190, vcc
	v_sub_f32_e32 v181, v181, v193
	v_sub_f32_e32 v193, 1.0, v167
	v_cmp_gt_f32_e32 vcc, s96, v193
	v_cndmask_b32_e64 v167, v167, 0, s[36:37]
	s_nop 0
	v_cndmask_b32_e64 v194, 0, 32, vcc
	v_ldexp_f32 v193, v193, v194
	v_log_f32_e32 v193, v193
	s_nop 0
	v_mul_f32_e32 v194, 0x3f317217, v193
	v_fma_f32 v194, v193, s97, -v194
	v_fmac_f32_e32 v194, 0x3377d1cf, v193
	v_fmac_f32_e32 v194, 0x3f317217, v193
	v_cmp_lt_f32_e64 s[0:1], |v193|, s94
	s_nop 1
	v_cndmask_b32_e64 v193, v193, v194, s[0:1]
	v_cndmask_b32_e32 v194, 0, v190, vcc
	v_sub_f32_e32 v193, v193, v194
	v_sub_f32_e32 v194, 1.0, v169
	v_cmp_gt_f32_e32 vcc, s96, v194
	v_cndmask_b32_e64 v169, v169, 0, s[36:37]
	s_nop 0
	v_cndmask_b32_e64 v195, 0, 32, vcc
	v_ldexp_f32 v194, v194, v195
	v_log_f32_e32 v194, v194
	v_cvt_pk_bf16_f32 v169, v167, v169
	v_mul_f32_e32 v195, 0x3f317217, v194
	v_fma_f32 v195, v194, s97, -v195
	v_fmac_f32_e32 v195, 0x3377d1cf, v194
	v_fmac_f32_e32 v195, 0x3f317217, v194
	v_cmp_lt_f32_e64 s[0:1], |v194|, s94
	s_nop 1
	v_cndmask_b32_e64 v194, v194, v195, s[0:1]
	v_cndmask_b32_e32 v195, 0, v190, vcc
	v_sub_f32_e32 v194, v194, v195
	v_rcp_f32_e32 v196, v161
	s_nop 0
	v_mul_f32_e32 v161, v173, v196
	v_rcp_f32_e32 v196, v160
	s_nop 0
	v_mul_f32_e32 v160, v171, v196
	v_sub_f32_e32 v195, 1.0, v160
	v_cmp_gt_f32_e32 vcc, s96, v195
	v_cndmask_b32_e64 v160, v160, 0, s[36:37]
	v_bfe_u32 v201, v160, 16, 1
	v_cndmask_b32_e64 v196, 0, 32, vcc
	v_ldexp_f32 v195, v195, v196
	v_log_f32_e32 v195, v195
	v_add3_u32 v160, v160, v201, s87
	v_lshrrev_b32_e32 v160, 16, v160
	v_mul_f32_e32 v196, 0x3f317217, v195
	v_fma_f32 v196, v195, s97, -v196
	v_fmac_f32_e32 v196, 0x3377d1cf, v195
	v_fmac_f32_e32 v196, 0x3f317217, v195
	v_cmp_lt_f32_e64 s[0:1], |v195|, s94
	s_nop 1
	v_cndmask_b32_e64 v195, v195, v196, s[0:1]
	v_cndmask_b32_e32 v196, 0, v190, vcc
	v_sub_f32_e32 v195, v195, v196
	v_rcp_f32_e32 v197, v159
	s_nop 0
	v_mul_f32_e32 v159, v172, v197
	v_rcp_f32_e32 v197, v158
	s_nop 0
	v_mul_f32_e32 v158, v170, v197
	v_sub_f32_e32 v196, 1.0, v158
	v_cmp_gt_f32_e32 vcc, s96, v196
	v_cndmask_b32_e64 v158, v158, 0, s[36:37]
	v_bfe_u32 v200, v158, 16, 1
	v_cndmask_b32_e64 v197, 0, 32, vcc
	v_ldexp_f32 v196, v196, v197
	v_log_f32_e32 v196, v196
	v_add3_u32 v158, v158, v200, s87
	v_mul_f32_e32 v197, 0x3f317217, v196
	v_fma_f32 v197, v196, s97, -v197
	v_fmac_f32_e32 v197, 0x3377d1cf, v196
	v_fmac_f32_e32 v197, 0x3f317217, v196
	v_cmp_lt_f32_e64 s[0:1], |v196|, s94
	v_and_or_b32 v160, v158, s88, v160
	s_nop 0
	v_cndmask_b32_e64 v196, v196, v197, s[0:1]
	v_cndmask_b32_e32 v197, 0, v190, vcc
	v_sub_f32_e32 v196, v196, v197
	v_sub_f32_e32 v197, 1.0, v161
	v_cmp_gt_f32_e32 vcc, s96, v197
	v_cndmask_b32_e64 v161, v161, 0, s[36:37]
	v_bfe_u32 v202, v161, 16, 1
	v_cndmask_b32_e64 v198, 0, 32, vcc
	v_ldexp_f32 v197, v197, v198
	v_log_f32_e32 v197, v197
	v_add3_u32 v161, v161, v202, s87
	v_lshrrev_b32_e32 v161, 16, v161
	v_mul_f32_e32 v198, 0x3f317217, v197
	v_fma_f32 v198, v197, s97, -v198
	v_fmac_f32_e32 v198, 0x3377d1cf, v197
	v_fmac_f32_e32 v198, 0x3f317217, v197
	v_cmp_lt_f32_e64 s[0:1], |v197|, s94
	s_nop 1
	v_cndmask_b32_e64 v197, v197, v198, s[0:1]
	v_cndmask_b32_e32 v198, 0, v190, vcc
	v_sub_f32_e32 v197, v197, v198
	v_sub_f32_e32 v198, 1.0, v159
	v_cmp_gt_f32_e32 vcc, s96, v198
	v_cndmask_b32_e64 v159, v159, 0, s[36:37]
	s_nop 0
	v_cndmask_b32_e64 v199, 0, 32, vcc
	v_ldexp_f32 v198, v198, v199
	v_log_f32_e32 v198, v198
	s_nop 0
	v_mul_f32_e32 v199, 0x3f317217, v198
	v_fma_f32 v199, v198, s97, -v199
	v_fmac_f32_e32 v199, 0x3377d1cf, v198
	v_fmac_f32_e32 v199, 0x3f317217, v198
	v_cmp_lt_f32_e64 s[0:1], |v198|, s94
	s_nop 1
	v_cndmask_b32_e64 v198, v198, v199, s[0:1]
	v_cndmask_b32_e32 v199, 0, v190, vcc
	v_sub_f32_e32 v198, v198, v199
	v_bfe_u32 v199, v159, 16, 1
	v_add3_u32 v159, v159, v199, s87
	v_and_or_b32 v161, v159, s88, v161
	v_mov_b32_e32 v159, v169
	v_mov_b32_e32 v158, v168
	global_store_dwordx4 v[156:157], v[158:161], off offset:256
	v_cndmask_b32_e64 v156, v166, 0, s[36:37]
	v_bfe_u32 v157, v156, 16, 1
	v_add3_u32 v156, v156, v157, s87
	v_cndmask_b32_e64 v157, v181, 0, s[36:37]
	v_bfe_u32 v158, v157, 16, 1
	v_lshrrev_b32_e32 v156, 16, v156
	v_add3_u32 v157, v157, v158, s87
	v_and_or_b32 v156, v157, s88, v156
	v_cndmask_b32_e64 v157, v193, 0, s[36:37]
	v_bfe_u32 v158, v157, 16, 1
	v_add3_u32 v157, v157, v158, s87
	v_cndmask_b32_e64 v158, v194, 0, s[36:37]
	v_bfe_u32 v159, v158, 16, 1
	v_lshrrev_b32_e32 v157, 16, v157
	v_add3_u32 v158, v158, v159, s87
	v_and_or_b32 v157, v158, s88, v157
	v_cndmask_b32_e64 v158, v195, 0, s[36:37]
	v_bfe_u32 v159, v158, 16, 1
	v_add3_u32 v158, v158, v159, s87
	v_cndmask_b32_e64 v159, v196, 0, s[36:37]
	v_bfe_u32 v160, v159, 16, 1
	v_lshrrev_b32_e32 v158, 16, v158
	v_add3_u32 v159, v159, v160, s87
	v_and_or_b32 v158, v159, s88, v158
	v_cndmask_b32_e64 v159, v197, 0, s[36:37]
	v_bfe_u32 v160, v159, 16, 1
	v_add3_u32 v159, v159, v160, s87
	v_cndmask_b32_e64 v160, v198, 0, s[36:37]
	v_bfe_u32 v161, v160, 16, 1
	v_lshrrev_b32_e32 v159, 16, v159
	v_add3_u32 v160, v160, v161, s87
	v_and_or_b32 v159, v160, s88, v159
	global_store_dwordx4 v[154:155], v[156:159], off offset:256
	v_or_b32_e32 v154, 48, v148
	v_cmp_gt_i32_e64 s[0:1], s23, v154
	v_mul_f32_e32 v158, 0x3fb8aa3b, v78
	v_exp_f32_e32 v166, v158
	v_mul_f32_e32 v158, 0x3fb8aa3b, v79
	v_exp_f32_e32 v168, v158
	v_mul_f32_e32 v158, 0x3fb8aa3b, v80
	v_exp_f32_e32 v167, v158
	v_cndmask_b32_e64 v155, v189, 0, s[0:1]
	v_add_u32_e32 v155, v155, v154
	v_cmp_gt_i32_e32 vcc, s93, v154
	v_cmp_gt_i32_e64 s[0:1], s95, v155
	v_pk_add_f32 v[166:167], v[166:167], 1.0 op_sel_hi:[1,0]
	s_and_b64 s[36:37], vcc, s[0:1]
	v_rcp_f32_e32 v181, v167
	v_mul_f32_e32 v158, 0x3fb8aa3b, v81
	v_exp_f32_e32 v169, v158
	v_mul_f32_e32 v158, 0x3fb8aa3b, v74
	v_mul_f32_e32 v167, v176, v181
	v_rcp_f32_e32 v181, v166
	v_pk_add_f32 v[168:169], v[168:169], 1.0 op_sel_hi:[1,0]
	v_mul_f32_e32 v159, 0x3fb8aa3b, v76
	v_exp_f32_e32 v160, v158
	v_mul_f32_e32 v180, v149, v181
	v_sub_f32_e32 v166, 1.0, v180
	v_cmp_gt_f32_e32 vcc, s96, v166
	v_exp_f32_e32 v161, v159
	v_mul_f32_e32 v158, 0x3fb8aa3b, v75
	v_cndmask_b32_e64 v181, 0, 32, vcc
	v_ldexp_f32 v166, v166, v181
	v_log_f32_e32 v166, v166
	v_pk_add_f32 v[160:161], v[160:161], 1.0 op_sel_hi:[1,0]
	v_mul_f32_e32 v159, 0x3fb8aa3b, v77
	v_exp_f32_e32 v158, v158
	v_mul_f32_e32 v181, 0x3f317217, v166
	v_fma_f32 v181, v166, s97, -v181
	v_fmac_f32_e32 v181, 0x3377d1cf, v166
	v_fmac_f32_e32 v181, 0x3f317217, v166
	v_cmp_lt_f32_e64 s[0:1], |v166|, s94
	v_exp_f32_e32 v159, v159
	v_cndmask_b32_e64 v180, v180, 0, s[36:37]
	v_cndmask_b32_e64 v166, v166, v181, s[0:1]
	v_cndmask_b32_e32 v181, 0, v190, vcc
	v_sub_f32_e32 v166, v166, v181
	v_rcp_f32_e32 v193, v169
	v_pk_add_f32 v[158:159], v[158:159], 1.0 op_sel_hi:[1,0]
	v_ashrrev_i32_e32 v155, 31, v154
	v_lshlrev_b64 v[154:155], 10, v[154:155]
	v_mul_f32_e32 v169, v174, v193
	v_rcp_f32_e32 v193, v168
	v_lshl_add_u64 v[156:157], v[150:151], 0, v[154:155]
	v_lshl_add_u64 v[154:155], v[152:153], 0, v[154:155]
	v_mul_f32_e32 v168, v138, v193
	v_sub_f32_e32 v181, 1.0, v168
	v_cmp_gt_f32_e32 vcc, s96, v181
	v_cndmask_b32_e64 v168, v168, 0, s[36:37]
	s_nop 0
	v_cndmask_b32_e64 v193, 0, 32, vcc
	v_ldexp_f32 v181, v181, v193
	v_log_f32_e32 v181, v181
	v_cvt_pk_bf16_f32 v168, v180, v168
	v_mul_f32_e32 v193, 0x3f317217, v181
	v_fma_f32 v193, v181, s97, -v193
	v_fmac_f32_e32 v193, 0x3377d1cf, v181
	v_fmac_f32_e32 v193, 0x3f317217, v181
	v_cmp_lt_f32_e64 s[0:1], |v181|, s94
	s_nop 1
	v_cndmask_b32_e64 v181, v181, v193, s[0:1]
	v_cndmask_b32_e32 v193, 0, v190, vcc
	v_sub_f32_e32 v181, v181, v193
	v_sub_f32_e32 v193, 1.0, v167
	v_cmp_gt_f32_e32 vcc, s96, v193
	v_cndmask_b32_e64 v167, v167, 0, s[36:37]
	s_nop 0
	v_cndmask_b32_e64 v194, 0, 32, vcc
	v_ldexp_f32 v193, v193, v194
	v_log_f32_e32 v193, v193
	s_nop 0
	v_mul_f32_e32 v194, 0x3f317217, v193
	v_fma_f32 v194, v193, s97, -v194
	v_fmac_f32_e32 v194, 0x3377d1cf, v193
	v_fmac_f32_e32 v194, 0x3f317217, v193
	v_cmp_lt_f32_e64 s[0:1], |v193|, s94
	s_nop 1
	v_cndmask_b32_e64 v193, v193, v194, s[0:1]
	v_cndmask_b32_e32 v194, 0, v190, vcc
	v_sub_f32_e32 v193, v193, v194
	v_sub_f32_e32 v194, 1.0, v169
	v_cmp_gt_f32_e32 vcc, s96, v194
	v_cndmask_b32_e64 v169, v169, 0, s[36:37]
	s_nop 0
	v_cndmask_b32_e64 v195, 0, 32, vcc
	v_ldexp_f32 v194, v194, v195
	v_log_f32_e32 v194, v194
	v_cvt_pk_bf16_f32 v169, v167, v169
	v_mul_f32_e32 v195, 0x3f317217, v194
	v_fma_f32 v195, v194, s97, -v195
	v_fmac_f32_e32 v195, 0x3377d1cf, v194
	v_fmac_f32_e32 v195, 0x3f317217, v194
	v_cmp_lt_f32_e64 s[0:1], |v194|, s94
	s_nop 1
	v_cndmask_b32_e64 v194, v194, v195, s[0:1]
	v_cndmask_b32_e32 v195, 0, v190, vcc
	v_sub_f32_e32 v194, v194, v195
	v_rcp_f32_e32 v196, v161
	s_nop 0
	v_mul_f32_e32 v161, v179, v196
	v_rcp_f32_e32 v196, v160
	s_nop 0
	v_mul_f32_e32 v160, v177, v196
	v_sub_f32_e32 v195, 1.0, v160
	v_cmp_gt_f32_e32 vcc, s96, v195
	v_cndmask_b32_e64 v160, v160, 0, s[36:37]
	v_bfe_u32 v201, v160, 16, 1
	v_cndmask_b32_e64 v196, 0, 32, vcc
	v_ldexp_f32 v195, v195, v196
	v_log_f32_e32 v195, v195
	v_add3_u32 v160, v160, v201, s87
	v_lshrrev_b32_e32 v160, 16, v160
	v_mul_f32_e32 v196, 0x3f317217, v195
	v_fma_f32 v196, v195, s97, -v196
	v_fmac_f32_e32 v196, 0x3377d1cf, v195
	v_fmac_f32_e32 v196, 0x3f317217, v195
	v_cmp_lt_f32_e64 s[0:1], |v195|, s94
	s_nop 1
	v_cndmask_b32_e64 v195, v195, v196, s[0:1]
	v_cndmask_b32_e32 v196, 0, v190, vcc
	v_sub_f32_e32 v195, v195, v196
	v_rcp_f32_e32 v197, v159
	s_nop 0
	v_mul_f32_e32 v159, v178, v197
	v_rcp_f32_e32 v197, v158
	s_nop 0
	v_mul_f32_e32 v158, v175, v197
	v_sub_f32_e32 v196, 1.0, v158
	v_cmp_gt_f32_e32 vcc, s96, v196
	v_cndmask_b32_e64 v158, v158, 0, s[36:37]
	v_bfe_u32 v200, v158, 16, 1
	v_cndmask_b32_e64 v197, 0, 32, vcc
	v_ldexp_f32 v196, v196, v197
	v_log_f32_e32 v196, v196
	v_add3_u32 v158, v158, v200, s87
	v_mul_f32_e32 v197, 0x3f317217, v196
	v_fma_f32 v197, v196, s97, -v197
	v_fmac_f32_e32 v197, 0x3377d1cf, v196
	v_fmac_f32_e32 v197, 0x3f317217, v196
	v_cmp_lt_f32_e64 s[0:1], |v196|, s94
	v_and_or_b32 v160, v158, s88, v160
	s_nop 0
	v_cndmask_b32_e64 v196, v196, v197, s[0:1]
	v_cndmask_b32_e32 v197, 0, v190, vcc
	v_sub_f32_e32 v196, v196, v197
	v_sub_f32_e32 v197, 1.0, v161
	v_cmp_gt_f32_e32 vcc, s96, v197
	v_cndmask_b32_e64 v161, v161, 0, s[36:37]
	v_bfe_u32 v202, v161, 16, 1
	v_cndmask_b32_e64 v198, 0, 32, vcc
	v_ldexp_f32 v197, v197, v198
	v_log_f32_e32 v197, v197
	v_add3_u32 v161, v161, v202, s87
	v_lshrrev_b32_e32 v161, 16, v161
	v_mul_f32_e32 v198, 0x3f317217, v197
	v_fma_f32 v198, v197, s97, -v198
	v_fmac_f32_e32 v198, 0x3377d1cf, v197
	v_fmac_f32_e32 v198, 0x3f317217, v197
	v_cmp_lt_f32_e64 s[0:1], |v197|, s94
	s_nop 1
	v_cndmask_b32_e64 v197, v197, v198, s[0:1]
	v_cndmask_b32_e32 v198, 0, v190, vcc
	v_sub_f32_e32 v197, v197, v198
	v_sub_f32_e32 v198, 1.0, v159
	v_cmp_gt_f32_e32 vcc, s96, v198
	v_cndmask_b32_e64 v159, v159, 0, s[36:37]
	s_nop 0
	v_cndmask_b32_e64 v199, 0, 32, vcc
	v_ldexp_f32 v198, v198, v199
	v_log_f32_e32 v198, v198
	s_nop 0
	v_mul_f32_e32 v199, 0x3f317217, v198
	v_fma_f32 v199, v198, s97, -v199
	v_fmac_f32_e32 v199, 0x3377d1cf, v198
	v_fmac_f32_e32 v199, 0x3f317217, v198
	v_cmp_lt_f32_e64 s[0:1], |v198|, s94
	s_nop 1
	v_cndmask_b32_e64 v198, v198, v199, s[0:1]
	v_cndmask_b32_e32 v199, 0, v190, vcc
	v_sub_f32_e32 v198, v198, v199
	v_bfe_u32 v199, v159, 16, 1
	v_add3_u32 v159, v159, v199, s87
	v_and_or_b32 v161, v159, s88, v161
	v_mov_b32_e32 v159, v169
	v_mov_b32_e32 v158, v168
	global_store_dwordx4 v[156:157], v[158:161], off
	s_nop 1
	v_cndmask_b32_e64 v158, v166, 0, s[36:37]
	v_bfe_u32 v159, v158, 16, 1
	v_add3_u32 v158, v158, v159, s87
	v_cndmask_b32_e64 v159, v181, 0, s[36:37]
	v_bfe_u32 v160, v159, 16, 1
	v_lshrrev_b32_e32 v158, 16, v158
	v_add3_u32 v159, v159, v160, s87
	v_and_or_b32 v158, v159, s88, v158
	v_cndmask_b32_e64 v159, v193, 0, s[36:37]
	v_bfe_u32 v160, v159, 16, 1
	v_add3_u32 v159, v159, v160, s87
	v_cndmask_b32_e64 v160, v194, 0, s[36:37]
	v_bfe_u32 v161, v160, 16, 1
	v_lshrrev_b32_e32 v159, 16, v159
	v_add3_u32 v160, v160, v161, s87
	v_and_or_b32 v159, v160, s88, v159
	v_cndmask_b32_e64 v160, v195, 0, s[36:37]
	v_bfe_u32 v161, v160, 16, 1
	v_add3_u32 v160, v160, v161, s87
	v_cndmask_b32_e64 v161, v196, 0, s[36:37]
	v_bfe_u32 v166, v161, 16, 1
	v_lshrrev_b32_e32 v160, 16, v160
	v_add3_u32 v161, v161, v166, s87
	v_and_or_b32 v160, v161, s88, v160
	v_cndmask_b32_e64 v161, v197, 0, s[36:37]
	v_bfe_u32 v166, v161, 16, 1
	v_add3_u32 v161, v161, v166, s87
	v_cndmask_b32_e64 v166, v198, 0, s[36:37]
	v_bfe_u32 v167, v166, 16, 1
	v_lshrrev_b32_e32 v161, 16, v161
	v_add3_u32 v166, v166, v167, s87
	v_and_or_b32 v161, v166, s88, v161
	global_store_dwordx4 v[154:155], v[158:161], off
	s_nop 1
	v_mul_f32_e32 v158, 0x3fb8aa3b, v70
	v_exp_f32_e32 v166, v158
	v_mul_f32_e32 v158, 0x3fb8aa3b, v71
	v_exp_f32_e32 v168, v158
	v_mul_f32_e32 v158, 0x3fb8aa3b, v72
	v_exp_f32_e32 v167, v158
	v_mul_f32_e32 v158, 0x3fb8aa3b, v73
	v_exp_f32_e32 v169, v158
	v_mul_f32_e32 v158, 0x3fb8aa3b, v66
	v_pk_add_f32 v[166:167], v[166:167], 1.0 op_sel_hi:[1,0]
	v_mul_f32_e32 v159, 0x3fb8aa3b, v68
	v_rcp_f32_e32 v181, v167
	v_pk_add_f32 v[168:169], v[168:169], 1.0 op_sel_hi:[1,0]
	v_exp_f32_e32 v160, v158
	v_exp_f32_e32 v161, v159
	v_mul_f32_e32 v167, v165, v181
	v_rcp_f32_e32 v181, v166
	v_pk_add_f32 v[160:161], v[160:161], 1.0 op_sel_hi:[1,0]
	v_mul_f32_e32 v158, 0x3fb8aa3b, v67
	v_mul_f32_e32 v159, 0x3fb8aa3b, v69
	v_mul_f32_e32 v180, v164, v181
	v_sub_f32_e32 v166, 1.0, v180
	v_cmp_gt_f32_e32 vcc, s96, v166
	v_exp_f32_e32 v158, v158
	v_exp_f32_e32 v159, v159
	v_cndmask_b32_e64 v181, 0, 32, vcc
	v_ldexp_f32 v166, v166, v181
	v_log_f32_e32 v166, v166
	v_pk_add_f32 v[158:159], v[158:159], 1.0 op_sel_hi:[1,0]
	v_cndmask_b32_e64 v180, v180, 0, s[36:37]
	v_mul_f32_e32 v181, 0x3f317217, v166
	v_fma_f32 v181, v166, s97, -v181
	v_fmac_f32_e32 v181, 0x3377d1cf, v166
	v_fmac_f32_e32 v181, 0x3f317217, v166
	v_cmp_lt_f32_e64 s[0:1], |v166|, s94
	s_nop 1
	v_cndmask_b32_e64 v166, v166, v181, s[0:1]
	v_cndmask_b32_e32 v181, 0, v190, vcc
	v_sub_f32_e32 v166, v166, v181
	v_rcp_f32_e32 v193, v169
	s_nop 0
	v_mul_f32_e32 v169, v163, v193
	v_rcp_f32_e32 v193, v168
	s_nop 0
	v_mul_f32_e32 v168, v162, v193
	v_sub_f32_e32 v181, 1.0, v168
	v_cmp_gt_f32_e32 vcc, s96, v181
	v_cndmask_b32_e64 v168, v168, 0, s[36:37]
	s_nop 0
	v_cndmask_b32_e64 v193, 0, 32, vcc
	v_ldexp_f32 v181, v181, v193
	v_log_f32_e32 v181, v181
	v_cvt_pk_bf16_f32 v168, v180, v168
	v_mul_f32_e32 v193, 0x3f317217, v181
	v_fma_f32 v193, v181, s97, -v193
	v_fmac_f32_e32 v193, 0x3377d1cf, v181
	v_fmac_f32_e32 v193, 0x3f317217, v181
	v_cmp_lt_f32_e64 s[0:1], |v181|, s94
	s_nop 1
	v_cndmask_b32_e64 v181, v181, v193, s[0:1]
	v_cndmask_b32_e32 v193, 0, v190, vcc
	v_sub_f32_e32 v181, v181, v193
	v_sub_f32_e32 v193, 1.0, v167
	v_cmp_gt_f32_e32 vcc, s96, v193
	v_cndmask_b32_e64 v167, v167, 0, s[36:37]
	s_nop 0
	v_cndmask_b32_e64 v194, 0, 32, vcc
	v_ldexp_f32 v193, v193, v194
	v_log_f32_e32 v193, v193
	s_nop 0
	v_mul_f32_e32 v194, 0x3f317217, v193
	v_fma_f32 v194, v193, s97, -v194
	v_fmac_f32_e32 v194, 0x3377d1cf, v193
	v_fmac_f32_e32 v194, 0x3f317217, v193
	v_cmp_lt_f32_e64 s[0:1], |v193|, s94
	s_nop 1
	v_cndmask_b32_e64 v193, v193, v194, s[0:1]
	v_cndmask_b32_e32 v194, 0, v190, vcc
	v_sub_f32_e32 v193, v193, v194
	v_sub_f32_e32 v194, 1.0, v169
	v_cmp_gt_f32_e32 vcc, s96, v194
	v_cndmask_b32_e64 v169, v169, 0, s[36:37]
	s_nop 0
	v_cndmask_b32_e64 v195, 0, 32, vcc
	v_ldexp_f32 v194, v194, v195
	v_log_f32_e32 v194, v194
	v_cvt_pk_bf16_f32 v169, v167, v169
	v_mul_f32_e32 v195, 0x3f317217, v194
	v_fma_f32 v195, v194, s97, -v195
	v_fmac_f32_e32 v195, 0x3377d1cf, v194
	v_fmac_f32_e32 v195, 0x3f317217, v194
	v_cmp_lt_f32_e64 s[0:1], |v194|, s94
	s_nop 1
	v_cndmask_b32_e64 v194, v194, v195, s[0:1]
	v_cndmask_b32_e32 v195, 0, v190, vcc
	v_sub_f32_e32 v194, v194, v195
	v_rcp_f32_e32 v196, v161
	s_nop 0
	v_mul_f32_e32 v161, v173, v196
	v_rcp_f32_e32 v196, v160
	s_nop 0
	v_mul_f32_e32 v160, v171, v196
	v_sub_f32_e32 v195, 1.0, v160
	v_cmp_gt_f32_e32 vcc, s96, v195
	v_cndmask_b32_e64 v160, v160, 0, s[36:37]
	v_bfe_u32 v201, v160, 16, 1
	v_cndmask_b32_e64 v196, 0, 32, vcc
	v_ldexp_f32 v195, v195, v196
	v_log_f32_e32 v195, v195
	v_add3_u32 v160, v160, v201, s87
	v_lshrrev_b32_e32 v160, 16, v160
	v_mul_f32_e32 v196, 0x3f317217, v195
	v_fma_f32 v196, v195, s97, -v196
	v_fmac_f32_e32 v196, 0x3377d1cf, v195
	v_fmac_f32_e32 v196, 0x3f317217, v195
	v_cmp_lt_f32_e64 s[0:1], |v195|, s94
	s_nop 1
	v_cndmask_b32_e64 v195, v195, v196, s[0:1]
	v_cndmask_b32_e32 v196, 0, v190, vcc
	v_sub_f32_e32 v195, v195, v196
	v_rcp_f32_e32 v197, v159
	s_nop 0
	v_mul_f32_e32 v159, v172, v197
	v_rcp_f32_e32 v197, v158
	s_nop 0
	v_mul_f32_e32 v158, v170, v197
	v_sub_f32_e32 v196, 1.0, v158
	v_cmp_gt_f32_e32 vcc, s96, v196
	v_cndmask_b32_e64 v158, v158, 0, s[36:37]
	v_bfe_u32 v200, v158, 16, 1
	v_cndmask_b32_e64 v197, 0, 32, vcc
	v_ldexp_f32 v196, v196, v197
	v_log_f32_e32 v196, v196
	v_add3_u32 v158, v158, v200, s87
	v_mul_f32_e32 v197, 0x3f317217, v196
	v_fma_f32 v197, v196, s97, -v197
	v_fmac_f32_e32 v197, 0x3377d1cf, v196
	v_fmac_f32_e32 v197, 0x3f317217, v196
	v_cmp_lt_f32_e64 s[0:1], |v196|, s94
	v_and_or_b32 v160, v158, s88, v160
	s_nop 0
	v_cndmask_b32_e64 v196, v196, v197, s[0:1]
	v_cndmask_b32_e32 v197, 0, v190, vcc
	v_sub_f32_e32 v196, v196, v197
	v_sub_f32_e32 v197, 1.0, v161
	v_cmp_gt_f32_e32 vcc, s96, v197
	v_cndmask_b32_e64 v161, v161, 0, s[36:37]
	v_bfe_u32 v202, v161, 16, 1
	v_cndmask_b32_e64 v198, 0, 32, vcc
	v_ldexp_f32 v197, v197, v198
	v_log_f32_e32 v197, v197
	v_add3_u32 v161, v161, v202, s87
	v_lshrrev_b32_e32 v161, 16, v161
	v_mul_f32_e32 v198, 0x3f317217, v197
	v_fma_f32 v198, v197, s97, -v198
	v_fmac_f32_e32 v198, 0x3377d1cf, v197
	v_fmac_f32_e32 v198, 0x3f317217, v197
	v_cmp_lt_f32_e64 s[0:1], |v197|, s94
	s_nop 1
	v_cndmask_b32_e64 v197, v197, v198, s[0:1]
	v_cndmask_b32_e32 v198, 0, v190, vcc
	v_sub_f32_e32 v197, v197, v198
	v_sub_f32_e32 v198, 1.0, v159
	v_cmp_gt_f32_e32 vcc, s96, v198
	v_cndmask_b32_e64 v159, v159, 0, s[36:37]
	s_nop 0
	v_cndmask_b32_e64 v199, 0, 32, vcc
	v_ldexp_f32 v198, v198, v199
	v_log_f32_e32 v198, v198
	s_nop 0
	v_mul_f32_e32 v199, 0x3f317217, v198
	v_fma_f32 v199, v198, s97, -v199
	v_fmac_f32_e32 v199, 0x3377d1cf, v198
	v_fmac_f32_e32 v199, 0x3f317217, v198
	v_cmp_lt_f32_e64 s[0:1], |v198|, s94
	s_nop 1
	v_cndmask_b32_e64 v198, v198, v199, s[0:1]
	v_cndmask_b32_e32 v199, 0, v190, vcc
	v_sub_f32_e32 v198, v198, v199
	v_bfe_u32 v199, v159, 16, 1
	v_add3_u32 v159, v159, v199, s87
	v_and_or_b32 v161, v159, s88, v161
	v_mov_b32_e32 v159, v169
	v_mov_b32_e32 v158, v168
	global_store_dwordx4 v[156:157], v[158:161], off offset:256
	v_cndmask_b32_e64 v156, v166, 0, s[36:37]
	v_bfe_u32 v157, v156, 16, 1
	v_add3_u32 v156, v156, v157, s87
	v_cndmask_b32_e64 v157, v181, 0, s[36:37]
	v_bfe_u32 v158, v157, 16, 1
	v_lshrrev_b32_e32 v156, 16, v156
	v_add3_u32 v157, v157, v158, s87
	v_and_or_b32 v156, v157, s88, v156
	v_cndmask_b32_e64 v157, v193, 0, s[36:37]
	v_bfe_u32 v158, v157, 16, 1
	v_add3_u32 v157, v157, v158, s87
	v_cndmask_b32_e64 v158, v194, 0, s[36:37]
	v_bfe_u32 v159, v158, 16, 1
	v_lshrrev_b32_e32 v157, 16, v157
	v_add3_u32 v158, v158, v159, s87
	v_and_or_b32 v157, v158, s88, v157
	v_cndmask_b32_e64 v158, v195, 0, s[36:37]
	v_bfe_u32 v159, v158, 16, 1
	v_add3_u32 v158, v158, v159, s87
	v_cndmask_b32_e64 v159, v196, 0, s[36:37]
	v_bfe_u32 v160, v159, 16, 1
	v_lshrrev_b32_e32 v158, 16, v158
	v_add3_u32 v159, v159, v160, s87
	v_and_or_b32 v158, v159, s88, v158
	v_cndmask_b32_e64 v159, v197, 0, s[36:37]
	v_bfe_u32 v160, v159, 16, 1
	v_add3_u32 v159, v159, v160, s87
	v_cndmask_b32_e64 v160, v198, 0, s[36:37]
	v_bfe_u32 v161, v160, 16, 1
	v_lshrrev_b32_e32 v159, 16, v159
	v_add3_u32 v160, v160, v161, s87
	v_and_or_b32 v159, v160, s88, v159
	global_store_dwordx4 v[154:155], v[156:159], off offset:256
	s_movk_i32 s0, 0x4080
	v_cmp_gt_i32_e32 vcc, s0, v148
	v_mul_f32_e32 v158, 0x3fb8aa3b, v62
	v_exp_f32_e32 v166, v158
	v_mul_f32_e32 v158, 0x3fb8aa3b, v63
	v_exp_f32_e32 v168, v158
	v_mul_f32_e32 v158, 0x3fb8aa3b, v64
	s_movk_i32 s0, 0x2000
	v_exp_f32_e32 v167, v158
	v_cmp_gt_i32_e64 s[0:1], s0, v148
	v_add_u32_e32 v154, 0x80, v148
	v_mul_f32_e32 v158, 0x3fb8aa3b, v65
	v_cndmask_b32_e64 v155, v189, 0, s[0:1]
	v_add_u32_e32 v155, v155, v154
	v_cmp_gt_i32_e64 s[0:1], s95, v155
	v_pk_add_f32 v[166:167], v[166:167], 1.0 op_sel_hi:[1,0]
	s_and_b64 s[36:37], vcc, s[0:1]
	v_rcp_f32_e32 v181, v167
	v_exp_f32_e32 v169, v158
	v_mul_f32_e32 v158, 0x3fb8aa3b, v58
	v_mul_f32_e32 v159, 0x3fb8aa3b, v60
	v_mul_f32_e32 v167, v176, v181
	v_rcp_f32_e32 v181, v166
	v_pk_add_f32 v[168:169], v[168:169], 1.0 op_sel_hi:[1,0]
	v_exp_f32_e32 v160, v158
	v_exp_f32_e32 v161, v159
	v_mul_f32_e32 v180, v149, v181
	v_sub_f32_e32 v166, 1.0, v180
	v_cmp_gt_f32_e32 vcc, s96, v166
	v_pk_add_f32 v[160:161], v[160:161], 1.0 op_sel_hi:[1,0]
	v_mul_f32_e32 v158, 0x3fb8aa3b, v59
	v_cndmask_b32_e64 v181, 0, 32, vcc
	v_ldexp_f32 v166, v166, v181
	v_log_f32_e32 v166, v166
	v_mul_f32_e32 v159, 0x3fb8aa3b, v61
	v_exp_f32_e32 v158, v158
	v_exp_f32_e32 v159, v159
	v_mul_f32_e32 v181, 0x3f317217, v166
	v_fma_f32 v181, v166, s97, -v181
	v_fmac_f32_e32 v181, 0x3377d1cf, v166
	v_fmac_f32_e32 v181, 0x3f317217, v166
	v_cmp_lt_f32_e64 s[0:1], |v166|, s94
	v_pk_add_f32 v[158:159], v[158:159], 1.0 op_sel_hi:[1,0]
	v_cndmask_b32_e64 v180, v180, 0, s[36:37]
	v_cndmask_b32_e64 v166, v166, v181, s[0:1]
	v_cndmask_b32_e32 v181, 0, v190, vcc
	v_sub_f32_e32 v166, v166, v181
	v_rcp_f32_e32 v193, v169
	v_ashrrev_i32_e32 v155, 31, v154
	v_lshlrev_b64 v[154:155], 10, v[154:155]
	v_lshl_add_u64 v[156:157], v[150:151], 0, v[154:155]
	v_mul_f32_e32 v169, v174, v193
	v_rcp_f32_e32 v193, v168
	v_lshl_add_u64 v[154:155], v[152:153], 0, v[154:155]
	v_mul_f32_e32 v168, v138, v193
	v_sub_f32_e32 v181, 1.0, v168
	v_cmp_gt_f32_e32 vcc, s96, v181
	v_cndmask_b32_e64 v168, v168, 0, s[36:37]
	s_nop 0
	v_cndmask_b32_e64 v193, 0, 32, vcc
	v_ldexp_f32 v181, v181, v193
	v_log_f32_e32 v181, v181
	v_cvt_pk_bf16_f32 v168, v180, v168
	v_mul_f32_e32 v193, 0x3f317217, v181
	v_fma_f32 v193, v181, s97, -v193
	v_fmac_f32_e32 v193, 0x3377d1cf, v181
	v_fmac_f32_e32 v193, 0x3f317217, v181
	v_cmp_lt_f32_e64 s[0:1], |v181|, s94
	s_nop 1
	v_cndmask_b32_e64 v181, v181, v193, s[0:1]
	v_cndmask_b32_e32 v193, 0, v190, vcc
	v_sub_f32_e32 v181, v181, v193
	v_sub_f32_e32 v193, 1.0, v167
	v_cmp_gt_f32_e32 vcc, s96, v193
	v_cndmask_b32_e64 v167, v167, 0, s[36:37]
	s_nop 0
	v_cndmask_b32_e64 v194, 0, 32, vcc
	v_ldexp_f32 v193, v193, v194
	v_log_f32_e32 v193, v193
	s_nop 0
	v_mul_f32_e32 v194, 0x3f317217, v193
	v_fma_f32 v194, v193, s97, -v194
	v_fmac_f32_e32 v194, 0x3377d1cf, v193
	v_fmac_f32_e32 v194, 0x3f317217, v193
	v_cmp_lt_f32_e64 s[0:1], |v193|, s94
	s_nop 1
	v_cndmask_b32_e64 v193, v193, v194, s[0:1]
	v_cndmask_b32_e32 v194, 0, v190, vcc
	v_sub_f32_e32 v193, v193, v194
	v_sub_f32_e32 v194, 1.0, v169
	v_cmp_gt_f32_e32 vcc, s96, v194
	v_cndmask_b32_e64 v169, v169, 0, s[36:37]
	s_nop 0
	v_cndmask_b32_e64 v195, 0, 32, vcc
	v_ldexp_f32 v194, v194, v195
	v_log_f32_e32 v194, v194
	v_cvt_pk_bf16_f32 v169, v167, v169
	v_mul_f32_e32 v195, 0x3f317217, v194
	v_fma_f32 v195, v194, s97, -v195
	v_fmac_f32_e32 v195, 0x3377d1cf, v194
	v_fmac_f32_e32 v195, 0x3f317217, v194
	v_cmp_lt_f32_e64 s[0:1], |v194|, s94
	s_nop 1
	v_cndmask_b32_e64 v194, v194, v195, s[0:1]
	v_cndmask_b32_e32 v195, 0, v190, vcc
	v_sub_f32_e32 v194, v194, v195
	v_rcp_f32_e32 v196, v161
	s_nop 0
	v_mul_f32_e32 v161, v179, v196
	v_rcp_f32_e32 v196, v160
	s_nop 0
	v_mul_f32_e32 v160, v177, v196
	v_sub_f32_e32 v195, 1.0, v160
	v_cmp_gt_f32_e32 vcc, s96, v195
	v_cndmask_b32_e64 v160, v160, 0, s[36:37]
	v_bfe_u32 v201, v160, 16, 1
	v_cndmask_b32_e64 v196, 0, 32, vcc
	v_ldexp_f32 v195, v195, v196
	v_log_f32_e32 v195, v195
	v_add3_u32 v160, v160, v201, s87
	v_lshrrev_b32_e32 v160, 16, v160
	v_mul_f32_e32 v196, 0x3f317217, v195
	v_fma_f32 v196, v195, s97, -v196
	v_fmac_f32_e32 v196, 0x3377d1cf, v195
	v_fmac_f32_e32 v196, 0x3f317217, v195
	v_cmp_lt_f32_e64 s[0:1], |v195|, s94
	s_nop 1
	v_cndmask_b32_e64 v195, v195, v196, s[0:1]
	v_cndmask_b32_e32 v196, 0, v190, vcc
	v_sub_f32_e32 v195, v195, v196
	v_rcp_f32_e32 v197, v159
	s_nop 0
	v_mul_f32_e32 v159, v178, v197
	v_rcp_f32_e32 v197, v158
	s_nop 0
	v_mul_f32_e32 v158, v175, v197
	v_sub_f32_e32 v196, 1.0, v158
	v_cmp_gt_f32_e32 vcc, s96, v196
	v_cndmask_b32_e64 v158, v158, 0, s[36:37]
	v_bfe_u32 v200, v158, 16, 1
	v_cndmask_b32_e64 v197, 0, 32, vcc
	v_ldexp_f32 v196, v196, v197
	v_log_f32_e32 v196, v196
	v_add3_u32 v158, v158, v200, s87
	v_mul_f32_e32 v197, 0x3f317217, v196
	v_fma_f32 v197, v196, s97, -v197
	v_fmac_f32_e32 v197, 0x3377d1cf, v196
	v_fmac_f32_e32 v197, 0x3f317217, v196
	v_cmp_lt_f32_e64 s[0:1], |v196|, s94
	v_and_or_b32 v160, v158, s88, v160
	s_nop 0
	v_cndmask_b32_e64 v196, v196, v197, s[0:1]
	v_cndmask_b32_e32 v197, 0, v190, vcc
	v_sub_f32_e32 v196, v196, v197
	v_sub_f32_e32 v197, 1.0, v161
	v_cmp_gt_f32_e32 vcc, s96, v197
	v_cndmask_b32_e64 v161, v161, 0, s[36:37]
	v_bfe_u32 v202, v161, 16, 1
	v_cndmask_b32_e64 v198, 0, 32, vcc
	v_ldexp_f32 v197, v197, v198
	v_log_f32_e32 v197, v197
	v_add3_u32 v161, v161, v202, s87
	v_lshrrev_b32_e32 v161, 16, v161
	v_mul_f32_e32 v198, 0x3f317217, v197
	v_fma_f32 v198, v197, s97, -v198
	v_fmac_f32_e32 v198, 0x3377d1cf, v197
	v_fmac_f32_e32 v198, 0x3f317217, v197
	v_cmp_lt_f32_e64 s[0:1], |v197|, s94
	s_nop 1
	v_cndmask_b32_e64 v197, v197, v198, s[0:1]
	v_cndmask_b32_e32 v198, 0, v190, vcc
	v_sub_f32_e32 v197, v197, v198
	v_sub_f32_e32 v198, 1.0, v159
	v_cmp_gt_f32_e32 vcc, s96, v198
	v_cndmask_b32_e64 v159, v159, 0, s[36:37]
	s_nop 0
	v_cndmask_b32_e64 v199, 0, 32, vcc
	v_ldexp_f32 v198, v198, v199
	v_log_f32_e32 v198, v198
	s_nop 0
	v_mul_f32_e32 v199, 0x3f317217, v198
	v_fma_f32 v199, v198, s97, -v199
	v_fmac_f32_e32 v199, 0x3377d1cf, v198
	v_fmac_f32_e32 v199, 0x3f317217, v198
	v_cmp_lt_f32_e64 s[0:1], |v198|, s94
	s_nop 1
	v_cndmask_b32_e64 v198, v198, v199, s[0:1]
	v_cndmask_b32_e32 v199, 0, v190, vcc
	v_sub_f32_e32 v198, v198, v199
	v_bfe_u32 v199, v159, 16, 1
	v_add3_u32 v159, v159, v199, s87
	v_and_or_b32 v161, v159, s88, v161
	v_mov_b32_e32 v159, v169
	v_mov_b32_e32 v158, v168
	global_store_dwordx4 v[156:157], v[158:161], off
	s_nop 1
	v_cndmask_b32_e64 v158, v166, 0, s[36:37]
	v_bfe_u32 v159, v158, 16, 1
	v_add3_u32 v158, v158, v159, s87
	v_cndmask_b32_e64 v159, v181, 0, s[36:37]
	v_bfe_u32 v160, v159, 16, 1
	v_lshrrev_b32_e32 v158, 16, v158
	v_add3_u32 v159, v159, v160, s87
	v_and_or_b32 v158, v159, s88, v158
	v_cndmask_b32_e64 v159, v193, 0, s[36:37]
	v_bfe_u32 v160, v159, 16, 1
	v_add3_u32 v159, v159, v160, s87
	v_cndmask_b32_e64 v160, v194, 0, s[36:37]
	v_bfe_u32 v161, v160, 16, 1
	v_lshrrev_b32_e32 v159, 16, v159
	v_add3_u32 v160, v160, v161, s87
	v_and_or_b32 v159, v160, s88, v159
	v_cndmask_b32_e64 v160, v195, 0, s[36:37]
	v_bfe_u32 v161, v160, 16, 1
	v_add3_u32 v160, v160, v161, s87
	v_cndmask_b32_e64 v161, v196, 0, s[36:37]
	v_bfe_u32 v166, v161, 16, 1
	v_lshrrev_b32_e32 v160, 16, v160
	v_add3_u32 v161, v161, v166, s87
	v_and_or_b32 v160, v161, s88, v160
	v_cndmask_b32_e64 v161, v197, 0, s[36:37]
	v_bfe_u32 v166, v161, 16, 1
	v_add3_u32 v161, v161, v166, s87
	v_cndmask_b32_e64 v166, v198, 0, s[36:37]
	v_bfe_u32 v167, v166, 16, 1
	v_lshrrev_b32_e32 v161, 16, v161
	v_add3_u32 v166, v166, v167, s87
	v_and_or_b32 v161, v166, s88, v161
	global_store_dwordx4 v[154:155], v[158:161], off
	s_nop 1
	v_mul_f32_e32 v158, 0x3fb8aa3b, v54
	v_exp_f32_e32 v166, v158
	v_mul_f32_e32 v158, 0x3fb8aa3b, v55
	v_exp_f32_e32 v168, v158
	v_mul_f32_e32 v158, 0x3fb8aa3b, v56
	v_exp_f32_e32 v167, v158
	v_mul_f32_e32 v158, 0x3fb8aa3b, v57
	v_exp_f32_e32 v169, v158
	v_mul_f32_e32 v158, 0x3fb8aa3b, v50
	v_pk_add_f32 v[166:167], v[166:167], 1.0 op_sel_hi:[1,0]
	v_mul_f32_e32 v159, 0x3fb8aa3b, v52
	v_rcp_f32_e32 v181, v167
	v_pk_add_f32 v[168:169], v[168:169], 1.0 op_sel_hi:[1,0]
	v_exp_f32_e32 v160, v158
	v_exp_f32_e32 v161, v159
	v_mul_f32_e32 v167, v165, v181
	v_rcp_f32_e32 v181, v166
	v_pk_add_f32 v[160:161], v[160:161], 1.0 op_sel_hi:[1,0]
	v_mul_f32_e32 v158, 0x3fb8aa3b, v51
	v_mul_f32_e32 v159, 0x3fb8aa3b, v53
	v_mul_f32_e32 v180, v164, v181
	v_sub_f32_e32 v166, 1.0, v180
	v_cmp_gt_f32_e32 vcc, s96, v166
	v_exp_f32_e32 v158, v158
	v_exp_f32_e32 v159, v159
	v_cndmask_b32_e64 v181, 0, 32, vcc
	v_ldexp_f32 v166, v166, v181
	v_log_f32_e32 v166, v166
	v_pk_add_f32 v[158:159], v[158:159], 1.0 op_sel_hi:[1,0]
	v_cndmask_b32_e64 v180, v180, 0, s[36:37]
	v_mul_f32_e32 v181, 0x3f317217, v166
	v_fma_f32 v181, v166, s97, -v181
	v_fmac_f32_e32 v181, 0x3377d1cf, v166
	v_fmac_f32_e32 v181, 0x3f317217, v166
	v_cmp_lt_f32_e64 s[0:1], |v166|, s94
	s_nop 1
	v_cndmask_b32_e64 v166, v166, v181, s[0:1]
	v_cndmask_b32_e32 v181, 0, v190, vcc
	v_sub_f32_e32 v166, v166, v181
	v_rcp_f32_e32 v193, v169
	s_nop 0
	v_mul_f32_e32 v169, v163, v193
	v_rcp_f32_e32 v193, v168
	s_nop 0
	v_mul_f32_e32 v168, v162, v193
	v_sub_f32_e32 v181, 1.0, v168
	v_cmp_gt_f32_e32 vcc, s96, v181
	v_cndmask_b32_e64 v168, v168, 0, s[36:37]
	s_nop 0
	v_cndmask_b32_e64 v193, 0, 32, vcc
	v_ldexp_f32 v181, v181, v193
	v_log_f32_e32 v181, v181
	v_cvt_pk_bf16_f32 v168, v180, v168
	v_mul_f32_e32 v193, 0x3f317217, v181
	v_fma_f32 v193, v181, s97, -v193
	v_fmac_f32_e32 v193, 0x3377d1cf, v181
	v_fmac_f32_e32 v193, 0x3f317217, v181
	v_cmp_lt_f32_e64 s[0:1], |v181|, s94
	s_nop 1
	v_cndmask_b32_e64 v181, v181, v193, s[0:1]
	v_cndmask_b32_e32 v193, 0, v190, vcc
	v_sub_f32_e32 v181, v181, v193
	v_sub_f32_e32 v193, 1.0, v167
	v_cmp_gt_f32_e32 vcc, s96, v193
	v_cndmask_b32_e64 v167, v167, 0, s[36:37]
	s_nop 0
	v_cndmask_b32_e64 v194, 0, 32, vcc
	v_ldexp_f32 v193, v193, v194
	v_log_f32_e32 v193, v193
	s_nop 0
	v_mul_f32_e32 v194, 0x3f317217, v193
	v_fma_f32 v194, v193, s97, -v194
	v_fmac_f32_e32 v194, 0x3377d1cf, v193
	v_fmac_f32_e32 v194, 0x3f317217, v193
	v_cmp_lt_f32_e64 s[0:1], |v193|, s94
	s_nop 1
	v_cndmask_b32_e64 v193, v193, v194, s[0:1]
	v_cndmask_b32_e32 v194, 0, v190, vcc
	v_sub_f32_e32 v193, v193, v194
	v_sub_f32_e32 v194, 1.0, v169
	v_cmp_gt_f32_e32 vcc, s96, v194
	v_cndmask_b32_e64 v169, v169, 0, s[36:37]
	s_nop 0
	v_cndmask_b32_e64 v195, 0, 32, vcc
	v_ldexp_f32 v194, v194, v195
	v_log_f32_e32 v194, v194
	v_cvt_pk_bf16_f32 v169, v167, v169
	v_mul_f32_e32 v195, 0x3f317217, v194
	v_fma_f32 v195, v194, s97, -v195
	v_fmac_f32_e32 v195, 0x3377d1cf, v194
	v_fmac_f32_e32 v195, 0x3f317217, v194
	v_cmp_lt_f32_e64 s[0:1], |v194|, s94
	s_nop 1
	v_cndmask_b32_e64 v194, v194, v195, s[0:1]
	v_cndmask_b32_e32 v195, 0, v190, vcc
	v_sub_f32_e32 v194, v194, v195
	v_rcp_f32_e32 v196, v161
	s_nop 0
	v_mul_f32_e32 v161, v173, v196
	v_rcp_f32_e32 v196, v160
	s_nop 0
	v_mul_f32_e32 v160, v171, v196
	v_sub_f32_e32 v195, 1.0, v160
	v_cmp_gt_f32_e32 vcc, s96, v195
	v_cndmask_b32_e64 v160, v160, 0, s[36:37]
	v_bfe_u32 v201, v160, 16, 1
	v_cndmask_b32_e64 v196, 0, 32, vcc
	v_ldexp_f32 v195, v195, v196
	v_log_f32_e32 v195, v195
	v_add3_u32 v160, v160, v201, s87
	v_lshrrev_b32_e32 v160, 16, v160
	v_mul_f32_e32 v196, 0x3f317217, v195
	v_fma_f32 v196, v195, s97, -v196
	v_fmac_f32_e32 v196, 0x3377d1cf, v195
	v_fmac_f32_e32 v196, 0x3f317217, v195
	v_cmp_lt_f32_e64 s[0:1], |v195|, s94
	s_nop 1
	v_cndmask_b32_e64 v195, v195, v196, s[0:1]
	v_cndmask_b32_e32 v196, 0, v190, vcc
	v_sub_f32_e32 v195, v195, v196
	v_rcp_f32_e32 v197, v159
	s_nop 0
	v_mul_f32_e32 v159, v172, v197
	v_rcp_f32_e32 v197, v158
	s_nop 0
	v_mul_f32_e32 v158, v170, v197
	v_sub_f32_e32 v196, 1.0, v158
	v_cmp_gt_f32_e32 vcc, s96, v196
	v_cndmask_b32_e64 v158, v158, 0, s[36:37]
	v_bfe_u32 v200, v158, 16, 1
	v_cndmask_b32_e64 v197, 0, 32, vcc
	v_ldexp_f32 v196, v196, v197
	v_log_f32_e32 v196, v196
	v_add3_u32 v158, v158, v200, s87
	v_mul_f32_e32 v197, 0x3f317217, v196
	v_fma_f32 v197, v196, s97, -v197
	v_fmac_f32_e32 v197, 0x3377d1cf, v196
	v_fmac_f32_e32 v197, 0x3f317217, v196
	v_cmp_lt_f32_e64 s[0:1], |v196|, s94
	v_and_or_b32 v160, v158, s88, v160
	s_nop 0
	v_cndmask_b32_e64 v196, v196, v197, s[0:1]
	v_cndmask_b32_e32 v197, 0, v190, vcc
	v_sub_f32_e32 v196, v196, v197
	v_sub_f32_e32 v197, 1.0, v161
	v_cmp_gt_f32_e32 vcc, s96, v197
	v_cndmask_b32_e64 v161, v161, 0, s[36:37]
	v_bfe_u32 v202, v161, 16, 1
	v_cndmask_b32_e64 v198, 0, 32, vcc
	v_ldexp_f32 v197, v197, v198
	v_log_f32_e32 v197, v197
	v_add3_u32 v161, v161, v202, s87
	v_lshrrev_b32_e32 v161, 16, v161
	v_mul_f32_e32 v198, 0x3f317217, v197
	v_fma_f32 v198, v197, s97, -v198
	v_fmac_f32_e32 v198, 0x3377d1cf, v197
	v_fmac_f32_e32 v198, 0x3f317217, v197
	v_cmp_lt_f32_e64 s[0:1], |v197|, s94
	s_nop 1
	v_cndmask_b32_e64 v197, v197, v198, s[0:1]
	v_cndmask_b32_e32 v198, 0, v190, vcc
	v_sub_f32_e32 v197, v197, v198
	v_sub_f32_e32 v198, 1.0, v159
	v_cmp_gt_f32_e32 vcc, s96, v198
	v_cndmask_b32_e64 v159, v159, 0, s[36:37]
	s_nop 0
	v_cndmask_b32_e64 v199, 0, 32, vcc
	v_ldexp_f32 v198, v198, v199
	v_log_f32_e32 v198, v198
	s_nop 0
	v_mul_f32_e32 v199, 0x3f317217, v198
	v_fma_f32 v199, v198, s97, -v199
	v_fmac_f32_e32 v199, 0x3377d1cf, v198
	v_fmac_f32_e32 v199, 0x3f317217, v198
	v_cmp_lt_f32_e64 s[0:1], |v198|, s94
	s_nop 1
	v_cndmask_b32_e64 v198, v198, v199, s[0:1]
	v_cndmask_b32_e32 v199, 0, v190, vcc
	v_sub_f32_e32 v198, v198, v199
	v_bfe_u32 v199, v159, 16, 1
	v_add3_u32 v159, v159, v199, s87
	v_and_or_b32 v161, v159, s88, v161
	v_mov_b32_e32 v159, v169
	v_mov_b32_e32 v158, v168
	global_store_dwordx4 v[156:157], v[158:161], off offset:256
	v_cndmask_b32_e64 v156, v166, 0, s[36:37]
	v_bfe_u32 v157, v156, 16, 1
	v_add3_u32 v156, v156, v157, s87
	v_cndmask_b32_e64 v157, v181, 0, s[36:37]
	v_bfe_u32 v158, v157, 16, 1
	v_lshrrev_b32_e32 v156, 16, v156
	v_add3_u32 v157, v157, v158, s87
	v_and_or_b32 v156, v157, s88, v156
	v_cndmask_b32_e64 v157, v193, 0, s[36:37]
	v_bfe_u32 v158, v157, 16, 1
	v_add3_u32 v157, v157, v158, s87
	v_cndmask_b32_e64 v158, v194, 0, s[36:37]
	v_bfe_u32 v159, v158, 16, 1
	v_lshrrev_b32_e32 v157, 16, v157
	v_add3_u32 v158, v158, v159, s87
	v_and_or_b32 v157, v158, s88, v157
	v_cndmask_b32_e64 v158, v195, 0, s[36:37]
	v_bfe_u32 v159, v158, 16, 1
	v_add3_u32 v158, v158, v159, s87
	v_cndmask_b32_e64 v159, v196, 0, s[36:37]
	v_bfe_u32 v160, v159, 16, 1
	v_lshrrev_b32_e32 v158, 16, v158
	v_add3_u32 v159, v159, v160, s87
	v_and_or_b32 v158, v159, s88, v158
	v_cndmask_b32_e64 v159, v197, 0, s[36:37]
	v_bfe_u32 v160, v159, 16, 1
	v_add3_u32 v159, v159, v160, s87
	v_cndmask_b32_e64 v160, v198, 0, s[36:37]
	v_bfe_u32 v161, v160, 16, 1
	v_lshrrev_b32_e32 v159, 16, v159
	v_add3_u32 v160, v160, v161, s87
	v_and_or_b32 v159, v160, s88, v159
	global_store_dwordx4 v[154:155], v[156:159], off offset:256
	s_movk_i32 s0, 0x4070
	v_cmp_gt_i32_e32 vcc, s0, v148
	v_mul_f32_e32 v158, 0x3fb8aa3b, v46
	v_exp_f32_e32 v166, v158
	v_mul_f32_e32 v158, 0x3fb8aa3b, v47
	v_exp_f32_e32 v168, v158
	v_mul_f32_e32 v158, 0x3fb8aa3b, v48
	s_movk_i32 s0, 0x1ff0
	v_exp_f32_e32 v167, v158
	v_cmp_gt_i32_e64 s[0:1], s0, v148
	v_add_u32_e32 v154, 0x90, v148
	v_mul_f32_e32 v158, 0x3fb8aa3b, v49
	v_cndmask_b32_e64 v155, v189, 0, s[0:1]
	v_add_u32_e32 v155, v155, v154
	v_cmp_gt_i32_e64 s[0:1], s95, v155
	v_pk_add_f32 v[166:167], v[166:167], 1.0 op_sel_hi:[1,0]
	s_and_b64 s[36:37], vcc, s[0:1]
	v_rcp_f32_e32 v181, v167
	v_exp_f32_e32 v169, v158
	v_mul_f32_e32 v158, 0x3fb8aa3b, v42
	v_mul_f32_e32 v159, 0x3fb8aa3b, v44
	v_mul_f32_e32 v167, v176, v181
	v_rcp_f32_e32 v181, v166
	v_pk_add_f32 v[168:169], v[168:169], 1.0 op_sel_hi:[1,0]
	v_exp_f32_e32 v160, v158
	v_exp_f32_e32 v161, v159
	v_mul_f32_e32 v180, v149, v181
	v_sub_f32_e32 v166, 1.0, v180
	v_cmp_gt_f32_e32 vcc, s96, v166
	v_pk_add_f32 v[160:161], v[160:161], 1.0 op_sel_hi:[1,0]
	v_mul_f32_e32 v158, 0x3fb8aa3b, v43
	v_cndmask_b32_e64 v181, 0, 32, vcc
	v_ldexp_f32 v166, v166, v181
	v_log_f32_e32 v166, v166
	v_mul_f32_e32 v159, 0x3fb8aa3b, v45
	v_exp_f32_e32 v158, v158
	v_exp_f32_e32 v159, v159
	v_mul_f32_e32 v181, 0x3f317217, v166
	v_fma_f32 v181, v166, s97, -v181
	v_fmac_f32_e32 v181, 0x3377d1cf, v166
	v_fmac_f32_e32 v181, 0x3f317217, v166
	v_cmp_lt_f32_e64 s[0:1], |v166|, s94
	v_pk_add_f32 v[158:159], v[158:159], 1.0 op_sel_hi:[1,0]
	v_cndmask_b32_e64 v180, v180, 0, s[36:37]
	v_cndmask_b32_e64 v166, v166, v181, s[0:1]
	v_cndmask_b32_e32 v181, 0, v190, vcc
	v_sub_f32_e32 v166, v166, v181
	v_rcp_f32_e32 v193, v169
	v_ashrrev_i32_e32 v155, 31, v154
	v_lshlrev_b64 v[154:155], 10, v[154:155]
	v_lshl_add_u64 v[156:157], v[150:151], 0, v[154:155]
	v_mul_f32_e32 v169, v174, v193
	v_rcp_f32_e32 v193, v168
	v_lshl_add_u64 v[154:155], v[152:153], 0, v[154:155]
	v_mul_f32_e32 v168, v138, v193
	v_sub_f32_e32 v181, 1.0, v168
	v_cmp_gt_f32_e32 vcc, s96, v181
	v_cndmask_b32_e64 v168, v168, 0, s[36:37]
	s_nop 0
	v_cndmask_b32_e64 v193, 0, 32, vcc
	v_ldexp_f32 v181, v181, v193
	v_log_f32_e32 v181, v181
	v_cvt_pk_bf16_f32 v168, v180, v168
	v_mul_f32_e32 v193, 0x3f317217, v181
	v_fma_f32 v193, v181, s97, -v193
	v_fmac_f32_e32 v193, 0x3377d1cf, v181
	v_fmac_f32_e32 v193, 0x3f317217, v181
	v_cmp_lt_f32_e64 s[0:1], |v181|, s94
	s_nop 1
	v_cndmask_b32_e64 v181, v181, v193, s[0:1]
	v_cndmask_b32_e32 v193, 0, v190, vcc
	v_sub_f32_e32 v181, v181, v193
	v_sub_f32_e32 v193, 1.0, v167
	v_cmp_gt_f32_e32 vcc, s96, v193
	v_cndmask_b32_e64 v167, v167, 0, s[36:37]
	s_nop 0
	v_cndmask_b32_e64 v194, 0, 32, vcc
	v_ldexp_f32 v193, v193, v194
	v_log_f32_e32 v193, v193
	s_nop 0
	v_mul_f32_e32 v194, 0x3f317217, v193
	v_fma_f32 v194, v193, s97, -v194
	v_fmac_f32_e32 v194, 0x3377d1cf, v193
	v_fmac_f32_e32 v194, 0x3f317217, v193
	v_cmp_lt_f32_e64 s[0:1], |v193|, s94
	s_nop 1
	v_cndmask_b32_e64 v193, v193, v194, s[0:1]
	v_cndmask_b32_e32 v194, 0, v190, vcc
	v_sub_f32_e32 v193, v193, v194
	v_sub_f32_e32 v194, 1.0, v169
	v_cmp_gt_f32_e32 vcc, s96, v194
	v_cndmask_b32_e64 v169, v169, 0, s[36:37]
	s_nop 0
	v_cndmask_b32_e64 v195, 0, 32, vcc
	v_ldexp_f32 v194, v194, v195
	v_log_f32_e32 v194, v194
	v_cvt_pk_bf16_f32 v169, v167, v169
	v_mul_f32_e32 v195, 0x3f317217, v194
	v_fma_f32 v195, v194, s97, -v195
	v_fmac_f32_e32 v195, 0x3377d1cf, v194
	v_fmac_f32_e32 v195, 0x3f317217, v194
	v_cmp_lt_f32_e64 s[0:1], |v194|, s94
	s_nop 1
	v_cndmask_b32_e64 v194, v194, v195, s[0:1]
	v_cndmask_b32_e32 v195, 0, v190, vcc
	v_sub_f32_e32 v194, v194, v195
	v_rcp_f32_e32 v196, v161
	s_nop 0
	v_mul_f32_e32 v161, v179, v196
	v_rcp_f32_e32 v196, v160
	s_nop 0
	v_mul_f32_e32 v160, v177, v196
	v_sub_f32_e32 v195, 1.0, v160
	v_cmp_gt_f32_e32 vcc, s96, v195
	v_cndmask_b32_e64 v160, v160, 0, s[36:37]
	v_bfe_u32 v201, v160, 16, 1
	v_cndmask_b32_e64 v196, 0, 32, vcc
	v_ldexp_f32 v195, v195, v196
	v_log_f32_e32 v195, v195
	v_add3_u32 v160, v160, v201, s87
	v_lshrrev_b32_e32 v160, 16, v160
	v_mul_f32_e32 v196, 0x3f317217, v195
	v_fma_f32 v196, v195, s97, -v196
	v_fmac_f32_e32 v196, 0x3377d1cf, v195
	v_fmac_f32_e32 v196, 0x3f317217, v195
	v_cmp_lt_f32_e64 s[0:1], |v195|, s94
	s_nop 1
	v_cndmask_b32_e64 v195, v195, v196, s[0:1]
	v_cndmask_b32_e32 v196, 0, v190, vcc
	v_sub_f32_e32 v195, v195, v196
	v_rcp_f32_e32 v197, v159
	s_nop 0
	v_mul_f32_e32 v159, v178, v197
	v_rcp_f32_e32 v197, v158
	s_nop 0
	v_mul_f32_e32 v158, v175, v197
	v_sub_f32_e32 v196, 1.0, v158
	v_cmp_gt_f32_e32 vcc, s96, v196
	v_cndmask_b32_e64 v158, v158, 0, s[36:37]
	v_bfe_u32 v200, v158, 16, 1
	v_cndmask_b32_e64 v197, 0, 32, vcc
	v_ldexp_f32 v196, v196, v197
	v_log_f32_e32 v196, v196
	v_add3_u32 v158, v158, v200, s87
	v_mul_f32_e32 v197, 0x3f317217, v196
	v_fma_f32 v197, v196, s97, -v197
	v_fmac_f32_e32 v197, 0x3377d1cf, v196
	v_fmac_f32_e32 v197, 0x3f317217, v196
	v_cmp_lt_f32_e64 s[0:1], |v196|, s94
	v_and_or_b32 v160, v158, s88, v160
	s_nop 0
	v_cndmask_b32_e64 v196, v196, v197, s[0:1]
	v_cndmask_b32_e32 v197, 0, v190, vcc
	v_sub_f32_e32 v196, v196, v197
	v_sub_f32_e32 v197, 1.0, v161
	v_cmp_gt_f32_e32 vcc, s96, v197
	v_cndmask_b32_e64 v161, v161, 0, s[36:37]
	v_bfe_u32 v202, v161, 16, 1
	v_cndmask_b32_e64 v198, 0, 32, vcc
	v_ldexp_f32 v197, v197, v198
	v_log_f32_e32 v197, v197
	v_add3_u32 v161, v161, v202, s87
	v_lshrrev_b32_e32 v161, 16, v161
	v_mul_f32_e32 v198, 0x3f317217, v197
	v_fma_f32 v198, v197, s97, -v198
	v_fmac_f32_e32 v198, 0x3377d1cf, v197
	v_fmac_f32_e32 v198, 0x3f317217, v197
	v_cmp_lt_f32_e64 s[0:1], |v197|, s94
	s_nop 1
	v_cndmask_b32_e64 v197, v197, v198, s[0:1]
	v_cndmask_b32_e32 v198, 0, v190, vcc
	v_sub_f32_e32 v197, v197, v198
	v_sub_f32_e32 v198, 1.0, v159
	v_cmp_gt_f32_e32 vcc, s96, v198
	v_cndmask_b32_e64 v159, v159, 0, s[36:37]
	s_nop 0
	v_cndmask_b32_e64 v199, 0, 32, vcc
	v_ldexp_f32 v198, v198, v199
	v_log_f32_e32 v198, v198
	s_nop 0
	v_mul_f32_e32 v199, 0x3f317217, v198
	v_fma_f32 v199, v198, s97, -v199
	v_fmac_f32_e32 v199, 0x3377d1cf, v198
	v_fmac_f32_e32 v199, 0x3f317217, v198
	v_cmp_lt_f32_e64 s[0:1], |v198|, s94
	s_nop 1
	v_cndmask_b32_e64 v198, v198, v199, s[0:1]
	v_cndmask_b32_e32 v199, 0, v190, vcc
	v_sub_f32_e32 v198, v198, v199
	v_bfe_u32 v199, v159, 16, 1
	v_add3_u32 v159, v159, v199, s87
	v_and_or_b32 v161, v159, s88, v161
	v_mov_b32_e32 v159, v169
	v_mov_b32_e32 v158, v168
	global_store_dwordx4 v[156:157], v[158:161], off
	s_nop 1
	v_cndmask_b32_e64 v158, v166, 0, s[36:37]
	v_bfe_u32 v159, v158, 16, 1
	v_add3_u32 v158, v158, v159, s87
	v_cndmask_b32_e64 v159, v181, 0, s[36:37]
	v_bfe_u32 v160, v159, 16, 1
	v_lshrrev_b32_e32 v158, 16, v158
	v_add3_u32 v159, v159, v160, s87
	v_and_or_b32 v158, v159, s88, v158
	v_cndmask_b32_e64 v159, v193, 0, s[36:37]
	v_bfe_u32 v160, v159, 16, 1
	v_add3_u32 v159, v159, v160, s87
	v_cndmask_b32_e64 v160, v194, 0, s[36:37]
	v_bfe_u32 v161, v160, 16, 1
	v_lshrrev_b32_e32 v159, 16, v159
	v_add3_u32 v160, v160, v161, s87
	v_and_or_b32 v159, v160, s88, v159
	v_cndmask_b32_e64 v160, v195, 0, s[36:37]
	v_bfe_u32 v161, v160, 16, 1
	v_add3_u32 v160, v160, v161, s87
	v_cndmask_b32_e64 v161, v196, 0, s[36:37]
	v_bfe_u32 v166, v161, 16, 1
	v_lshrrev_b32_e32 v160, 16, v160
	v_add3_u32 v161, v161, v166, s87
	v_and_or_b32 v160, v161, s88, v160
	v_cndmask_b32_e64 v161, v197, 0, s[36:37]
	v_bfe_u32 v166, v161, 16, 1
	v_add3_u32 v161, v161, v166, s87
	v_cndmask_b32_e64 v166, v198, 0, s[36:37]
	v_bfe_u32 v167, v166, 16, 1
	v_lshrrev_b32_e32 v161, 16, v161
	v_add3_u32 v166, v166, v167, s87
	v_and_or_b32 v161, v166, s88, v161
	global_store_dwordx4 v[154:155], v[158:161], off
	s_nop 1
	v_mul_f32_e32 v158, 0x3fb8aa3b, v38
	v_exp_f32_e32 v166, v158
	v_mul_f32_e32 v158, 0x3fb8aa3b, v39
	v_exp_f32_e32 v168, v158
	v_mul_f32_e32 v158, 0x3fb8aa3b, v40
	v_exp_f32_e32 v167, v158
	v_mul_f32_e32 v158, 0x3fb8aa3b, v41
	v_exp_f32_e32 v169, v158
	v_mul_f32_e32 v158, 0x3fb8aa3b, v34
	v_pk_add_f32 v[166:167], v[166:167], 1.0 op_sel_hi:[1,0]
	v_mul_f32_e32 v159, 0x3fb8aa3b, v36
	v_rcp_f32_e32 v181, v167
	v_pk_add_f32 v[168:169], v[168:169], 1.0 op_sel_hi:[1,0]
	v_exp_f32_e32 v160, v158
	v_exp_f32_e32 v161, v159
	v_mul_f32_e32 v167, v165, v181
	v_rcp_f32_e32 v181, v166
	v_pk_add_f32 v[160:161], v[160:161], 1.0 op_sel_hi:[1,0]
	v_mul_f32_e32 v158, 0x3fb8aa3b, v35
	v_mul_f32_e32 v159, 0x3fb8aa3b, v37
	v_mul_f32_e32 v180, v164, v181
	v_sub_f32_e32 v166, 1.0, v180
	v_cmp_gt_f32_e32 vcc, s96, v166
	v_exp_f32_e32 v158, v158
	v_exp_f32_e32 v159, v159
	v_cndmask_b32_e64 v181, 0, 32, vcc
	v_ldexp_f32 v166, v166, v181
	v_log_f32_e32 v166, v166
	v_pk_add_f32 v[158:159], v[158:159], 1.0 op_sel_hi:[1,0]
	v_cndmask_b32_e64 v180, v180, 0, s[36:37]
	v_mul_f32_e32 v181, 0x3f317217, v166
	v_fma_f32 v181, v166, s97, -v181
	v_fmac_f32_e32 v181, 0x3377d1cf, v166
	v_fmac_f32_e32 v181, 0x3f317217, v166
	v_cmp_lt_f32_e64 s[0:1], |v166|, s94
	s_nop 1
	v_cndmask_b32_e64 v166, v166, v181, s[0:1]
	v_cndmask_b32_e32 v181, 0, v190, vcc
	v_sub_f32_e32 v166, v166, v181
	v_rcp_f32_e32 v193, v169
	s_nop 0
	v_mul_f32_e32 v169, v163, v193
	v_rcp_f32_e32 v193, v168
	s_nop 0
	v_mul_f32_e32 v168, v162, v193
	v_sub_f32_e32 v181, 1.0, v168
	v_cmp_gt_f32_e32 vcc, s96, v181
	v_cndmask_b32_e64 v168, v168, 0, s[36:37]
	s_nop 0
	v_cndmask_b32_e64 v193, 0, 32, vcc
	v_ldexp_f32 v181, v181, v193
	v_log_f32_e32 v181, v181
	v_cvt_pk_bf16_f32 v168, v180, v168
	v_mul_f32_e32 v193, 0x3f317217, v181
	v_fma_f32 v193, v181, s97, -v193
	v_fmac_f32_e32 v193, 0x3377d1cf, v181
	v_fmac_f32_e32 v193, 0x3f317217, v181
	v_cmp_lt_f32_e64 s[0:1], |v181|, s94
	s_nop 1
	v_cndmask_b32_e64 v181, v181, v193, s[0:1]
	v_cndmask_b32_e32 v193, 0, v190, vcc
	v_sub_f32_e32 v181, v181, v193
	v_sub_f32_e32 v193, 1.0, v167
	v_cmp_gt_f32_e32 vcc, s96, v193
	v_cndmask_b32_e64 v167, v167, 0, s[36:37]
	s_nop 0
	v_cndmask_b32_e64 v194, 0, 32, vcc
	v_ldexp_f32 v193, v193, v194
	v_log_f32_e32 v193, v193
	s_nop 0
	v_mul_f32_e32 v194, 0x3f317217, v193
	v_fma_f32 v194, v193, s97, -v194
	v_fmac_f32_e32 v194, 0x3377d1cf, v193
	v_fmac_f32_e32 v194, 0x3f317217, v193
	v_cmp_lt_f32_e64 s[0:1], |v193|, s94
	s_nop 1
	v_cndmask_b32_e64 v193, v193, v194, s[0:1]
	v_cndmask_b32_e32 v194, 0, v190, vcc
	v_sub_f32_e32 v193, v193, v194
	v_sub_f32_e32 v194, 1.0, v169
	v_cmp_gt_f32_e32 vcc, s96, v194
	v_cndmask_b32_e64 v169, v169, 0, s[36:37]
	s_nop 0
	v_cndmask_b32_e64 v195, 0, 32, vcc
	v_ldexp_f32 v194, v194, v195
	v_log_f32_e32 v194, v194
	v_cvt_pk_bf16_f32 v169, v167, v169
	v_mul_f32_e32 v195, 0x3f317217, v194
	v_fma_f32 v195, v194, s97, -v195
	v_fmac_f32_e32 v195, 0x3377d1cf, v194
	v_fmac_f32_e32 v195, 0x3f317217, v194
	v_cmp_lt_f32_e64 s[0:1], |v194|, s94
	s_nop 1
	v_cndmask_b32_e64 v194, v194, v195, s[0:1]
	v_cndmask_b32_e32 v195, 0, v190, vcc
	v_sub_f32_e32 v194, v194, v195
	v_rcp_f32_e32 v196, v161
	s_nop 0
	v_mul_f32_e32 v161, v173, v196
	v_rcp_f32_e32 v196, v160
	s_nop 0
	v_mul_f32_e32 v160, v171, v196
	v_sub_f32_e32 v195, 1.0, v160
	v_cmp_gt_f32_e32 vcc, s96, v195
	v_cndmask_b32_e64 v160, v160, 0, s[36:37]
	v_bfe_u32 v201, v160, 16, 1
	v_cndmask_b32_e64 v196, 0, 32, vcc
	v_ldexp_f32 v195, v195, v196
	v_log_f32_e32 v195, v195
	v_add3_u32 v160, v160, v201, s87
	v_lshrrev_b32_e32 v160, 16, v160
	v_mul_f32_e32 v196, 0x3f317217, v195
	v_fma_f32 v196, v195, s97, -v196
	v_fmac_f32_e32 v196, 0x3377d1cf, v195
	v_fmac_f32_e32 v196, 0x3f317217, v195
	v_cmp_lt_f32_e64 s[0:1], |v195|, s94
	s_nop 1
	v_cndmask_b32_e64 v195, v195, v196, s[0:1]
	v_cndmask_b32_e32 v196, 0, v190, vcc
	v_sub_f32_e32 v195, v195, v196
	v_rcp_f32_e32 v197, v159
	s_nop 0
	v_mul_f32_e32 v159, v172, v197
	v_rcp_f32_e32 v197, v158
	s_nop 0
	v_mul_f32_e32 v158, v170, v197
	v_sub_f32_e32 v196, 1.0, v158
	v_cmp_gt_f32_e32 vcc, s96, v196
	v_cndmask_b32_e64 v158, v158, 0, s[36:37]
	v_bfe_u32 v200, v158, 16, 1
	v_cndmask_b32_e64 v197, 0, 32, vcc
	v_ldexp_f32 v196, v196, v197
	v_log_f32_e32 v196, v196
	v_add3_u32 v158, v158, v200, s87
	v_mul_f32_e32 v197, 0x3f317217, v196
	v_fma_f32 v197, v196, s97, -v197
	v_fmac_f32_e32 v197, 0x3377d1cf, v196
	v_fmac_f32_e32 v197, 0x3f317217, v196
	v_cmp_lt_f32_e64 s[0:1], |v196|, s94
	v_and_or_b32 v160, v158, s88, v160
	s_nop 0
	v_cndmask_b32_e64 v196, v196, v197, s[0:1]
	v_cndmask_b32_e32 v197, 0, v190, vcc
	v_sub_f32_e32 v196, v196, v197
	v_sub_f32_e32 v197, 1.0, v161
	v_cmp_gt_f32_e32 vcc, s96, v197
	v_cndmask_b32_e64 v161, v161, 0, s[36:37]
	v_bfe_u32 v202, v161, 16, 1
	v_cndmask_b32_e64 v198, 0, 32, vcc
	v_ldexp_f32 v197, v197, v198
	v_log_f32_e32 v197, v197
	v_add3_u32 v161, v161, v202, s87
	v_lshrrev_b32_e32 v161, 16, v161
	v_mul_f32_e32 v198, 0x3f317217, v197
	v_fma_f32 v198, v197, s97, -v198
	v_fmac_f32_e32 v198, 0x3377d1cf, v197
	v_fmac_f32_e32 v198, 0x3f317217, v197
	v_cmp_lt_f32_e64 s[0:1], |v197|, s94
	s_nop 1
	v_cndmask_b32_e64 v197, v197, v198, s[0:1]
	v_cndmask_b32_e32 v198, 0, v190, vcc
	v_sub_f32_e32 v197, v197, v198
	v_sub_f32_e32 v198, 1.0, v159
	v_cmp_gt_f32_e32 vcc, s96, v198
	v_cndmask_b32_e64 v159, v159, 0, s[36:37]
	s_nop 0
	v_cndmask_b32_e64 v199, 0, 32, vcc
	v_ldexp_f32 v198, v198, v199
	v_log_f32_e32 v198, v198
	s_nop 0
	v_mul_f32_e32 v199, 0x3f317217, v198
	v_fma_f32 v199, v198, s97, -v199
	v_fmac_f32_e32 v199, 0x3377d1cf, v198
	v_fmac_f32_e32 v199, 0x3f317217, v198
	v_cmp_lt_f32_e64 s[0:1], |v198|, s94
	s_nop 1
	v_cndmask_b32_e64 v198, v198, v199, s[0:1]
	v_cndmask_b32_e32 v199, 0, v190, vcc
	v_sub_f32_e32 v198, v198, v199
	v_bfe_u32 v199, v159, 16, 1
	v_add3_u32 v159, v159, v199, s87
	v_and_or_b32 v161, v159, s88, v161
	v_mov_b32_e32 v159, v169
	v_mov_b32_e32 v158, v168
	global_store_dwordx4 v[156:157], v[158:161], off offset:256
	v_cndmask_b32_e64 v156, v166, 0, s[36:37]
	v_bfe_u32 v157, v156, 16, 1
	v_add3_u32 v156, v156, v157, s87
	v_cndmask_b32_e64 v157, v181, 0, s[36:37]
	v_bfe_u32 v158, v157, 16, 1
	v_lshrrev_b32_e32 v156, 16, v156
	v_add3_u32 v157, v157, v158, s87
	v_and_or_b32 v156, v157, s88, v156
	v_cndmask_b32_e64 v157, v193, 0, s[36:37]
	v_bfe_u32 v158, v157, 16, 1
	v_add3_u32 v157, v157, v158, s87
	v_cndmask_b32_e64 v158, v194, 0, s[36:37]
	v_bfe_u32 v159, v158, 16, 1
	v_lshrrev_b32_e32 v157, 16, v157
	v_add3_u32 v158, v158, v159, s87
	v_and_or_b32 v157, v158, s88, v157
	v_cndmask_b32_e64 v158, v195, 0, s[36:37]
	v_bfe_u32 v159, v158, 16, 1
	v_add3_u32 v158, v158, v159, s87
	v_cndmask_b32_e64 v159, v196, 0, s[36:37]
	v_bfe_u32 v160, v159, 16, 1
	v_lshrrev_b32_e32 v158, 16, v158
	v_add3_u32 v159, v159, v160, s87
	v_and_or_b32 v158, v159, s88, v158
	v_cndmask_b32_e64 v159, v197, 0, s[36:37]
	v_bfe_u32 v160, v159, 16, 1
	v_add3_u32 v159, v159, v160, s87
	v_cndmask_b32_e64 v160, v198, 0, s[36:37]
	v_bfe_u32 v161, v160, 16, 1
	v_lshrrev_b32_e32 v159, 16, v159
	v_add3_u32 v160, v160, v161, s87
	v_and_or_b32 v159, v160, s88, v159
	global_store_dwordx4 v[154:155], v[156:159], off offset:256
	s_movk_i32 s0, 0x4060
	v_cmp_gt_i32_e32 vcc, s0, v148
	v_mul_f32_e32 v158, 0x3fb8aa3b, v30
	v_exp_f32_e32 v166, v158
	v_mul_f32_e32 v158, 0x3fb8aa3b, v31
	v_exp_f32_e32 v168, v158
	v_mul_f32_e32 v158, 0x3fb8aa3b, v32
	s_movk_i32 s0, 0x1fe0
	v_exp_f32_e32 v167, v158
	v_cmp_gt_i32_e64 s[0:1], s0, v148
	v_add_u32_e32 v154, 0xa0, v148
	v_mul_f32_e32 v158, 0x3fb8aa3b, v33
	v_cndmask_b32_e64 v155, v189, 0, s[0:1]
	v_add_u32_e32 v155, v155, v154
	v_cmp_gt_i32_e64 s[0:1], s95, v155
	v_pk_add_f32 v[166:167], v[166:167], 1.0 op_sel_hi:[1,0]
	s_and_b64 s[36:37], vcc, s[0:1]
	v_rcp_f32_e32 v181, v167
	v_exp_f32_e32 v169, v158
	v_mul_f32_e32 v158, 0x3fb8aa3b, v26
	v_mul_f32_e32 v159, 0x3fb8aa3b, v28
	v_mul_f32_e32 v167, v176, v181
	v_rcp_f32_e32 v181, v166
	v_pk_add_f32 v[168:169], v[168:169], 1.0 op_sel_hi:[1,0]
	v_exp_f32_e32 v160, v158
	v_exp_f32_e32 v161, v159
	v_mul_f32_e32 v180, v149, v181
	v_sub_f32_e32 v166, 1.0, v180
	v_cmp_gt_f32_e32 vcc, s96, v166
	v_pk_add_f32 v[160:161], v[160:161], 1.0 op_sel_hi:[1,0]
	v_mul_f32_e32 v158, 0x3fb8aa3b, v27
	v_cndmask_b32_e64 v181, 0, 32, vcc
	v_ldexp_f32 v166, v166, v181
	v_log_f32_e32 v166, v166
	v_mul_f32_e32 v159, 0x3fb8aa3b, v29
	v_exp_f32_e32 v158, v158
	v_exp_f32_e32 v159, v159
	v_mul_f32_e32 v181, 0x3f317217, v166
	v_fma_f32 v181, v166, s97, -v181
	v_fmac_f32_e32 v181, 0x3377d1cf, v166
	v_fmac_f32_e32 v181, 0x3f317217, v166
	v_cmp_lt_f32_e64 s[0:1], |v166|, s94
	v_pk_add_f32 v[158:159], v[158:159], 1.0 op_sel_hi:[1,0]
	v_cndmask_b32_e64 v180, v180, 0, s[36:37]
	v_cndmask_b32_e64 v166, v166, v181, s[0:1]
	v_cndmask_b32_e32 v181, 0, v190, vcc
	v_sub_f32_e32 v166, v166, v181
	v_rcp_f32_e32 v193, v169
	v_ashrrev_i32_e32 v155, 31, v154
	v_lshlrev_b64 v[154:155], 10, v[154:155]
	v_lshl_add_u64 v[156:157], v[150:151], 0, v[154:155]
	v_mul_f32_e32 v169, v174, v193
	v_rcp_f32_e32 v193, v168
	v_lshl_add_u64 v[154:155], v[152:153], 0, v[154:155]
	v_mul_f32_e32 v168, v138, v193
	v_sub_f32_e32 v181, 1.0, v168
	v_cmp_gt_f32_e32 vcc, s96, v181
	v_cndmask_b32_e64 v168, v168, 0, s[36:37]
	s_nop 0
	v_cndmask_b32_e64 v193, 0, 32, vcc
	v_ldexp_f32 v181, v181, v193
	v_log_f32_e32 v181, v181
	v_cvt_pk_bf16_f32 v168, v180, v168
	v_mul_f32_e32 v193, 0x3f317217, v181
	v_fma_f32 v193, v181, s97, -v193
	v_fmac_f32_e32 v193, 0x3377d1cf, v181
	v_fmac_f32_e32 v193, 0x3f317217, v181
	v_cmp_lt_f32_e64 s[0:1], |v181|, s94
	s_nop 1
	v_cndmask_b32_e64 v181, v181, v193, s[0:1]
	v_cndmask_b32_e32 v193, 0, v190, vcc
	v_sub_f32_e32 v181, v181, v193
	v_sub_f32_e32 v193, 1.0, v167
	v_cmp_gt_f32_e32 vcc, s96, v193
	v_cndmask_b32_e64 v167, v167, 0, s[36:37]
	s_nop 0
	v_cndmask_b32_e64 v194, 0, 32, vcc
	v_ldexp_f32 v193, v193, v194
	v_log_f32_e32 v193, v193
	s_nop 0
	v_mul_f32_e32 v194, 0x3f317217, v193
	v_fma_f32 v194, v193, s97, -v194
	v_fmac_f32_e32 v194, 0x3377d1cf, v193
	v_fmac_f32_e32 v194, 0x3f317217, v193
	v_cmp_lt_f32_e64 s[0:1], |v193|, s94
	s_nop 1
	v_cndmask_b32_e64 v193, v193, v194, s[0:1]
	v_cndmask_b32_e32 v194, 0, v190, vcc
	v_sub_f32_e32 v193, v193, v194
	v_sub_f32_e32 v194, 1.0, v169
	v_cmp_gt_f32_e32 vcc, s96, v194
	v_cndmask_b32_e64 v169, v169, 0, s[36:37]
	s_nop 0
	v_cndmask_b32_e64 v195, 0, 32, vcc
	v_ldexp_f32 v194, v194, v195
	v_log_f32_e32 v194, v194
	v_cvt_pk_bf16_f32 v169, v167, v169
	v_mul_f32_e32 v195, 0x3f317217, v194
	v_fma_f32 v195, v194, s97, -v195
	v_fmac_f32_e32 v195, 0x3377d1cf, v194
	v_fmac_f32_e32 v195, 0x3f317217, v194
	v_cmp_lt_f32_e64 s[0:1], |v194|, s94
	s_nop 1
	v_cndmask_b32_e64 v194, v194, v195, s[0:1]
	v_cndmask_b32_e32 v195, 0, v190, vcc
	v_sub_f32_e32 v194, v194, v195
	v_rcp_f32_e32 v196, v161
	s_nop 0
	v_mul_f32_e32 v161, v179, v196
	v_rcp_f32_e32 v196, v160
	s_nop 0
	v_mul_f32_e32 v160, v177, v196
	v_sub_f32_e32 v195, 1.0, v160
	v_cmp_gt_f32_e32 vcc, s96, v195
	v_cndmask_b32_e64 v160, v160, 0, s[36:37]
	v_bfe_u32 v201, v160, 16, 1
	v_cndmask_b32_e64 v196, 0, 32, vcc
	v_ldexp_f32 v195, v195, v196
	v_log_f32_e32 v195, v195
	v_add3_u32 v160, v160, v201, s87
	v_lshrrev_b32_e32 v160, 16, v160
	v_mul_f32_e32 v196, 0x3f317217, v195
	v_fma_f32 v196, v195, s97, -v196
	v_fmac_f32_e32 v196, 0x3377d1cf, v195
	v_fmac_f32_e32 v196, 0x3f317217, v195
	v_cmp_lt_f32_e64 s[0:1], |v195|, s94
	s_nop 1
	v_cndmask_b32_e64 v195, v195, v196, s[0:1]
	v_cndmask_b32_e32 v196, 0, v190, vcc
	v_sub_f32_e32 v195, v195, v196
	v_rcp_f32_e32 v197, v159
	s_nop 0
	v_mul_f32_e32 v159, v178, v197
	v_rcp_f32_e32 v197, v158
	s_nop 0
	v_mul_f32_e32 v158, v175, v197
	v_sub_f32_e32 v196, 1.0, v158
	v_cmp_gt_f32_e32 vcc, s96, v196
	v_cndmask_b32_e64 v158, v158, 0, s[36:37]
	v_bfe_u32 v200, v158, 16, 1
	v_cndmask_b32_e64 v197, 0, 32, vcc
	v_ldexp_f32 v196, v196, v197
	v_log_f32_e32 v196, v196
	v_add3_u32 v158, v158, v200, s87
	v_mul_f32_e32 v197, 0x3f317217, v196
	v_fma_f32 v197, v196, s97, -v197
	v_fmac_f32_e32 v197, 0x3377d1cf, v196
	v_fmac_f32_e32 v197, 0x3f317217, v196
	v_cmp_lt_f32_e64 s[0:1], |v196|, s94
	v_and_or_b32 v160, v158, s88, v160
	s_nop 0
	v_cndmask_b32_e64 v196, v196, v197, s[0:1]
	v_cndmask_b32_e32 v197, 0, v190, vcc
	v_sub_f32_e32 v196, v196, v197
	v_sub_f32_e32 v197, 1.0, v161
	v_cmp_gt_f32_e32 vcc, s96, v197
	v_cndmask_b32_e64 v161, v161, 0, s[36:37]
	v_bfe_u32 v202, v161, 16, 1
	v_cndmask_b32_e64 v198, 0, 32, vcc
	v_ldexp_f32 v197, v197, v198
	v_log_f32_e32 v197, v197
	v_add3_u32 v161, v161, v202, s87
	v_lshrrev_b32_e32 v161, 16, v161
	v_mul_f32_e32 v198, 0x3f317217, v197
	v_fma_f32 v198, v197, s97, -v198
	v_fmac_f32_e32 v198, 0x3377d1cf, v197
	v_fmac_f32_e32 v198, 0x3f317217, v197
	v_cmp_lt_f32_e64 s[0:1], |v197|, s94
	s_nop 1
	v_cndmask_b32_e64 v197, v197, v198, s[0:1]
	v_cndmask_b32_e32 v198, 0, v190, vcc
	v_sub_f32_e32 v197, v197, v198
	v_sub_f32_e32 v198, 1.0, v159
	v_cmp_gt_f32_e32 vcc, s96, v198
	v_cndmask_b32_e64 v159, v159, 0, s[36:37]
	s_nop 0
	v_cndmask_b32_e64 v199, 0, 32, vcc
	v_ldexp_f32 v198, v198, v199
	v_log_f32_e32 v198, v198
	s_nop 0
	v_mul_f32_e32 v199, 0x3f317217, v198
	v_fma_f32 v199, v198, s97, -v199
	v_fmac_f32_e32 v199, 0x3377d1cf, v198
	v_fmac_f32_e32 v199, 0x3f317217, v198
	v_cmp_lt_f32_e64 s[0:1], |v198|, s94
	s_nop 1
	v_cndmask_b32_e64 v198, v198, v199, s[0:1]
	v_cndmask_b32_e32 v199, 0, v190, vcc
	v_sub_f32_e32 v198, v198, v199
	v_bfe_u32 v199, v159, 16, 1
	v_add3_u32 v159, v159, v199, s87
	v_and_or_b32 v161, v159, s88, v161
	v_mov_b32_e32 v159, v169
	v_mov_b32_e32 v158, v168
	global_store_dwordx4 v[156:157], v[158:161], off
	s_nop 1
	v_cndmask_b32_e64 v158, v166, 0, s[36:37]
	v_bfe_u32 v159, v158, 16, 1
	v_add3_u32 v158, v158, v159, s87
	v_cndmask_b32_e64 v159, v181, 0, s[36:37]
	v_bfe_u32 v160, v159, 16, 1
	v_lshrrev_b32_e32 v158, 16, v158
	v_add3_u32 v159, v159, v160, s87
	v_and_or_b32 v158, v159, s88, v158
	v_cndmask_b32_e64 v159, v193, 0, s[36:37]
	v_bfe_u32 v160, v159, 16, 1
	v_add3_u32 v159, v159, v160, s87
	v_cndmask_b32_e64 v160, v194, 0, s[36:37]
	v_bfe_u32 v161, v160, 16, 1
	v_lshrrev_b32_e32 v159, 16, v159
	v_add3_u32 v160, v160, v161, s87
	v_and_or_b32 v159, v160, s88, v159
	v_cndmask_b32_e64 v160, v195, 0, s[36:37]
	v_bfe_u32 v161, v160, 16, 1
	v_add3_u32 v160, v160, v161, s87
	v_cndmask_b32_e64 v161, v196, 0, s[36:37]
	v_bfe_u32 v166, v161, 16, 1
	v_lshrrev_b32_e32 v160, 16, v160
	v_add3_u32 v161, v161, v166, s87
	v_and_or_b32 v160, v161, s88, v160
	v_cndmask_b32_e64 v161, v197, 0, s[36:37]
	v_bfe_u32 v166, v161, 16, 1
	v_add3_u32 v161, v161, v166, s87
	v_cndmask_b32_e64 v166, v198, 0, s[36:37]
	v_bfe_u32 v167, v166, 16, 1
	v_lshrrev_b32_e32 v161, 16, v161
	v_add3_u32 v166, v166, v167, s87
	v_and_or_b32 v161, v166, s88, v161
	global_store_dwordx4 v[154:155], v[158:161], off
	s_nop 1
	v_mul_f32_e32 v158, 0x3fb8aa3b, v22
	v_exp_f32_e32 v166, v158
	v_mul_f32_e32 v158, 0x3fb8aa3b, v23
	v_exp_f32_e32 v168, v158
	v_mul_f32_e32 v158, 0x3fb8aa3b, v24
	v_exp_f32_e32 v167, v158
	v_mul_f32_e32 v158, 0x3fb8aa3b, v25
	v_exp_f32_e32 v169, v158
	v_mul_f32_e32 v158, 0x3fb8aa3b, v18
	v_pk_add_f32 v[166:167], v[166:167], 1.0 op_sel_hi:[1,0]
	v_mul_f32_e32 v159, 0x3fb8aa3b, v20
	v_rcp_f32_e32 v181, v167
	v_pk_add_f32 v[168:169], v[168:169], 1.0 op_sel_hi:[1,0]
	v_exp_f32_e32 v160, v158
	v_exp_f32_e32 v161, v159
	v_mul_f32_e32 v167, v165, v181
	v_rcp_f32_e32 v181, v166
	v_pk_add_f32 v[160:161], v[160:161], 1.0 op_sel_hi:[1,0]
	v_mul_f32_e32 v158, 0x3fb8aa3b, v19
	v_mul_f32_e32 v159, 0x3fb8aa3b, v21
	v_mul_f32_e32 v180, v164, v181
	v_sub_f32_e32 v166, 1.0, v180
	v_cmp_gt_f32_e32 vcc, s96, v166
	v_exp_f32_e32 v158, v158
	v_exp_f32_e32 v159, v159
	v_cndmask_b32_e64 v181, 0, 32, vcc
	v_ldexp_f32 v166, v166, v181
	v_log_f32_e32 v166, v166
	v_pk_add_f32 v[158:159], v[158:159], 1.0 op_sel_hi:[1,0]
	v_cndmask_b32_e64 v180, v180, 0, s[36:37]
	v_mul_f32_e32 v181, 0x3f317217, v166
	v_fma_f32 v181, v166, s97, -v181
	v_fmac_f32_e32 v181, 0x3377d1cf, v166
	v_fmac_f32_e32 v181, 0x3f317217, v166
	v_cmp_lt_f32_e64 s[0:1], |v166|, s94
	s_nop 1
	v_cndmask_b32_e64 v166, v166, v181, s[0:1]
	v_cndmask_b32_e32 v181, 0, v190, vcc
	v_sub_f32_e32 v166, v166, v181
	v_rcp_f32_e32 v193, v169
	s_nop 0
	v_mul_f32_e32 v169, v163, v193
	v_rcp_f32_e32 v193, v168
	s_nop 0
	v_mul_f32_e32 v168, v162, v193
	v_sub_f32_e32 v181, 1.0, v168
	v_cmp_gt_f32_e32 vcc, s96, v181
	v_cndmask_b32_e64 v168, v168, 0, s[36:37]
	s_nop 0
	v_cndmask_b32_e64 v193, 0, 32, vcc
	v_ldexp_f32 v181, v181, v193
	v_log_f32_e32 v181, v181
	v_cvt_pk_bf16_f32 v168, v180, v168
	v_mul_f32_e32 v193, 0x3f317217, v181
	v_fma_f32 v193, v181, s97, -v193
	v_fmac_f32_e32 v193, 0x3377d1cf, v181
	v_fmac_f32_e32 v193, 0x3f317217, v181
	v_cmp_lt_f32_e64 s[0:1], |v181|, s94
	s_nop 1
	v_cndmask_b32_e64 v181, v181, v193, s[0:1]
	v_cndmask_b32_e32 v193, 0, v190, vcc
	v_sub_f32_e32 v181, v181, v193
	v_sub_f32_e32 v193, 1.0, v167
	v_cmp_gt_f32_e32 vcc, s96, v193
	v_cndmask_b32_e64 v167, v167, 0, s[36:37]
	s_nop 0
	v_cndmask_b32_e64 v194, 0, 32, vcc
	v_ldexp_f32 v193, v193, v194
	v_log_f32_e32 v193, v193
	s_nop 0
	v_mul_f32_e32 v194, 0x3f317217, v193
	v_fma_f32 v194, v193, s97, -v194
	v_fmac_f32_e32 v194, 0x3377d1cf, v193
	v_fmac_f32_e32 v194, 0x3f317217, v193
	v_cmp_lt_f32_e64 s[0:1], |v193|, s94
	s_nop 1
	v_cndmask_b32_e64 v193, v193, v194, s[0:1]
	v_cndmask_b32_e32 v194, 0, v190, vcc
	v_sub_f32_e32 v193, v193, v194
	v_sub_f32_e32 v194, 1.0, v169
	v_cmp_gt_f32_e32 vcc, s96, v194
	v_cndmask_b32_e64 v169, v169, 0, s[36:37]
	s_nop 0
	v_cndmask_b32_e64 v195, 0, 32, vcc
	v_ldexp_f32 v194, v194, v195
	v_log_f32_e32 v194, v194
	v_cvt_pk_bf16_f32 v169, v167, v169
	v_mul_f32_e32 v195, 0x3f317217, v194
	v_fma_f32 v195, v194, s97, -v195
	v_fmac_f32_e32 v195, 0x3377d1cf, v194
	v_fmac_f32_e32 v195, 0x3f317217, v194
	v_cmp_lt_f32_e64 s[0:1], |v194|, s94
	s_nop 1
	v_cndmask_b32_e64 v194, v194, v195, s[0:1]
	v_cndmask_b32_e32 v195, 0, v190, vcc
	v_sub_f32_e32 v194, v194, v195
	v_rcp_f32_e32 v196, v161
	s_nop 0
	v_mul_f32_e32 v161, v173, v196
	v_rcp_f32_e32 v196, v160
	s_nop 0
	v_mul_f32_e32 v160, v171, v196
	v_sub_f32_e32 v195, 1.0, v160
	v_cmp_gt_f32_e32 vcc, s96, v195
	v_cndmask_b32_e64 v160, v160, 0, s[36:37]
	v_bfe_u32 v201, v160, 16, 1
	v_cndmask_b32_e64 v196, 0, 32, vcc
	v_ldexp_f32 v195, v195, v196
	v_log_f32_e32 v195, v195
	v_add3_u32 v160, v160, v201, s87
	v_lshrrev_b32_e32 v160, 16, v160
	v_mul_f32_e32 v196, 0x3f317217, v195
	v_fma_f32 v196, v195, s97, -v196
	v_fmac_f32_e32 v196, 0x3377d1cf, v195
	v_fmac_f32_e32 v196, 0x3f317217, v195
	v_cmp_lt_f32_e64 s[0:1], |v195|, s94
	s_nop 1
	v_cndmask_b32_e64 v195, v195, v196, s[0:1]
	v_cndmask_b32_e32 v196, 0, v190, vcc
	v_sub_f32_e32 v195, v195, v196
	v_rcp_f32_e32 v197, v159
	s_nop 0
	v_mul_f32_e32 v159, v172, v197
	v_rcp_f32_e32 v197, v158
	s_nop 0
	v_mul_f32_e32 v158, v170, v197
	v_sub_f32_e32 v196, 1.0, v158
	v_cmp_gt_f32_e32 vcc, s96, v196
	v_cndmask_b32_e64 v158, v158, 0, s[36:37]
	v_bfe_u32 v200, v158, 16, 1
	v_cndmask_b32_e64 v197, 0, 32, vcc
	v_ldexp_f32 v196, v196, v197
	v_log_f32_e32 v196, v196
	v_add3_u32 v158, v158, v200, s87
	v_mul_f32_e32 v197, 0x3f317217, v196
	v_fma_f32 v197, v196, s97, -v197
	v_fmac_f32_e32 v197, 0x3377d1cf, v196
	v_fmac_f32_e32 v197, 0x3f317217, v196
	v_cmp_lt_f32_e64 s[0:1], |v196|, s94
	v_and_or_b32 v160, v158, s88, v160
	s_nop 0
	v_cndmask_b32_e64 v196, v196, v197, s[0:1]
	v_cndmask_b32_e32 v197, 0, v190, vcc
	v_sub_f32_e32 v196, v196, v197
	v_sub_f32_e32 v197, 1.0, v161
	v_cmp_gt_f32_e32 vcc, s96, v197
	v_cndmask_b32_e64 v161, v161, 0, s[36:37]
	v_bfe_u32 v202, v161, 16, 1
	v_cndmask_b32_e64 v198, 0, 32, vcc
	v_ldexp_f32 v197, v197, v198
	v_log_f32_e32 v197, v197
	v_add3_u32 v161, v161, v202, s87
	v_lshrrev_b32_e32 v161, 16, v161
	v_mul_f32_e32 v198, 0x3f317217, v197
	v_fma_f32 v198, v197, s97, -v198
	v_fmac_f32_e32 v198, 0x3377d1cf, v197
	v_fmac_f32_e32 v198, 0x3f317217, v197
	v_cmp_lt_f32_e64 s[0:1], |v197|, s94
	s_nop 1
	v_cndmask_b32_e64 v197, v197, v198, s[0:1]
	v_cndmask_b32_e32 v198, 0, v190, vcc
	v_sub_f32_e32 v197, v197, v198
	v_sub_f32_e32 v198, 1.0, v159
	v_cmp_gt_f32_e32 vcc, s96, v198
	v_cndmask_b32_e64 v159, v159, 0, s[36:37]
	s_nop 0
	v_cndmask_b32_e64 v199, 0, 32, vcc
	v_ldexp_f32 v198, v198, v199
	v_log_f32_e32 v198, v198
	s_nop 0
	v_mul_f32_e32 v199, 0x3f317217, v198
	v_fma_f32 v199, v198, s97, -v199
	v_fmac_f32_e32 v199, 0x3377d1cf, v198
	v_fmac_f32_e32 v199, 0x3f317217, v198
	v_cmp_lt_f32_e64 s[0:1], |v198|, s94
	s_nop 1
	v_cndmask_b32_e64 v198, v198, v199, s[0:1]
	v_cndmask_b32_e32 v199, 0, v190, vcc
	v_sub_f32_e32 v198, v198, v199
	v_bfe_u32 v199, v159, 16, 1
	v_add3_u32 v159, v159, v199, s87
	v_and_or_b32 v161, v159, s88, v161
	v_mov_b32_e32 v159, v169
	v_mov_b32_e32 v158, v168
	global_store_dwordx4 v[156:157], v[158:161], off offset:256
	v_cndmask_b32_e64 v156, v166, 0, s[36:37]
	v_bfe_u32 v157, v156, 16, 1
	v_add3_u32 v156, v156, v157, s87
	v_cndmask_b32_e64 v157, v181, 0, s[36:37]
	v_bfe_u32 v158, v157, 16, 1
	v_lshrrev_b32_e32 v156, 16, v156
	v_add3_u32 v157, v157, v158, s87
	v_and_or_b32 v156, v157, s88, v156
	v_cndmask_b32_e64 v157, v193, 0, s[36:37]
	v_bfe_u32 v158, v157, 16, 1
	v_add3_u32 v157, v157, v158, s87
	v_cndmask_b32_e64 v158, v194, 0, s[36:37]
	v_bfe_u32 v159, v158, 16, 1
	v_lshrrev_b32_e32 v157, 16, v157
	v_add3_u32 v158, v158, v159, s87
	v_and_or_b32 v157, v158, s88, v157
	v_cndmask_b32_e64 v158, v195, 0, s[36:37]
	v_bfe_u32 v159, v158, 16, 1
	v_add3_u32 v158, v158, v159, s87
	v_cndmask_b32_e64 v159, v196, 0, s[36:37]
	v_bfe_u32 v160, v159, 16, 1
	v_lshrrev_b32_e32 v158, 16, v158
	v_add3_u32 v159, v159, v160, s87
	v_and_or_b32 v158, v159, s88, v158
	v_cndmask_b32_e64 v159, v197, 0, s[36:37]
	v_bfe_u32 v160, v159, 16, 1
	v_add3_u32 v159, v159, v160, s87
	v_cndmask_b32_e64 v160, v198, 0, s[36:37]
	v_bfe_u32 v161, v160, 16, 1
	s_movk_i32 s0, 0x4050
	v_lshrrev_b32_e32 v159, 16, v159
	v_add3_u32 v160, v160, v161, s87
	v_cmp_gt_i32_e32 vcc, s0, v148
	s_movk_i32 s0, 0x1fd0
	v_and_or_b32 v159, v160, s88, v159
	v_cmp_gt_i32_e64 s[0:1], s0, v148
	global_store_dwordx4 v[154:155], v[156:159], off offset:256
	v_add_u32_e32 v154, 0xb0, v148
	v_cndmask_b32_e64 v155, v189, 0, s[0:1]
	v_add_u32_e32 v155, v155, v154
	v_cmp_gt_i32_e64 s[0:1], s95, v155
	v_ashrrev_i32_e32 v155, 31, v154
	v_lshlrev_b64 v[156:157], 10, v[154:155]
	v_lshl_add_u64 v[154:155], v[150:151], 0, v[156:157]
	v_lshl_add_u64 v[150:151], v[152:153], 0, v[156:157]
	v_mul_f32_e32 v152, 0x3fb8aa3b, v14
	v_exp_f32_e32 v158, v152
	v_mul_f32_e32 v152, 0x3fb8aa3b, v15
	v_exp_f32_e32 v160, v152
	v_mul_f32_e32 v152, 0x3fb8aa3b, v16
	v_exp_f32_e32 v159, v152
	s_and_b64 s[36:37], vcc, s[0:1]
	v_mul_f32_e32 v152, 0x3fb8aa3b, v17
	v_exp_f32_e32 v161, v152
	v_pk_add_f32 v[158:159], v[158:159], 1.0 op_sel_hi:[1,0]
	v_mul_f32_e32 v152, 0x3fb8aa3b, v10
	v_rcp_f32_e32 v167, v159
	v_mul_f32_e32 v153, 0x3fb8aa3b, v12
	v_exp_f32_e32 v156, v152
	v_exp_f32_e32 v157, v153
	v_mul_f32_e32 v166, v176, v167
	v_rcp_f32_e32 v167, v158
	v_pk_add_f32 v[156:157], v[156:157], 1.0 op_sel_hi:[1,0]
	v_mul_f32_e32 v152, 0x3fb8aa3b, v11
	v_mul_f32_e32 v153, 0x3fb8aa3b, v13
	v_mul_f32_e32 v167, v149, v167
	v_sub_f32_e32 v149, 1.0, v167
	v_cmp_gt_f32_e32 vcc, s96, v149
	v_exp_f32_e32 v152, v152
	v_exp_f32_e32 v153, v153
	v_cndmask_b32_e64 v158, 0, 32, vcc
	v_ldexp_f32 v149, v149, v158
	v_log_f32_e32 v149, v149
	v_pk_add_f32 v[152:153], v[152:153], 1.0 op_sel_hi:[1,0]
	v_mul_f32_e32 v158, 0x3f317217, v149
	v_fma_f32 v158, v149, s97, -v158
	v_fmac_f32_e32 v158, 0x3377d1cf, v149
	v_fmac_f32_e32 v158, 0x3f317217, v149
	v_cmp_lt_f32_e64 s[0:1], |v149|, s94
	s_nop 1
	v_cndmask_b32_e64 v149, v149, v158, s[0:1]
	v_cndmask_b32_e32 v158, 0, v190, vcc
	v_sub_f32_e32 v149, v149, v158
	v_pk_add_f32 v[158:159], v[160:161], 1.0 op_sel_hi:[1,0]
	s_nop 0
	v_rcp_f32_e32 v161, v159
	s_nop 0
	v_mul_f32_e32 v159, v174, v161
	v_rcp_f32_e32 v161, v158
	s_nop 0
	v_mul_f32_e32 v138, v138, v161
	v_sub_f32_e32 v158, 1.0, v138
	v_cmp_gt_f32_e32 vcc, s96, v158
	v_cndmask_b32_e64 v138, v138, 0, s[36:37]
	s_nop 0
	v_cndmask_b32_e64 v160, 0, 32, vcc
	v_ldexp_f32 v158, v158, v160
	v_log_f32_e32 v158, v158
	s_nop 0
	v_mul_f32_e32 v160, 0x3f317217, v158
	v_fma_f32 v160, v158, s97, -v160
	v_fmac_f32_e32 v160, 0x3377d1cf, v158
	v_fmac_f32_e32 v160, 0x3f317217, v158
	v_cmp_lt_f32_e64 s[0:1], |v158|, s94
	s_nop 1
	v_cndmask_b32_e64 v158, v158, v160, s[0:1]
	v_cndmask_b32_e32 v160, 0, v190, vcc
	v_sub_f32_e32 v160, v158, v160
	v_sub_f32_e32 v158, 1.0, v166
	v_cmp_gt_f32_e32 vcc, s96, v158
	s_nop 1
	v_cndmask_b32_e64 v161, 0, 32, vcc
	v_ldexp_f32 v158, v158, v161
	v_log_f32_e32 v158, v158
	s_nop 0
	v_mul_f32_e32 v161, 0x3f317217, v158
	v_fma_f32 v161, v158, s97, -v161
	v_fmac_f32_e32 v161, 0x3377d1cf, v158
	v_fmac_f32_e32 v161, 0x3f317217, v158
	v_cmp_lt_f32_e64 s[0:1], |v158|, s94
	s_nop 1
	v_cndmask_b32_e64 v158, v158, v161, s[0:1]
	v_cndmask_b32_e32 v161, 0, v190, vcc
	v_sub_f32_e32 v161, v158, v161
	v_sub_f32_e32 v158, 1.0, v159
	v_cmp_gt_f32_e32 vcc, s96, v158
	v_cndmask_b32_e64 v159, v159, 0, s[36:37]
	s_nop 0
	v_cndmask_b32_e64 v168, 0, 32, vcc
	v_ldexp_f32 v158, v158, v168
	v_log_f32_e32 v158, v158
	s_nop 0
	v_mul_f32_e32 v168, 0x3f317217, v158
	v_fma_f32 v168, v158, s97, -v168
	v_fmac_f32_e32 v168, 0x3377d1cf, v158
	v_fmac_f32_e32 v168, 0x3f317217, v158
	v_cmp_lt_f32_e64 s[0:1], |v158|, s94
	s_nop 1
	v_cndmask_b32_e64 v158, v158, v168, s[0:1]
	v_cndmask_b32_e32 v168, 0, v190, vcc
	v_sub_f32_e32 v168, v158, v168
	v_cndmask_b32_e64 v158, v166, 0, s[36:37]
	v_cndmask_b32_e64 v166, v167, 0, s[36:37]
	v_rcp_f32_e32 v169, v157
	s_nop 0
	v_mul_f32_e32 v157, v179, v169
	v_rcp_f32_e32 v169, v156
	s_nop 0
	v_mul_f32_e32 v156, v177, v169
	v_sub_f32_e32 v167, 1.0, v156
	v_cmp_gt_f32_e32 vcc, s96, v167
	v_cndmask_b32_e64 v156, v156, 0, s[36:37]
	s_nop 0
	v_cndmask_b32_e64 v169, 0, 32, vcc
	v_ldexp_f32 v167, v167, v169
	v_log_f32_e32 v167, v167
	s_nop 0
	v_mul_f32_e32 v169, 0x3f317217, v167
	v_fma_f32 v169, v167, s97, -v169
	v_fmac_f32_e32 v169, 0x3377d1cf, v167
	v_fmac_f32_e32 v169, 0x3f317217, v167
	v_cmp_lt_f32_e64 s[0:1], |v167|, s94
	s_nop 1
	v_cndmask_b32_e64 v167, v167, v169, s[0:1]
	v_cndmask_b32_e32 v169, 0, v190, vcc
	v_sub_f32_e32 v167, v167, v169
	v_rcp_f32_e32 v174, v153
	s_nop 0
	v_mul_f32_e32 v153, v178, v174
	v_rcp_f32_e32 v174, v152
	v_cvt_pk_bf16_f32 v138, v166, v138
	v_mul_f32_e32 v152, v175, v174
	v_sub_f32_e32 v169, 1.0, v152
	v_cmp_gt_f32_e32 vcc, s96, v169
	v_cndmask_b32_e64 v152, v152, 0, s[36:37]
	v_cndmask_b32_e64 v174, 0, 32, vcc
	v_ldexp_f32 v169, v169, v174
	v_log_f32_e32 v169, v169
	v_bfe_u32 v178, v159, 16, 1
	v_add3_u32 v178, v159, v178, s87
	v_cvt_pk_bf16_f32 v152, v156, v152
	v_mul_f32_e32 v174, 0x3f317217, v169
	v_fma_f32 v174, v169, s97, -v174
	v_fmac_f32_e32 v174, 0x3377d1cf, v169
	v_fmac_f32_e32 v174, 0x3f317217, v169
	v_cmp_lt_f32_e64 s[0:1], |v169|, s94
	v_cndmask_b32_e64 v169, v169, v174, s[0:1]
	v_cndmask_b32_e32 v174, 0, v190, vcc
	v_sub_f32_e32 v169, v169, v174
	v_sub_f32_e32 v174, 1.0, v157
	v_cmp_gt_f32_e32 vcc, s96, v174
	v_cndmask_b32_e64 v175, 0, 32, vcc
	v_ldexp_f32 v174, v174, v175
	v_log_f32_e32 v174, v174
	v_cndmask_b32_e64 v157, v157, 0, s[36:37]
	v_mul_f32_e32 v175, 0x3f317217, v174
	v_fma_f32 v175, v174, s97, -v175
	v_fmac_f32_e32 v175, 0x3377d1cf, v174
	v_fmac_f32_e32 v175, 0x3f317217, v174
	v_cmp_lt_f32_e64 s[0:1], |v174|, s94
	v_bfe_u32 v179, v157, 16, 1
	v_add3_u32 v157, v157, v179, s87
	v_cndmask_b32_e64 v174, v174, v175, s[0:1]
	v_cndmask_b32_e32 v175, 0, v190, vcc
	v_sub_f32_e32 v174, v174, v175
	v_sub_f32_e32 v175, 1.0, v153
	v_cmp_gt_f32_e32 vcc, s96, v175
	v_cndmask_b32_e64 v153, v153, 0, s[36:37]
	v_lshrrev_b32_e32 v157, 16, v157
	v_cndmask_b32_e64 v176, 0, 32, vcc
	v_ldexp_f32 v175, v175, v176
	v_log_f32_e32 v175, v175
	s_nop 0
	v_mul_f32_e32 v176, 0x3f317217, v175
	v_fma_f32 v176, v175, s97, -v176
	v_fmac_f32_e32 v176, 0x3377d1cf, v175
	v_fmac_f32_e32 v176, 0x3f317217, v175
	v_cmp_lt_f32_e64 s[0:1], |v175|, s94
	s_nop 1
	v_cndmask_b32_e64 v175, v175, v176, s[0:1]
	v_cndmask_b32_e32 v176, 0, v190, vcc
	v_sub_f32_e32 v175, v175, v176
	v_bfe_u32 v176, v153, 16, 1
	v_add3_u32 v153, v153, v176, s87
	v_bfe_u32 v176, v158, 16, 1
	v_add3_u32 v158, v158, v176, s87
	v_lshrrev_b32_e32 v176, 16, v158
	v_mov_b32_e32 v158, v152
	v_mov_b32_e32 v156, v138
	v_cndmask_b32_e64 v138, v149, 0, s[36:37]
	v_bfe_u32 v149, v138, 16, 1
	v_add3_u32 v138, v138, v149, s87
	v_cndmask_b32_e64 v149, v160, 0, s[36:37]
	v_bfe_u32 v152, v149, 16, 1
	v_and_or_b32 v159, v153, s88, v157
	v_and_or_b32 v157, v178, s88, v176
	v_lshrrev_b32_e32 v138, 16, v138
	v_add3_u32 v149, v149, v152, s87
	global_store_dwordx4 v[154:155], v[156:159], off
	s_nop 1
	v_and_or_b32 v156, v149, s88, v138
	v_cndmask_b32_e64 v138, v161, 0, s[36:37]
	v_bfe_u32 v149, v138, 16, 1
	v_add3_u32 v138, v138, v149, s87
	v_cndmask_b32_e64 v149, v168, 0, s[36:37]
	v_bfe_u32 v152, v149, 16, 1
	v_lshrrev_b32_e32 v138, 16, v138
	v_add3_u32 v149, v149, v152, s87
	v_and_or_b32 v157, v149, s88, v138
	v_cndmask_b32_e64 v138, v167, 0, s[36:37]
	v_bfe_u32 v149, v138, 16, 1
	v_add3_u32 v138, v138, v149, s87
	v_cndmask_b32_e64 v149, v169, 0, s[36:37]
	v_bfe_u32 v152, v149, 16, 1
	v_lshrrev_b32_e32 v138, 16, v138
	v_add3_u32 v149, v149, v152, s87
	v_and_or_b32 v158, v149, s88, v138
	v_cndmask_b32_e64 v138, v174, 0, s[36:37]
	v_bfe_u32 v149, v138, 16, 1
	v_add3_u32 v138, v138, v149, s87
	v_cndmask_b32_e64 v149, v175, 0, s[36:37]
	v_bfe_u32 v152, v149, 16, 1
	v_lshrrev_b32_e32 v138, 16, v138
	v_add3_u32 v149, v149, v152, s87
	v_and_or_b32 v159, v149, s88, v138
	v_mul_f32_e32 v138, 0x3fb8aa3b, v6
	global_store_dwordx4 v[150:151], v[156:159], off
	s_nop 1
	v_exp_f32_e32 v158, v138
	v_mul_f32_e32 v138, 0x3fb8aa3b, v7
	v_exp_f32_e32 v160, v138
	v_mul_f32_e32 v138, 0x3fb8aa3b, v8
	v_exp_f32_e32 v159, v138
	v_mul_f32_e32 v138, 0x3fb8aa3b, v9
	v_exp_f32_e32 v161, v138
	v_mul_f32_e32 v138, 0x3fb8aa3b, v2
	v_exp_f32_e32 v156, v138
	v_mul_f32_e32 v138, 0x3fb8aa3b, v3
	v_exp_f32_e32 v152, v138
	v_mul_f32_e32 v138, 0x3fb8aa3b, v4
	v_exp_f32_e32 v157, v138
	v_mul_f32_e32 v138, 0x3fb8aa3b, v5
	v_pk_add_f32 v[158:159], v[158:159], 1.0 op_sel_hi:[1,0]
	v_exp_f32_e32 v153, v138
	v_rcp_f32_e32 v149, v159
	v_pk_add_f32 v[156:157], v[156:157], 1.0 op_sel_hi:[1,0]
	v_pk_add_f32 v[152:153], v[152:153], 1.0 op_sel_hi:[1,0]
	v_mul_f32_e32 v149, v165, v149
	v_rcp_f32_e32 v159, v158
	s_nop 0
	v_mul_f32_e32 v164, v164, v159
	v_sub_f32_e32 v138, 1.0, v164
	v_cmp_gt_f32_e32 vcc, s96, v138
	s_nop 1
	v_cndmask_b32_e64 v158, 0, 32, vcc
	v_ldexp_f32 v138, v138, v158
	v_log_f32_e32 v138, v138
	s_nop 0
	v_mul_f32_e32 v158, 0x3f317217, v138
	v_fma_f32 v158, v138, s97, -v158
	v_fmac_f32_e32 v158, 0x3377d1cf, v138
	v_fmac_f32_e32 v158, 0x3f317217, v138
	v_cmp_lt_f32_e64 s[0:1], |v138|, s94
	s_nop 1
	v_cndmask_b32_e64 v138, v138, v158, s[0:1]
	v_cndmask_b32_e32 v158, 0, v190, vcc
	v_sub_f32_e32 v138, v138, v158
	v_pk_add_f32 v[158:159], v[160:161], 1.0 op_sel_hi:[1,0]
	v_cndmask_b32_e64 v138, v138, 0, s[36:37]
	v_rcp_f32_e32 v161, v159
	s_nop 0
	v_mul_f32_e32 v159, v163, v161
	v_rcp_f32_e32 v161, v158
	s_nop 0
	v_mul_f32_e32 v158, v162, v161
	v_sub_f32_e32 v160, 1.0, v158
	v_cmp_gt_f32_e32 vcc, s96, v160
	v_cndmask_b32_e64 v158, v158, 0, s[36:37]
	s_nop 0
	v_cndmask_b32_e64 v161, 0, 32, vcc
	v_ldexp_f32 v160, v160, v161
	v_log_f32_e32 v160, v160
	s_nop 0
	v_mul_f32_e32 v161, 0x3f317217, v160
	v_fma_f32 v161, v160, s97, -v161
	v_fmac_f32_e32 v161, 0x3377d1cf, v160
	v_fmac_f32_e32 v161, 0x3f317217, v160
	v_cmp_lt_f32_e64 s[0:1], |v160|, s94
	s_nop 1
	v_cndmask_b32_e64 v160, v160, v161, s[0:1]
	v_cndmask_b32_e32 v161, 0, v190, vcc
	v_sub_f32_e32 v160, v160, v161
	v_sub_f32_e32 v161, 1.0, v149
	v_cmp_gt_f32_e32 vcc, s96, v161
	v_cndmask_b32_e64 v149, v149, 0, s[36:37]
	s_nop 0
	v_cndmask_b32_e64 v162, 0, 32, vcc
	v_ldexp_f32 v161, v161, v162
	v_log_f32_e32 v161, v161
	s_nop 0
	v_mul_f32_e32 v162, 0x3f317217, v161
	v_fma_f32 v162, v161, s97, -v162
	v_fmac_f32_e32 v162, 0x3377d1cf, v161
	v_fmac_f32_e32 v162, 0x3f317217, v161
	v_cmp_lt_f32_e64 s[0:1], |v161|, s94
	s_nop 1
	v_cndmask_b32_e64 v161, v161, v162, s[0:1]
	v_cndmask_b32_e32 v162, 0, v190, vcc
	v_sub_f32_e32 v161, v161, v162
	v_sub_f32_e32 v162, 1.0, v159
	v_cmp_gt_f32_e32 vcc, s96, v162
	v_cndmask_b32_e64 v159, v159, 0, s[36:37]
	s_nop 0
	v_cndmask_b32_e64 v163, 0, 32, vcc
	v_ldexp_f32 v162, v162, v163
	v_log_f32_e32 v162, v162
	s_nop 0
	v_mul_f32_e32 v163, 0x3f317217, v162
	v_fma_f32 v163, v162, s97, -v163
	v_fmac_f32_e32 v163, 0x3377d1cf, v162
	v_fmac_f32_e32 v163, 0x3f317217, v162
	v_cmp_lt_f32_e64 s[0:1], |v162|, s94
	s_nop 1
	v_cndmask_b32_e64 v162, v162, v163, s[0:1]
	v_cndmask_b32_e32 v163, 0, v190, vcc
	v_sub_f32_e32 v162, v162, v163
	v_cndmask_b32_e64 v163, v164, 0, s[36:37]
	v_rcp_f32_e32 v165, v157
	s_nop 0
	v_mul_f32_e32 v157, v173, v165
	v_rcp_f32_e32 v165, v156
	s_nop 0
	v_mul_f32_e32 v156, v171, v165
	v_sub_f32_e32 v164, 1.0, v156
	v_cmp_gt_f32_e32 vcc, s96, v164
	v_cndmask_b32_e64 v156, v156, 0, s[36:37]
	v_bfe_u32 v171, v158, 16, 1
	v_cndmask_b32_e64 v165, 0, 32, vcc
	v_ldexp_f32 v164, v164, v165
	v_log_f32_e32 v164, v164
	v_add3_u32 v171, v158, v171, s87
	v_bfe_u32 v158, v163, 16, 1
	v_add3_u32 v158, v163, v158, s87
	v_mul_f32_e32 v165, 0x3f317217, v164
	v_fma_f32 v165, v164, s97, -v165
	v_fmac_f32_e32 v165, 0x3377d1cf, v164
	v_fmac_f32_e32 v165, 0x3f317217, v164
	v_cmp_lt_f32_e64 s[0:1], |v164|, s94
	v_lshrrev_b32_e32 v163, 16, v158
	s_nop 0
	v_cndmask_b32_e64 v164, v164, v165, s[0:1]
	v_cndmask_b32_e32 v165, 0, v190, vcc
	v_sub_f32_e32 v164, v164, v165
	v_rcp_f32_e32 v166, v153
	s_nop 0
	v_mul_f32_e32 v153, v172, v166
	v_rcp_f32_e32 v166, v152
	s_nop 0
	v_mul_f32_e32 v152, v170, v166
	v_sub_f32_e32 v165, 1.0, v152
	v_cmp_gt_f32_e32 vcc, s96, v165
	v_cndmask_b32_e64 v152, v152, 0, s[36:37]
	v_bfe_u32 v169, v152, 16, 1
	v_cndmask_b32_e64 v166, 0, 32, vcc
	v_ldexp_f32 v165, v165, v166
	v_log_f32_e32 v165, v165
	v_bfe_u32 v170, v159, 16, 1
	v_add3_u32 v170, v159, v170, s87
	v_add3_u32 v152, v152, v169, s87
	v_mul_f32_e32 v166, 0x3f317217, v165
	v_fma_f32 v166, v165, s97, -v166
	v_fmac_f32_e32 v166, 0x3377d1cf, v165
	v_fmac_f32_e32 v166, 0x3f317217, v165
	v_cmp_lt_f32_e64 s[0:1], |v165|, s94
	v_bfe_u32 v159, v149, 16, 1
	v_add3_u32 v149, v149, v159, s87
	v_cndmask_b32_e64 v165, v165, v166, s[0:1]
	v_cndmask_b32_e32 v166, 0, v190, vcc
	v_sub_f32_e32 v165, v165, v166
	v_sub_f32_e32 v166, 1.0, v157
	v_cmp_gt_f32_e32 vcc, s96, v166
	v_cndmask_b32_e64 v157, v157, 0, s[36:37]
	v_bfe_u32 v169, v157, 16, 1
	v_cndmask_b32_e64 v167, 0, 32, vcc
	v_ldexp_f32 v166, v166, v167
	v_log_f32_e32 v166, v166
	v_add3_u32 v157, v157, v169, s87
	v_lshrrev_b32_e32 v149, 16, v149
	v_lshrrev_b32_e32 v157, 16, v157
	v_mul_f32_e32 v167, 0x3f317217, v166
	v_fma_f32 v167, v166, s97, -v167
	v_fmac_f32_e32 v167, 0x3377d1cf, v166
	v_fmac_f32_e32 v167, 0x3f317217, v166
	v_cmp_lt_f32_e64 s[0:1], |v166|, s94
	s_nop 1
	v_cndmask_b32_e64 v166, v166, v167, s[0:1]
	v_cndmask_b32_e32 v167, 0, v190, vcc
	v_sub_f32_e32 v166, v166, v167
	v_sub_f32_e32 v167, 1.0, v153
	v_cmp_gt_f32_e32 vcc, s96, v167
	v_cndmask_b32_e64 v153, v153, 0, s[36:37]
	s_nop 0
	v_cndmask_b32_e64 v168, 0, 32, vcc
	v_ldexp_f32 v167, v167, v168
	v_log_f32_e32 v167, v167
	s_nop 0
	v_mul_f32_e32 v168, 0x3f317217, v167
	v_fma_f32 v168, v167, s97, -v168
	v_fmac_f32_e32 v168, 0x3377d1cf, v167
	v_fmac_f32_e32 v168, 0x3f317217, v167
	v_cmp_lt_f32_e64 s[0:1], |v167|, s94
	s_nop 1
	v_cndmask_b32_e64 v167, v167, v168, s[0:1]
	v_cndmask_b32_e32 v168, 0, v190, vcc
	v_sub_f32_e32 v167, v167, v168
	v_bfe_u32 v168, v153, 16, 1
	v_add3_u32 v153, v153, v168, s87
	v_bfe_u32 v168, v156, 16, 1
	v_add3_u32 v156, v156, v168, s87
	v_and_or_b32 v159, v153, s88, v157
	v_and_or_b32 v157, v170, s88, v149
	v_bfe_u32 v149, v138, 16, 1
	v_lshrrev_b32_e32 v156, 16, v156
	v_add3_u32 v138, v138, v149, s87
	v_cndmask_b32_e64 v149, v160, 0, s[36:37]
	v_and_or_b32 v158, v152, s88, v156
	v_bfe_u32 v152, v149, 16, 1
	v_lshrrev_b32_e32 v138, 16, v138
	v_add3_u32 v149, v149, v152, s87
	v_and_or_b32 v152, v149, s88, v138
	v_cndmask_b32_e64 v138, v161, 0, s[36:37]
	v_bfe_u32 v149, v138, 16, 1
	v_add3_u32 v138, v138, v149, s87
	v_cndmask_b32_e64 v149, v162, 0, s[36:37]
	v_bfe_u32 v153, v149, 16, 1
	v_lshrrev_b32_e32 v138, 16, v138
	v_add3_u32 v149, v149, v153, s87
	v_and_or_b32 v153, v149, s88, v138
	v_cndmask_b32_e64 v138, v164, 0, s[36:37]
	v_bfe_u32 v149, v138, 16, 1
	v_and_or_b32 v156, v171, s88, v163
	v_add3_u32 v138, v138, v149, s87
	v_cndmask_b32_e64 v149, v165, 0, s[36:37]
	global_store_dwordx4 v[154:155], v[156:159], off offset:256
	v_bfe_u32 v154, v149, 16, 1
	v_lshrrev_b32_e32 v138, 16, v138
	v_add3_u32 v149, v149, v154, s87
	v_and_or_b32 v154, v149, s88, v138
	v_cndmask_b32_e64 v138, v166, 0, s[36:37]
	v_bfe_u32 v149, v138, 16, 1
	v_add3_u32 v138, v138, v149, s87
	v_cndmask_b32_e64 v149, v167, 0, s[36:37]
	v_bfe_u32 v155, v149, 16, 1
	v_lshrrev_b32_e32 v138, 16, v138
	v_add3_u32 v149, v149, v155, s87
	v_and_or_b32 v155, v149, s88, v138
	global_store_dwordx4 v[150:151], v[152:155], off offset:256

.LBB0_246:
	s_andn2_b64 vcc, exec, s[4:5]
	s_mov_b64 s[0:1], -1
	s_cbranch_vccnz .LBB0_132
	s_andn2_b64 vcc, exec, s[6:7]
	s_cbranch_vccnz .LBB0_131
	s_barrier
	s_branch .LBB0_131
	s_nop 0
	s_nop 0
	s_nop 0
	s_nop 0
	s_nop 0
	s_nop 0
	s_nop 0
	s_nop 0
	s_nop 0
	s_nop 0
	s_nop 0
	s_nop 0
	s_nop 0
	s_nop 0
	s_nop 0
	s_nop 0
	s_nop 0
	s_nop 0
	s_nop 0
	s_nop 0
	s_nop 0
	s_nop 0
	s_nop 0
	s_nop 0
	s_nop 0
	s_nop 0
	s_nop 0
	s_nop 0
	s_nop 0
	s_nop 0
	s_nop 0
	s_nop 0
	s_nop 0
	s_nop 0
	s_nop 0
	s_nop 0
	s_nop 0
	s_nop 0
	s_nop 0
	s_nop 0
	s_nop 0
	s_nop 0
	s_nop 0
	s_nop 0
	s_nop 0
	s_nop 0
	s_nop 0
	s_nop 0
	s_nop 0
	s_nop 0
	s_nop 0
	s_nop 0
	s_nop 0
	s_nop 0
	s_nop 0
	s_nop 0
	s_nop 0
	s_nop 0
	s_nop 0
	s_nop 0
	s_nop 0
	s_nop 0
	s_nop 0
	s_nop 0
	s_nop 0
	s_nop 0
	s_nop 0
	s_nop 0
	s_nop 0
	s_nop 0
	s_nop 0
	s_nop 0
	s_nop 0
	s_nop 0
	s_nop 0
	s_nop 0
	s_nop 0
	s_nop 0
	s_nop 0
	s_nop 0
	s_nop 0
	s_nop 0
	s_nop 0
	s_nop 0
	s_nop 0
	s_nop 0
	s_nop 0
	s_nop 0
	s_nop 0
	s_nop 0
	s_nop 0
	s_nop 0
	s_nop 0
	s_nop 0
	s_nop 0
	s_nop 0
	s_nop 0
	s_nop 0
	s_nop 0
	s_nop 0
	s_nop 0
	s_nop 0
	s_nop 0
	s_nop 0
	s_nop 0
	s_nop 0
	s_nop 0
	s_nop 0
	s_nop 0
	s_nop 0
	s_nop 0
	s_nop 0
	s_nop 0
	s_nop 0
	s_nop 0
	s_nop 0
	s_nop 0
	s_nop 0
	s_nop 0
	s_nop 0
	s_nop 0
	s_nop 0
	s_nop 0
	s_nop 0
	s_nop 0
	s_nop 0
	s_nop 0
	s_nop 0
	s_nop 0
	s_nop 0
	s_nop 0
	s_nop 0
	s_nop 0
	s_nop 0
	s_nop 0
	s_nop 0
	s_nop 0
	s_nop 0
	s_nop 0
	s_nop 0
	s_nop 0
	s_nop 0
	s_nop 0
	s_nop 0
	s_nop 0
	s_nop 0
	s_nop 0
	s_nop 0
	s_nop 0
	s_nop 0
	s_nop 0
	s_nop 0
	s_nop 0
	s_nop 0
	s_nop 0
	s_nop 0
	s_nop 0
	s_nop 0
	s_nop 0
	s_nop 0
	s_nop 0
	s_nop 0
	s_nop 0
	s_nop 0
	s_nop 0
	s_nop 0
	s_nop 0
	s_nop 0
	s_nop 0
	s_nop 0
	s_nop 0
	s_nop 0
	s_nop 0
	s_nop 0
	s_nop 0
	s_nop 0
	s_nop 0
	s_nop 0
	s_nop 0
	s_nop 0
	s_nop 0
	s_nop 0
	s_nop 0
	s_nop 0
	s_nop 0
	s_nop 0
	s_nop 0
	s_nop 0
	s_nop 0
	s_nop 0
	s_nop 0
	s_nop 0
	s_nop 0
	s_nop 0
	s_nop 0
	s_nop 0
	s_nop 0
	s_nop 0
	s_nop 0
	s_nop 0
	s_nop 0
	s_nop 0
	s_nop 0
	s_nop 0
	s_nop 0
	s_nop 0
	s_nop 0
	s_nop 0
	s_nop 0
	s_nop 0
	s_nop 0
	s_nop 0
	s_nop 0
	s_nop 0
	s_nop 0
	s_nop 0
	s_nop 0
	s_nop 0
	s_nop 0
	s_nop 0
	s_nop 0
	s_nop 0
	s_nop 0
	s_nop 0
	s_nop 0
	s_nop 0
	s_nop 0
	s_nop 0
	s_nop 0
	s_nop 0
	s_nop 0
	s_nop 0
	s_nop 0
	s_nop 0
	s_nop 0
	s_nop 0
	s_nop 0
	s_nop 0
	s_nop 0
	s_nop 0
	s_nop 0
	s_nop 0
	s_nop 0
	s_nop 0
	s_nop 0
	s_nop 0
	s_nop 0
	s_nop 0
	s_nop 0
	s_nop 0
	s_nop 0
	s_nop 0
	s_nop 0
	s_nop 0
	s_nop 0
	s_nop 0
	s_nop 0
	s_nop 0
	s_nop 0
	s_nop 0
	s_nop 0
	s_nop 0
	s_nop 0
	s_nop 0
	s_nop 0
	s_nop 0
	s_nop 0
	s_nop 0
	s_nop 0
	s_nop 0
	s_nop 0
	s_nop 0
	s_nop 0
	s_nop 0
	s_nop 0
	s_nop 0
	s_nop 0
	s_nop 0
	s_nop 0
	s_nop 0
	s_nop 0
	s_nop 0
	s_nop 0
	s_nop 0
	s_nop 0
	s_nop 0
	s_nop 0
	s_nop 0
	s_nop 0
	s_nop 0
	s_nop 0
	s_nop 0
	s_nop 0
	s_nop 0
	s_nop 0
	s_nop 0
	s_nop 0
	s_nop 0
	s_nop 0
	s_nop 0
	s_nop 0
	s_nop 0
	s_nop 0
	s_nop 0
	s_nop 0
	s_nop 0
	s_nop 0
	s_nop 0
	s_nop 0
	s_nop 0
	s_nop 0
	s_nop 0
	s_nop 0
	s_nop 0
	s_nop 0
	s_nop 0
	s_nop 0
	s_nop 0
	s_nop 0
	s_nop 0
	s_nop 0
	s_nop 0
	s_nop 0
	s_nop 0
	s_nop 0
	s_nop 0
	s_nop 0
	s_nop 0
	s_nop 0
	s_nop 0
	s_nop 0
	s_nop 0
	s_nop 0
	s_nop 0
	s_nop 0
	s_nop 0
	s_nop 0
	s_nop 0
	s_nop 0
	s_nop 0
	s_nop 0
	s_nop 0
	s_nop 0
	s_nop 0
	s_nop 0
	s_nop 0
	s_nop 0
	s_nop 0
	s_nop 0
	s_nop 0
	s_nop 0
	s_nop 0
	s_nop 0
	s_nop 0
	s_nop 0
	s_nop 0
	s_nop 0
	s_nop 0
	s_nop 0
	s_nop 0
	s_nop 0
	s_nop 0
	s_nop 0
	s_nop 0
	s_nop 0
	s_nop 0
	s_nop 0
	s_nop 0
	s_nop 0
	s_nop 0
	s_nop 0
	s_nop 0
	s_nop 0
	s_nop 0
	s_nop 0
	s_nop 0
	s_nop 0
	s_nop 0
	s_nop 0
	s_nop 0
	s_nop 0
	s_nop 0
	s_nop 0
	s_nop 0
	s_nop 0
	s_nop 0
	s_nop 0
	s_nop 0
	s_nop 0
	s_nop 0
	s_nop 0
	s_nop 0
	s_nop 0
	s_nop 0
	s_nop 0
	s_nop 0
	s_nop 0
	s_nop 0
	s_nop 0
	s_nop 0
	s_nop 0
	s_nop 0
	s_nop 0
	s_nop 0
	s_nop 0
	s_nop 0
	s_nop 0
	s_nop 0
	s_nop 0
	s_nop 0
	s_nop 0
	s_nop 0
	s_nop 0
	s_nop 0
	s_nop 0
	s_nop 0
	s_nop 0
	s_nop 0
	s_nop 0
	s_nop 0
	s_nop 0
	s_nop 0
	s_nop 0
	s_nop 0
	s_nop 0
	s_nop 0
	s_nop 0
	s_nop 0
	s_nop 0
	s_nop 0
	s_nop 0
	s_nop 0
	s_nop 0
	s_nop 0
	s_nop 0
	s_nop 0
	s_nop 0
	s_nop 0
	s_nop 0
	s_nop 0
	s_nop 0
	s_nop 0
	s_nop 0
	s_nop 0
	s_nop 0
	s_nop 0
	s_nop 0
	s_nop 0
	s_nop 0
	s_nop 0
	s_nop 0
	s_nop 0
	s_nop 0
	s_nop 0
	s_nop 0
	s_nop 0
	s_nop 0
	s_nop 0
	s_nop 0
	s_nop 0
	s_nop 0
	s_nop 0
	s_nop 0
	s_nop 0
	s_nop 0
	s_nop 0
	s_nop 0
	s_nop 0
	s_nop 0
	s_nop 0
	s_nop 0
	s_nop 0
	s_nop 0
	s_nop 0
	s_nop 0
	s_nop 0
	s_nop 0
	s_nop 0
	s_nop 0
	s_nop 0
	s_nop 0
	s_nop 0
	s_nop 0
	s_nop 0
	s_nop 0
	s_nop 0
	s_nop 0
	s_nop 0
	s_nop 0
	s_nop 0
	s_nop 0
	s_nop 0
	s_nop 0
	s_nop 0
	s_nop 0
	s_nop 0
	s_nop 0
	s_nop 0
	s_nop 0
	s_nop 0
	s_nop 0
	s_nop 0
	s_nop 0
	s_nop 0
	s_nop 0
	s_nop 0
	s_nop 0
	s_nop 0
	s_nop 0
	s_nop 0
	s_nop 0
	s_nop 0
	s_nop 0
	s_nop 0
	s_nop 0
	s_nop 0
	s_nop 0
	s_nop 0
	s_nop 0
	s_nop 0
	s_nop 0
	s_nop 0
	s_nop 0
	s_nop 0
	s_nop 0
	s_nop 0
	s_nop 0
	s_nop 0
	s_nop 0
	s_nop 0
	s_nop 0
	s_nop 0
	s_nop 0
	s_nop 0
	s_nop 0
	s_nop 0
	s_nop 0
	s_nop 0
	s_nop 0
	s_nop 0
	s_nop 0
	s_nop 0
	s_nop 0
	s_nop 0
	s_nop 0
	s_nop 0
	s_nop 0
	s_nop 0
	s_nop 0
	s_nop 0
	s_nop 0
	s_nop 0
	s_nop 0
	s_nop 0
	s_nop 0
	s_nop 0
	s_nop 0
	s_nop 0
	s_nop 0
	s_nop 0
	s_nop 0
	s_nop 0
	s_nop 0
	s_nop 0
	s_nop 0
	s_nop 0
	s_nop 0
	s_nop 0
	s_nop 0
	s_nop 0
	s_nop 0
	s_nop 0
	s_nop 0
	s_nop 0
	s_nop 0
	s_nop 0
	s_nop 0
	s_nop 0
	s_nop 0
	s_nop 0
	s_nop 0
	s_nop 0
	s_nop 0
	s_nop 0
	s_nop 0
	s_nop 0
	s_nop 0
	s_nop 0
	s_nop 0
	s_nop 0
	s_nop 0
	s_nop 0
	s_nop 0
	s_nop 0
	s_nop 0
	s_nop 0
	s_nop 0
	s_nop 0
	s_nop 0
	s_nop 0
	s_nop 0
	s_nop 0
	s_nop 0
	s_nop 0
	s_nop 0
	s_nop 0
	s_nop 0
	s_nop 0
	s_nop 0
	s_nop 0
	s_nop 0
	s_nop 0
	s_nop 0
	s_nop 0
	s_nop 0
	s_nop 0
	s_nop 0
	s_nop 0
	s_nop 0
	s_nop 0
	s_nop 0
	s_nop 0
	s_nop 0
	s_nop 0
	s_nop 0
	s_nop 0
	s_nop 0
	s_nop 0
	s_nop 0
	s_nop 0
	s_nop 0
	s_nop 0
	s_nop 0
	s_nop 0
	s_nop 0
	s_nop 0
	s_nop 0
	s_nop 0
	s_nop 0
	s_nop 0
	s_nop 0
	s_nop 0
	s_nop 0
	s_nop 0
	s_nop 0
	s_nop 0
	s_nop 0
	s_nop 0
	s_nop 0
	s_nop 0
	s_nop 0
	s_nop 0
	s_nop 0
	s_nop 0
	s_nop 0
	s_nop 0
	s_nop 0
	s_nop 0
	s_nop 0
	s_nop 0
	s_nop 0
	s_nop 0
	s_nop 0
	s_nop 0
	s_nop 0
	s_nop 0
	s_nop 0
	s_nop 0
	s_nop 0
	s_nop 0
	s_nop 0
	s_nop 0
	s_nop 0
	s_nop 0
	s_nop 0
	s_nop 0
	s_nop 0
	s_nop 0
	s_nop 0
	s_nop 0
	s_nop 0
	s_nop 0
	s_nop 0
	s_nop 0
	s_nop 0
	s_nop 0
	s_nop 0
	s_nop 0
	s_nop 0
	s_nop 0
	s_nop 0
	s_nop 0
	s_nop 0
	s_nop 0
	s_nop 0
	s_nop 0
	s_nop 0
	s_nop 0
	s_nop 0
	s_nop 0
	s_nop 0
	s_nop 0
	s_nop 0
	s_nop 0
	s_nop 0
	s_nop 0
	s_nop 0
	s_nop 0
	s_nop 0
	s_nop 0
	s_nop 0
	s_nop 0
	s_nop 0
	s_nop 0
	s_nop 0
	s_nop 0
	s_nop 0
	s_nop 0
	s_nop 0
	s_nop 0
	s_nop 0
	s_nop 0
	s_nop 0
	s_nop 0
	s_nop 0
	s_nop 0
	s_nop 0
	s_nop 0
	s_nop 0
	s_nop 0
	s_nop 0
	s_nop 0
	s_nop 0
	s_nop 0
	s_nop 0
	s_nop 0
	s_nop 0
	s_nop 0
	s_nop 0
	s_nop 0
	s_nop 0
	s_nop 0
	s_nop 0
	s_nop 0
	s_nop 0
	s_nop 0
	s_nop 0
	s_nop 0
	s_nop 0
	s_nop 0
	s_nop 0
	s_nop 0
	s_nop 0
	s_nop 0
	s_nop 0
	s_nop 0
	s_nop 0
	s_nop 0
	s_nop 0
	s_nop 0
	s_nop 0
	s_nop 0
	s_nop 0
	s_nop 0
	s_nop 0
	s_nop 0
	s_nop 0
	s_nop 0
	s_nop 0
	s_nop 0
	s_nop 0
	s_nop 0
	s_nop 0
	s_nop 0
	s_nop 0
	s_nop 0
	s_nop 0
	s_nop 0
	s_nop 0
	s_nop 0
	s_nop 0
	s_nop 0
	s_nop 0
	s_nop 0
	s_nop 0
	s_nop 0
	s_nop 0
	s_nop 0
	s_nop 0
	s_nop 0
	s_nop 0
	s_nop 0
	s_nop 0
	s_nop 0
	s_nop 0
	s_nop 0
	s_nop 0
	s_nop 0
	s_nop 0
	s_nop 0
	s_nop 0
	s_nop 0
	s_nop 0
	s_nop 0
	s_nop 0
	s_nop 0
	s_nop 0
	s_nop 0
	s_nop 0
	s_nop 0
	s_nop 0
	s_nop 0
	s_nop 0
	s_nop 0
	s_nop 0
	s_nop 0
	s_nop 0
	s_nop 0
	s_nop 0
	s_nop 0
	s_nop 0
	s_nop 0
	s_nop 0
	s_nop 0
	s_nop 0
	s_nop 0
	s_nop 0
	s_nop 0
	s_nop 0
	s_nop 0
	s_nop 0
	s_nop 0
	s_nop 0
	s_nop 0
	s_nop 0
	s_nop 0
	s_nop 0
	s_nop 0
	s_nop 0
	s_nop 0
	s_nop 0
	s_nop 0
	s_nop 0
	s_nop 0
	s_nop 0
	s_nop 0
	s_nop 0
	s_nop 0
	s_nop 0
	s_nop 0
	s_nop 0
	s_nop 0
	s_nop 0
	s_nop 0
	s_nop 0
	s_nop 0
	s_nop 0
	s_nop 0
	s_nop 0
	s_nop 0
	s_nop 0
	s_nop 0
	s_nop 0
	s_nop 0
	s_nop 0
	s_nop 0
	s_nop 0
	s_nop 0
	s_nop 0
	s_nop 0
	s_nop 0
	s_nop 0
	s_nop 0
	s_nop 0
	s_nop 0
	s_nop 0
	s_nop 0
	s_nop 0
	s_nop 0
	s_nop 0
	s_nop 0
	s_nop 0
	s_nop 0
	s_nop 0
	s_nop 0
	s_nop 0
	s_nop 0
	s_nop 0
	s_nop 0
	s_nop 0
	s_nop 0
	s_nop 0
	s_nop 0
	s_nop 0
	s_nop 0
	s_nop 0
	s_nop 0
	s_nop 0
	s_nop 0
	s_nop 0
	s_nop 0
	s_nop 0
	s_nop 0
	s_nop 0
	s_nop 0
	s_nop 0
	s_nop 0
	s_nop 0
	s_nop 0
	s_nop 0
	s_nop 0
	s_nop 0
	s_nop 0
	s_nop 0
	s_nop 0
	s_nop 0
	s_nop 0
	s_nop 0
	s_nop 0
	s_nop 0
	s_nop 0
	s_nop 0
	s_nop 0
	s_nop 0
	s_nop 0
	s_nop 0
	s_nop 0
	s_nop 0
	s_nop 0
	s_nop 0
	s_nop 0
	s_nop 0
	s_nop 0
	s_nop 0
	s_nop 0
	s_nop 0
	s_nop 0
	s_nop 0
	s_nop 0
	s_nop 0
	s_nop 0
	s_nop 0
	s_nop 0
	s_nop 0
	s_nop 0
	s_nop 0
	s_nop 0
	s_nop 0
	s_nop 0
	s_nop 0
	s_nop 0
	s_nop 0
	s_nop 0
	s_nop 0
	s_nop 0
	s_nop 0
	s_nop 0
	s_nop 0
	s_nop 0
	s_nop 0
	s_nop 0
	s_nop 0
	s_nop 0
	s_nop 0
	s_nop 0
	s_nop 0
	s_nop 0
	s_nop 0
	s_nop 0
	s_nop 0
	s_nop 0
	s_nop 0
	s_nop 0
	s_nop 0
	s_nop 0
	s_nop 0
	s_nop 0
	s_nop 0
	s_nop 0
	s_nop 0
	s_nop 0
	s_nop 0
	s_nop 0
	s_nop 0
	s_nop 0
	s_nop 0
	s_nop 0
	s_nop 0
	s_nop 0
	s_nop 0
	s_nop 0
	s_nop 0
	s_nop 0
	s_nop 0
	s_nop 0
	s_nop 0
	s_nop 0
	s_nop 0
	s_nop 0
	s_nop 0
	s_nop 0
	s_nop 0
	s_nop 0
	s_nop 0
	s_nop 0
	s_nop 0
	s_nop 0
	s_nop 0
	s_nop 0
	s_nop 0
	s_nop 0
	s_nop 0
	s_nop 0
	s_nop 0
	s_nop 0
	s_nop 0
	s_nop 0
	s_nop 0
	s_nop 0
	s_nop 0
	s_nop 0
	s_nop 0
	s_nop 0
	s_nop 0
	s_nop 0
	s_nop 0
	s_nop 0
	s_nop 0
	s_nop 0
	s_nop 0
	s_nop 0
	s_nop 0
	s_nop 0
	s_nop 0
	s_nop 0
	s_nop 0
	s_nop 0
	s_nop 0
	s_nop 0
	s_nop 0
	s_nop 0
	s_nop 0
	s_nop 0
	s_nop 0
	s_nop 0
	s_nop 0
	s_nop 0
	s_nop 0
	s_nop 0
	s_nop 0
	s_nop 0
	s_nop 0
	s_nop 0
	s_nop 0
	s_nop 0
	s_nop 0
	s_nop 0
	s_nop 0
	s_nop 0
	s_nop 0
	s_nop 0
	s_nop 0
	s_nop 0
	s_nop 0
	s_nop 0
	s_nop 0
	s_nop 0
	s_nop 0
	s_nop 0
	s_nop 0
	s_nop 0
	s_nop 0
	s_nop 0
	s_nop 0
	s_nop 0
	s_nop 0
	s_nop 0
	s_nop 0
	s_nop 0
	s_nop 0
	s_nop 0
	s_nop 0
	s_nop 0
	s_nop 0
	s_nop 0
	s_nop 0
	s_nop 0
	s_nop 0
	s_nop 0
	s_nop 0
	s_nop 0
	s_nop 0
	s_nop 0
	s_nop 0
	s_nop 0
	s_nop 0
	s_nop 0
	s_nop 0
	s_nop 0
	s_nop 0
	s_nop 0
	s_nop 0
	s_nop 0
	s_nop 0
	s_nop 0
	s_nop 0
	s_nop 0
	s_nop 0
	s_nop 0
	s_nop 0
	s_nop 0
	s_nop 0
	s_nop 0
	s_nop 0
	s_nop 0
	s_nop 0
	s_nop 0
	s_nop 0
	s_nop 0
	s_nop 0
	s_nop 0
	s_nop 0
	s_nop 0
	s_nop 0
	s_nop 0
	s_nop 0
	s_nop 0
	s_nop 0
	s_nop 0
	s_nop 0
	s_nop 0
	s_nop 0
	s_nop 0
	s_nop 0
	s_nop 0
	s_nop 0
	s_nop 0
	s_nop 0
	s_nop 0
	s_nop 0
	s_nop 0
	s_nop 0
	s_nop 0
	s_nop 0
	s_nop 0
	s_nop 0
	s_nop 0
	s_nop 0
	s_nop 0
	s_nop 0
	s_nop 0
	s_nop 0
	s_nop 0
	s_nop 0
	s_nop 0
	s_nop 0
	s_nop 0
	s_nop 0
	s_nop 0
	s_nop 0
	s_nop 0
	s_nop 0
	s_nop 0
	s_nop 0
	s_nop 0
	s_nop 0
	s_nop 0
	s_nop 0
	s_nop 0
	s_nop 0
	s_nop 0
	s_nop 0
	s_nop 0
	s_nop 0
	s_nop 0
	s_nop 0
	s_nop 0
	s_nop 0
	s_nop 0
	s_nop 0
	s_nop 0
	s_nop 0
	s_nop 0
	s_nop 0
	s_nop 0
	s_nop 0
	s_nop 0
	s_nop 0
	s_nop 0
	s_nop 0
	s_nop 0
	s_nop 0
	s_nop 0
	s_nop 0
	s_nop 0
	s_nop 0
	s_nop 0
	s_nop 0
	s_nop 0
	s_nop 0
	s_nop 0
	s_nop 0
	s_nop 0
	s_nop 0
	s_nop 0
	s_nop 0
	s_nop 0
	s_nop 0
	s_nop 0
	s_nop 0
	s_nop 0
	s_nop 0
	s_nop 0
	s_nop 0
	s_nop 0
	s_nop 0
	s_nop 0
	s_nop 0
	s_nop 0
	s_nop 0
	s_nop 0
	s_nop 0
	s_nop 0
	s_nop 0
	s_nop 0
	s_nop 0
	s_nop 0
	s_nop 0
	s_nop 0
	s_nop 0
	s_nop 0

.LBB0_267:
	s_cmp_eq_u32 s33, 0
	s_cselect_b64 vcc, -1, 0
	s_cmp_eq_u32 s33, 1
	v_cndmask_b32_e32 v17, 0, v16, vcc
	s_cselect_b64 vcc, -1, 0
	s_cmp_eq_u32 s33, 2
	v_cndmask_b32_e32 v17, v17, v1, vcc
	s_cselect_b64 vcc, -1, 0
	s_cmp_eq_u32 s33, 3
	v_cndmask_b32_e32 v17, v17, v2, vcc
	s_cselect_b64 vcc, -1, 0
	s_cmp_eq_u32 s33, 4
	v_cndmask_b32_e32 v17, v17, v3, vcc
	s_cselect_b64 vcc, -1, 0
	s_cmp_eq_u32 s33, 5
	v_cndmask_b32_e32 v17, v17, v4, vcc
	s_cselect_b64 vcc, -1, 0
	s_cmp_eq_u32 s33, 6
	v_cndmask_b32_e32 v17, v17, v5, vcc
	s_cselect_b64 vcc, -1, 0
	s_cmp_eq_u32 s33, 7
	v_cndmask_b32_e32 v17, v17, v6, vcc
	s_cselect_b64 vcc, -1, 0
	s_cmp_eq_u32 s33, 8
	v_cndmask_b32_e32 v17, v17, v7, vcc
	s_cselect_b64 vcc, -1, 0
	s_cmp_eq_u32 s33, 9
	v_cndmask_b32_e32 v17, v17, v8, vcc
	s_cselect_b64 vcc, -1, 0
	s_cmp_eq_u32 s33, 10
	v_cndmask_b32_e32 v17, v17, v9, vcc
	s_cselect_b64 vcc, -1, 0
	s_cmp_eq_u32 s33, 11
	v_cndmask_b32_e32 v17, v17, v10, vcc
	s_cselect_b64 vcc, -1, 0
	s_cmp_eq_u32 s33, 12
	v_cndmask_b32_e32 v17, v17, v11, vcc
	s_cselect_b64 vcc, -1, 0
	s_cmp_eq_u32 s33, 13
	v_cndmask_b32_e32 v17, v17, v12, vcc
	s_cselect_b64 vcc, -1, 0
	s_cmp_eq_u32 s33, 14
	v_cndmask_b32_e32 v17, v17, v13, vcc
	s_cselect_b64 vcc, -1, 0
	s_cmp_eq_u32 s33, 15
	v_cndmask_b32_e32 v17, v17, v14, vcc
	s_cselect_b64 vcc, -1, 0
	v_cndmask_b32_e32 v17, v17, v15, vcc
	v_cmp_ne_u32_e32 vcc, 0, v16
	s_add_i32 s2, 0, 0x23fc0
	s_nop 0
	v_cndmask_b32_e64 v16, 0, 1, vcc
	v_cmp_ne_u32_e32 vcc, 0, v1
	s_nop 1
	v_addc_co_u32_e32 v1, vcc, 0, v16, vcc
	s_nop 1
	v_cmp_ne_u32_e32 vcc, 0, v2
	s_nop 1
	v_cndmask_b32_e64 v2, 0, 1, vcc
	v_cmp_ne_u32_e32 vcc, 0, v3
	v_max_u32_e32 v3, 1, v17
	s_nop 0
	v_addc_co_u32_e32 v1, vcc, v1, v2, vcc
	s_nop 1
	v_cmp_ne_u32_e32 vcc, 0, v4
	s_nop 1
	v_cndmask_b32_e64 v2, 0, 1, vcc
	v_cmp_ne_u32_e32 vcc, 0, v5
	s_nop 1
	v_addc_co_u32_e32 v1, vcc, v1, v2, vcc
	s_nop 1
	v_cmp_ne_u32_e32 vcc, 0, v6
	s_nop 1
	v_cndmask_b32_e64 v2, 0, 1, vcc
	v_cmp_ne_u32_e32 vcc, 0, v7
	s_nop 1
	v_addc_co_u32_e32 v1, vcc, v1, v2, vcc
	s_nop 1
	v_cmp_ne_u32_e32 vcc, 0, v8
	s_nop 1
	v_cndmask_b32_e64 v2, 0, 1, vcc
	v_cmp_ne_u32_e32 vcc, 0, v9
	s_nop 1
	v_addc_co_u32_e32 v1, vcc, v1, v2, vcc
	s_nop 1
	v_cmp_ne_u32_e32 vcc, 0, v10
	s_nop 1
	v_cndmask_b32_e64 v2, 0, 1, vcc
	v_cmp_ne_u32_e32 vcc, 0, v11
	s_nop 1
	v_addc_co_u32_e32 v1, vcc, v1, v2, vcc
	s_nop 1
	v_cmp_ne_u32_e32 vcc, 0, v12
	s_nop 1
	v_cndmask_b32_e64 v2, 0, 1, vcc
	v_cmp_ne_u32_e32 vcc, 0, v13
	s_nop 1
	v_addc_co_u32_e32 v1, vcc, v1, v2, vcc
	s_nop 1
	v_cmp_ne_u32_e32 vcc, 0, v14
	s_nop 1
	v_cndmask_b32_e64 v2, 0, 1, vcc
	v_cmp_ne_u32_e32 vcc, 0, v15
	s_nop 1
	v_addc_co_u32_e32 v1, vcc, v1, v2, vcc
	v_mov_b32_e32 v2, s2
	s_add_i32 s2, 0, 0x23fc4
	v_max_u32_e32 v1, 1, v1
	ds_write_b32 v2, v3
	v_mov_b32_e32 v2, s2
	ds_write_b32 v2, v1

.LBB0_274:
	s_and_b32 s20, s24, 0xff
	s_mov_b64 s[18:19], -1
	s_cmp_lg_u32 s20, 0
	s_mov_b64 s[22:23], -1
	s_sleep 2
	s_cbranch_scc1 .LBB0_277
	global_load_dword v3, v1, s[10:11] sc1
	s_waitcnt vmcnt(0)
	v_cmp_eq_u32_e32 vcc, 0, v3
	s_cbranch_vccnz .LBB0_279
	s_mov_b64 s[22:23], 0
	s_mov_b64 s[20:21], -1

.LBB0_291:
	s_and_b32 s18, s24, 0xff
	s_cmp_lg_u32 s18, 0
	s_mov_b64 s[20:21], -1
	s_sleep 2
	s_cbranch_scc1 .LBB0_294
	global_load_dword v2, v1, s[10:11] sc1
	s_waitcnt vmcnt(0)
	v_cmp_eq_u32_e32 vcc, 0, v2
	s_cbranch_vccnz .LBB0_296
	s_mov_b64 s[20:21], 0
	s_mov_b64 s[18:19], -1

.LBB0_989:
	s_andn2_b64 vcc, exec, s[6:7]
	s_cbranch_vccnz .LBB0_1062
	s_add_i32 s0, s9, -1
	s_cmp_gt_u32 s0, 1
	s_mov_b64 s[0:1], -1
	s_cbranch_scc0 .LBB0_996
	s_cmp_eq_u32 s9, 5
	s_waitcnt lgkmcnt(0)
	v_mov_b32_e32 v133, 0
	s_cbranch_scc1 .LBB0_993
	v_lshlrev_b32_e32 v132, 1, v1
	v_lshl_add_u64 v[134:135], s[10:11], 0, v[132:133]
	v_mul_f32_e32 v132, 0xbfb8aa3b, v126
	v_exp_f32_e32 v136, v132
	v_mul_f32_e32 v132, 0xbfb8aa3b, v128
	v_exp_f32_e32 v137, v132
	v_ashrrev_i32_e32 v131, 31, v130
	v_lshlrev_b64 v[132:133], 10, v[130:131]
	v_mul_f32_e32 v131, 0xbfb8aa3b, v127
	v_pk_add_f32 v[136:137], v[136:137], 1.0 op_sel_hi:[1,0]
	v_exp_f32_e32 v138, v131
	v_rcp_f32_e32 v141, v137
	v_mul_f32_e32 v131, 0xbfb8aa3b, v129
	v_exp_f32_e32 v139, v131
	v_lshl_add_u64 v[132:133], v[134:135], 0, v[132:133]
	v_rcp_f32_e32 v143, v136
	v_mul_f32_e32 v131, v128, v141
	v_pk_add_f32 v[138:139], v[138:139], 1.0 op_sel_hi:[1,0]
	v_rcp_f32_e32 v142, v138
	v_mul_f32_e32 v141, v126, v143
	v_rcp_f32_e32 v143, v139
	v_mul_f32_e32 v142, v127, v142
	v_mul_f32_e32 v136, 0xbfb8aa3b, v122
	v_mul_f32_e32 v137, 0xbfb8aa3b, v124
	v_exp_f32_e32 v136, v136
	v_exp_f32_e32 v137, v137
	v_mul_f32_e32 v140, v129, v143
	v_mul_f32_e32 v138, 0xbfb8aa3b, v123
	v_pk_add_f32 v[136:137], v[136:137], 1.0 op_sel_hi:[1,0]
	v_mul_f32_e32 v139, 0xbfb8aa3b, v125
	v_rcp_f32_e32 v144, v137
	v_exp_f32_e32 v138, v138
	v_exp_f32_e32 v139, v139
	v_rcp_f32_e32 v147, v136
	v_mul_f32_e32 v137, v124, v144
	v_pk_add_f32 v[138:139], v[138:139], 1.0 op_sel_hi:[1,0]
	v_rcp_f32_e32 v146, v138
	v_mul_f32_e32 v136, v122, v147
	v_rcp_f32_e32 v147, v139
	v_mul_f32_e32 v138, v123, v146
	s_movk_i32 s0, 0x7fff
	v_bfe_u32 v144, v138, 16, 1
	v_bfe_u32 v146, v142, 16, 1
	v_mul_f32_e32 v139, v125, v147
	v_add3_u32 v142, v142, v146, s0
	v_add3_u32 v138, v138, v144, s0
	v_bfe_u32 v144, v131, 16, 1
	v_bfe_u32 v146, v137, 16, 1
	v_bfe_u32 v143, v139, 16, 1
	v_bfe_u32 v145, v140, 16, 1
	v_add3_u32 v137, v137, v146, s0
	v_add3_u32 v131, v131, v144, s0
	v_add3_u32 v140, v140, v145, s0
	v_add3_u32 v139, v139, v143, s0
	v_lshrrev_b32_e32 v131, 16, v131
	v_lshrrev_b32_e32 v137, 16, v137
	s_mov_b32 s1, 0xffff0000
	v_bfe_u32 v143, v141, 16, 1
	v_and_or_b32 v139, v139, s1, v137
	v_and_or_b32 v137, v140, s1, v131
	v_mul_f32_e32 v131, 0xbfb8aa3b, v118
	v_add3_u32 v141, v141, v143, s0
	v_exp_f32_e32 v140, v131
	v_mul_f32_e32 v131, 0xbfb8aa3b, v120
	v_bfe_u32 v145, v136, 16, 1
	v_lshrrev_b32_e32 v143, 16, v141
	v_exp_f32_e32 v141, v131
	v_add3_u32 v136, v136, v145, s0
	v_lshrrev_b32_e32 v136, 16, v136
	v_and_or_b32 v138, v138, s1, v136
	v_and_or_b32 v136, v142, s1, v143
	global_store_dwordx4 v[132:133], v[136:139], off
	v_mul_f32_e32 v131, 0xbfb8aa3b, v119
	s_nop 0
	v_pk_add_f32 v[136:137], v[140:141], 1.0 op_sel_hi:[1,0]
	v_exp_f32_e32 v138, v131
	v_rcp_f32_e32 v141, v137
	v_mul_f32_e32 v131, 0xbfb8aa3b, v121
	v_exp_f32_e32 v139, v131
	v_rcp_f32_e32 v143, v136
	v_mul_f32_e32 v131, v120, v141
	v_pk_add_f32 v[138:139], v[138:139], 1.0 op_sel_hi:[1,0]
	v_rcp_f32_e32 v142, v138
	v_mul_f32_e32 v141, v118, v143
	v_rcp_f32_e32 v143, v139
	v_mul_f32_e32 v142, v119, v142
	v_mul_f32_e32 v136, 0xbfb8aa3b, v114
	v_mul_f32_e32 v137, 0xbfb8aa3b, v116
	v_exp_f32_e32 v136, v136
	v_exp_f32_e32 v137, v137
	v_mul_f32_e32 v140, v121, v143
	v_mul_f32_e32 v138, 0xbfb8aa3b, v115
	v_pk_add_f32 v[136:137], v[136:137], 1.0 op_sel_hi:[1,0]
	v_mul_f32_e32 v139, 0xbfb8aa3b, v117
	v_rcp_f32_e32 v144, v137
	v_exp_f32_e32 v138, v138
	v_exp_f32_e32 v139, v139
	v_rcp_f32_e32 v147, v136
	v_mul_f32_e32 v137, v116, v144
	v_pk_add_f32 v[138:139], v[138:139], 1.0 op_sel_hi:[1,0]
	v_rcp_f32_e32 v146, v138
	v_mul_f32_e32 v136, v114, v147
	v_rcp_f32_e32 v147, v139
	v_mul_f32_e32 v138, v115, v146
	v_mul_f32_e32 v139, v117, v147
	v_bfe_u32 v143, v139, 16, 1
	v_bfe_u32 v144, v138, 16, 1
	v_bfe_u32 v145, v140, 16, 1
	v_bfe_u32 v146, v142, 16, 1
	v_add3_u32 v142, v142, v146, s0
	v_add3_u32 v140, v140, v145, s0
	v_add3_u32 v138, v138, v144, s0
	v_add3_u32 v139, v139, v143, s0
	v_bfe_u32 v143, v141, 16, 1
	v_bfe_u32 v144, v131, 16, 1
	v_bfe_u32 v145, v136, 16, 1
	v_bfe_u32 v146, v137, 16, 1
	v_add3_u32 v137, v137, v146, s0
	v_add3_u32 v136, v136, v145, s0
	v_add3_u32 v131, v131, v144, s0
	v_add3_u32 v141, v141, v143, s0
	v_lshrrev_b32_e32 v141, 16, v141
	v_lshrrev_b32_e32 v131, 16, v131
	v_lshrrev_b32_e32 v136, 16, v136
	v_lshrrev_b32_e32 v137, 16, v137
	v_and_or_b32 v139, v139, s1, v137
	v_and_or_b32 v138, v138, s1, v136
	v_and_or_b32 v137, v140, s1, v131
	v_and_or_b32 v136, v142, s1, v141
	v_mul_f32_e32 v131, 0xbfb8aa3b, v110
	global_store_dwordx4 v[132:133], v[136:139], off offset:256
	s_nop 1
	v_exp_f32_e32 v138, v131
	v_mul_f32_e32 v131, 0xbfb8aa3b, v112
	v_exp_f32_e32 v139, v131
	v_mul_f32_e32 v131, 0xbfb8aa3b, v111
	v_exp_f32_e32 v140, v131
	v_mul_f32_e32 v131, 0xbfb8aa3b, v113
	v_pk_add_f32 v[138:139], v[138:139], 1.0 op_sel_hi:[1,0]
	v_exp_f32_e32 v141, v131
	v_rcp_f32_e32 v143, v139
	v_pk_add_f32 v[140:141], v[140:141], 1.0 op_sel_hi:[1,0]
	v_or_b32_e32 v136, 16, v130
	v_ashrrev_i32_e32 v137, 31, v136
	v_rcp_f32_e32 v145, v138
	v_mul_f32_e32 v131, v112, v143
	v_lshlrev_b64 v[136:137], 10, v[136:137]
	v_rcp_f32_e32 v144, v140
	v_mul_f32_e32 v143, v110, v145
	v_lshl_add_u64 v[136:137], v[134:135], 0, v[136:137]
	v_rcp_f32_e32 v145, v141
	v_mul_f32_e32 v144, v111, v144
	v_mul_f32_e32 v138, 0xbfb8aa3b, v106
	v_mul_f32_e32 v139, 0xbfb8aa3b, v108
	v_exp_f32_e32 v138, v138
	v_exp_f32_e32 v139, v139
	v_mul_f32_e32 v142, v113, v145
	v_mul_f32_e32 v140, 0xbfb8aa3b, v107
	v_pk_add_f32 v[138:139], v[138:139], 1.0 op_sel_hi:[1,0]
	v_mul_f32_e32 v141, 0xbfb8aa3b, v109
	v_rcp_f32_e32 v146, v139
	v_exp_f32_e32 v140, v140
	v_exp_f32_e32 v141, v141
	v_rcp_f32_e32 v149, v138
	v_mul_f32_e32 v139, v108, v146
	v_pk_add_f32 v[140:141], v[140:141], 1.0 op_sel_hi:[1,0]
	v_rcp_f32_e32 v148, v140
	v_mul_f32_e32 v138, v106, v149
	v_rcp_f32_e32 v149, v141
	v_mul_f32_e32 v140, v107, v148
	v_bfe_u32 v146, v140, 16, 1
	v_bfe_u32 v148, v144, 16, 1
	v_mul_f32_e32 v141, v109, v149
	v_add3_u32 v144, v144, v148, s0
	v_add3_u32 v140, v140, v146, s0
	v_bfe_u32 v146, v131, 16, 1
	v_bfe_u32 v148, v139, 16, 1
	v_bfe_u32 v145, v141, 16, 1
	v_bfe_u32 v147, v142, 16, 1
	v_add3_u32 v139, v139, v148, s0
	v_add3_u32 v131, v131, v146, s0
	v_add3_u32 v142, v142, v147, s0
	v_add3_u32 v141, v141, v145, s0
	v_lshrrev_b32_e32 v131, 16, v131
	v_lshrrev_b32_e32 v139, 16, v139
	v_bfe_u32 v145, v143, 16, 1
	v_and_or_b32 v141, v141, s1, v139
	v_and_or_b32 v139, v142, s1, v131
	v_mul_f32_e32 v131, 0xbfb8aa3b, v102
	v_add3_u32 v143, v143, v145, s0
	v_exp_f32_e32 v142, v131
	v_mul_f32_e32 v131, 0xbfb8aa3b, v104
	v_bfe_u32 v147, v138, 16, 1
	v_lshrrev_b32_e32 v145, 16, v143
	v_exp_f32_e32 v143, v131
	v_add3_u32 v138, v138, v147, s0
	v_lshrrev_b32_e32 v138, 16, v138
	v_and_or_b32 v140, v140, s1, v138
	v_and_or_b32 v138, v144, s1, v145
	global_store_dwordx4 v[136:137], v[138:141], off
	v_mul_f32_e32 v131, 0xbfb8aa3b, v103
	s_nop 0
	v_pk_add_f32 v[138:139], v[142:143], 1.0 op_sel_hi:[1,0]
	v_exp_f32_e32 v140, v131
	v_rcp_f32_e32 v143, v139
	v_mul_f32_e32 v131, 0xbfb8aa3b, v105
	v_exp_f32_e32 v141, v131
	v_rcp_f32_e32 v145, v138
	v_mul_f32_e32 v131, v104, v143
	v_pk_add_f32 v[140:141], v[140:141], 1.0 op_sel_hi:[1,0]
	v_rcp_f32_e32 v144, v140
	v_mul_f32_e32 v143, v102, v145
	v_rcp_f32_e32 v145, v141
	v_mul_f32_e32 v144, v103, v144
	v_mul_f32_e32 v138, 0xbfb8aa3b, v98
	v_mul_f32_e32 v139, 0xbfb8aa3b, v100
	v_exp_f32_e32 v138, v138
	v_exp_f32_e32 v139, v139
	v_mul_f32_e32 v142, v105, v145
	v_mul_f32_e32 v140, 0xbfb8aa3b, v99
	v_pk_add_f32 v[138:139], v[138:139], 1.0 op_sel_hi:[1,0]
	v_mul_f32_e32 v141, 0xbfb8aa3b, v101
	v_rcp_f32_e32 v146, v139
	v_exp_f32_e32 v140, v140
	v_exp_f32_e32 v141, v141
	v_rcp_f32_e32 v149, v138
	v_mul_f32_e32 v139, v100, v146
	v_pk_add_f32 v[140:141], v[140:141], 1.0 op_sel_hi:[1,0]
	v_rcp_f32_e32 v148, v140
	v_mul_f32_e32 v138, v98, v149
	v_rcp_f32_e32 v149, v141
	v_mul_f32_e32 v140, v99, v148
	v_mul_f32_e32 v141, v101, v149
	v_bfe_u32 v145, v141, 16, 1
	v_bfe_u32 v146, v140, 16, 1
	v_bfe_u32 v147, v142, 16, 1
	v_bfe_u32 v148, v144, 16, 1
	v_add3_u32 v144, v144, v148, s0
	v_add3_u32 v142, v142, v147, s0
	v_add3_u32 v140, v140, v146, s0
	v_add3_u32 v141, v141, v145, s0
	v_bfe_u32 v145, v143, 16, 1
	v_bfe_u32 v146, v131, 16, 1
	v_bfe_u32 v147, v138, 16, 1
	v_bfe_u32 v148, v139, 16, 1
	v_add3_u32 v139, v139, v148, s0
	v_add3_u32 v138, v138, v147, s0
	v_add3_u32 v131, v131, v146, s0
	v_add3_u32 v143, v143, v145, s0
	v_lshrrev_b32_e32 v143, 16, v143
	v_lshrrev_b32_e32 v131, 16, v131
	v_lshrrev_b32_e32 v138, 16, v138
	v_lshrrev_b32_e32 v139, 16, v139
	v_and_or_b32 v141, v141, s1, v139
	v_and_or_b32 v140, v140, s1, v138
	v_and_or_b32 v139, v142, s1, v131
	v_and_or_b32 v138, v144, s1, v143
	v_mul_f32_e32 v131, 0xbfb8aa3b, v94
	global_store_dwordx4 v[136:137], v[138:141], off offset:256
	v_or_b32_e32 v136, 32, v130
	v_ashrrev_i32_e32 v137, 31, v136
	v_exp_f32_e32 v138, v131
	v_mul_f32_e32 v131, 0xbfb8aa3b, v96
	v_exp_f32_e32 v139, v131
	v_mul_f32_e32 v131, 0xbfb8aa3b, v95
	v_exp_f32_e32 v140, v131
	v_mul_f32_e32 v131, 0xbfb8aa3b, v97
	v_pk_add_f32 v[138:139], v[138:139], 1.0 op_sel_hi:[1,0]
	v_exp_f32_e32 v141, v131
	v_rcp_f32_e32 v143, v139
	v_pk_add_f32 v[140:141], v[140:141], 1.0 op_sel_hi:[1,0]
	v_lshlrev_b64 v[136:137], 10, v[136:137]
	v_lshl_add_u64 v[136:137], v[134:135], 0, v[136:137]
	v_rcp_f32_e32 v145, v138
	v_mul_f32_e32 v131, v96, v143
	v_rcp_f32_e32 v144, v140
	v_mul_f32_e32 v143, v94, v145
	v_rcp_f32_e32 v145, v141
	v_mul_f32_e32 v144, v95, v144
	v_mul_f32_e32 v138, 0xbfb8aa3b, v90
	v_mul_f32_e32 v139, 0xbfb8aa3b, v92
	v_exp_f32_e32 v138, v138
	v_exp_f32_e32 v139, v139
	v_mul_f32_e32 v142, v97, v145
	v_mul_f32_e32 v140, 0xbfb8aa3b, v91
	v_pk_add_f32 v[138:139], v[138:139], 1.0 op_sel_hi:[1,0]
	v_mul_f32_e32 v141, 0xbfb8aa3b, v93
	v_rcp_f32_e32 v146, v139
	v_exp_f32_e32 v140, v140
	v_exp_f32_e32 v141, v141
	v_rcp_f32_e32 v149, v138
	v_mul_f32_e32 v139, v92, v146
	v_pk_add_f32 v[140:141], v[140:141], 1.0 op_sel_hi:[1,0]
	v_rcp_f32_e32 v148, v140
	v_mul_f32_e32 v138, v90, v149
	v_rcp_f32_e32 v149, v141
	v_mul_f32_e32 v140, v91, v148
	v_bfe_u32 v146, v140, 16, 1
	v_bfe_u32 v148, v144, 16, 1
	v_mul_f32_e32 v141, v93, v149
	v_add3_u32 v144, v144, v148, s0
	v_add3_u32 v140, v140, v146, s0
	v_bfe_u32 v146, v131, 16, 1
	v_bfe_u32 v148, v139, 16, 1
	v_bfe_u32 v145, v141, 16, 1
	v_bfe_u32 v147, v142, 16, 1
	v_add3_u32 v139, v139, v148, s0
	v_add3_u32 v131, v131, v146, s0
	v_add3_u32 v142, v142, v147, s0
	v_add3_u32 v141, v141, v145, s0
	v_lshrrev_b32_e32 v131, 16, v131
	v_lshrrev_b32_e32 v139, 16, v139
	v_bfe_u32 v145, v143, 16, 1
	v_and_or_b32 v141, v141, s1, v139
	v_and_or_b32 v139, v142, s1, v131
	v_mul_f32_e32 v131, 0xbfb8aa3b, v86
	v_add3_u32 v143, v143, v145, s0
	v_exp_f32_e32 v142, v131
	v_mul_f32_e32 v131, 0xbfb8aa3b, v88
	v_bfe_u32 v147, v138, 16, 1
	v_lshrrev_b32_e32 v145, 16, v143
	v_exp_f32_e32 v143, v131
	v_add3_u32 v138, v138, v147, s0
	v_lshrrev_b32_e32 v138, 16, v138
	v_and_or_b32 v140, v140, s1, v138
	v_and_or_b32 v138, v144, s1, v145
	global_store_dwordx4 v[136:137], v[138:141], off
	v_mul_f32_e32 v131, 0xbfb8aa3b, v87
	s_nop 0
	v_pk_add_f32 v[138:139], v[142:143], 1.0 op_sel_hi:[1,0]
	v_exp_f32_e32 v140, v131
	v_rcp_f32_e32 v143, v139
	v_mul_f32_e32 v131, 0xbfb8aa3b, v89
	v_exp_f32_e32 v141, v131
	v_rcp_f32_e32 v145, v138
	v_mul_f32_e32 v131, v88, v143
	v_pk_add_f32 v[140:141], v[140:141], 1.0 op_sel_hi:[1,0]
	v_rcp_f32_e32 v144, v140
	v_mul_f32_e32 v143, v86, v145
	v_rcp_f32_e32 v145, v141
	v_mul_f32_e32 v144, v87, v144
	v_mul_f32_e32 v138, 0xbfb8aa3b, v82
	v_mul_f32_e32 v139, 0xbfb8aa3b, v84
	v_exp_f32_e32 v138, v138
	v_exp_f32_e32 v139, v139
	v_mul_f32_e32 v142, v89, v145
	v_mul_f32_e32 v140, 0xbfb8aa3b, v83
	v_pk_add_f32 v[138:139], v[138:139], 1.0 op_sel_hi:[1,0]
	v_mul_f32_e32 v141, 0xbfb8aa3b, v85
	v_rcp_f32_e32 v146, v139
	v_exp_f32_e32 v140, v140
	v_exp_f32_e32 v141, v141
	v_rcp_f32_e32 v149, v138
	v_mul_f32_e32 v139, v84, v146
	v_pk_add_f32 v[140:141], v[140:141], 1.0 op_sel_hi:[1,0]
	v_rcp_f32_e32 v148, v140
	v_mul_f32_e32 v138, v82, v149
	v_rcp_f32_e32 v149, v141
	v_mul_f32_e32 v140, v83, v148
	v_mul_f32_e32 v141, v85, v149
	v_bfe_u32 v145, v141, 16, 1
	v_bfe_u32 v146, v140, 16, 1
	v_bfe_u32 v147, v142, 16, 1
	v_bfe_u32 v148, v144, 16, 1
	v_add3_u32 v144, v144, v148, s0
	v_add3_u32 v142, v142, v147, s0
	v_add3_u32 v140, v140, v146, s0
	v_add3_u32 v141, v141, v145, s0
	v_bfe_u32 v145, v143, 16, 1
	v_bfe_u32 v146, v131, 16, 1
	v_bfe_u32 v147, v138, 16, 1
	v_bfe_u32 v148, v139, 16, 1
	v_add3_u32 v139, v139, v148, s0
	v_add3_u32 v138, v138, v147, s0
	v_add3_u32 v131, v131, v146, s0
	v_add3_u32 v143, v143, v145, s0
	v_lshrrev_b32_e32 v143, 16, v143
	v_lshrrev_b32_e32 v131, 16, v131
	v_lshrrev_b32_e32 v138, 16, v138
	v_lshrrev_b32_e32 v139, 16, v139
	v_and_or_b32 v141, v141, s1, v139
	v_and_or_b32 v140, v140, s1, v138
	v_and_or_b32 v139, v142, s1, v131
	v_and_or_b32 v138, v144, s1, v143
	v_mul_f32_e32 v131, 0xbfb8aa3b, v78
	global_store_dwordx4 v[136:137], v[138:141], off offset:256
	v_or_b32_e32 v136, 48, v130
	v_ashrrev_i32_e32 v137, 31, v136
	v_exp_f32_e32 v138, v131
	v_mul_f32_e32 v131, 0xbfb8aa3b, v80
	v_exp_f32_e32 v139, v131
	v_lshlrev_b64 v[136:137], 10, v[136:137]
	v_lshl_add_u64 v[134:135], v[134:135], 0, v[136:137]
	v_mul_f32_e32 v131, 0xbfb8aa3b, v79
	v_pk_add_f32 v[136:137], v[138:139], 1.0 op_sel_hi:[1,0]
	v_exp_f32_e32 v138, v131
	v_rcp_f32_e32 v141, v137
	v_mul_f32_e32 v131, 0xbfb8aa3b, v81
	v_exp_f32_e32 v139, v131
	v_rcp_f32_e32 v143, v136
	v_mul_f32_e32 v131, v80, v141
	v_pk_add_f32 v[138:139], v[138:139], 1.0 op_sel_hi:[1,0]
	v_rcp_f32_e32 v142, v138
	v_mul_f32_e32 v141, v78, v143
	v_rcp_f32_e32 v143, v139
	v_mul_f32_e32 v142, v79, v142
	v_mul_f32_e32 v136, 0xbfb8aa3b, v74
	v_mul_f32_e32 v137, 0xbfb8aa3b, v76
	v_exp_f32_e32 v136, v136
	v_exp_f32_e32 v137, v137
	v_mul_f32_e32 v140, v81, v143
	v_mul_f32_e32 v138, 0xbfb8aa3b, v75
	v_pk_add_f32 v[136:137], v[136:137], 1.0 op_sel_hi:[1,0]
	v_mul_f32_e32 v139, 0xbfb8aa3b, v77
	v_rcp_f32_e32 v144, v137
	v_exp_f32_e32 v138, v138
	v_exp_f32_e32 v139, v139
	v_rcp_f32_e32 v147, v136
	v_mul_f32_e32 v137, v76, v144
	v_pk_add_f32 v[138:139], v[138:139], 1.0 op_sel_hi:[1,0]
	v_rcp_f32_e32 v146, v138
	v_mul_f32_e32 v136, v74, v147
	v_rcp_f32_e32 v147, v139
	v_mul_f32_e32 v138, v75, v146
	v_bfe_u32 v144, v138, 16, 1
	v_bfe_u32 v146, v142, 16, 1
	v_mul_f32_e32 v139, v77, v147
	v_add3_u32 v142, v142, v146, s0
	v_add3_u32 v138, v138, v144, s0
	v_bfe_u32 v144, v131, 16, 1
	v_bfe_u32 v146, v137, 16, 1
	v_bfe_u32 v143, v139, 16, 1
	v_bfe_u32 v145, v140, 16, 1
	v_add3_u32 v137, v137, v146, s0
	v_add3_u32 v131, v131, v144, s0
	v_add3_u32 v140, v140, v145, s0
	v_add3_u32 v139, v139, v143, s0
	v_lshrrev_b32_e32 v131, 16, v131
	v_lshrrev_b32_e32 v137, 16, v137
	v_bfe_u32 v143, v141, 16, 1
	v_and_or_b32 v139, v139, s1, v137
	v_and_or_b32 v137, v140, s1, v131
	v_mul_f32_e32 v131, 0xbfb8aa3b, v70
	v_add3_u32 v141, v141, v143, s0
	v_exp_f32_e32 v140, v131
	v_mul_f32_e32 v131, 0xbfb8aa3b, v72
	v_bfe_u32 v145, v136, 16, 1
	v_lshrrev_b32_e32 v143, 16, v141
	v_exp_f32_e32 v141, v131
	v_add3_u32 v136, v136, v145, s0
	v_lshrrev_b32_e32 v136, 16, v136
	v_and_or_b32 v138, v138, s1, v136
	v_and_or_b32 v136, v142, s1, v143
	global_store_dwordx4 v[134:135], v[136:139], off
	v_mul_f32_e32 v131, 0xbfb8aa3b, v71
	s_nop 0
	v_pk_add_f32 v[136:137], v[140:141], 1.0 op_sel_hi:[1,0]
	v_exp_f32_e32 v138, v131
	v_rcp_f32_e32 v141, v137
	v_mul_f32_e32 v131, 0xbfb8aa3b, v73
	v_exp_f32_e32 v139, v131
	v_rcp_f32_e32 v143, v136
	v_mul_f32_e32 v131, v72, v141
	v_pk_add_f32 v[138:139], v[138:139], 1.0 op_sel_hi:[1,0]
	v_rcp_f32_e32 v142, v138
	v_mul_f32_e32 v141, v70, v143
	v_rcp_f32_e32 v143, v139
	v_mul_f32_e32 v142, v71, v142
	v_mul_f32_e32 v136, 0xbfb8aa3b, v66
	v_mul_f32_e32 v137, 0xbfb8aa3b, v68
	v_exp_f32_e32 v136, v136
	v_exp_f32_e32 v137, v137
	v_mul_f32_e32 v140, v73, v143
	v_mul_f32_e32 v138, 0xbfb8aa3b, v67
	v_pk_add_f32 v[136:137], v[136:137], 1.0 op_sel_hi:[1,0]
	v_mul_f32_e32 v139, 0xbfb8aa3b, v69
	v_rcp_f32_e32 v144, v137
	v_exp_f32_e32 v138, v138
	v_exp_f32_e32 v139, v139
	v_rcp_f32_e32 v147, v136
	v_mul_f32_e32 v137, v68, v144
	v_pk_add_f32 v[138:139], v[138:139], 1.0 op_sel_hi:[1,0]
	v_rcp_f32_e32 v146, v138
	v_mul_f32_e32 v136, v66, v147
	v_rcp_f32_e32 v147, v139
	v_mul_f32_e32 v138, v67, v146
	s_mov_b64 s[2:3], 0x20000
	v_mul_f32_e32 v139, v69, v147
	v_bfe_u32 v143, v139, 16, 1
	v_bfe_u32 v144, v138, 16, 1
	v_bfe_u32 v145, v140, 16, 1
	v_bfe_u32 v146, v142, 16, 1
	v_add3_u32 v142, v142, v146, s0
	v_add3_u32 v140, v140, v145, s0
	v_add3_u32 v138, v138, v144, s0
	v_add3_u32 v139, v139, v143, s0
	v_bfe_u32 v143, v141, 16, 1
	v_bfe_u32 v144, v131, 16, 1
	v_bfe_u32 v145, v136, 16, 1
	v_bfe_u32 v146, v137, 16, 1
	v_add3_u32 v137, v137, v146, s0
	v_add3_u32 v136, v136, v145, s0
	v_add3_u32 v131, v131, v144, s0
	v_add3_u32 v141, v141, v143, s0
	v_lshrrev_b32_e32 v141, 16, v141
	v_lshrrev_b32_e32 v131, 16, v131
	v_lshrrev_b32_e32 v136, 16, v136
	v_lshrrev_b32_e32 v137, 16, v137
	v_and_or_b32 v139, v139, s1, v137
	v_and_or_b32 v138, v138, s1, v136
	v_and_or_b32 v137, v140, s1, v131
	v_and_or_b32 v136, v142, s1, v141
	v_mul_f32_e32 v131, 0xbfb8aa3b, v62
	global_store_dwordx4 v[134:135], v[136:139], off offset:256
	v_lshl_add_u64 v[134:135], v[132:133], 0, s[2:3]
	s_nop 0
	v_exp_f32_e32 v136, v131
	v_mul_f32_e32 v131, 0xbfb8aa3b, v64
	v_exp_f32_e32 v137, v131
	v_mul_f32_e32 v131, 0xbfb8aa3b, v63
	v_exp_f32_e32 v138, v131
	v_mul_f32_e32 v131, 0xbfb8aa3b, v65
	v_pk_add_f32 v[136:137], v[136:137], 1.0 op_sel_hi:[1,0]
	v_exp_f32_e32 v139, v131
	v_rcp_f32_e32 v141, v137
	v_pk_add_f32 v[138:139], v[138:139], 1.0 op_sel_hi:[1,0]
	v_rcp_f32_e32 v143, v136
	v_mul_f32_e32 v131, v64, v141
	v_rcp_f32_e32 v142, v138
	v_mul_f32_e32 v141, v62, v143
	v_rcp_f32_e32 v143, v139
	v_mul_f32_e32 v142, v63, v142
	v_mul_f32_e32 v136, 0xbfb8aa3b, v58
	v_mul_f32_e32 v137, 0xbfb8aa3b, v60
	v_exp_f32_e32 v136, v136
	v_exp_f32_e32 v137, v137
	v_mul_f32_e32 v140, v65, v143
	v_mul_f32_e32 v138, 0xbfb8aa3b, v59
	v_pk_add_f32 v[136:137], v[136:137], 1.0 op_sel_hi:[1,0]
	v_mul_f32_e32 v139, 0xbfb8aa3b, v61
	v_rcp_f32_e32 v144, v137
	v_exp_f32_e32 v138, v138
	v_exp_f32_e32 v139, v139
	v_rcp_f32_e32 v147, v136
	v_mul_f32_e32 v137, v60, v144
	v_pk_add_f32 v[138:139], v[138:139], 1.0 op_sel_hi:[1,0]
	v_rcp_f32_e32 v146, v138
	v_mul_f32_e32 v136, v58, v147
	v_rcp_f32_e32 v147, v139
	v_mul_f32_e32 v138, v59, v146
	s_mov_b32 s2, 0x20000
	v_bfe_u32 v144, v138, 16, 1
	v_bfe_u32 v146, v142, 16, 1
	v_mul_f32_e32 v139, v61, v147
	v_add3_u32 v142, v142, v146, s0
	v_add3_u32 v138, v138, v144, s0
	v_bfe_u32 v144, v131, 16, 1
	v_bfe_u32 v146, v137, 16, 1
	v_bfe_u32 v143, v139, 16, 1
	v_bfe_u32 v145, v140, 16, 1
	v_add3_u32 v137, v137, v146, s0
	v_add3_u32 v131, v131, v144, s0
	v_add3_u32 v140, v140, v145, s0
	v_add3_u32 v139, v139, v143, s0
	v_bfe_u32 v143, v141, 16, 1
	v_bfe_u32 v145, v136, 16, 1
	v_lshrrev_b32_e32 v131, 16, v131
	v_lshrrev_b32_e32 v137, 16, v137
	v_add3_u32 v136, v136, v145, s0
	v_add3_u32 v141, v141, v143, s0
	v_and_or_b32 v139, v139, s1, v137
	v_and_or_b32 v137, v140, s1, v131
	v_mul_f32_e32 v131, 0xbfb8aa3b, v54
	v_lshrrev_b32_e32 v141, 16, v141
	v_lshrrev_b32_e32 v136, 16, v136
	v_exp_f32_e32 v140, v131
	v_mul_f32_e32 v131, 0xbfb8aa3b, v56
	v_and_or_b32 v138, v138, s1, v136
	v_and_or_b32 v136, v142, s1, v141
	v_exp_f32_e32 v141, v131
	v_add_co_u32_e32 v142, vcc, s2, v132
	v_mul_f32_e32 v131, 0xbfb8aa3b, v55
	s_nop 0
	v_addc_co_u32_e32 v143, vcc, 0, v133, vcc
	global_store_dwordx4 v[142:143], v[136:139], off
	s_nop 1
	v_pk_add_f32 v[136:137], v[140:141], 1.0 op_sel_hi:[1,0]
	v_exp_f32_e32 v138, v131
	v_rcp_f32_e32 v141, v137
	v_mul_f32_e32 v131, 0xbfb8aa3b, v57
	v_exp_f32_e32 v139, v131
	v_rcp_f32_e32 v143, v136
	v_mul_f32_e32 v131, v56, v141
	v_pk_add_f32 v[138:139], v[138:139], 1.0 op_sel_hi:[1,0]
	v_rcp_f32_e32 v142, v138
	v_mul_f32_e32 v141, v54, v143
	v_rcp_f32_e32 v143, v139
	v_mul_f32_e32 v142, v55, v142
	v_mul_f32_e32 v136, 0xbfb8aa3b, v50
	v_mul_f32_e32 v137, 0xbfb8aa3b, v52
	v_exp_f32_e32 v136, v136
	v_exp_f32_e32 v137, v137
	v_mul_f32_e32 v140, v57, v143
	v_mul_f32_e32 v138, 0xbfb8aa3b, v51
	v_pk_add_f32 v[136:137], v[136:137], 1.0 op_sel_hi:[1,0]
	v_mul_f32_e32 v139, 0xbfb8aa3b, v53
	v_rcp_f32_e32 v144, v137
	v_exp_f32_e32 v138, v138
	v_exp_f32_e32 v139, v139
	v_rcp_f32_e32 v147, v136
	v_mul_f32_e32 v137, v52, v144
	v_pk_add_f32 v[138:139], v[138:139], 1.0 op_sel_hi:[1,0]
	v_rcp_f32_e32 v146, v138
	v_mul_f32_e32 v136, v50, v147
	v_rcp_f32_e32 v147, v139
	v_mul_f32_e32 v138, v51, v146
	s_mov_b64 s[2:3], 0x24000
	v_mul_f32_e32 v139, v53, v147
	v_bfe_u32 v143, v139, 16, 1
	v_bfe_u32 v144, v138, 16, 1
	v_bfe_u32 v145, v140, 16, 1
	v_bfe_u32 v146, v142, 16, 1
	v_add3_u32 v142, v142, v146, s0
	v_add3_u32 v140, v140, v145, s0
	v_add3_u32 v138, v138, v144, s0
	v_add3_u32 v139, v139, v143, s0
	v_bfe_u32 v143, v141, 16, 1
	v_bfe_u32 v144, v131, 16, 1
	v_bfe_u32 v145, v136, 16, 1
	v_bfe_u32 v146, v137, 16, 1
	v_add3_u32 v137, v137, v146, s0
	v_add3_u32 v136, v136, v145, s0
	v_add3_u32 v131, v131, v144, s0
	v_add3_u32 v141, v141, v143, s0
	v_lshrrev_b32_e32 v141, 16, v141
	v_lshrrev_b32_e32 v131, 16, v131
	v_lshrrev_b32_e32 v136, 16, v136
	v_lshrrev_b32_e32 v137, 16, v137
	v_and_or_b32 v139, v139, s1, v137
	v_and_or_b32 v138, v138, s1, v136
	v_and_or_b32 v137, v140, s1, v131
	v_and_or_b32 v136, v142, s1, v141
	v_mul_f32_e32 v131, 0xbfb8aa3b, v46
	global_store_dwordx4 v[134:135], v[136:139], off offset:256
	v_lshl_add_u64 v[134:135], v[132:133], 0, s[2:3]
	s_nop 0
	v_exp_f32_e32 v136, v131
	v_mul_f32_e32 v131, 0xbfb8aa3b, v48
	v_exp_f32_e32 v137, v131
	v_mul_f32_e32 v131, 0xbfb8aa3b, v47
	v_exp_f32_e32 v138, v131
	v_mul_f32_e32 v131, 0xbfb8aa3b, v49
	v_pk_add_f32 v[136:137], v[136:137], 1.0 op_sel_hi:[1,0]
	v_exp_f32_e32 v139, v131
	v_rcp_f32_e32 v141, v137
	v_pk_add_f32 v[138:139], v[138:139], 1.0 op_sel_hi:[1,0]
	v_rcp_f32_e32 v143, v136
	v_mul_f32_e32 v131, v48, v141
	v_rcp_f32_e32 v142, v138
	v_mul_f32_e32 v141, v46, v143
	v_rcp_f32_e32 v143, v139
	v_mul_f32_e32 v142, v47, v142
	v_mul_f32_e32 v136, 0xbfb8aa3b, v42
	v_mul_f32_e32 v137, 0xbfb8aa3b, v44
	v_exp_f32_e32 v136, v136
	v_exp_f32_e32 v137, v137
	v_mul_f32_e32 v140, v49, v143
	v_mul_f32_e32 v138, 0xbfb8aa3b, v43
	v_pk_add_f32 v[136:137], v[136:137], 1.0 op_sel_hi:[1,0]
	v_mul_f32_e32 v139, 0xbfb8aa3b, v45
	v_rcp_f32_e32 v144, v137
	v_exp_f32_e32 v138, v138
	v_exp_f32_e32 v139, v139
	v_rcp_f32_e32 v147, v136
	v_mul_f32_e32 v137, v44, v144
	v_pk_add_f32 v[138:139], v[138:139], 1.0 op_sel_hi:[1,0]
	v_rcp_f32_e32 v146, v138
	v_mul_f32_e32 v136, v42, v147
	v_rcp_f32_e32 v147, v139
	v_mul_f32_e32 v138, v43, v146
	s_mov_b32 s2, 0x24000
	v_bfe_u32 v144, v138, 16, 1
	v_bfe_u32 v146, v142, 16, 1
	v_mul_f32_e32 v139, v45, v147
	v_add3_u32 v142, v142, v146, s0
	v_add3_u32 v138, v138, v144, s0
	v_bfe_u32 v144, v131, 16, 1
	v_bfe_u32 v146, v137, 16, 1
	v_bfe_u32 v143, v139, 16, 1
	v_bfe_u32 v145, v140, 16, 1
	v_add3_u32 v137, v137, v146, s0
	v_add3_u32 v131, v131, v144, s0
	v_add3_u32 v140, v140, v145, s0
	v_add3_u32 v139, v139, v143, s0
	v_bfe_u32 v143, v141, 16, 1
	v_bfe_u32 v145, v136, 16, 1
	v_lshrrev_b32_e32 v131, 16, v131
	v_lshrrev_b32_e32 v137, 16, v137
	v_add3_u32 v136, v136, v145, s0
	v_add3_u32 v141, v141, v143, s0
	v_and_or_b32 v139, v139, s1, v137
	v_and_or_b32 v137, v140, s1, v131
	v_mul_f32_e32 v131, 0xbfb8aa3b, v38
	v_lshrrev_b32_e32 v141, 16, v141
	v_lshrrev_b32_e32 v136, 16, v136
	v_exp_f32_e32 v140, v131
	v_mul_f32_e32 v131, 0xbfb8aa3b, v40
	v_and_or_b32 v138, v138, s1, v136
	v_and_or_b32 v136, v142, s1, v141
	v_exp_f32_e32 v141, v131
	v_add_co_u32_e32 v142, vcc, s2, v132
	v_mul_f32_e32 v131, 0xbfb8aa3b, v39
	s_nop 0
	v_addc_co_u32_e32 v143, vcc, 0, v133, vcc
	global_store_dwordx4 v[142:143], v[136:139], off
	s_nop 1
	v_pk_add_f32 v[136:137], v[140:141], 1.0 op_sel_hi:[1,0]
	v_exp_f32_e32 v138, v131
	v_rcp_f32_e32 v141, v137
	v_mul_f32_e32 v131, 0xbfb8aa3b, v41
	v_exp_f32_e32 v139, v131
	v_rcp_f32_e32 v143, v136
	v_mul_f32_e32 v131, v40, v141
	v_pk_add_f32 v[138:139], v[138:139], 1.0 op_sel_hi:[1,0]
	v_rcp_f32_e32 v142, v138
	v_mul_f32_e32 v141, v38, v143
	v_rcp_f32_e32 v143, v139
	v_mul_f32_e32 v142, v39, v142
	v_mul_f32_e32 v136, 0xbfb8aa3b, v34
	v_mul_f32_e32 v137, 0xbfb8aa3b, v36
	v_exp_f32_e32 v136, v136
	v_exp_f32_e32 v137, v137
	v_mul_f32_e32 v140, v41, v143
	v_mul_f32_e32 v138, 0xbfb8aa3b, v35
	v_pk_add_f32 v[136:137], v[136:137], 1.0 op_sel_hi:[1,0]
	v_mul_f32_e32 v139, 0xbfb8aa3b, v37
	v_rcp_f32_e32 v144, v137
	v_exp_f32_e32 v138, v138
	v_exp_f32_e32 v139, v139
	v_rcp_f32_e32 v147, v136
	v_mul_f32_e32 v137, v36, v144
	v_pk_add_f32 v[138:139], v[138:139], 1.0 op_sel_hi:[1,0]
	v_rcp_f32_e32 v146, v138
	v_mul_f32_e32 v136, v34, v147
	v_rcp_f32_e32 v147, v139
	v_mul_f32_e32 v138, v35, v146
	s_mov_b64 s[2:3], 0x28000
	v_mul_f32_e32 v139, v37, v147
	v_bfe_u32 v143, v139, 16, 1
	v_bfe_u32 v144, v138, 16, 1
	v_bfe_u32 v145, v140, 16, 1
	v_bfe_u32 v146, v142, 16, 1
	v_add3_u32 v142, v142, v146, s0
	v_add3_u32 v140, v140, v145, s0
	v_add3_u32 v138, v138, v144, s0
	v_add3_u32 v139, v139, v143, s0
	v_bfe_u32 v143, v141, 16, 1
	v_bfe_u32 v144, v131, 16, 1
	v_bfe_u32 v145, v136, 16, 1
	v_bfe_u32 v146, v137, 16, 1
	v_add3_u32 v137, v137, v146, s0
	v_add3_u32 v136, v136, v145, s0
	v_add3_u32 v131, v131, v144, s0
	v_add3_u32 v141, v141, v143, s0
	v_lshrrev_b32_e32 v141, 16, v141
	v_lshrrev_b32_e32 v131, 16, v131
	v_lshrrev_b32_e32 v136, 16, v136
	v_lshrrev_b32_e32 v137, 16, v137
	v_and_or_b32 v139, v139, s1, v137
	v_and_or_b32 v138, v138, s1, v136
	v_and_or_b32 v137, v140, s1, v131
	v_and_or_b32 v136, v142, s1, v141
	v_mul_f32_e32 v131, 0xbfb8aa3b, v30
	global_store_dwordx4 v[134:135], v[136:139], off offset:256
	v_lshl_add_u64 v[134:135], v[132:133], 0, s[2:3]
	s_nop 0
	v_exp_f32_e32 v136, v131
	v_mul_f32_e32 v131, 0xbfb8aa3b, v32
	v_exp_f32_e32 v137, v131
	v_mul_f32_e32 v131, 0xbfb8aa3b, v31
	v_exp_f32_e32 v138, v131
	v_mul_f32_e32 v131, 0xbfb8aa3b, v33
	v_pk_add_f32 v[136:137], v[136:137], 1.0 op_sel_hi:[1,0]
	v_exp_f32_e32 v139, v131
	v_rcp_f32_e32 v141, v137
	v_pk_add_f32 v[138:139], v[138:139], 1.0 op_sel_hi:[1,0]
	v_rcp_f32_e32 v143, v136
	v_mul_f32_e32 v131, v32, v141
	v_rcp_f32_e32 v142, v138
	v_mul_f32_e32 v141, v30, v143
	v_rcp_f32_e32 v143, v139
	v_mul_f32_e32 v142, v31, v142
	v_mul_f32_e32 v136, 0xbfb8aa3b, v26
	v_mul_f32_e32 v137, 0xbfb8aa3b, v28
	v_exp_f32_e32 v136, v136
	v_exp_f32_e32 v137, v137
	v_mul_f32_e32 v140, v33, v143
	v_mul_f32_e32 v138, 0xbfb8aa3b, v27
	v_pk_add_f32 v[136:137], v[136:137], 1.0 op_sel_hi:[1,0]
	v_mul_f32_e32 v139, 0xbfb8aa3b, v29
	v_rcp_f32_e32 v144, v137
	v_exp_f32_e32 v138, v138
	v_exp_f32_e32 v139, v139
	v_rcp_f32_e32 v147, v136
	v_mul_f32_e32 v137, v28, v144
	v_pk_add_f32 v[138:139], v[138:139], 1.0 op_sel_hi:[1,0]
	v_rcp_f32_e32 v146, v138
	v_mul_f32_e32 v136, v26, v147
	v_rcp_f32_e32 v147, v139
	v_mul_f32_e32 v138, v27, v146
	s_mov_b32 s2, 0x28000
	v_bfe_u32 v144, v138, 16, 1
	v_bfe_u32 v146, v142, 16, 1
	v_mul_f32_e32 v139, v29, v147
	v_add3_u32 v142, v142, v146, s0
	v_add3_u32 v138, v138, v144, s0
	v_bfe_u32 v144, v131, 16, 1
	v_bfe_u32 v146, v137, 16, 1
	v_bfe_u32 v143, v139, 16, 1
	v_bfe_u32 v145, v140, 16, 1
	v_add3_u32 v137, v137, v146, s0
	v_add3_u32 v131, v131, v144, s0
	v_add3_u32 v140, v140, v145, s0
	v_add3_u32 v139, v139, v143, s0
	v_bfe_u32 v143, v141, 16, 1
	v_bfe_u32 v145, v136, 16, 1
	v_lshrrev_b32_e32 v131, 16, v131
	v_lshrrev_b32_e32 v137, 16, v137
	v_add3_u32 v136, v136, v145, s0
	v_add3_u32 v141, v141, v143, s0
	v_and_or_b32 v139, v139, s1, v137
	v_and_or_b32 v137, v140, s1, v131
	v_mul_f32_e32 v131, 0xbfb8aa3b, v22
	v_lshrrev_b32_e32 v141, 16, v141
	v_lshrrev_b32_e32 v136, 16, v136
	v_exp_f32_e32 v140, v131
	v_mul_f32_e32 v131, 0xbfb8aa3b, v24
	v_and_or_b32 v138, v138, s1, v136
	v_and_or_b32 v136, v142, s1, v141
	v_exp_f32_e32 v141, v131
	v_add_co_u32_e32 v142, vcc, s2, v132
	v_mul_f32_e32 v131, 0xbfb8aa3b, v23
	s_nop 0
	v_addc_co_u32_e32 v143, vcc, 0, v133, vcc
	global_store_dwordx4 v[142:143], v[136:139], off
	s_nop 1
	v_pk_add_f32 v[136:137], v[140:141], 1.0 op_sel_hi:[1,0]
	v_exp_f32_e32 v138, v131
	v_rcp_f32_e32 v141, v137
	v_mul_f32_e32 v131, 0xbfb8aa3b, v25
	v_exp_f32_e32 v139, v131
	v_rcp_f32_e32 v143, v136
	v_mul_f32_e32 v131, v24, v141
	v_pk_add_f32 v[138:139], v[138:139], 1.0 op_sel_hi:[1,0]
	v_rcp_f32_e32 v142, v138
	v_mul_f32_e32 v141, v22, v143
	v_rcp_f32_e32 v143, v139
	v_mul_f32_e32 v142, v23, v142
	v_mul_f32_e32 v136, 0xbfb8aa3b, v18
	v_mul_f32_e32 v137, 0xbfb8aa3b, v20
	v_exp_f32_e32 v136, v136
	v_exp_f32_e32 v137, v137
	v_mul_f32_e32 v140, v25, v143
	v_mul_f32_e32 v138, 0xbfb8aa3b, v19
	v_pk_add_f32 v[136:137], v[136:137], 1.0 op_sel_hi:[1,0]
	v_mul_f32_e32 v139, 0xbfb8aa3b, v21
	v_rcp_f32_e32 v144, v137
	v_exp_f32_e32 v138, v138
	v_exp_f32_e32 v139, v139
	v_rcp_f32_e32 v147, v136
	v_mul_f32_e32 v137, v20, v144
	v_pk_add_f32 v[138:139], v[138:139], 1.0 op_sel_hi:[1,0]
	v_rcp_f32_e32 v146, v138
	v_mul_f32_e32 v136, v18, v147
	v_rcp_f32_e32 v147, v139
	v_mul_f32_e32 v138, v19, v146
	s_mov_b64 s[2:3], 0x2c000
	v_mul_f32_e32 v139, v21, v147
	v_bfe_u32 v143, v139, 16, 1
	v_bfe_u32 v144, v138, 16, 1
	v_bfe_u32 v145, v140, 16, 1
	v_bfe_u32 v146, v142, 16, 1
	v_add3_u32 v142, v142, v146, s0
	v_add3_u32 v140, v140, v145, s0
	v_add3_u32 v138, v138, v144, s0
	v_add3_u32 v139, v139, v143, s0
	v_bfe_u32 v143, v141, 16, 1
	v_bfe_u32 v144, v131, 16, 1
	v_bfe_u32 v145, v136, 16, 1
	v_bfe_u32 v146, v137, 16, 1
	v_add3_u32 v137, v137, v146, s0
	v_add3_u32 v136, v136, v145, s0
	v_add3_u32 v131, v131, v144, s0
	v_add3_u32 v141, v141, v143, s0
	v_lshrrev_b32_e32 v141, 16, v141
	v_lshrrev_b32_e32 v131, 16, v131
	v_lshrrev_b32_e32 v136, 16, v136
	v_lshrrev_b32_e32 v137, 16, v137
	v_and_or_b32 v139, v139, s1, v137
	v_and_or_b32 v138, v138, s1, v136
	v_and_or_b32 v137, v140, s1, v131
	v_and_or_b32 v136, v142, s1, v141
	v_mul_f32_e32 v131, 0xbfb8aa3b, v14
	global_store_dwordx4 v[134:135], v[136:139], off offset:256
	v_lshl_add_u64 v[134:135], v[132:133], 0, s[2:3]
	s_nop 0
	v_exp_f32_e32 v136, v131
	v_mul_f32_e32 v131, 0xbfb8aa3b, v16
	v_exp_f32_e32 v137, v131
	v_mul_f32_e32 v131, 0xbfb8aa3b, v15
	v_exp_f32_e32 v138, v131
	v_mul_f32_e32 v131, 0xbfb8aa3b, v17
	v_pk_add_f32 v[136:137], v[136:137], 1.0 op_sel_hi:[1,0]
	v_exp_f32_e32 v139, v131
	v_rcp_f32_e32 v141, v137
	v_pk_add_f32 v[138:139], v[138:139], 1.0 op_sel_hi:[1,0]
	v_rcp_f32_e32 v143, v136
	v_mul_f32_e32 v131, v16, v141
	v_rcp_f32_e32 v142, v138
	v_mul_f32_e32 v141, v14, v143
	v_rcp_f32_e32 v143, v139
	v_mul_f32_e32 v142, v15, v142
	v_mul_f32_e32 v136, 0xbfb8aa3b, v10
	v_mul_f32_e32 v137, 0xbfb8aa3b, v12
	v_exp_f32_e32 v136, v136
	v_exp_f32_e32 v137, v137
	v_mul_f32_e32 v140, v17, v143
	v_mul_f32_e32 v138, 0xbfb8aa3b, v11
	v_pk_add_f32 v[136:137], v[136:137], 1.0 op_sel_hi:[1,0]
	v_mul_f32_e32 v139, 0xbfb8aa3b, v13
	v_rcp_f32_e32 v144, v137
	v_exp_f32_e32 v138, v138
	v_exp_f32_e32 v139, v139
	v_rcp_f32_e32 v147, v136
	v_mul_f32_e32 v137, v12, v144
	v_pk_add_f32 v[138:139], v[138:139], 1.0 op_sel_hi:[1,0]
	v_rcp_f32_e32 v146, v138
	v_mul_f32_e32 v136, v10, v147
	v_rcp_f32_e32 v147, v139
	v_mul_f32_e32 v138, v11, v146
	s_mov_b32 s2, 0x2c000
	v_bfe_u32 v144, v138, 16, 1
	v_bfe_u32 v146, v142, 16, 1
	v_mul_f32_e32 v139, v13, v147
	v_add3_u32 v142, v142, v146, s0
	v_add3_u32 v138, v138, v144, s0
	v_bfe_u32 v144, v131, 16, 1
	v_bfe_u32 v146, v137, 16, 1
	v_bfe_u32 v143, v139, 16, 1
	v_bfe_u32 v145, v140, 16, 1
	v_add3_u32 v137, v137, v146, s0
	v_add3_u32 v131, v131, v144, s0
	v_add3_u32 v140, v140, v145, s0
	v_add3_u32 v139, v139, v143, s0
	v_bfe_u32 v143, v141, 16, 1
	v_bfe_u32 v145, v136, 16, 1
	v_lshrrev_b32_e32 v131, 16, v131
	v_lshrrev_b32_e32 v137, 16, v137
	v_add3_u32 v136, v136, v145, s0
	v_add3_u32 v141, v141, v143, s0
	v_and_or_b32 v139, v139, s1, v137
	v_and_or_b32 v137, v140, s1, v131
	v_mul_f32_e32 v131, 0xbfb8aa3b, v6
	v_lshrrev_b32_e32 v141, 16, v141
	v_lshrrev_b32_e32 v136, 16, v136
	v_exp_f32_e32 v140, v131
	v_mul_f32_e32 v131, 0xbfb8aa3b, v8
	v_and_or_b32 v138, v138, s1, v136
	v_and_or_b32 v136, v142, s1, v141
	v_exp_f32_e32 v141, v131
	v_add_co_u32_e32 v132, vcc, s2, v132
	v_mul_f32_e32 v131, 0xbfb8aa3b, v7
	s_nop 0
	v_addc_co_u32_e32 v133, vcc, 0, v133, vcc
	global_store_dwordx4 v[132:133], v[136:139], off
	v_pk_add_f32 v[132:133], v[140:141], 1.0 op_sel_hi:[1,0]
	s_nop 0
	v_rcp_f32_e32 v139, v133
	v_exp_f32_e32 v136, v131
	v_mul_f32_e32 v131, 0xbfb8aa3b, v9
	v_exp_f32_e32 v137, v131
	v_rcp_f32_e32 v141, v132
	v_mul_f32_e32 v131, v8, v139
	v_pk_add_f32 v[136:137], v[136:137], 1.0 op_sel_hi:[1,0]
	v_rcp_f32_e32 v140, v136
	v_mul_f32_e32 v139, v6, v141
	v_rcp_f32_e32 v141, v137
	v_mul_f32_e32 v140, v7, v140
	v_mul_f32_e32 v132, 0xbfb8aa3b, v2
	v_mul_f32_e32 v133, 0xbfb8aa3b, v4
	v_exp_f32_e32 v132, v132
	v_exp_f32_e32 v133, v133
	v_mul_f32_e32 v138, v9, v141
	v_mul_f32_e32 v136, 0xbfb8aa3b, v3
	v_pk_add_f32 v[132:133], v[132:133], 1.0 op_sel_hi:[1,0]
	v_mul_f32_e32 v137, 0xbfb8aa3b, v5
	v_rcp_f32_e32 v142, v133
	v_exp_f32_e32 v136, v136
	v_exp_f32_e32 v137, v137
	v_rcp_f32_e32 v145, v132
	v_mul_f32_e32 v133, v4, v142
	v_pk_add_f32 v[136:137], v[136:137], 1.0 op_sel_hi:[1,0]
	v_rcp_f32_e32 v144, v136
	v_mul_f32_e32 v132, v2, v145
	v_rcp_f32_e32 v145, v137
	v_mul_f32_e32 v136, v3, v144
	v_mul_f32_e32 v137, v5, v145
	v_bfe_u32 v141, v137, 16, 1
	v_bfe_u32 v142, v136, 16, 1
	v_bfe_u32 v143, v138, 16, 1
	v_bfe_u32 v144, v140, 16, 1
	v_add3_u32 v140, v140, v144, s0
	v_add3_u32 v143, v138, v143, s0
	v_add3_u32 v136, v136, v142, s0
	v_add3_u32 v137, v137, v141, s0
	v_bfe_u32 v138, v139, 16, 1
	v_bfe_u32 v141, v131, 16, 1
	v_bfe_u32 v142, v132, 16, 1
	v_bfe_u32 v144, v133, 16, 1
	v_add3_u32 v133, v133, v144, s0
	v_add3_u32 v132, v132, v142, s0
	v_add3_u32 v131, v131, v141, s0
	v_add3_u32 v138, v139, v138, s0
	v_lshrrev_b32_e32 v141, 16, v138
	v_lshrrev_b32_e32 v131, 16, v131
	v_lshrrev_b32_e32 v132, 16, v132
	v_lshrrev_b32_e32 v133, 16, v133
	v_and_or_b32 v139, v137, s1, v133
	v_and_or_b32 v138, v136, s1, v132
	v_and_or_b32 v137, v143, s1, v131
	v_and_or_b32 v136, v140, s1, v141
	s_mov_b64 s[0:1], 0
	global_store_dwordx4 v[134:135], v[136:139], off offset:256
.LBB0_993:
	s_andn2_b64 vcc, exec, s[0:1]
	s_cbranch_vccnz .LBB0_995
	v_readlane_b32 s16, v254, 4
	v_readlane_b32 s17, v254, 5
	v_readlane_b32 s18, v254, 6
	v_readlane_b32 s19, v254, 7
	v_readlane_b32 s20, v254, 8
	v_readlane_b32 s21, v254, 9
	v_lshlrev_b32_e32 v131, 2, v1
	v_readlane_b32 s22, v254, 10
	v_readlane_b32 s23, v254, 11
	s_mov_b64 s[16:17], s[20:21]
	global_load_dwordx4 v[140:143], v131, s[16:17] offset:2048
	global_load_dwordx4 v[144:147], v131, s[16:17]
	global_load_dwordx4 v[148:151], v131, s[16:17] offset:16
	global_load_dwordx4 v[156:159], v131, s[16:17] offset:2064
	global_load_dwordx4 v[160:163], v131, s[16:17] offset:2560
	global_load_dwordx4 v[164:167], v131, s[16:17] offset:512
	global_load_dwordx4 v[168:171], v131, s[16:17] offset:528
	global_load_dwordx4 v[172:175], v131, s[16:17] offset:2576
	s_mov_b64 s[18:19], s[22:23]
	s_movk_i32 s20, 0x2080
	v_mov_b32_e32 v154, 0xffffdf80
	v_cmp_gt_i32_e32 vcc, s20, v130
	v_lshlrev_b32_e32 v134, 1, v1
	v_mov_b32_e32 v135, 0
	v_ashrrev_i32_e32 v131, 31, v130
	v_cndmask_b32_e64 v153, v154, 0, vcc
	s_mov_b64 s[2:3], 0xb800000
	s_movk_i32 s18, 0x70
	v_lshl_add_u64 v[132:133], s[10:11], 0, v[134:135]
	v_lshl_add_u64 v[134:135], s[72:73], 0, v[134:135]
	v_lshlrev_b64 v[136:137], 10, v[130:131]
	v_add_u32_e32 v131, v153, v130
	v_lshl_add_u64 v[134:135], v[134:135], 0, s[2:3]
	v_cmp_gt_i32_e64 s[2:3], s18, v131
	v_mul_f32_e32 v152, 0x3fb8aa3b, v128
	v_mul_f32_e32 v155, 0x3fb8aa3b, v129
	v_exp_f32_e32 v177, v152
	v_exp_f32_e32 v179, v155
	v_mul_f32_e32 v138, 0x3fb8aa3b, v126
	v_exp_f32_e32 v176, v138
	v_mul_f32_e32 v139, 0x3fb8aa3b, v127
	s_mov_b32 s14, 0x800000
	v_exp_f32_e32 v178, v139
	s_mov_b32 s9, 0x3f317217
	s_mov_b32 s15, 0x7f800000
	s_movk_i32 s19, 0x4100
	v_cmp_gt_i32_e64 s[0:1], s19, v130
	s_movk_i32 s16, 0x7fff
	s_mov_b32 s17, 0xffff0000
	v_lshl_add_u64 v[138:139], v[132:133], 0, v[136:137]
	v_lshl_add_u64 v[136:137], v[134:135], 0, v[136:137]
	v_readlane_b32 s24, v254, 12
	v_readlane_b32 s25, v254, 13
	v_readlane_b32 s26, v254, 14
	v_readlane_b32 s27, v254, 15
	v_readlane_b32 s28, v254, 16
	v_readlane_b32 s29, v254, 17
	v_readlane_b32 s30, v254, 18
	v_readlane_b32 s31, v254, 19
	s_waitcnt vmcnt(0)
	v_sub_f32_e32 v131, v144, v140
	v_sub_f32_e32 v140, v145, v141
	v_sub_f32_e32 v141, v146, v142
	v_sub_f32_e32 v142, v147, v143
	v_sub_f32_e32 v143, v148, v156
	v_mul_f32_e32 v131, 0x3fb8aa3b, v131
	v_sub_f32_e32 v156, v171, v175
	v_mul_f32_e32 v141, 0x3fb8aa3b, v141
	v_sub_f32_e32 v144, v149, v157
	v_sub_f32_e32 v147, v164, v160
	v_mul_f32_e32 v164, 0x3fb8aa3b, v156
	v_exp_f32_e32 v156, v131
	v_exp_f32_e32 v157, v141
	v_sub_f32_e32 v152, v169, v173
	v_sub_f32_e32 v145, v150, v158
	v_sub_f32_e32 v149, v166, v162
	v_pk_add_f32 v[156:157], v[156:157], 1.0 op_sel_hi:[1,0]
	v_sub_f32_e32 v150, v167, v163
	v_mul_f32_e32 v140, 0x3fb8aa3b, v140
	v_mul_f32_e32 v162, 0x3fb8aa3b, v152
	v_sub_f32_e32 v148, v165, v161
	v_mul_f32_e32 v145, 0x3fb8aa3b, v145
	v_mul_f32_e32 v150, 0x3fb8aa3b, v150
	v_exp_f32_e32 v158, v140
	v_exp_f32_e32 v140, v162
	v_mul_f32_e32 v131, 0x3fb8aa3b, v122
	v_rcp_f32_e32 v162, v156
	v_sub_f32_e32 v146, v151, v159
	v_sub_f32_e32 v151, v168, v172
	v_mul_f32_e32 v144, 0x3fb8aa3b, v144
	v_mul_f32_e32 v148, 0x3fb8aa3b, v148
	v_exp_f32_e32 v161, v145
	v_exp_f32_e32 v145, v150
	v_exp_f32_e32 v150, v131
	v_mul_f32_e32 v131, 0x3fb8aa3b, v123
	v_mul_f32_e32 v142, 0x3fb8aa3b, v142
	v_mul_f32_e32 v151, 0x3fb8aa3b, v151
	v_exp_f32_e32 v152, v144
	v_exp_f32_e32 v144, v148
	v_exp_f32_e32 v148, v131
	v_mul_f32_e32 v131, 0x3fb8aa3b, v124
	v_sub_f32_e32 v153, v170, v174
	v_mul_f32_e32 v146, 0x3fb8aa3b, v146
	v_mul_f32_e32 v147, 0x3fb8aa3b, v147
	v_mul_f32_e32 v149, 0x3fb8aa3b, v149
	v_exp_f32_e32 v159, v142
	v_exp_f32_e32 v142, v151
	v_exp_f32_e32 v151, v131
	v_mul_f32_e32 v131, 0x3fb8aa3b, v125
	v_mul_f32_e32 v163, 0x3fb8aa3b, v153
	v_exp_f32_e32 v153, v146
	v_exp_f32_e32 v146, v147
	v_exp_f32_e32 v147, v149
	v_exp_f32_e32 v149, v131
	v_mul_f32_e32 v143, 0x3fb8aa3b, v143
	v_exp_f32_e32 v160, v143
	v_exp_f32_e32 v143, v163
	v_exp_f32_e32 v141, v164
	v_rcp_f32_e32 v164, v157
	v_mov_b32_e32 v156, v162
	v_pk_add_f32 v[158:159], v[158:159], 1.0 op_sel_hi:[1,0]
	v_rcp_f32_e32 v163, v158
	v_mov_b32_e32 v157, v164
	v_pk_add_f32 v[160:161], v[160:161], 1.0 op_sel_hi:[1,0]
	v_div_scale_f32 v164, s[4:5], v159, v159, 1.0
	v_rcp_f32_e32 v165, v164
	v_mov_b32_e32 v155, v163
	v_fma_f32 v131, -v164, v165, 1.0
	v_fmac_f32_e32 v165, v131, v165
	v_div_scale_f32 v131, vcc, 1.0, v159, 1.0
	v_mul_f32_e32 v158, v131, v165
	v_fma_f32 v162, -v164, v158, v131
	v_fmac_f32_e32 v158, v162, v165
	v_pk_add_f32 v[162:163], v[176:177], 1.0 op_sel_hi:[1,0]
	v_fma_f32 v131, -v164, v158, v131
	v_div_scale_f32 v166, s[4:5], v163, v163, v157
	v_rcp_f32_e32 v167, v166
	v_div_fmas_f32 v131, v131, v165, v158
	v_pk_add_f32 v[150:151], v[150:151], 1.0 op_sel_hi:[1,0]
	v_pk_add_f32 v[148:149], v[148:149], 1.0 op_sel_hi:[1,0]
	v_fma_f32 v158, -v166, v167, 1.0
	v_fmac_f32_e32 v167, v158, v167
	v_div_scale_f32 v158, vcc, v157, v163, v157
	v_mul_f32_e32 v164, v158, v167
	v_fma_f32 v165, -v166, v164, v158
	v_fmac_f32_e32 v164, v165, v167
	v_rcp_f32_e32 v168, v162
	v_fma_f32 v158, -v166, v164, v158
	v_div_fmas_f32 v164, v158, v167, v164
	v_pk_add_f32 v[146:147], v[146:147], 1.0 op_sel_hi:[1,0]
	v_mul_f32_e32 v165, v156, v168
	v_sub_f32_e32 v158, 1.0, v165
	v_cmp_gt_f32_e64 s[4:5], s14, v158
	v_pk_add_f32 v[142:143], v[142:143], 1.0 op_sel_hi:[1,0]
	s_nop 0
	v_cndmask_b32_e64 v162, 0, 32, s[4:5]
	v_ldexp_f32 v158, v158, v162
	v_log_f32_e32 v166, v158
	v_div_fixup_f32 v158, v131, v159, 1.0
	v_div_fixup_f32 v159, v164, v163, v157
	v_pk_add_f32 v[162:163], v[178:179], 1.0 op_sel_hi:[1,0]
	v_mul_f32_e32 v131, 0x3f317217, v166
	v_div_scale_f32 v164, s[6:7], v163, v163, v158
	v_rcp_f32_e32 v167, v164
	v_fma_f32 v131, v166, s9, -v131
	v_fmac_f32_e32 v131, 0x3377d1cf, v166
	v_fmac_f32_e32 v131, 0x3f317217, v166
	v_cmp_lt_f32_e64 vcc, |v166|, s15
	v_fma_f32 v168, -v164, v167, 1.0
	v_fmac_f32_e32 v167, v168, v167
	v_cndmask_b32_e32 v166, v166, v131, vcc
	v_div_scale_f32 v168, vcc, v158, v163, v158
	v_mul_f32_e32 v169, v168, v167
	v_fma_f32 v170, -v164, v169, v168
	v_fmac_f32_e32 v169, v170, v167
	v_rcp_f32_e32 v171, v162
	v_fma_f32 v164, -v164, v169, v168
	v_div_fmas_f32 v164, v164, v167, v169
	v_mov_b32_e32 v131, 0x41b17218
	v_mul_f32_e32 v162, v155, v171
	v_sub_f32_e32 v167, 1.0, v162
	v_cmp_gt_f32_e32 vcc, s14, v167
	v_div_fixup_f32 v163, v164, v163, v158
	s_nop 0
	v_cndmask_b32_e64 v168, 0, 32, vcc
	v_ldexp_f32 v167, v167, v168
	v_log_f32_e32 v167, v167
	v_cndmask_b32_e64 v168, 0, v131, s[4:5]
	v_sub_f32_e32 v166, v166, v168
	v_sub_f32_e32 v168, 1.0, v159
	v_cmp_gt_f32_e64 s[4:5], s14, v168
	v_mul_f32_e32 v164, 0x3f317217, v167
	v_fma_f32 v164, v167, s9, -v164
	v_cndmask_b32_e64 v169, 0, 32, s[4:5]
	v_ldexp_f32 v168, v168, v169
	v_fmac_f32_e32 v164, 0x3377d1cf, v167
	v_log_f32_e32 v168, v168
	v_fmac_f32_e32 v164, 0x3f317217, v167
	v_cmp_lt_f32_e64 s[6:7], |v167|, s15
	v_sub_f32_e32 v169, 1.0, v163
	s_nop 0
	v_cndmask_b32_e64 v164, v167, v164, s[6:7]
	v_cndmask_b32_e32 v167, 0, v131, vcc
	v_cmp_gt_f32_e32 vcc, s14, v169
	v_sub_f32_e32 v164, v164, v167
	v_mul_f32_e32 v167, 0x3f317217, v168
	v_cndmask_b32_e64 v170, 0, 32, vcc
	v_ldexp_f32 v169, v169, v170
	v_fma_f32 v167, v168, s9, -v167
	v_log_f32_e32 v169, v169
	v_fmac_f32_e32 v167, 0x3377d1cf, v168
	v_fmac_f32_e32 v167, 0x3f317217, v168
	v_cmp_lt_f32_e64 s[6:7], |v168|, s15
	s_nop 1
	v_cndmask_b32_e64 v167, v168, v167, s[6:7]
	v_cndmask_b32_e64 v168, 0, v131, s[4:5]
	v_sub_f32_e32 v167, v167, v168
	v_mul_f32_e32 v168, 0x3f317217, v169
	v_fma_f32 v168, v169, s9, -v168
	v_fmac_f32_e32 v168, 0x3377d1cf, v169
	v_fmac_f32_e32 v168, 0x3f317217, v169
	v_cmp_lt_f32_e64 s[4:5], |v169|, s15
	s_nop 1
	v_cndmask_b32_e64 v168, v169, v168, s[4:5]
	v_cndmask_b32_e32 v169, 0, v131, vcc
	s_and_b64 s[4:5], s[0:1], s[2:3]
	v_sub_f32_e32 v168, v168, v169
	v_cndmask_b32_e64 v169, v159, 0, s[4:5]
	v_rcp_f32_e32 v170, v160
	v_cndmask_b32_e64 v171, v162, 0, s[4:5]
	v_cndmask_b32_e64 v172, v163, 0, s[4:5]
	v_cndmask_b32_e64 v165, v165, 0, s[4:5]
	v_rcp_f32_e32 v173, v161
	v_mov_b32_e32 v159, v170
	v_pk_add_f32 v[162:163], v[152:153], 1.0 op_sel_hi:[1,0]
	v_div_scale_f32 v153, s[0:1], v162, v162, 1.0
	v_rcp_f32_e32 v174, v153
	v_mov_b32_e32 v152, v173
	v_fma_f32 v160, -v153, v174, 1.0
	v_fmac_f32_e32 v174, v160, v174
	v_div_scale_f32 v160, vcc, 1.0, v162, 1.0
	v_mul_f32_e32 v161, v160, v174
	v_fma_f32 v170, -v153, v161, v160
	v_fmac_f32_e32 v161, v170, v174
	v_div_scale_f32 v170, s[0:1], v163, v163, 1.0
	v_rcp_f32_e32 v173, v170
	v_fma_f32 v153, -v153, v161, v160
	v_div_fmas_f32 v153, v153, v174, v161
	v_fma_f32 v160, -v170, v173, 1.0
	v_fmac_f32_e32 v173, v160, v173
	v_div_scale_f32 v160, vcc, 1.0, v163, 1.0
	v_mul_f32_e32 v161, v160, v173
	v_fma_f32 v174, -v170, v161, v160
	v_fmac_f32_e32 v161, v174, v173
	v_rcp_f32_e32 v175, v151
	v_fma_f32 v160, -v170, v161, v160
	v_div_fmas_f32 v161, v160, v173, v161
	v_rcp_f32_e32 v176, v150
	v_mul_f32_e32 v151, v152, v175
	v_mul_f32_e32 v150, v159, v176
	v_sub_f32_e32 v160, 1.0, v150
	v_cmp_gt_f32_e64 s[0:1], s14, v160
	v_cndmask_b32_e64 v150, v150, 0, s[4:5]
	v_bfe_u32 v176, v171, 16, 1
	v_cndmask_b32_e64 v173, 0, 32, s[0:1]
	v_ldexp_f32 v160, v160, v173
	v_log_f32_e32 v173, v160
	v_div_fixup_f32 v160, v153, v162, 1.0
	v_div_fixup_f32 v153, v161, v163, 1.0
	v_rcp_f32_e32 v163, v149
	v_mul_f32_e32 v161, 0x3f317217, v173
	v_fma_f32 v161, v173, s9, -v161
	v_fmac_f32_e32 v161, 0x3377d1cf, v173
	v_fmac_f32_e32 v161, 0x3f317217, v173
	v_cmp_lt_f32_e64 vcc, |v173|, s15
	s_nop 1
	v_cndmask_b32_e32 v161, v173, v161, vcc
	v_rcp_f32_e32 v175, v148
	v_mul_f32_e32 v149, v153, v163
	v_mul_f32_e32 v148, v160, v175
	v_sub_f32_e32 v163, 1.0, v148
	v_cmp_gt_f32_e32 vcc, s14, v163
	v_cndmask_b32_e64 v148, v148, 0, s[4:5]
	v_bfe_u32 v175, v172, 16, 1
	v_cndmask_b32_e64 v170, 0, 32, vcc
	v_ldexp_f32 v163, v163, v170
	v_log_f32_e32 v163, v163
	v_cndmask_b32_e64 v170, 0, v131, s[0:1]
	v_sub_f32_e32 v161, v161, v170
	v_sub_f32_e32 v170, 1.0, v151
	v_cmp_gt_f32_e64 s[0:1], s14, v170
	v_mul_f32_e32 v162, 0x3f317217, v163
	v_fma_f32 v162, v163, s9, -v162
	v_cndmask_b32_e64 v173, 0, 32, s[0:1]
	v_ldexp_f32 v170, v170, v173
	v_fmac_f32_e32 v162, 0x3377d1cf, v163
	v_log_f32_e32 v170, v170
	v_fmac_f32_e32 v162, 0x3f317217, v163
	v_cmp_lt_f32_e64 s[2:3], |v163|, s15
	v_sub_f32_e32 v173, 1.0, v149
	v_cndmask_b32_e64 v149, v149, 0, s[4:5]
	v_cndmask_b32_e64 v162, v163, v162, s[2:3]
	v_cndmask_b32_e32 v163, 0, v131, vcc
	v_cmp_gt_f32_e32 vcc, s14, v173
	v_sub_f32_e32 v162, v162, v163
	v_mul_f32_e32 v163, 0x3f317217, v170
	v_cndmask_b32_e64 v174, 0, 32, vcc
	v_ldexp_f32 v173, v173, v174
	v_fma_f32 v163, v170, s9, -v163
	v_log_f32_e32 v173, v173
	v_fmac_f32_e32 v163, 0x3377d1cf, v170
	v_fmac_f32_e32 v163, 0x3f317217, v170
	v_cmp_lt_f32_e64 s[2:3], |v170|, s15
	v_cndmask_b32_e64 v151, v151, 0, s[4:5]
	v_bfe_u32 v174, v148, 16, 1
	v_cndmask_b32_e64 v163, v170, v163, s[2:3]
	v_cndmask_b32_e64 v170, 0, v131, s[0:1]
	v_sub_f32_e32 v163, v163, v170
	v_mul_f32_e32 v170, 0x3f317217, v173
	v_fma_f32 v170, v173, s9, -v170
	v_fmac_f32_e32 v170, 0x3377d1cf, v173
	v_fmac_f32_e32 v170, 0x3f317217, v173
	v_cmp_lt_f32_e64 s[0:1], |v173|, s15
	v_add3_u32 v171, v171, v176, s16
	v_add3_u32 v172, v172, v175, s16
	v_cndmask_b32_e64 v170, v173, v170, s[0:1]
	v_cndmask_b32_e32 v173, 0, v131, vcc
	v_sub_f32_e32 v170, v170, v173
	v_bfe_u32 v173, v149, 16, 1
	v_add3_u32 v148, v148, v174, s16
	v_add3_u32 v149, v149, v173, s16
	v_bfe_u32 v173, v165, 16, 1
	v_bfe_u32 v174, v169, 16, 1
	v_bfe_u32 v175, v150, 16, 1
	v_bfe_u32 v176, v151, 16, 1
	v_add3_u32 v151, v151, v176, s16
	v_add3_u32 v150, v150, v175, s16
	v_add3_u32 v169, v169, v174, s16
	v_add3_u32 v165, v165, v173, s16
	v_lshrrev_b32_e32 v165, 16, v165
	v_lshrrev_b32_e32 v169, 16, v169
	v_lshrrev_b32_e32 v150, 16, v150
	v_lshrrev_b32_e32 v151, 16, v151
	v_and_or_b32 v151, v149, s17, v151
	v_and_or_b32 v150, v148, s17, v150
	v_and_or_b32 v149, v172, s17, v169
	v_and_or_b32 v148, v171, s17, v165
	global_store_dwordx4 v[138:139], v[148:151], off
	s_nop 1
	v_cndmask_b32_e64 v148, v166, 0, s[4:5]
	v_bfe_u32 v149, v148, 16, 1
	v_add3_u32 v148, v148, v149, s16
	v_cndmask_b32_e64 v149, v164, 0, s[4:5]
	v_bfe_u32 v150, v149, 16, 1
	v_lshrrev_b32_e32 v148, 16, v148
	v_add3_u32 v149, v149, v150, s16
	v_and_or_b32 v148, v149, s17, v148
	v_cndmask_b32_e64 v149, v167, 0, s[4:5]
	v_bfe_u32 v150, v149, 16, 1
	v_add3_u32 v149, v149, v150, s16
	v_cndmask_b32_e64 v150, v168, 0, s[4:5]
	v_bfe_u32 v151, v150, 16, 1
	v_lshrrev_b32_e32 v149, 16, v149
	v_add3_u32 v150, v150, v151, s16
	v_and_or_b32 v149, v150, s17, v149
	v_cndmask_b32_e64 v150, v161, 0, s[4:5]
	v_bfe_u32 v151, v150, 16, 1
	v_add3_u32 v150, v150, v151, s16
	v_cndmask_b32_e64 v151, v162, 0, s[4:5]
	v_bfe_u32 v161, v151, 16, 1
	v_lshrrev_b32_e32 v150, 16, v150
	v_add3_u32 v151, v151, v161, s16
	v_and_or_b32 v150, v151, s17, v150
	v_cndmask_b32_e64 v151, v163, 0, s[4:5]
	v_bfe_u32 v161, v151, 16, 1
	v_add3_u32 v151, v151, v161, s16
	v_cndmask_b32_e64 v161, v170, 0, s[4:5]
	v_bfe_u32 v162, v161, 16, 1
	v_lshrrev_b32_e32 v151, 16, v151
	v_add3_u32 v161, v161, v162, s16
	v_and_or_b32 v151, v161, s17, v151
	v_rcp_f32_e32 v166, v146
	global_store_dwordx4 v[136:137], v[148:151], off
	v_rcp_f32_e32 v169, v147
	v_mov_b32_e32 v146, v166
	v_mul_f32_e32 v148, 0x3fb8aa3b, v118
	v_pk_add_f32 v[166:167], v[144:145], 1.0 op_sel_hi:[1,0]
	v_div_scale_f32 v145, s[0:1], v166, v166, 1.0
	v_rcp_f32_e32 v170, v145
	v_mov_b32_e32 v144, v169
	v_exp_f32_e32 v162, v148
	v_mul_f32_e32 v148, 0x3fb8aa3b, v119
	v_fma_f32 v147, -v145, v170, 1.0
	v_fmac_f32_e32 v170, v147, v170
	v_div_scale_f32 v147, vcc, 1.0, v166, 1.0
	v_mul_f32_e32 v161, v147, v170
	v_fma_f32 v168, -v145, v161, v147
	v_fmac_f32_e32 v161, v168, v170
	v_div_scale_f32 v168, s[0:1], v167, v167, 1.0
	v_rcp_f32_e32 v169, v168
	v_exp_f32_e32 v164, v148
	v_mul_f32_e32 v148, 0x3fb8aa3b, v120
	v_exp_f32_e32 v163, v148
	v_fma_f32 v145, -v145, v161, v147
	v_fma_f32 v147, -v168, v169, 1.0
	v_div_fmas_f32 v145, v145, v170, v161
	v_fmac_f32_e32 v169, v147, v169
	v_div_scale_f32 v147, vcc, 1.0, v167, 1.0
	v_mul_f32_e32 v161, v147, v169
	v_fma_f32 v170, -v168, v161, v147
	v_pk_add_f32 v[162:163], v[162:163], 1.0 op_sel_hi:[1,0]
	v_fmac_f32_e32 v161, v170, v169
	v_div_scale_f32 v170, s[0:1], v163, v163, v144
	v_rcp_f32_e32 v171, v170
	v_fma_f32 v147, -v168, v161, v147
	v_div_fmas_f32 v161, v147, v169, v161
	v_mul_f32_e32 v148, 0x3fb8aa3b, v121
	v_fma_f32 v147, -v170, v171, 1.0
	v_fmac_f32_e32 v171, v147, v171
	v_div_scale_f32 v147, vcc, v144, v163, v144
	v_mul_f32_e32 v168, v147, v171
	v_fma_f32 v169, -v170, v168, v147
	v_fmac_f32_e32 v168, v169, v171
	v_rcp_f32_e32 v172, v162
	v_fma_f32 v147, -v170, v168, v147
	v_div_fmas_f32 v168, v147, v171, v168
	v_exp_f32_e32 v165, v148
	v_mul_f32_e32 v169, v146, v172
	v_sub_f32_e32 v147, 1.0, v169
	v_cmp_gt_f32_e64 s[0:1], s14, v147
	v_mul_f32_e32 v148, 0x3fb8aa3b, v114
	v_mul_f32_e32 v149, 0x3fb8aa3b, v116
	v_cndmask_b32_e64 v162, 0, 32, s[0:1]
	v_ldexp_f32 v147, v147, v162
	v_log_f32_e32 v170, v147
	v_div_fixup_f32 v147, v145, v166, 1.0
	v_div_fixup_f32 v145, v161, v167, 1.0
	v_div_fixup_f32 v161, v168, v163, v144
	v_mul_f32_e32 v162, 0x3f317217, v170
	v_fma_f32 v166, v170, s9, -v162
	v_pk_add_f32 v[162:163], v[164:165], 1.0 op_sel_hi:[1,0]
	v_fmac_f32_e32 v166, 0x3377d1cf, v170
	v_rcp_f32_e32 v165, v163
	v_fmac_f32_e32 v166, 0x3f317217, v170
	v_cmp_lt_f32_e64 vcc, |v170|, s15
	v_exp_f32_e32 v150, v148
	s_nop 0
	v_cndmask_b32_e32 v166, v170, v166, vcc
	v_rcp_f32_e32 v171, v162
	v_mul_f32_e32 v163, v145, v165
	v_mul_f32_e32 v162, v147, v171
	v_sub_f32_e32 v165, 1.0, v162
	v_cmp_gt_f32_e32 vcc, s14, v165
	v_cndmask_b32_e64 v171, v162, 0, s[4:5]
	v_cndmask_b32_e64 v172, v163, 0, s[4:5]
	v_cndmask_b32_e64 v167, 0, 32, vcc
	v_ldexp_f32 v165, v165, v167
	v_log_f32_e32 v165, v165
	v_cndmask_b32_e64 v167, 0, v131, s[0:1]
	v_sub_f32_e32 v166, v166, v167
	v_sub_f32_e32 v167, 1.0, v161
	v_cmp_gt_f32_e64 s[0:1], s14, v167
	v_mul_f32_e32 v164, 0x3f317217, v165
	v_fma_f32 v164, v165, s9, -v164
	v_cndmask_b32_e64 v168, 0, 32, s[0:1]
	v_ldexp_f32 v167, v167, v168
	v_fmac_f32_e32 v164, 0x3377d1cf, v165
	v_log_f32_e32 v167, v167
	v_fmac_f32_e32 v164, 0x3f317217, v165
	v_cmp_lt_f32_e64 s[2:3], |v165|, s15
	v_sub_f32_e32 v168, 1.0, v163
	v_exp_f32_e32 v151, v149
	v_cndmask_b32_e64 v164, v165, v164, s[2:3]
	v_cndmask_b32_e32 v165, 0, v131, vcc
	v_cmp_gt_f32_e32 vcc, s14, v168
	v_sub_f32_e32 v164, v164, v165
	v_mul_f32_e32 v165, 0x3f317217, v167
	v_cndmask_b32_e64 v170, 0, 32, vcc
	v_ldexp_f32 v168, v168, v170
	v_fma_f32 v165, v167, s9, -v165
	v_log_f32_e32 v168, v168
	v_fmac_f32_e32 v165, 0x3377d1cf, v167
	v_fmac_f32_e32 v165, 0x3f317217, v167
	v_cmp_lt_f32_e64 s[2:3], |v167|, s15
	v_pk_add_f32 v[150:151], v[150:151], 1.0 op_sel_hi:[1,0]
	v_mul_f32_e32 v148, 0x3fb8aa3b, v115
	v_cndmask_b32_e64 v165, v167, v165, s[2:3]
	v_cndmask_b32_e64 v167, 0, v131, s[0:1]
	v_sub_f32_e32 v165, v165, v167
	v_mul_f32_e32 v167, 0x3f317217, v168
	v_fma_f32 v167, v168, s9, -v167
	v_fmac_f32_e32 v167, 0x3377d1cf, v168
	v_fmac_f32_e32 v167, 0x3f317217, v168
	v_cmp_lt_f32_e64 s[0:1], |v168|, s15
	v_mul_f32_e32 v149, 0x3fb8aa3b, v117
	v_exp_f32_e32 v148, v148
	v_cndmask_b32_e64 v167, v168, v167, s[0:1]
	v_cndmask_b32_e32 v168, 0, v131, vcc
	v_sub_f32_e32 v167, v167, v168
	v_rcp_f32_e32 v170, v142
	v_exp_f32_e32 v149, v149
	v_cndmask_b32_e64 v161, v161, 0, s[4:5]
	v_cndmask_b32_e64 v169, v169, 0, s[4:5]
	v_rcp_f32_e32 v173, v143
	v_mov_b32_e32 v142, v170
	v_pk_add_f32 v[148:149], v[148:149], 1.0 op_sel_hi:[1,0]
	v_pk_add_f32 v[162:163], v[140:141], 1.0 op_sel_hi:[1,0]
	v_div_scale_f32 v141, s[0:1], v162, v162, 1.0
	v_rcp_f32_e32 v174, v141
	v_mov_b32_e32 v140, v173
	v_fma_f32 v143, -v141, v174, 1.0
	v_fmac_f32_e32 v174, v143, v174
	v_div_scale_f32 v143, vcc, 1.0, v162, 1.0
	v_mul_f32_e32 v168, v143, v174
	v_fma_f32 v170, -v141, v168, v143
	v_fmac_f32_e32 v168, v170, v174
	v_div_scale_f32 v170, s[0:1], v163, v163, 1.0
	v_rcp_f32_e32 v173, v170
	v_fma_f32 v141, -v141, v168, v143
	v_div_fmas_f32 v141, v141, v174, v168
	v_fma_f32 v143, -v170, v173, 1.0
	v_fmac_f32_e32 v173, v143, v173
	v_div_scale_f32 v143, vcc, 1.0, v163, 1.0
	v_mul_f32_e32 v168, v143, v173
	v_fma_f32 v174, -v170, v168, v143
	v_fmac_f32_e32 v168, v174, v173
	v_rcp_f32_e32 v175, v151
	v_fma_f32 v143, -v170, v168, v143
	v_div_fmas_f32 v168, v143, v173, v168
	v_rcp_f32_e32 v176, v150
	v_mul_f32_e32 v151, v140, v175
	v_mul_f32_e32 v150, v142, v176
	v_sub_f32_e32 v143, 1.0, v150
	v_cmp_gt_f32_e64 s[0:1], s14, v143
	v_cndmask_b32_e64 v150, v150, 0, s[4:5]
	v_bfe_u32 v176, v171, 16, 1
	v_cndmask_b32_e64 v173, 0, 32, s[0:1]
	v_ldexp_f32 v143, v143, v173
	v_log_f32_e32 v173, v143
	v_div_fixup_f32 v143, v141, v162, 1.0
	v_div_fixup_f32 v141, v168, v163, 1.0
	v_rcp_f32_e32 v168, v149
	v_mul_f32_e32 v162, 0x3f317217, v173
	v_fma_f32 v162, v173, s9, -v162
	v_fmac_f32_e32 v162, 0x3377d1cf, v173
	v_fmac_f32_e32 v162, 0x3f317217, v173
	v_cmp_lt_f32_e64 vcc, |v173|, s15
	s_nop 1
	v_cndmask_b32_e32 v162, v173, v162, vcc
	v_rcp_f32_e32 v175, v148
	v_mul_f32_e32 v149, v141, v168
	v_mul_f32_e32 v148, v143, v175
	v_sub_f32_e32 v168, 1.0, v148
	v_cmp_gt_f32_e32 vcc, s14, v168
	v_cndmask_b32_e64 v148, v148, 0, s[4:5]
	v_bfe_u32 v175, v172, 16, 1
	v_cndmask_b32_e64 v170, 0, 32, vcc
	v_ldexp_f32 v168, v168, v170
	v_log_f32_e32 v168, v168
	v_cndmask_b32_e64 v170, 0, v131, s[0:1]
	v_sub_f32_e32 v162, v162, v170
	v_sub_f32_e32 v170, 1.0, v151
	v_cmp_gt_f32_e64 s[0:1], s14, v170
	v_mul_f32_e32 v163, 0x3f317217, v168
	v_fma_f32 v163, v168, s9, -v163
	v_cndmask_b32_e64 v173, 0, 32, s[0:1]
	v_ldexp_f32 v170, v170, v173
	v_fmac_f32_e32 v163, 0x3377d1cf, v168
	v_log_f32_e32 v170, v170
	v_fmac_f32_e32 v163, 0x3f317217, v168
	v_cmp_lt_f32_e64 s[2:3], |v168|, s15
	v_sub_f32_e32 v173, 1.0, v149
	v_cndmask_b32_e64 v149, v149, 0, s[4:5]
	v_cndmask_b32_e64 v163, v168, v163, s[2:3]
	v_cndmask_b32_e32 v168, 0, v131, vcc
	v_cmp_gt_f32_e32 vcc, s14, v173
	v_sub_f32_e32 v163, v163, v168
	v_mul_f32_e32 v168, 0x3f317217, v170
	v_cndmask_b32_e64 v174, 0, 32, vcc
	v_ldexp_f32 v173, v173, v174
	v_fma_f32 v168, v170, s9, -v168
	v_log_f32_e32 v173, v173
	v_fmac_f32_e32 v168, 0x3377d1cf, v170
	v_fmac_f32_e32 v168, 0x3f317217, v170
	v_cmp_lt_f32_e64 s[2:3], |v170|, s15
	v_cndmask_b32_e64 v151, v151, 0, s[4:5]
	v_bfe_u32 v174, v148, 16, 1
	v_cndmask_b32_e64 v168, v170, v168, s[2:3]
	v_cndmask_b32_e64 v170, 0, v131, s[0:1]
	v_sub_f32_e32 v168, v168, v170
	v_mul_f32_e32 v170, 0x3f317217, v173
	v_fma_f32 v170, v173, s9, -v170
	v_fmac_f32_e32 v170, 0x3377d1cf, v173
	v_fmac_f32_e32 v170, 0x3f317217, v173
	v_cmp_lt_f32_e64 s[0:1], |v173|, s15
	v_add3_u32 v171, v171, v176, s16
	v_add3_u32 v172, v172, v175, s16
	v_cndmask_b32_e64 v170, v173, v170, s[0:1]
	v_cndmask_b32_e32 v173, 0, v131, vcc
	v_sub_f32_e32 v170, v170, v173
	v_bfe_u32 v173, v149, 16, 1
	v_add3_u32 v148, v148, v174, s16
	v_add3_u32 v149, v149, v173, s16
	v_bfe_u32 v173, v169, 16, 1
	v_bfe_u32 v174, v161, 16, 1
	v_bfe_u32 v175, v150, 16, 1
	v_bfe_u32 v176, v151, 16, 1
	v_add3_u32 v151, v151, v176, s16
	v_add3_u32 v150, v150, v175, s16
	v_add3_u32 v161, v161, v174, s16
	v_add3_u32 v169, v169, v173, s16
	v_lshrrev_b32_e32 v169, 16, v169
	v_lshrrev_b32_e32 v161, 16, v161
	v_lshrrev_b32_e32 v150, 16, v150
	v_lshrrev_b32_e32 v151, 16, v151
	v_and_or_b32 v151, v149, s17, v151
	v_and_or_b32 v150, v148, s17, v150
	v_and_or_b32 v149, v172, s17, v161
	v_and_or_b32 v148, v171, s17, v169
	global_store_dwordx4 v[138:139], v[148:151], off offset:256
	v_cndmask_b32_e64 v138, v166, 0, s[4:5]
	v_bfe_u32 v139, v138, 16, 1
	v_add3_u32 v138, v138, v139, s16
	v_cndmask_b32_e64 v139, v164, 0, s[4:5]
	v_bfe_u32 v148, v139, 16, 1
	v_lshrrev_b32_e32 v138, 16, v138
	v_add3_u32 v139, v139, v148, s16
	v_and_or_b32 v148, v139, s17, v138
	v_cndmask_b32_e64 v138, v165, 0, s[4:5]
	v_bfe_u32 v139, v138, 16, 1
	v_add3_u32 v138, v138, v139, s16
	v_cndmask_b32_e64 v139, v167, 0, s[4:5]
	v_bfe_u32 v149, v139, 16, 1
	v_lshrrev_b32_e32 v138, 16, v138
	v_add3_u32 v139, v139, v149, s16
	v_and_or_b32 v149, v139, s17, v138
	v_cndmask_b32_e64 v138, v162, 0, s[4:5]
	v_bfe_u32 v139, v138, 16, 1
	v_add3_u32 v138, v138, v139, s16
	v_cndmask_b32_e64 v139, v163, 0, s[4:5]
	v_bfe_u32 v150, v139, 16, 1
	v_lshrrev_b32_e32 v138, 16, v138
	v_add3_u32 v139, v139, v150, s16
	v_and_or_b32 v150, v139, s17, v138
	v_cndmask_b32_e64 v138, v168, 0, s[4:5]
	v_bfe_u32 v139, v138, 16, 1
	v_add3_u32 v138, v138, v139, s16
	v_cndmask_b32_e64 v139, v170, 0, s[4:5]
	v_bfe_u32 v151, v139, 16, 1
	v_lshrrev_b32_e32 v138, 16, v138
	v_add3_u32 v139, v139, v151, s16
	v_and_or_b32 v151, v139, s17, v138
	global_store_dwordx4 v[136:137], v[148:151], off offset:256
	v_mul_f32_e32 v161, 0x3fb8aa3b, v106
	v_exp_f32_e32 v162, v161
	v_mul_f32_e32 v149, 0x3fb8aa3b, v111
	v_mul_f32_e32 v148, 0x3fb8aa3b, v110
	v_exp_f32_e32 v150, v149
	v_mul_f32_e32 v149, 0x3fb8aa3b, v112
	v_exp_f32_e32 v148, v148
	v_exp_f32_e32 v149, v149
	v_mul_f32_e32 v161, 0x3fb8aa3b, v107
	v_or_b32_e32 v136, 16, v130
	v_exp_f32_e32 v164, v161
	v_pk_add_f32 v[148:149], v[148:149], 1.0 op_sel_hi:[1,0]
	v_mul_f32_e32 v161, 0x3fb8aa3b, v108
	v_div_scale_f32 v165, s[4:5], v149, v149, v157
	v_rcp_f32_e32 v166, v165
	v_cmp_gt_i32_e32 vcc, s20, v136
	v_exp_f32_e32 v163, v161
	v_mul_f32_e32 v151, 0x3fb8aa3b, v113
	v_fma_f32 v161, -v165, v166, 1.0
	v_cndmask_b32_e64 v137, v154, 0, vcc
	v_fmac_f32_e32 v166, v161, v166
	v_div_scale_f32 v161, vcc, v157, v149, v157
	v_mul_f32_e32 v167, v161, v166
	v_fma_f32 v168, -v165, v167, v161
	v_fmac_f32_e32 v167, v168, v166
	v_rcp_f32_e32 v169, v148
	v_fma_f32 v161, -v165, v167, v161
	v_div_fmas_f32 v161, v161, v166, v167
	v_exp_f32_e32 v151, v151
	v_mul_f32_e32 v166, v156, v169
	v_sub_f32_e32 v148, 1.0, v166
	v_cmp_gt_f32_e64 s[4:5], s14, v148
	v_div_fixup_f32 v161, v161, v149, v157
	v_add_u32_e32 v137, v137, v136
	v_cndmask_b32_e64 v165, 0, 32, s[4:5]
	v_ldexp_f32 v148, v148, v165
	v_log_f32_e32 v167, v148
	v_mul_f32_e32 v148, 0x3fb8aa3b, v109
	v_exp_f32_e32 v165, v148
	v_cmp_gt_i32_e64 s[0:1], s19, v136
	v_mul_f32_e32 v148, 0x3f317217, v167
	v_fma_f32 v168, v167, s9, -v148
	v_pk_add_f32 v[148:149], v[150:151], 1.0 op_sel_hi:[1,0]
	v_fmac_f32_e32 v168, 0x3377d1cf, v167
	v_rcp_f32_e32 v151, v149
	v_fmac_f32_e32 v168, 0x3f317217, v167
	v_cmp_lt_f32_e64 vcc, |v167|, s15
	v_cmp_gt_i32_e64 s[2:3], s18, v137
	v_ashrrev_i32_e32 v137, 31, v136
	v_cndmask_b32_e32 v167, v167, v168, vcc
	v_rcp_f32_e32 v171, v148
	v_mul_f32_e32 v150, v158, v151
	v_mul_f32_e32 v151, v155, v171
	v_sub_f32_e32 v148, 1.0, v151
	v_cmp_gt_f32_e32 vcc, s14, v148
	v_lshlrev_b64 v[136:137], 10, v[136:137]
	v_lshl_add_u64 v[138:139], v[132:133], 0, v[136:137]
	v_cndmask_b32_e64 v168, 0, 32, vcc
	v_ldexp_f32 v148, v148, v168
	v_log_f32_e32 v148, v148
	v_cndmask_b32_e64 v168, 0, v131, s[4:5]
	v_sub_f32_e32 v167, v167, v168
	v_sub_f32_e32 v168, 1.0, v161
	v_mul_f32_e32 v149, 0x3f317217, v148
	v_fma_f32 v149, v148, s9, -v149
	v_cmp_gt_f32_e64 s[4:5], s14, v168
	v_fmac_f32_e32 v149, 0x3377d1cf, v148
	v_fmac_f32_e32 v149, 0x3f317217, v148
	v_cndmask_b32_e64 v169, 0, 32, s[4:5]
	v_ldexp_f32 v168, v168, v169
	v_cmp_lt_f32_e64 s[6:7], |v148|, s15
	v_log_f32_e32 v168, v168
	v_lshl_add_u64 v[136:137], v[134:135], 0, v[136:137]
	v_cndmask_b32_e64 v148, v148, v149, s[6:7]
	v_cndmask_b32_e32 v149, 0, v131, vcc
	v_sub_f32_e32 v169, v148, v149
	v_sub_f32_e32 v149, 1.0, v150
	v_cmp_gt_f32_e32 vcc, s14, v149
	v_mul_f32_e32 v148, 0x3f317217, v168
	v_fma_f32 v148, v168, s9, -v148
	v_cndmask_b32_e64 v170, 0, 32, vcc
	v_ldexp_f32 v149, v149, v170
	v_log_f32_e32 v149, v149
	v_fmac_f32_e32 v148, 0x3377d1cf, v168
	v_fmac_f32_e32 v148, 0x3f317217, v168
	v_cmp_lt_f32_e64 s[6:7], |v168|, s15
	s_nop 1
	v_cndmask_b32_e64 v148, v168, v148, s[6:7]
	v_cndmask_b32_e64 v168, 0, v131, s[4:5]
	v_sub_f32_e32 v168, v148, v168
	v_mul_f32_e32 v148, 0x3f317217, v149
	v_fma_f32 v148, v149, s9, -v148
	v_fmac_f32_e32 v148, 0x3377d1cf, v149
	v_fmac_f32_e32 v148, 0x3f317217, v149
	v_cmp_lt_f32_e64 s[4:5], |v149|, s15
	s_nop 1
	v_cndmask_b32_e64 v148, v149, v148, s[4:5]
	v_cndmask_b32_e32 v149, 0, v131, vcc
	v_sub_f32_e32 v170, v148, v149
	v_pk_add_f32 v[148:149], v[162:163], 1.0 op_sel_hi:[1,0]
	s_nop 0
	v_rcp_f32_e32 v163, v149
	s_and_b64 s[4:5], s[0:1], s[2:3]
	v_cndmask_b32_e64 v151, v151, 0, s[4:5]
	v_cndmask_b32_e64 v150, v150, 0, s[4:5]
	v_rcp_f32_e32 v174, v148
	v_mul_f32_e32 v162, v152, v163
	v_mul_f32_e32 v163, v159, v174
	v_sub_f32_e32 v148, 1.0, v163
	v_cmp_gt_f32_e64 s[0:1], s14, v148
	v_cndmask_b32_e64 v161, v161, 0, s[4:5]
	v_cndmask_b32_e64 v166, v166, 0, s[4:5]
	v_cndmask_b32_e64 v171, 0, 32, s[0:1]
	v_ldexp_f32 v148, v148, v171
	v_log_f32_e32 v171, v148
	v_cndmask_b32_e64 v163, v163, 0, s[4:5]
	v_bfe_u32 v176, v151, 16, 1
	v_add3_u32 v176, v151, v176, s16
	v_mul_f32_e32 v148, 0x3f317217, v171
	v_fma_f32 v172, v171, s9, -v148
	v_pk_add_f32 v[148:149], v[164:165], 1.0 op_sel_hi:[1,0]
	v_fmac_f32_e32 v172, 0x3377d1cf, v171
	v_rcp_f32_e32 v165, v149
	v_fmac_f32_e32 v172, 0x3f317217, v171
	v_cmp_lt_f32_e64 vcc, |v171|, s15
	v_bfe_u32 v151, v161, 16, 1
	v_add3_u32 v151, v161, v151, s16
	v_cndmask_b32_e32 v171, v171, v172, vcc
	v_rcp_f32_e32 v175, v148
	v_mul_f32_e32 v149, v153, v165
	v_mul_f32_e32 v148, v160, v175
	v_sub_f32_e32 v165, 1.0, v148
	v_cmp_gt_f32_e32 vcc, s14, v165
	v_cndmask_b32_e64 v148, v148, 0, s[4:5]
	v_bfe_u32 v175, v150, 16, 1
	v_cndmask_b32_e64 v172, 0, 32, vcc
	v_ldexp_f32 v165, v165, v172
	v_log_f32_e32 v165, v165
	v_cndmask_b32_e64 v172, 0, v131, s[0:1]
	v_sub_f32_e32 v171, v171, v172
	v_sub_f32_e32 v172, 1.0, v162
	v_cmp_gt_f32_e64 s[0:1], s14, v172
	v_mul_f32_e32 v164, 0x3f317217, v165
	v_fma_f32 v164, v165, s9, -v164
	v_cndmask_b32_e64 v173, 0, 32, s[0:1]
	v_ldexp_f32 v172, v172, v173
	v_fmac_f32_e32 v164, 0x3377d1cf, v165
	v_log_f32_e32 v172, v172
	v_fmac_f32_e32 v164, 0x3f317217, v165
	v_cmp_lt_f32_e64 s[2:3], |v165|, s15
	v_sub_f32_e32 v173, 1.0, v149
	v_cndmask_b32_e64 v149, v149, 0, s[4:5]
	v_cndmask_b32_e64 v164, v165, v164, s[2:3]
	v_cndmask_b32_e32 v165, 0, v131, vcc
	v_cmp_gt_f32_e32 vcc, s14, v173
	v_sub_f32_e32 v164, v164, v165
	v_mul_f32_e32 v165, 0x3f317217, v172
	v_cndmask_b32_e64 v174, 0, 32, vcc
	v_ldexp_f32 v173, v173, v174
	v_fma_f32 v165, v172, s9, -v165
	v_log_f32_e32 v173, v173
	v_fmac_f32_e32 v165, 0x3377d1cf, v172
	v_fmac_f32_e32 v165, 0x3f317217, v172
	v_cmp_lt_f32_e64 s[2:3], |v172|, s15
	v_cndmask_b32_e64 v162, v162, 0, s[4:5]
	v_bfe_u32 v174, v148, 16, 1
	v_cndmask_b32_e64 v165, v172, v165, s[2:3]
	v_cndmask_b32_e64 v172, 0, v131, s[0:1]
	v_sub_f32_e32 v165, v165, v172
	v_mul_f32_e32 v172, 0x3f317217, v173
	v_fma_f32 v172, v173, s9, -v172
	v_fmac_f32_e32 v172, 0x3377d1cf, v173
	v_fmac_f32_e32 v172, 0x3f317217, v173
	v_cmp_lt_f32_e64 s[0:1], |v173|, s15
	v_add3_u32 v175, v150, v175, s16
	v_add3_u32 v148, v148, v174, s16
	v_cndmask_b32_e64 v172, v173, v172, s[0:1]
	v_cndmask_b32_e32 v173, 0, v131, vcc
	v_sub_f32_e32 v172, v172, v173
	v_bfe_u32 v173, v149, 16, 1
	v_add3_u32 v149, v149, v173, s16
	v_bfe_u32 v150, v166, 16, 1
	v_bfe_u32 v173, v163, 16, 1
	v_bfe_u32 v174, v162, 16, 1
	v_add3_u32 v162, v162, v174, s16
	v_add3_u32 v163, v163, v173, s16
	v_add3_u32 v150, v166, v150, s16
	v_lshrrev_b32_e32 v161, 16, v150
	v_lshrrev_b32_e32 v166, 16, v151
	v_lshrrev_b32_e32 v150, 16, v163
	v_lshrrev_b32_e32 v151, 16, v162
	v_and_or_b32 v151, v149, s17, v151
	v_and_or_b32 v150, v148, s17, v150
	v_and_or_b32 v149, v175, s17, v166
	v_and_or_b32 v148, v176, s17, v161
	global_store_dwordx4 v[138:139], v[148:151], off
	s_nop 1
	v_cndmask_b32_e64 v148, v167, 0, s[4:5]
	v_bfe_u32 v149, v148, 16, 1
	v_add3_u32 v148, v148, v149, s16
	v_cndmask_b32_e64 v149, v169, 0, s[4:5]
	v_bfe_u32 v150, v149, 16, 1
	v_lshrrev_b32_e32 v148, 16, v148
	v_add3_u32 v149, v149, v150, s16
	v_and_or_b32 v148, v149, s17, v148
	v_cndmask_b32_e64 v149, v168, 0, s[4:5]
	v_bfe_u32 v150, v149, 16, 1
	v_add3_u32 v149, v149, v150, s16
	v_cndmask_b32_e64 v150, v170, 0, s[4:5]
	v_bfe_u32 v151, v150, 16, 1
	v_lshrrev_b32_e32 v149, 16, v149
	v_add3_u32 v150, v150, v151, s16
	v_and_or_b32 v149, v150, s17, v149
	v_cndmask_b32_e64 v150, v171, 0, s[4:5]
	v_bfe_u32 v151, v150, 16, 1
	v_add3_u32 v150, v150, v151, s16
	v_cndmask_b32_e64 v151, v164, 0, s[4:5]
	v_bfe_u32 v161, v151, 16, 1
	v_lshrrev_b32_e32 v150, 16, v150
	v_add3_u32 v151, v151, v161, s16
	v_and_or_b32 v150, v151, s17, v150
	v_cndmask_b32_e64 v151, v165, 0, s[4:5]
	v_bfe_u32 v161, v151, 16, 1
	v_add3_u32 v151, v151, v161, s16
	v_cndmask_b32_e64 v161, v172, 0, s[4:5]
	v_bfe_u32 v162, v161, 16, 1
	v_lshrrev_b32_e32 v151, 16, v151
	v_add3_u32 v161, v161, v162, s16
	v_and_or_b32 v151, v161, s17, v151
	global_store_dwordx4 v[136:137], v[148:151], off
	v_mul_f32_e32 v161, 0x3fb8aa3b, v98
	v_exp_f32_e32 v162, v161
	v_mul_f32_e32 v149, 0x3fb8aa3b, v103
	v_mul_f32_e32 v148, 0x3fb8aa3b, v102
	v_exp_f32_e32 v150, v149
	v_mul_f32_e32 v149, 0x3fb8aa3b, v104
	v_exp_f32_e32 v148, v148
	v_exp_f32_e32 v149, v149
	v_mul_f32_e32 v161, 0x3fb8aa3b, v99
	v_exp_f32_e32 v164, v161
	v_mul_f32_e32 v161, 0x3fb8aa3b, v100
	v_pk_add_f32 v[148:149], v[148:149], 1.0 op_sel_hi:[1,0]
	v_exp_f32_e32 v163, v161
	v_rcp_f32_e32 v166, v149
	v_mul_f32_e32 v151, 0x3fb8aa3b, v105
	v_exp_f32_e32 v151, v151
	v_rcp_f32_e32 v169, v148
	v_mul_f32_e32 v161, v144, v166
	v_mul_f32_e32 v166, v146, v169
	v_sub_f32_e32 v148, 1.0, v166
	v_cmp_gt_f32_e64 s[0:1], s14, v148
	v_cndmask_b32_e64 v166, v166, 0, s[4:5]
	s_nop 0
	v_cndmask_b32_e64 v165, 0, 32, s[0:1]
	v_ldexp_f32 v148, v148, v165
	v_log_f32_e32 v167, v148
	v_mul_f32_e32 v148, 0x3fb8aa3b, v101
	v_exp_f32_e32 v165, v148
	v_mul_f32_e32 v148, 0x3f317217, v167
	v_fma_f32 v168, v167, s9, -v148
	v_pk_add_f32 v[148:149], v[150:151], 1.0 op_sel_hi:[1,0]
	v_fmac_f32_e32 v168, 0x3377d1cf, v167
	v_rcp_f32_e32 v151, v149
	v_fmac_f32_e32 v168, 0x3f317217, v167
	v_cmp_lt_f32_e64 vcc, |v167|, s15
	s_nop 1
	v_cndmask_b32_e32 v167, v167, v168, vcc
	v_rcp_f32_e32 v171, v148
	v_mul_f32_e32 v150, v145, v151
	v_mul_f32_e32 v151, v147, v171
	v_sub_f32_e32 v148, 1.0, v151
	v_cmp_gt_f32_e32 vcc, s14, v148
	v_cndmask_b32_e64 v151, v151, 0, s[4:5]
	v_bfe_u32 v176, v151, 16, 1
	v_cndmask_b32_e64 v168, 0, 32, vcc
	v_ldexp_f32 v148, v148, v168
	v_log_f32_e32 v148, v148
	v_cndmask_b32_e64 v168, 0, v131, s[0:1]
	v_sub_f32_e32 v167, v167, v168
	v_sub_f32_e32 v168, 1.0, v161
	v_mul_f32_e32 v149, 0x3f317217, v148
	v_fma_f32 v149, v148, s9, -v149
	v_cmp_gt_f32_e64 s[0:1], s14, v168
	v_fmac_f32_e32 v149, 0x3377d1cf, v148
	v_fmac_f32_e32 v149, 0x3f317217, v148
	v_cndmask_b32_e64 v169, 0, 32, s[0:1]
	v_ldexp_f32 v168, v168, v169
	v_cmp_lt_f32_e64 s[2:3], |v148|, s15
	v_log_f32_e32 v168, v168
	v_cndmask_b32_e64 v161, v161, 0, s[4:5]
	v_cndmask_b32_e64 v148, v148, v149, s[2:3]
	v_cndmask_b32_e32 v149, 0, v131, vcc
	v_sub_f32_e32 v169, v148, v149
	v_sub_f32_e32 v149, 1.0, v150
	v_cmp_gt_f32_e32 vcc, s14, v149
	v_mul_f32_e32 v148, 0x3f317217, v168
	v_fma_f32 v148, v168, s9, -v148
	v_cndmask_b32_e64 v170, 0, 32, vcc
	v_ldexp_f32 v149, v149, v170
	v_log_f32_e32 v149, v149
	v_fmac_f32_e32 v148, 0x3377d1cf, v168
	v_fmac_f32_e32 v148, 0x3f317217, v168
	v_cmp_lt_f32_e64 s[2:3], |v168|, s15
	v_cndmask_b32_e32 v171, 0, v131, vcc
	v_cndmask_b32_e64 v150, v150, 0, s[4:5]
	v_cndmask_b32_e64 v148, v168, v148, s[2:3]
	v_cndmask_b32_e64 v168, 0, v131, s[0:1]
	v_sub_f32_e32 v168, v148, v168
	v_mul_f32_e32 v148, 0x3f317217, v149
	v_fma_f32 v148, v149, s9, -v148
	v_fmac_f32_e32 v148, 0x3377d1cf, v149
	v_fmac_f32_e32 v148, 0x3f317217, v149
	v_cmp_lt_f32_e64 s[0:1], |v149|, s15
	v_add3_u32 v176, v151, v176, s16
	v_bfe_u32 v151, v161, 16, 1
	v_cndmask_b32_e64 v170, v149, v148, s[0:1]
	v_pk_add_f32 v[148:149], v[162:163], 1.0 op_sel_hi:[1,0]
	v_sub_f32_e32 v170, v170, v171
	v_rcp_f32_e32 v163, v149
	v_add3_u32 v151, v161, v151, s16
	v_rcp_f32_e32 v174, v148
	v_mul_f32_e32 v162, v140, v163
	v_mul_f32_e32 v163, v142, v174
	v_sub_f32_e32 v148, 1.0, v163
	v_cmp_gt_f32_e64 s[0:1], s14, v148
	v_cndmask_b32_e64 v163, v163, 0, s[4:5]
	s_nop 0
	v_cndmask_b32_e64 v171, 0, 32, s[0:1]
	v_ldexp_f32 v148, v148, v171
	v_log_f32_e32 v171, v148
	s_nop 0
	v_mul_f32_e32 v148, 0x3f317217, v171
	v_fma_f32 v172, v171, s9, -v148
	v_pk_add_f32 v[148:149], v[164:165], 1.0 op_sel_hi:[1,0]
	v_fmac_f32_e32 v172, 0x3377d1cf, v171
	v_rcp_f32_e32 v165, v149
	v_fmac_f32_e32 v172, 0x3f317217, v171
	v_cmp_lt_f32_e64 vcc, |v171|, s15
	s_nop 1
	v_cndmask_b32_e32 v171, v171, v172, vcc
	v_rcp_f32_e32 v175, v148
	v_mul_f32_e32 v149, v141, v165
	v_mul_f32_e32 v148, v143, v175
	v_sub_f32_e32 v165, 1.0, v148
	v_cmp_gt_f32_e32 vcc, s14, v165
	v_cndmask_b32_e64 v148, v148, 0, s[4:5]
	v_bfe_u32 v175, v150, 16, 1
	v_cndmask_b32_e64 v172, 0, 32, vcc
	v_ldexp_f32 v165, v165, v172
	v_log_f32_e32 v165, v165
	v_cndmask_b32_e64 v172, 0, v131, s[0:1]
	v_sub_f32_e32 v171, v171, v172
	v_sub_f32_e32 v172, 1.0, v162
	v_cmp_gt_f32_e64 s[0:1], s14, v172
	v_mul_f32_e32 v164, 0x3f317217, v165
	v_fma_f32 v164, v165, s9, -v164
	v_cndmask_b32_e64 v173, 0, 32, s[0:1]
	v_ldexp_f32 v172, v172, v173
	v_fmac_f32_e32 v164, 0x3377d1cf, v165
	v_log_f32_e32 v172, v172
	v_fmac_f32_e32 v164, 0x3f317217, v165
	v_cmp_lt_f32_e64 s[2:3], |v165|, s15
	v_sub_f32_e32 v173, 1.0, v149
	v_cndmask_b32_e64 v149, v149, 0, s[4:5]
	v_cndmask_b32_e64 v164, v165, v164, s[2:3]
	v_cndmask_b32_e32 v165, 0, v131, vcc
	v_cmp_gt_f32_e32 vcc, s14, v173
	v_sub_f32_e32 v164, v164, v165
	v_mul_f32_e32 v165, 0x3f317217, v172
	v_cndmask_b32_e64 v174, 0, 32, vcc
	v_ldexp_f32 v173, v173, v174
	v_fma_f32 v165, v172, s9, -v165
	v_log_f32_e32 v173, v173
	v_fmac_f32_e32 v165, 0x3377d1cf, v172
	v_fmac_f32_e32 v165, 0x3f317217, v172
	v_cmp_lt_f32_e64 s[2:3], |v172|, s15
	v_cndmask_b32_e64 v162, v162, 0, s[4:5]
	v_bfe_u32 v174, v148, 16, 1
	v_cndmask_b32_e64 v165, v172, v165, s[2:3]
	v_cndmask_b32_e64 v172, 0, v131, s[0:1]
	v_sub_f32_e32 v165, v165, v172
	v_mul_f32_e32 v172, 0x3f317217, v173
	v_fma_f32 v172, v173, s9, -v172
	v_fmac_f32_e32 v172, 0x3377d1cf, v173
	v_fmac_f32_e32 v172, 0x3f317217, v173
	v_cmp_lt_f32_e64 s[0:1], |v173|, s15
	v_add3_u32 v175, v150, v175, s16
	v_add3_u32 v148, v148, v174, s16
	v_cndmask_b32_e64 v172, v173, v172, s[0:1]
	v_cndmask_b32_e32 v173, 0, v131, vcc
	v_sub_f32_e32 v172, v172, v173
	v_bfe_u32 v173, v149, 16, 1
	v_add3_u32 v149, v149, v173, s16
	v_bfe_u32 v150, v166, 16, 1
	v_bfe_u32 v173, v163, 16, 1
	v_bfe_u32 v174, v162, 16, 1
	v_add3_u32 v162, v162, v174, s16
	v_add3_u32 v163, v163, v173, s16
	v_add3_u32 v150, v166, v150, s16
	v_lshrrev_b32_e32 v161, 16, v150
	v_lshrrev_b32_e32 v166, 16, v151
	v_lshrrev_b32_e32 v150, 16, v163
	v_lshrrev_b32_e32 v151, 16, v162
	v_and_or_b32 v151, v149, s17, v151
	v_and_or_b32 v150, v148, s17, v150
	v_and_or_b32 v149, v175, s17, v166
	v_and_or_b32 v148, v176, s17, v161
	global_store_dwordx4 v[138:139], v[148:151], off offset:256
	v_cndmask_b32_e64 v138, v167, 0, s[4:5]
	v_bfe_u32 v139, v138, 16, 1
	v_add3_u32 v138, v138, v139, s16
	v_cndmask_b32_e64 v139, v169, 0, s[4:5]
	v_bfe_u32 v148, v139, 16, 1
	v_lshrrev_b32_e32 v138, 16, v138
	v_add3_u32 v139, v139, v148, s16
	v_and_or_b32 v148, v139, s17, v138
	v_cndmask_b32_e64 v138, v168, 0, s[4:5]
	v_bfe_u32 v139, v138, 16, 1
	v_add3_u32 v138, v138, v139, s16
	v_cndmask_b32_e64 v139, v170, 0, s[4:5]
	v_bfe_u32 v149, v139, 16, 1
	v_lshrrev_b32_e32 v138, 16, v138
	v_add3_u32 v139, v139, v149, s16
	v_and_or_b32 v149, v139, s17, v138
	v_cndmask_b32_e64 v138, v171, 0, s[4:5]
	v_bfe_u32 v139, v138, 16, 1
	v_add3_u32 v138, v138, v139, s16
	v_cndmask_b32_e64 v139, v164, 0, s[4:5]
	v_bfe_u32 v150, v139, 16, 1
	v_lshrrev_b32_e32 v138, 16, v138
	v_add3_u32 v139, v139, v150, s16
	v_and_or_b32 v150, v139, s17, v138
	v_cndmask_b32_e64 v138, v165, 0, s[4:5]
	v_bfe_u32 v139, v138, 16, 1
	v_add3_u32 v138, v138, v139, s16
	v_cndmask_b32_e64 v139, v172, 0, s[4:5]
	v_bfe_u32 v151, v139, 16, 1
	v_lshrrev_b32_e32 v138, 16, v138
	v_add3_u32 v139, v139, v151, s16
	v_and_or_b32 v151, v139, s17, v138
	global_store_dwordx4 v[136:137], v[148:151], off offset:256
	v_mul_f32_e32 v161, 0x3fb8aa3b, v90
	v_exp_f32_e32 v162, v161
	v_mul_f32_e32 v149, 0x3fb8aa3b, v95
	v_mul_f32_e32 v148, 0x3fb8aa3b, v94
	v_exp_f32_e32 v150, v149
	v_mul_f32_e32 v149, 0x3fb8aa3b, v96
	v_exp_f32_e32 v148, v148
	v_exp_f32_e32 v149, v149
	v_mul_f32_e32 v161, 0x3fb8aa3b, v91
	v_or_b32_e32 v136, 32, v130
	v_exp_f32_e32 v164, v161
	v_pk_add_f32 v[148:149], v[148:149], 1.0 op_sel_hi:[1,0]
	v_mul_f32_e32 v161, 0x3fb8aa3b, v92
	v_div_scale_f32 v165, s[4:5], v149, v149, v157
	v_rcp_f32_e32 v166, v165
	v_cmp_gt_i32_e32 vcc, s20, v136
	v_exp_f32_e32 v163, v161
	v_mul_f32_e32 v151, 0x3fb8aa3b, v97
	v_fma_f32 v161, -v165, v166, 1.0
	v_cndmask_b32_e64 v137, v154, 0, vcc
	v_fmac_f32_e32 v166, v161, v166
	v_div_scale_f32 v161, vcc, v157, v149, v157
	v_mul_f32_e32 v167, v161, v166
	v_fma_f32 v168, -v165, v167, v161
	v_fmac_f32_e32 v167, v168, v166
	v_rcp_f32_e32 v169, v148
	v_fma_f32 v161, -v165, v167, v161
	v_div_fmas_f32 v161, v161, v166, v167
	v_exp_f32_e32 v151, v151
	v_mul_f32_e32 v166, v156, v169
	v_sub_f32_e32 v148, 1.0, v166
	v_cmp_gt_f32_e64 s[4:5], s14, v148
	v_div_fixup_f32 v161, v161, v149, v157
	v_add_u32_e32 v137, v137, v136
	v_cndmask_b32_e64 v165, 0, 32, s[4:5]
	v_ldexp_f32 v148, v148, v165
	v_log_f32_e32 v167, v148
	v_mul_f32_e32 v148, 0x3fb8aa3b, v93
	v_exp_f32_e32 v165, v148
	v_cmp_gt_i32_e64 s[0:1], s19, v136
	v_mul_f32_e32 v148, 0x3f317217, v167
	v_fma_f32 v168, v167, s9, -v148
	v_pk_add_f32 v[148:149], v[150:151], 1.0 op_sel_hi:[1,0]
	v_fmac_f32_e32 v168, 0x3377d1cf, v167
	v_rcp_f32_e32 v151, v149
	v_fmac_f32_e32 v168, 0x3f317217, v167
	v_cmp_lt_f32_e64 vcc, |v167|, s15
	v_cmp_gt_i32_e64 s[2:3], s18, v137
	v_ashrrev_i32_e32 v137, 31, v136
	v_cndmask_b32_e32 v167, v167, v168, vcc
	v_rcp_f32_e32 v171, v148
	v_mul_f32_e32 v150, v158, v151
	v_mul_f32_e32 v151, v155, v171
	v_sub_f32_e32 v148, 1.0, v151
	v_cmp_gt_f32_e32 vcc, s14, v148
	v_lshlrev_b64 v[136:137], 10, v[136:137]
	v_lshl_add_u64 v[138:139], v[132:133], 0, v[136:137]
	v_cndmask_b32_e64 v168, 0, 32, vcc
	v_ldexp_f32 v148, v148, v168
	v_log_f32_e32 v148, v148
	v_cndmask_b32_e64 v168, 0, v131, s[4:5]
	v_sub_f32_e32 v167, v167, v168
	v_sub_f32_e32 v168, 1.0, v161
	v_mul_f32_e32 v149, 0x3f317217, v148
	v_fma_f32 v149, v148, s9, -v149
	v_cmp_gt_f32_e64 s[4:5], s14, v168
	v_fmac_f32_e32 v149, 0x3377d1cf, v148
	v_fmac_f32_e32 v149, 0x3f317217, v148
	v_cndmask_b32_e64 v169, 0, 32, s[4:5]
	v_ldexp_f32 v168, v168, v169
	v_cmp_lt_f32_e64 s[6:7], |v148|, s15
	v_log_f32_e32 v168, v168
	v_lshl_add_u64 v[136:137], v[134:135], 0, v[136:137]
	v_cndmask_b32_e64 v148, v148, v149, s[6:7]
	v_cndmask_b32_e32 v149, 0, v131, vcc
	v_sub_f32_e32 v169, v148, v149
	v_sub_f32_e32 v149, 1.0, v150
	v_cmp_gt_f32_e32 vcc, s14, v149
	v_mul_f32_e32 v148, 0x3f317217, v168
	v_fma_f32 v148, v168, s9, -v148
	v_cndmask_b32_e64 v170, 0, 32, vcc
	v_ldexp_f32 v149, v149, v170
	v_log_f32_e32 v149, v149
	v_fmac_f32_e32 v148, 0x3377d1cf, v168
	v_fmac_f32_e32 v148, 0x3f317217, v168
	v_cmp_lt_f32_e64 s[6:7], |v168|, s15
	s_nop 1
	v_cndmask_b32_e64 v148, v168, v148, s[6:7]
	v_cndmask_b32_e64 v168, 0, v131, s[4:5]
	v_sub_f32_e32 v168, v148, v168
	v_mul_f32_e32 v148, 0x3f317217, v149
	v_fma_f32 v148, v149, s9, -v148
	v_fmac_f32_e32 v148, 0x3377d1cf, v149
	v_fmac_f32_e32 v148, 0x3f317217, v149
	v_cmp_lt_f32_e64 s[4:5], |v149|, s15
	s_nop 1
	v_cndmask_b32_e64 v148, v149, v148, s[4:5]
	v_cndmask_b32_e32 v149, 0, v131, vcc
	v_sub_f32_e32 v170, v148, v149
	v_pk_add_f32 v[148:149], v[162:163], 1.0 op_sel_hi:[1,0]
	s_nop 0
	v_rcp_f32_e32 v163, v149
	s_and_b64 s[4:5], s[0:1], s[2:3]
	v_cndmask_b32_e64 v151, v151, 0, s[4:5]
	v_cndmask_b32_e64 v150, v150, 0, s[4:5]
	v_rcp_f32_e32 v174, v148
	v_mul_f32_e32 v162, v152, v163
	v_mul_f32_e32 v163, v159, v174
	v_sub_f32_e32 v148, 1.0, v163
	v_cmp_gt_f32_e64 s[0:1], s14, v148
	v_cndmask_b32_e64 v161, v161, 0, s[4:5]
	v_cndmask_b32_e64 v166, v166, 0, s[4:5]
	v_cndmask_b32_e64 v171, 0, 32, s[0:1]
	v_ldexp_f32 v148, v148, v171
	v_log_f32_e32 v171, v148
	v_cndmask_b32_e64 v163, v163, 0, s[4:5]
	v_bfe_u32 v176, v151, 16, 1
	v_add3_u32 v176, v151, v176, s16
	v_mul_f32_e32 v148, 0x3f317217, v171
	v_fma_f32 v172, v171, s9, -v148
	v_pk_add_f32 v[148:149], v[164:165], 1.0 op_sel_hi:[1,0]
	v_fmac_f32_e32 v172, 0x3377d1cf, v171
	v_rcp_f32_e32 v165, v149
	v_fmac_f32_e32 v172, 0x3f317217, v171
	v_cmp_lt_f32_e64 vcc, |v171|, s15
	v_bfe_u32 v151, v161, 16, 1
	v_add3_u32 v151, v161, v151, s16
	v_cndmask_b32_e32 v171, v171, v172, vcc
	v_rcp_f32_e32 v175, v148
	v_mul_f32_e32 v149, v153, v165
	v_mul_f32_e32 v148, v160, v175
	v_sub_f32_e32 v165, 1.0, v148
	v_cmp_gt_f32_e32 vcc, s14, v165
	v_cndmask_b32_e64 v148, v148, 0, s[4:5]
	v_bfe_u32 v175, v150, 16, 1
	v_cndmask_b32_e64 v172, 0, 32, vcc
	v_ldexp_f32 v165, v165, v172
	v_log_f32_e32 v165, v165
	v_cndmask_b32_e64 v172, 0, v131, s[0:1]
	v_sub_f32_e32 v171, v171, v172
	v_sub_f32_e32 v172, 1.0, v162
	v_cmp_gt_f32_e64 s[0:1], s14, v172
	v_mul_f32_e32 v164, 0x3f317217, v165
	v_fma_f32 v164, v165, s9, -v164
	v_cndmask_b32_e64 v173, 0, 32, s[0:1]
	v_ldexp_f32 v172, v172, v173
	v_fmac_f32_e32 v164, 0x3377d1cf, v165
	v_log_f32_e32 v172, v172
	v_fmac_f32_e32 v164, 0x3f317217, v165
	v_cmp_lt_f32_e64 s[2:3], |v165|, s15
	v_sub_f32_e32 v173, 1.0, v149
	v_cndmask_b32_e64 v149, v149, 0, s[4:5]
	v_cndmask_b32_e64 v164, v165, v164, s[2:3]
	v_cndmask_b32_e32 v165, 0, v131, vcc
	v_cmp_gt_f32_e32 vcc, s14, v173
	v_sub_f32_e32 v164, v164, v165
	v_mul_f32_e32 v165, 0x3f317217, v172
	v_cndmask_b32_e64 v174, 0, 32, vcc
	v_ldexp_f32 v173, v173, v174
	v_fma_f32 v165, v172, s9, -v165
	v_log_f32_e32 v173, v173
	v_fmac_f32_e32 v165, 0x3377d1cf, v172
	v_fmac_f32_e32 v165, 0x3f317217, v172
	v_cmp_lt_f32_e64 s[2:3], |v172|, s15
	v_cndmask_b32_e64 v162, v162, 0, s[4:5]
	v_bfe_u32 v174, v148, 16, 1
	v_cndmask_b32_e64 v165, v172, v165, s[2:3]
	v_cndmask_b32_e64 v172, 0, v131, s[0:1]
	v_sub_f32_e32 v165, v165, v172
	v_mul_f32_e32 v172, 0x3f317217, v173
	v_fma_f32 v172, v173, s9, -v172
	v_fmac_f32_e32 v172, 0x3377d1cf, v173
	v_fmac_f32_e32 v172, 0x3f317217, v173
	v_cmp_lt_f32_e64 s[0:1], |v173|, s15
	v_add3_u32 v175, v150, v175, s16
	v_add3_u32 v148, v148, v174, s16
	v_cndmask_b32_e64 v172, v173, v172, s[0:1]
	v_cndmask_b32_e32 v173, 0, v131, vcc
	v_sub_f32_e32 v172, v172, v173
	v_bfe_u32 v173, v149, 16, 1
	v_add3_u32 v149, v149, v173, s16
	v_bfe_u32 v150, v166, 16, 1
	v_bfe_u32 v173, v163, 16, 1
	v_bfe_u32 v174, v162, 16, 1
	v_add3_u32 v162, v162, v174, s16
	v_add3_u32 v163, v163, v173, s16
	v_add3_u32 v150, v166, v150, s16
	v_lshrrev_b32_e32 v161, 16, v150
	v_lshrrev_b32_e32 v166, 16, v151
	v_lshrrev_b32_e32 v150, 16, v163
	v_lshrrev_b32_e32 v151, 16, v162
	v_and_or_b32 v151, v149, s17, v151
	v_and_or_b32 v150, v148, s17, v150
	v_and_or_b32 v149, v175, s17, v166
	v_and_or_b32 v148, v176, s17, v161
	global_store_dwordx4 v[138:139], v[148:151], off
	s_nop 1
	v_cndmask_b32_e64 v148, v167, 0, s[4:5]
	v_bfe_u32 v149, v148, 16, 1
	v_add3_u32 v148, v148, v149, s16
	v_cndmask_b32_e64 v149, v169, 0, s[4:5]
	v_bfe_u32 v150, v149, 16, 1
	v_lshrrev_b32_e32 v148, 16, v148
	v_add3_u32 v149, v149, v150, s16
	v_and_or_b32 v148, v149, s17, v148
	v_cndmask_b32_e64 v149, v168, 0, s[4:5]
	v_bfe_u32 v150, v149, 16, 1
	v_add3_u32 v149, v149, v150, s16
	v_cndmask_b32_e64 v150, v170, 0, s[4:5]
	v_bfe_u32 v151, v150, 16, 1
	v_lshrrev_b32_e32 v149, 16, v149
	v_add3_u32 v150, v150, v151, s16
	v_and_or_b32 v149, v150, s17, v149
	v_cndmask_b32_e64 v150, v171, 0, s[4:5]
	v_bfe_u32 v151, v150, 16, 1
	v_add3_u32 v150, v150, v151, s16
	v_cndmask_b32_e64 v151, v164, 0, s[4:5]
	v_bfe_u32 v161, v151, 16, 1
	v_lshrrev_b32_e32 v150, 16, v150
	v_add3_u32 v151, v151, v161, s16
	v_and_or_b32 v150, v151, s17, v150
	v_cndmask_b32_e64 v151, v165, 0, s[4:5]
	v_bfe_u32 v161, v151, 16, 1
	v_add3_u32 v151, v151, v161, s16
	v_cndmask_b32_e64 v161, v172, 0, s[4:5]
	v_bfe_u32 v162, v161, 16, 1
	v_lshrrev_b32_e32 v151, 16, v151
	v_add3_u32 v161, v161, v162, s16
	v_and_or_b32 v151, v161, s17, v151
	global_store_dwordx4 v[136:137], v[148:151], off
	v_mul_f32_e32 v161, 0x3fb8aa3b, v82
	v_exp_f32_e32 v162, v161
	v_mul_f32_e32 v149, 0x3fb8aa3b, v87
	v_mul_f32_e32 v148, 0x3fb8aa3b, v86
	v_exp_f32_e32 v150, v149
	v_mul_f32_e32 v149, 0x3fb8aa3b, v88
	v_exp_f32_e32 v148, v148
	v_exp_f32_e32 v149, v149
	v_mul_f32_e32 v161, 0x3fb8aa3b, v83
	v_exp_f32_e32 v164, v161
	v_mul_f32_e32 v161, 0x3fb8aa3b, v84
	v_pk_add_f32 v[148:149], v[148:149], 1.0 op_sel_hi:[1,0]
	v_exp_f32_e32 v163, v161
	v_rcp_f32_e32 v166, v149
	v_mul_f32_e32 v151, 0x3fb8aa3b, v89
	v_exp_f32_e32 v151, v151
	v_rcp_f32_e32 v169, v148
	v_mul_f32_e32 v161, v144, v166
	v_mul_f32_e32 v166, v146, v169
	v_sub_f32_e32 v148, 1.0, v166
	v_cmp_gt_f32_e64 s[0:1], s14, v148
	v_cndmask_b32_e64 v166, v166, 0, s[4:5]
	s_nop 0
	v_cndmask_b32_e64 v165, 0, 32, s[0:1]
	v_ldexp_f32 v148, v148, v165
	v_log_f32_e32 v167, v148
	v_mul_f32_e32 v148, 0x3fb8aa3b, v85
	v_exp_f32_e32 v165, v148
	v_mul_f32_e32 v148, 0x3f317217, v167
	v_fma_f32 v168, v167, s9, -v148
	v_pk_add_f32 v[148:149], v[150:151], 1.0 op_sel_hi:[1,0]
	v_fmac_f32_e32 v168, 0x3377d1cf, v167
	v_rcp_f32_e32 v151, v149
	v_fmac_f32_e32 v168, 0x3f317217, v167
	v_cmp_lt_f32_e64 vcc, |v167|, s15
	s_nop 1
	v_cndmask_b32_e32 v167, v167, v168, vcc
	v_rcp_f32_e32 v171, v148
	v_mul_f32_e32 v150, v145, v151
	v_mul_f32_e32 v151, v147, v171
	v_sub_f32_e32 v148, 1.0, v151
	v_cmp_gt_f32_e32 vcc, s14, v148
	v_cndmask_b32_e64 v151, v151, 0, s[4:5]
	v_bfe_u32 v176, v151, 16, 1
	v_cndmask_b32_e64 v168, 0, 32, vcc
	v_ldexp_f32 v148, v148, v168
	v_log_f32_e32 v148, v148
	v_cndmask_b32_e64 v168, 0, v131, s[0:1]
	v_sub_f32_e32 v167, v167, v168
	v_sub_f32_e32 v168, 1.0, v161
	v_mul_f32_e32 v149, 0x3f317217, v148
	v_fma_f32 v149, v148, s9, -v149
	v_cmp_gt_f32_e64 s[0:1], s14, v168
	v_fmac_f32_e32 v149, 0x3377d1cf, v148
	v_fmac_f32_e32 v149, 0x3f317217, v148
	v_cndmask_b32_e64 v169, 0, 32, s[0:1]
	v_ldexp_f32 v168, v168, v169
	v_cmp_lt_f32_e64 s[2:3], |v148|, s15
	v_log_f32_e32 v168, v168
	v_cndmask_b32_e64 v161, v161, 0, s[4:5]
	v_cndmask_b32_e64 v148, v148, v149, s[2:3]
	v_cndmask_b32_e32 v149, 0, v131, vcc
	v_sub_f32_e32 v169, v148, v149
	v_sub_f32_e32 v149, 1.0, v150
	v_cmp_gt_f32_e32 vcc, s14, v149
	v_mul_f32_e32 v148, 0x3f317217, v168
	v_fma_f32 v148, v168, s9, -v148
	v_cndmask_b32_e64 v170, 0, 32, vcc
	v_ldexp_f32 v149, v149, v170
	v_log_f32_e32 v149, v149
	v_fmac_f32_e32 v148, 0x3377d1cf, v168
	v_fmac_f32_e32 v148, 0x3f317217, v168
	v_cmp_lt_f32_e64 s[2:3], |v168|, s15
	v_cndmask_b32_e32 v171, 0, v131, vcc
	v_cndmask_b32_e64 v150, v150, 0, s[4:5]
	v_cndmask_b32_e64 v148, v168, v148, s[2:3]
	v_cndmask_b32_e64 v168, 0, v131, s[0:1]
	v_sub_f32_e32 v168, v148, v168
	v_mul_f32_e32 v148, 0x3f317217, v149
	v_fma_f32 v148, v149, s9, -v148
	v_fmac_f32_e32 v148, 0x3377d1cf, v149
	v_fmac_f32_e32 v148, 0x3f317217, v149
	v_cmp_lt_f32_e64 s[0:1], |v149|, s15
	v_add3_u32 v176, v151, v176, s16
	v_bfe_u32 v151, v161, 16, 1
	v_cndmask_b32_e64 v170, v149, v148, s[0:1]
	v_pk_add_f32 v[148:149], v[162:163], 1.0 op_sel_hi:[1,0]
	v_sub_f32_e32 v170, v170, v171
	v_rcp_f32_e32 v163, v149
	v_add3_u32 v151, v161, v151, s16
	v_rcp_f32_e32 v174, v148
	v_mul_f32_e32 v162, v140, v163
	v_mul_f32_e32 v163, v142, v174
	v_sub_f32_e32 v148, 1.0, v163
	v_cmp_gt_f32_e64 s[0:1], s14, v148
	v_cndmask_b32_e64 v163, v163, 0, s[4:5]
	s_nop 0
	v_cndmask_b32_e64 v171, 0, 32, s[0:1]
	v_ldexp_f32 v148, v148, v171
	v_log_f32_e32 v171, v148
	s_nop 0
	v_mul_f32_e32 v148, 0x3f317217, v171
	v_fma_f32 v172, v171, s9, -v148
	v_pk_add_f32 v[148:149], v[164:165], 1.0 op_sel_hi:[1,0]
	v_fmac_f32_e32 v172, 0x3377d1cf, v171
	v_rcp_f32_e32 v165, v149
	v_fmac_f32_e32 v172, 0x3f317217, v171
	v_cmp_lt_f32_e64 vcc, |v171|, s15
	s_nop 1
	v_cndmask_b32_e32 v171, v171, v172, vcc
	v_rcp_f32_e32 v175, v148
	v_mul_f32_e32 v149, v141, v165
	v_mul_f32_e32 v148, v143, v175
	v_sub_f32_e32 v165, 1.0, v148
	v_cmp_gt_f32_e32 vcc, s14, v165
	v_cndmask_b32_e64 v148, v148, 0, s[4:5]
	v_bfe_u32 v175, v150, 16, 1
	v_cndmask_b32_e64 v172, 0, 32, vcc
	v_ldexp_f32 v165, v165, v172
	v_log_f32_e32 v165, v165
	v_cndmask_b32_e64 v172, 0, v131, s[0:1]
	v_sub_f32_e32 v171, v171, v172
	v_sub_f32_e32 v172, 1.0, v162
	v_cmp_gt_f32_e64 s[0:1], s14, v172
	v_mul_f32_e32 v164, 0x3f317217, v165
	v_fma_f32 v164, v165, s9, -v164
	v_cndmask_b32_e64 v173, 0, 32, s[0:1]
	v_ldexp_f32 v172, v172, v173
	v_fmac_f32_e32 v164, 0x3377d1cf, v165
	v_log_f32_e32 v172, v172
	v_fmac_f32_e32 v164, 0x3f317217, v165
	v_cmp_lt_f32_e64 s[2:3], |v165|, s15
	v_sub_f32_e32 v173, 1.0, v149
	v_cndmask_b32_e64 v149, v149, 0, s[4:5]
	v_cndmask_b32_e64 v164, v165, v164, s[2:3]
	v_cndmask_b32_e32 v165, 0, v131, vcc
	v_cmp_gt_f32_e32 vcc, s14, v173
	v_sub_f32_e32 v164, v164, v165
	v_mul_f32_e32 v165, 0x3f317217, v172
	v_cndmask_b32_e64 v174, 0, 32, vcc
	v_ldexp_f32 v173, v173, v174
	v_fma_f32 v165, v172, s9, -v165
	v_log_f32_e32 v173, v173
	v_fmac_f32_e32 v165, 0x3377d1cf, v172
	v_fmac_f32_e32 v165, 0x3f317217, v172
	v_cmp_lt_f32_e64 s[2:3], |v172|, s15
	v_cndmask_b32_e64 v162, v162, 0, s[4:5]
	v_bfe_u32 v174, v148, 16, 1
	v_cndmask_b32_e64 v165, v172, v165, s[2:3]
	v_cndmask_b32_e64 v172, 0, v131, s[0:1]
	v_sub_f32_e32 v165, v165, v172
	v_mul_f32_e32 v172, 0x3f317217, v173
	v_fma_f32 v172, v173, s9, -v172
	v_fmac_f32_e32 v172, 0x3377d1cf, v173
	v_fmac_f32_e32 v172, 0x3f317217, v173
	v_cmp_lt_f32_e64 s[0:1], |v173|, s15
	v_add3_u32 v175, v150, v175, s16
	v_add3_u32 v148, v148, v174, s16
	v_cndmask_b32_e64 v172, v173, v172, s[0:1]
	v_cndmask_b32_e32 v173, 0, v131, vcc
	v_sub_f32_e32 v172, v172, v173
	v_bfe_u32 v173, v149, 16, 1
	v_add3_u32 v149, v149, v173, s16
	v_bfe_u32 v150, v166, 16, 1
	v_bfe_u32 v173, v163, 16, 1
	v_bfe_u32 v174, v162, 16, 1
	v_add3_u32 v162, v162, v174, s16
	v_add3_u32 v163, v163, v173, s16
	v_add3_u32 v150, v166, v150, s16
	v_lshrrev_b32_e32 v161, 16, v150
	v_lshrrev_b32_e32 v166, 16, v151
	v_lshrrev_b32_e32 v150, 16, v163
	v_lshrrev_b32_e32 v151, 16, v162
	v_and_or_b32 v151, v149, s17, v151
	v_and_or_b32 v150, v148, s17, v150
	v_and_or_b32 v149, v175, s17, v166
	v_and_or_b32 v148, v176, s17, v161
	global_store_dwordx4 v[138:139], v[148:151], off offset:256
	v_cndmask_b32_e64 v138, v167, 0, s[4:5]
	v_bfe_u32 v139, v138, 16, 1
	v_add3_u32 v138, v138, v139, s16
	v_cndmask_b32_e64 v139, v169, 0, s[4:5]
	v_bfe_u32 v148, v139, 16, 1
	v_lshrrev_b32_e32 v138, 16, v138
	v_add3_u32 v139, v139, v148, s16
	v_and_or_b32 v148, v139, s17, v138
	v_cndmask_b32_e64 v138, v168, 0, s[4:5]
	v_bfe_u32 v139, v138, 16, 1
	v_add3_u32 v138, v138, v139, s16
	v_cndmask_b32_e64 v139, v170, 0, s[4:5]
	v_bfe_u32 v149, v139, 16, 1
	v_lshrrev_b32_e32 v138, 16, v138
	v_add3_u32 v139, v139, v149, s16
	v_and_or_b32 v149, v139, s17, v138
	v_cndmask_b32_e64 v138, v171, 0, s[4:5]
	v_bfe_u32 v139, v138, 16, 1
	v_add3_u32 v138, v138, v139, s16
	v_cndmask_b32_e64 v139, v164, 0, s[4:5]
	v_bfe_u32 v150, v139, 16, 1
	v_lshrrev_b32_e32 v138, 16, v138
	v_add3_u32 v139, v139, v150, s16
	v_and_or_b32 v150, v139, s17, v138
	v_cndmask_b32_e64 v138, v165, 0, s[4:5]
	v_bfe_u32 v139, v138, 16, 1
	v_add3_u32 v138, v138, v139, s16
	v_cndmask_b32_e64 v139, v172, 0, s[4:5]
	v_bfe_u32 v151, v139, 16, 1
	v_lshrrev_b32_e32 v138, 16, v138
	v_add3_u32 v139, v139, v151, s16
	v_and_or_b32 v151, v139, s17, v138
	global_store_dwordx4 v[136:137], v[148:151], off offset:256
	v_mul_f32_e32 v161, 0x3fb8aa3b, v74
	v_exp_f32_e32 v162, v161
	v_mul_f32_e32 v149, 0x3fb8aa3b, v79
	v_mul_f32_e32 v148, 0x3fb8aa3b, v78
	v_exp_f32_e32 v150, v149
	v_mul_f32_e32 v149, 0x3fb8aa3b, v80
	v_exp_f32_e32 v148, v148
	v_exp_f32_e32 v149, v149
	v_mul_f32_e32 v161, 0x3fb8aa3b, v75
	v_or_b32_e32 v136, 48, v130
	v_exp_f32_e32 v164, v161
	v_pk_add_f32 v[148:149], v[148:149], 1.0 op_sel_hi:[1,0]
	v_mul_f32_e32 v161, 0x3fb8aa3b, v76
	v_div_scale_f32 v165, s[4:5], v149, v149, v157
	v_rcp_f32_e32 v166, v165
	v_cmp_gt_i32_e32 vcc, s20, v136
	v_exp_f32_e32 v163, v161
	v_mul_f32_e32 v151, 0x3fb8aa3b, v81
	v_fma_f32 v161, -v165, v166, 1.0
	v_cndmask_b32_e64 v137, v154, 0, vcc
	v_fmac_f32_e32 v166, v161, v166
	v_div_scale_f32 v161, vcc, v157, v149, v157
	v_mul_f32_e32 v167, v161, v166
	v_fma_f32 v168, -v165, v167, v161
	v_fmac_f32_e32 v167, v168, v166
	v_rcp_f32_e32 v169, v148
	v_fma_f32 v161, -v165, v167, v161
	v_div_fmas_f32 v161, v161, v166, v167
	v_exp_f32_e32 v151, v151
	v_mul_f32_e32 v166, v156, v169
	v_sub_f32_e32 v148, 1.0, v166
	v_cmp_gt_f32_e64 s[4:5], s14, v148
	v_div_fixup_f32 v161, v161, v149, v157
	v_add_u32_e32 v137, v137, v136
	v_cndmask_b32_e64 v165, 0, 32, s[4:5]
	v_ldexp_f32 v148, v148, v165
	v_log_f32_e32 v167, v148
	v_mul_f32_e32 v148, 0x3fb8aa3b, v77
	v_exp_f32_e32 v165, v148
	v_cmp_gt_i32_e64 s[0:1], s19, v136
	v_mul_f32_e32 v148, 0x3f317217, v167
	v_fma_f32 v168, v167, s9, -v148
	v_pk_add_f32 v[148:149], v[150:151], 1.0 op_sel_hi:[1,0]
	v_fmac_f32_e32 v168, 0x3377d1cf, v167
	v_rcp_f32_e32 v151, v149
	v_fmac_f32_e32 v168, 0x3f317217, v167
	v_cmp_lt_f32_e64 vcc, |v167|, s15
	v_cmp_gt_i32_e64 s[2:3], s18, v137
	v_ashrrev_i32_e32 v137, 31, v136
	v_cndmask_b32_e32 v167, v167, v168, vcc
	v_rcp_f32_e32 v171, v148
	v_mul_f32_e32 v150, v158, v151
	v_mul_f32_e32 v151, v155, v171
	v_sub_f32_e32 v148, 1.0, v151
	v_cmp_gt_f32_e32 vcc, s14, v148
	v_lshlrev_b64 v[136:137], 10, v[136:137]
	v_lshl_add_u64 v[138:139], v[132:133], 0, v[136:137]
	v_cndmask_b32_e64 v168, 0, 32, vcc
	v_ldexp_f32 v148, v148, v168
	v_log_f32_e32 v148, v148
	v_cndmask_b32_e64 v168, 0, v131, s[4:5]
	v_sub_f32_e32 v167, v167, v168
	v_sub_f32_e32 v168, 1.0, v161
	v_mul_f32_e32 v149, 0x3f317217, v148
	v_fma_f32 v149, v148, s9, -v149
	v_cmp_gt_f32_e64 s[4:5], s14, v168
	v_fmac_f32_e32 v149, 0x3377d1cf, v148
	v_fmac_f32_e32 v149, 0x3f317217, v148
	v_cndmask_b32_e64 v169, 0, 32, s[4:5]
	v_ldexp_f32 v168, v168, v169
	v_cmp_lt_f32_e64 s[6:7], |v148|, s15
	v_log_f32_e32 v168, v168
	v_lshl_add_u64 v[136:137], v[134:135], 0, v[136:137]
	v_cndmask_b32_e64 v148, v148, v149, s[6:7]
	v_cndmask_b32_e32 v149, 0, v131, vcc
	v_sub_f32_e32 v169, v148, v149
	v_sub_f32_e32 v149, 1.0, v150
	v_cmp_gt_f32_e32 vcc, s14, v149
	v_mul_f32_e32 v148, 0x3f317217, v168
	v_fma_f32 v148, v168, s9, -v148
	v_cndmask_b32_e64 v170, 0, 32, vcc
	v_ldexp_f32 v149, v149, v170
	v_log_f32_e32 v149, v149
	v_fmac_f32_e32 v148, 0x3377d1cf, v168
	v_fmac_f32_e32 v148, 0x3f317217, v168
	v_cmp_lt_f32_e64 s[6:7], |v168|, s15
	s_nop 1
	v_cndmask_b32_e64 v148, v168, v148, s[6:7]
	v_cndmask_b32_e64 v168, 0, v131, s[4:5]
	v_sub_f32_e32 v168, v148, v168
	v_mul_f32_e32 v148, 0x3f317217, v149
	v_fma_f32 v148, v149, s9, -v148
	v_fmac_f32_e32 v148, 0x3377d1cf, v149
	v_fmac_f32_e32 v148, 0x3f317217, v149
	v_cmp_lt_f32_e64 s[4:5], |v149|, s15
	s_nop 1
	v_cndmask_b32_e64 v148, v149, v148, s[4:5]
	v_cndmask_b32_e32 v149, 0, v131, vcc
	v_sub_f32_e32 v170, v148, v149
	v_pk_add_f32 v[148:149], v[162:163], 1.0 op_sel_hi:[1,0]
	s_nop 0
	v_rcp_f32_e32 v163, v149
	s_and_b64 s[4:5], s[0:1], s[2:3]
	v_cndmask_b32_e64 v151, v151, 0, s[4:5]
	v_cndmask_b32_e64 v150, v150, 0, s[4:5]
	v_rcp_f32_e32 v174, v148
	v_mul_f32_e32 v162, v152, v163
	v_mul_f32_e32 v163, v159, v174
	v_sub_f32_e32 v148, 1.0, v163
	v_cmp_gt_f32_e64 s[0:1], s14, v148
	v_cndmask_b32_e64 v161, v161, 0, s[4:5]
	v_cndmask_b32_e64 v166, v166, 0, s[4:5]
	v_cndmask_b32_e64 v171, 0, 32, s[0:1]
	v_ldexp_f32 v148, v148, v171
	v_log_f32_e32 v171, v148
	v_cndmask_b32_e64 v163, v163, 0, s[4:5]
	v_bfe_u32 v176, v151, 16, 1
	v_add3_u32 v176, v151, v176, s16
	v_mul_f32_e32 v148, 0x3f317217, v171
	v_fma_f32 v172, v171, s9, -v148
	v_pk_add_f32 v[148:149], v[164:165], 1.0 op_sel_hi:[1,0]
	v_fmac_f32_e32 v172, 0x3377d1cf, v171
	v_rcp_f32_e32 v165, v149
	v_fmac_f32_e32 v172, 0x3f317217, v171
	v_cmp_lt_f32_e64 vcc, |v171|, s15
	v_bfe_u32 v151, v161, 16, 1
	v_add3_u32 v151, v161, v151, s16
	v_cndmask_b32_e32 v171, v171, v172, vcc
	v_rcp_f32_e32 v175, v148
	v_mul_f32_e32 v149, v153, v165
	v_mul_f32_e32 v148, v160, v175
	v_sub_f32_e32 v165, 1.0, v148
	v_cmp_gt_f32_e32 vcc, s14, v165
	v_cndmask_b32_e64 v148, v148, 0, s[4:5]
	v_bfe_u32 v175, v150, 16, 1
	v_cndmask_b32_e64 v172, 0, 32, vcc
	v_ldexp_f32 v165, v165, v172
	v_log_f32_e32 v165, v165
	v_cndmask_b32_e64 v172, 0, v131, s[0:1]
	v_sub_f32_e32 v171, v171, v172
	v_sub_f32_e32 v172, 1.0, v162
	v_cmp_gt_f32_e64 s[0:1], s14, v172
	v_mul_f32_e32 v164, 0x3f317217, v165
	v_fma_f32 v164, v165, s9, -v164
	v_cndmask_b32_e64 v173, 0, 32, s[0:1]
	v_ldexp_f32 v172, v172, v173
	v_fmac_f32_e32 v164, 0x3377d1cf, v165
	v_log_f32_e32 v172, v172
	v_fmac_f32_e32 v164, 0x3f317217, v165
	v_cmp_lt_f32_e64 s[2:3], |v165|, s15
	v_sub_f32_e32 v173, 1.0, v149
	v_cndmask_b32_e64 v149, v149, 0, s[4:5]
	v_cndmask_b32_e64 v164, v165, v164, s[2:3]
	v_cndmask_b32_e32 v165, 0, v131, vcc
	v_cmp_gt_f32_e32 vcc, s14, v173
	v_sub_f32_e32 v164, v164, v165
	v_mul_f32_e32 v165, 0x3f317217, v172
	v_cndmask_b32_e64 v174, 0, 32, vcc
	v_ldexp_f32 v173, v173, v174
	v_fma_f32 v165, v172, s9, -v165
	v_log_f32_e32 v173, v173
	v_fmac_f32_e32 v165, 0x3377d1cf, v172
	v_fmac_f32_e32 v165, 0x3f317217, v172
	v_cmp_lt_f32_e64 s[2:3], |v172|, s15
	v_cndmask_b32_e64 v162, v162, 0, s[4:5]
	v_bfe_u32 v174, v148, 16, 1
	v_cndmask_b32_e64 v165, v172, v165, s[2:3]
	v_cndmask_b32_e64 v172, 0, v131, s[0:1]
	v_sub_f32_e32 v165, v165, v172
	v_mul_f32_e32 v172, 0x3f317217, v173
	v_fma_f32 v172, v173, s9, -v172
	v_fmac_f32_e32 v172, 0x3377d1cf, v173
	v_fmac_f32_e32 v172, 0x3f317217, v173
	v_cmp_lt_f32_e64 s[0:1], |v173|, s15
	v_add3_u32 v175, v150, v175, s16
	v_add3_u32 v148, v148, v174, s16
	v_cndmask_b32_e64 v172, v173, v172, s[0:1]
	v_cndmask_b32_e32 v173, 0, v131, vcc
	v_sub_f32_e32 v172, v172, v173
	v_bfe_u32 v173, v149, 16, 1
	v_add3_u32 v149, v149, v173, s16
	v_bfe_u32 v150, v166, 16, 1
	v_bfe_u32 v173, v163, 16, 1
	v_bfe_u32 v174, v162, 16, 1
	v_add3_u32 v162, v162, v174, s16
	v_add3_u32 v163, v163, v173, s16
	v_add3_u32 v150, v166, v150, s16
	v_lshrrev_b32_e32 v161, 16, v150
	v_lshrrev_b32_e32 v166, 16, v151
	v_lshrrev_b32_e32 v150, 16, v163
	v_lshrrev_b32_e32 v151, 16, v162
	v_and_or_b32 v151, v149, s17, v151
	v_and_or_b32 v150, v148, s17, v150
	v_and_or_b32 v149, v175, s17, v166
	v_and_or_b32 v148, v176, s17, v161
	global_store_dwordx4 v[138:139], v[148:151], off
	s_nop 1
	v_cndmask_b32_e64 v148, v167, 0, s[4:5]
	v_bfe_u32 v149, v148, 16, 1
	v_add3_u32 v148, v148, v149, s16
	v_cndmask_b32_e64 v149, v169, 0, s[4:5]
	v_bfe_u32 v150, v149, 16, 1
	v_lshrrev_b32_e32 v148, 16, v148
	v_add3_u32 v149, v149, v150, s16
	v_and_or_b32 v148, v149, s17, v148
	v_cndmask_b32_e64 v149, v168, 0, s[4:5]
	v_bfe_u32 v150, v149, 16, 1
	v_add3_u32 v149, v149, v150, s16
	v_cndmask_b32_e64 v150, v170, 0, s[4:5]
	v_bfe_u32 v151, v150, 16, 1
	v_lshrrev_b32_e32 v149, 16, v149
	v_add3_u32 v150, v150, v151, s16
	v_and_or_b32 v149, v150, s17, v149
	v_cndmask_b32_e64 v150, v171, 0, s[4:5]
	v_bfe_u32 v151, v150, 16, 1
	v_add3_u32 v150, v150, v151, s16
	v_cndmask_b32_e64 v151, v164, 0, s[4:5]
	v_bfe_u32 v161, v151, 16, 1
	v_lshrrev_b32_e32 v150, 16, v150
	v_add3_u32 v151, v151, v161, s16
	v_and_or_b32 v150, v151, s17, v150
	v_cndmask_b32_e64 v151, v165, 0, s[4:5]
	v_bfe_u32 v161, v151, 16, 1
	v_add3_u32 v151, v151, v161, s16
	v_cndmask_b32_e64 v161, v172, 0, s[4:5]
	v_bfe_u32 v162, v161, 16, 1
	v_lshrrev_b32_e32 v151, 16, v151
	v_add3_u32 v161, v161, v162, s16
	v_and_or_b32 v151, v161, s17, v151
	global_store_dwordx4 v[136:137], v[148:151], off
	v_mul_f32_e32 v161, 0x3fb8aa3b, v66
	v_exp_f32_e32 v162, v161
	v_mul_f32_e32 v149, 0x3fb8aa3b, v71
	v_mul_f32_e32 v148, 0x3fb8aa3b, v70
	v_exp_f32_e32 v150, v149
	v_mul_f32_e32 v149, 0x3fb8aa3b, v72
	v_exp_f32_e32 v148, v148
	v_exp_f32_e32 v149, v149
	v_mul_f32_e32 v161, 0x3fb8aa3b, v67
	v_exp_f32_e32 v164, v161
	v_mul_f32_e32 v161, 0x3fb8aa3b, v68
	v_pk_add_f32 v[148:149], v[148:149], 1.0 op_sel_hi:[1,0]
	v_exp_f32_e32 v163, v161
	v_rcp_f32_e32 v166, v149
	v_mul_f32_e32 v151, 0x3fb8aa3b, v73
	v_exp_f32_e32 v151, v151
	v_rcp_f32_e32 v169, v148
	v_mul_f32_e32 v161, v144, v166
	v_mul_f32_e32 v166, v146, v169
	v_sub_f32_e32 v148, 1.0, v166
	v_cmp_gt_f32_e64 s[0:1], s14, v148
	v_cndmask_b32_e64 v166, v166, 0, s[4:5]
	s_nop 0
	v_cndmask_b32_e64 v165, 0, 32, s[0:1]
	v_ldexp_f32 v148, v148, v165
	v_log_f32_e32 v167, v148
	v_mul_f32_e32 v148, 0x3fb8aa3b, v69
	v_exp_f32_e32 v165, v148
	v_mul_f32_e32 v148, 0x3f317217, v167
	v_fma_f32 v168, v167, s9, -v148
	v_pk_add_f32 v[148:149], v[150:151], 1.0 op_sel_hi:[1,0]
	v_fmac_f32_e32 v168, 0x3377d1cf, v167
	v_rcp_f32_e32 v151, v149
	v_fmac_f32_e32 v168, 0x3f317217, v167
	v_cmp_lt_f32_e64 vcc, |v167|, s15
	s_nop 1
	v_cndmask_b32_e32 v167, v167, v168, vcc
	v_rcp_f32_e32 v171, v148
	v_mul_f32_e32 v150, v145, v151
	v_mul_f32_e32 v151, v147, v171
	v_sub_f32_e32 v148, 1.0, v151
	v_cmp_gt_f32_e32 vcc, s14, v148
	v_cndmask_b32_e64 v151, v151, 0, s[4:5]
	v_bfe_u32 v176, v151, 16, 1
	v_cndmask_b32_e64 v168, 0, 32, vcc
	v_ldexp_f32 v148, v148, v168
	v_log_f32_e32 v148, v148
	v_cndmask_b32_e64 v168, 0, v131, s[0:1]
	v_sub_f32_e32 v167, v167, v168
	v_sub_f32_e32 v168, 1.0, v161
	v_mul_f32_e32 v149, 0x3f317217, v148
	v_fma_f32 v149, v148, s9, -v149
	v_cmp_gt_f32_e64 s[0:1], s14, v168
	v_fmac_f32_e32 v149, 0x3377d1cf, v148
	v_fmac_f32_e32 v149, 0x3f317217, v148
	v_cndmask_b32_e64 v169, 0, 32, s[0:1]
	v_ldexp_f32 v168, v168, v169
	v_cmp_lt_f32_e64 s[2:3], |v148|, s15
	v_log_f32_e32 v168, v168
	v_cndmask_b32_e64 v161, v161, 0, s[4:5]
	v_cndmask_b32_e64 v148, v148, v149, s[2:3]
	v_cndmask_b32_e32 v149, 0, v131, vcc
	v_sub_f32_e32 v169, v148, v149
	v_sub_f32_e32 v149, 1.0, v150
	v_cmp_gt_f32_e32 vcc, s14, v149
	v_mul_f32_e32 v148, 0x3f317217, v168
	v_fma_f32 v148, v168, s9, -v148
	v_cndmask_b32_e64 v170, 0, 32, vcc
	v_ldexp_f32 v149, v149, v170
	v_log_f32_e32 v149, v149
	v_fmac_f32_e32 v148, 0x3377d1cf, v168
	v_fmac_f32_e32 v148, 0x3f317217, v168
	v_cmp_lt_f32_e64 s[2:3], |v168|, s15
	v_cndmask_b32_e32 v171, 0, v131, vcc
	v_cndmask_b32_e64 v150, v150, 0, s[4:5]
	v_cndmask_b32_e64 v148, v168, v148, s[2:3]
	v_cndmask_b32_e64 v168, 0, v131, s[0:1]
	v_sub_f32_e32 v168, v148, v168
	v_mul_f32_e32 v148, 0x3f317217, v149
	v_fma_f32 v148, v149, s9, -v148
	v_fmac_f32_e32 v148, 0x3377d1cf, v149
	v_fmac_f32_e32 v148, 0x3f317217, v149
	v_cmp_lt_f32_e64 s[0:1], |v149|, s15
	v_add3_u32 v176, v151, v176, s16
	v_bfe_u32 v151, v161, 16, 1
	v_cndmask_b32_e64 v170, v149, v148, s[0:1]
	v_pk_add_f32 v[148:149], v[162:163], 1.0 op_sel_hi:[1,0]
	v_sub_f32_e32 v170, v170, v171
	v_rcp_f32_e32 v163, v149
	v_add3_u32 v151, v161, v151, s16
	v_rcp_f32_e32 v174, v148
	v_mul_f32_e32 v162, v140, v163
	v_mul_f32_e32 v163, v142, v174
	v_sub_f32_e32 v148, 1.0, v163
	v_cmp_gt_f32_e64 s[0:1], s14, v148
	v_cndmask_b32_e64 v163, v163, 0, s[4:5]
	s_nop 0
	v_cndmask_b32_e64 v171, 0, 32, s[0:1]
	v_ldexp_f32 v148, v148, v171
	v_log_f32_e32 v171, v148
	s_nop 0
	v_mul_f32_e32 v148, 0x3f317217, v171
	v_fma_f32 v172, v171, s9, -v148
	v_pk_add_f32 v[148:149], v[164:165], 1.0 op_sel_hi:[1,0]
	v_fmac_f32_e32 v172, 0x3377d1cf, v171
	v_rcp_f32_e32 v165, v149
	v_fmac_f32_e32 v172, 0x3f317217, v171
	v_cmp_lt_f32_e64 vcc, |v171|, s15
	s_nop 1
	v_cndmask_b32_e32 v171, v171, v172, vcc
	v_rcp_f32_e32 v175, v148
	v_mul_f32_e32 v149, v141, v165
	v_mul_f32_e32 v148, v143, v175
	v_sub_f32_e32 v165, 1.0, v148
	v_cmp_gt_f32_e32 vcc, s14, v165
	v_cndmask_b32_e64 v148, v148, 0, s[4:5]
	v_bfe_u32 v175, v150, 16, 1
	v_cndmask_b32_e64 v172, 0, 32, vcc
	v_ldexp_f32 v165, v165, v172
	v_log_f32_e32 v165, v165
	v_cndmask_b32_e64 v172, 0, v131, s[0:1]
	v_sub_f32_e32 v171, v171, v172
	v_sub_f32_e32 v172, 1.0, v162
	v_cmp_gt_f32_e64 s[0:1], s14, v172
	v_mul_f32_e32 v164, 0x3f317217, v165
	v_fma_f32 v164, v165, s9, -v164
	v_cndmask_b32_e64 v173, 0, 32, s[0:1]
	v_ldexp_f32 v172, v172, v173
	v_fmac_f32_e32 v164, 0x3377d1cf, v165
	v_log_f32_e32 v172, v172
	v_fmac_f32_e32 v164, 0x3f317217, v165
	v_cmp_lt_f32_e64 s[2:3], |v165|, s15
	v_sub_f32_e32 v173, 1.0, v149
	v_cndmask_b32_e64 v149, v149, 0, s[4:5]
	v_cndmask_b32_e64 v164, v165, v164, s[2:3]
	v_cndmask_b32_e32 v165, 0, v131, vcc
	v_cmp_gt_f32_e32 vcc, s14, v173
	v_sub_f32_e32 v164, v164, v165
	v_mul_f32_e32 v165, 0x3f317217, v172
	v_cndmask_b32_e64 v174, 0, 32, vcc
	v_ldexp_f32 v173, v173, v174
	v_fma_f32 v165, v172, s9, -v165
	v_log_f32_e32 v173, v173
	v_fmac_f32_e32 v165, 0x3377d1cf, v172
	v_fmac_f32_e32 v165, 0x3f317217, v172
	v_cmp_lt_f32_e64 s[2:3], |v172|, s15
	v_cndmask_b32_e64 v162, v162, 0, s[4:5]
	v_bfe_u32 v174, v148, 16, 1
	v_cndmask_b32_e64 v165, v172, v165, s[2:3]
	v_cndmask_b32_e64 v172, 0, v131, s[0:1]
	v_sub_f32_e32 v165, v165, v172
	v_mul_f32_e32 v172, 0x3f317217, v173
	v_fma_f32 v172, v173, s9, -v172
	v_fmac_f32_e32 v172, 0x3377d1cf, v173
	v_fmac_f32_e32 v172, 0x3f317217, v173
	v_cmp_lt_f32_e64 s[0:1], |v173|, s15
	v_add3_u32 v175, v150, v175, s16
	v_add3_u32 v148, v148, v174, s16
	v_cndmask_b32_e64 v172, v173, v172, s[0:1]
	v_cndmask_b32_e32 v173, 0, v131, vcc
	v_sub_f32_e32 v172, v172, v173
	v_bfe_u32 v173, v149, 16, 1
	v_add3_u32 v149, v149, v173, s16
	v_bfe_u32 v150, v166, 16, 1
	v_bfe_u32 v173, v163, 16, 1
	v_bfe_u32 v174, v162, 16, 1
	v_add3_u32 v162, v162, v174, s16
	v_add3_u32 v163, v163, v173, s16
	v_add3_u32 v150, v166, v150, s16
	v_lshrrev_b32_e32 v161, 16, v150
	v_lshrrev_b32_e32 v166, 16, v151
	v_lshrrev_b32_e32 v150, 16, v163
	v_lshrrev_b32_e32 v151, 16, v162
	v_and_or_b32 v151, v149, s17, v151
	v_and_or_b32 v150, v148, s17, v150
	v_and_or_b32 v149, v175, s17, v166
	v_and_or_b32 v148, v176, s17, v161
	global_store_dwordx4 v[138:139], v[148:151], off offset:256
	v_cndmask_b32_e64 v138, v167, 0, s[4:5]
	v_bfe_u32 v139, v138, 16, 1
	v_add3_u32 v138, v138, v139, s16
	v_cndmask_b32_e64 v139, v169, 0, s[4:5]
	v_bfe_u32 v148, v139, 16, 1
	v_lshrrev_b32_e32 v138, 16, v138
	v_add3_u32 v139, v139, v148, s16
	v_and_or_b32 v148, v139, s17, v138
	v_cndmask_b32_e64 v138, v168, 0, s[4:5]
	v_bfe_u32 v139, v138, 16, 1
	v_add3_u32 v138, v138, v139, s16
	v_cndmask_b32_e64 v139, v170, 0, s[4:5]
	v_bfe_u32 v149, v139, 16, 1
	v_lshrrev_b32_e32 v138, 16, v138
	v_add3_u32 v139, v139, v149, s16
	v_and_or_b32 v149, v139, s17, v138
	v_cndmask_b32_e64 v138, v171, 0, s[4:5]
	v_bfe_u32 v139, v138, 16, 1
	v_add3_u32 v138, v138, v139, s16
	v_cndmask_b32_e64 v139, v164, 0, s[4:5]
	v_bfe_u32 v150, v139, 16, 1
	v_lshrrev_b32_e32 v138, 16, v138
	v_add3_u32 v139, v139, v150, s16
	v_and_or_b32 v150, v139, s17, v138
	v_cndmask_b32_e64 v138, v165, 0, s[4:5]
	v_bfe_u32 v139, v138, 16, 1
	v_add3_u32 v138, v138, v139, s16
	v_cndmask_b32_e64 v139, v172, 0, s[4:5]
	v_bfe_u32 v151, v139, 16, 1
	v_lshrrev_b32_e32 v138, 16, v138
	v_add3_u32 v139, v139, v151, s16
	v_and_or_b32 v151, v139, s17, v138
	global_store_dwordx4 v[136:137], v[148:151], off offset:256
	v_mul_f32_e32 v161, 0x3fb8aa3b, v58
	v_exp_f32_e32 v162, v161
	v_mul_f32_e32 v149, 0x3fb8aa3b, v63
	v_mul_f32_e32 v148, 0x3fb8aa3b, v62
	v_exp_f32_e32 v150, v149
	v_mul_f32_e32 v149, 0x3fb8aa3b, v64
	v_exp_f32_e32 v148, v148
	v_exp_f32_e32 v149, v149
	v_mul_f32_e32 v161, 0x3fb8aa3b, v59
	s_movk_i32 s2, 0x2000
	v_exp_f32_e32 v164, v161
	v_pk_add_f32 v[148:149], v[148:149], 1.0 op_sel_hi:[1,0]
	v_mul_f32_e32 v161, 0x3fb8aa3b, v60
	v_div_scale_f32 v165, s[4:5], v149, v149, v157
	v_rcp_f32_e32 v166, v165
	v_cmp_gt_i32_e32 vcc, s2, v130
	v_exp_f32_e32 v163, v161
	v_mul_f32_e32 v151, 0x3fb8aa3b, v65
	v_fma_f32 v161, -v165, v166, 1.0
	v_cndmask_b32_e64 v137, v154, 0, vcc
	v_fmac_f32_e32 v166, v161, v166
	v_div_scale_f32 v161, vcc, v157, v149, v157
	v_mul_f32_e32 v167, v161, v166
	v_fma_f32 v168, -v165, v167, v161
	v_fmac_f32_e32 v167, v168, v166
	v_rcp_f32_e32 v169, v148
	v_fma_f32 v161, -v165, v167, v161
	v_div_fmas_f32 v161, v161, v166, v167
	v_exp_f32_e32 v151, v151
	v_mul_f32_e32 v166, v156, v169
	v_sub_f32_e32 v148, 1.0, v166
	v_cmp_gt_f32_e64 s[4:5], s14, v148
	v_div_fixup_f32 v161, v161, v149, v157
	v_add_u32_e32 v136, 0x80, v130
	v_cndmask_b32_e64 v165, 0, 32, s[4:5]
	v_ldexp_f32 v148, v148, v165
	v_log_f32_e32 v167, v148
	v_mul_f32_e32 v148, 0x3fb8aa3b, v61
	v_exp_f32_e32 v165, v148
	s_movk_i32 s0, 0x4080
	v_mul_f32_e32 v148, 0x3f317217, v167
	v_fma_f32 v168, v167, s9, -v148
	v_pk_add_f32 v[148:149], v[150:151], 1.0 op_sel_hi:[1,0]
	v_fmac_f32_e32 v168, 0x3377d1cf, v167
	v_rcp_f32_e32 v151, v149
	v_fmac_f32_e32 v168, 0x3f317217, v167
	v_cmp_lt_f32_e64 vcc, |v167|, s15
	v_add_u32_e32 v137, v137, v136
	v_cmp_gt_i32_e64 s[0:1], s0, v130
	v_cndmask_b32_e32 v167, v167, v168, vcc
	v_rcp_f32_e32 v171, v148
	v_mul_f32_e32 v150, v158, v151
	v_mul_f32_e32 v151, v155, v171
	v_sub_f32_e32 v148, 1.0, v151
	v_cmp_gt_f32_e32 vcc, s14, v148
	v_cmp_gt_i32_e64 s[2:3], s18, v137
	v_ashrrev_i32_e32 v137, 31, v136
	v_cndmask_b32_e64 v168, 0, 32, vcc
	v_ldexp_f32 v148, v148, v168
	v_log_f32_e32 v148, v148
	v_cndmask_b32_e64 v168, 0, v131, s[4:5]
	v_sub_f32_e32 v167, v167, v168
	v_sub_f32_e32 v168, 1.0, v161
	v_mul_f32_e32 v149, 0x3f317217, v148
	v_fma_f32 v149, v148, s9, -v149
	v_cmp_gt_f32_e64 s[4:5], s14, v168
	v_fmac_f32_e32 v149, 0x3377d1cf, v148
	v_fmac_f32_e32 v149, 0x3f317217, v148
	v_cndmask_b32_e64 v169, 0, 32, s[4:5]
	v_ldexp_f32 v168, v168, v169
	v_cmp_lt_f32_e64 s[6:7], |v148|, s15
	v_log_f32_e32 v168, v168
	v_lshlrev_b64 v[136:137], 10, v[136:137]
	v_cndmask_b32_e64 v148, v148, v149, s[6:7]
	v_cndmask_b32_e32 v149, 0, v131, vcc
	v_sub_f32_e32 v169, v148, v149
	v_sub_f32_e32 v149, 1.0, v150
	v_cmp_gt_f32_e32 vcc, s14, v149
	v_mul_f32_e32 v148, 0x3f317217, v168
	v_fma_f32 v148, v168, s9, -v148
	v_cndmask_b32_e64 v170, 0, 32, vcc
	v_ldexp_f32 v149, v149, v170
	v_log_f32_e32 v149, v149
	v_fmac_f32_e32 v148, 0x3377d1cf, v168
	v_fmac_f32_e32 v148, 0x3f317217, v168
	v_cmp_lt_f32_e64 s[6:7], |v168|, s15
	v_lshl_add_u64 v[138:139], v[132:133], 0, v[136:137]
	v_lshl_add_u64 v[136:137], v[134:135], 0, v[136:137]
	v_cndmask_b32_e64 v148, v168, v148, s[6:7]
	v_cndmask_b32_e64 v168, 0, v131, s[4:5]
	v_sub_f32_e32 v168, v148, v168
	v_mul_f32_e32 v148, 0x3f317217, v149
	v_fma_f32 v148, v149, s9, -v148
	v_fmac_f32_e32 v148, 0x3377d1cf, v149
	v_fmac_f32_e32 v148, 0x3f317217, v149
	v_cmp_lt_f32_e64 s[4:5], |v149|, s15
	s_nop 1
	v_cndmask_b32_e64 v148, v149, v148, s[4:5]
	v_cndmask_b32_e32 v149, 0, v131, vcc
	v_sub_f32_e32 v170, v148, v149
	v_pk_add_f32 v[148:149], v[162:163], 1.0 op_sel_hi:[1,0]
	s_nop 0
	v_rcp_f32_e32 v163, v149
	s_and_b64 s[4:5], s[0:1], s[2:3]
	v_cndmask_b32_e64 v151, v151, 0, s[4:5]
	v_cndmask_b32_e64 v150, v150, 0, s[4:5]
	v_rcp_f32_e32 v174, v148
	v_mul_f32_e32 v162, v152, v163
	v_mul_f32_e32 v163, v159, v174
	v_sub_f32_e32 v148, 1.0, v163
	v_cmp_gt_f32_e64 s[0:1], s14, v148
	v_cndmask_b32_e64 v161, v161, 0, s[4:5]
	v_cndmask_b32_e64 v166, v166, 0, s[4:5]
	v_cndmask_b32_e64 v171, 0, 32, s[0:1]
	v_ldexp_f32 v148, v148, v171
	v_log_f32_e32 v171, v148
	v_cndmask_b32_e64 v163, v163, 0, s[4:5]
	v_bfe_u32 v176, v151, 16, 1
	v_add3_u32 v176, v151, v176, s16
	v_mul_f32_e32 v148, 0x3f317217, v171
	v_fma_f32 v172, v171, s9, -v148
	v_pk_add_f32 v[148:149], v[164:165], 1.0 op_sel_hi:[1,0]
	v_fmac_f32_e32 v172, 0x3377d1cf, v171
	v_rcp_f32_e32 v165, v149
	v_fmac_f32_e32 v172, 0x3f317217, v171
	v_cmp_lt_f32_e64 vcc, |v171|, s15
	v_bfe_u32 v151, v161, 16, 1
	v_add3_u32 v151, v161, v151, s16
	v_cndmask_b32_e32 v171, v171, v172, vcc
	v_rcp_f32_e32 v175, v148
	v_mul_f32_e32 v149, v153, v165
	v_mul_f32_e32 v148, v160, v175
	v_sub_f32_e32 v165, 1.0, v148
	v_cmp_gt_f32_e32 vcc, s14, v165
	v_cndmask_b32_e64 v148, v148, 0, s[4:5]
	v_bfe_u32 v175, v150, 16, 1
	v_cndmask_b32_e64 v172, 0, 32, vcc
	v_ldexp_f32 v165, v165, v172
	v_log_f32_e32 v165, v165
	v_cndmask_b32_e64 v172, 0, v131, s[0:1]
	v_sub_f32_e32 v171, v171, v172
	v_sub_f32_e32 v172, 1.0, v162
	v_cmp_gt_f32_e64 s[0:1], s14, v172
	v_mul_f32_e32 v164, 0x3f317217, v165
	v_fma_f32 v164, v165, s9, -v164
	v_cndmask_b32_e64 v173, 0, 32, s[0:1]
	v_ldexp_f32 v172, v172, v173
	v_fmac_f32_e32 v164, 0x3377d1cf, v165
	v_log_f32_e32 v172, v172
	v_fmac_f32_e32 v164, 0x3f317217, v165
	v_cmp_lt_f32_e64 s[2:3], |v165|, s15
	v_sub_f32_e32 v173, 1.0, v149
	v_cndmask_b32_e64 v149, v149, 0, s[4:5]
	v_cndmask_b32_e64 v164, v165, v164, s[2:3]
	v_cndmask_b32_e32 v165, 0, v131, vcc
	v_cmp_gt_f32_e32 vcc, s14, v173
	v_sub_f32_e32 v164, v164, v165
	v_mul_f32_e32 v165, 0x3f317217, v172
	v_cndmask_b32_e64 v174, 0, 32, vcc
	v_ldexp_f32 v173, v173, v174
	v_fma_f32 v165, v172, s9, -v165
	v_log_f32_e32 v173, v173
	v_fmac_f32_e32 v165, 0x3377d1cf, v172
	v_fmac_f32_e32 v165, 0x3f317217, v172
	v_cmp_lt_f32_e64 s[2:3], |v172|, s15
	v_cndmask_b32_e64 v162, v162, 0, s[4:5]
	v_bfe_u32 v174, v148, 16, 1
	v_cndmask_b32_e64 v165, v172, v165, s[2:3]
	v_cndmask_b32_e64 v172, 0, v131, s[0:1]
	v_sub_f32_e32 v165, v165, v172
	v_mul_f32_e32 v172, 0x3f317217, v173
	v_fma_f32 v172, v173, s9, -v172
	v_fmac_f32_e32 v172, 0x3377d1cf, v173
	v_fmac_f32_e32 v172, 0x3f317217, v173
	v_cmp_lt_f32_e64 s[0:1], |v173|, s15
	v_add3_u32 v175, v150, v175, s16
	v_add3_u32 v148, v148, v174, s16
	v_cndmask_b32_e64 v172, v173, v172, s[0:1]
	v_cndmask_b32_e32 v173, 0, v131, vcc
	v_sub_f32_e32 v172, v172, v173
	v_bfe_u32 v173, v149, 16, 1
	v_add3_u32 v149, v149, v173, s16
	v_bfe_u32 v150, v166, 16, 1
	v_bfe_u32 v173, v163, 16, 1
	v_bfe_u32 v174, v162, 16, 1
	v_add3_u32 v162, v162, v174, s16
	v_add3_u32 v163, v163, v173, s16
	v_add3_u32 v150, v166, v150, s16
	v_lshrrev_b32_e32 v161, 16, v150
	v_lshrrev_b32_e32 v166, 16, v151
	v_lshrrev_b32_e32 v150, 16, v163
	v_lshrrev_b32_e32 v151, 16, v162
	v_and_or_b32 v151, v149, s17, v151
	v_and_or_b32 v150, v148, s17, v150
	v_and_or_b32 v149, v175, s17, v166
	v_and_or_b32 v148, v176, s17, v161
	global_store_dwordx4 v[138:139], v[148:151], off
	s_nop 1
	v_cndmask_b32_e64 v148, v167, 0, s[4:5]
	v_bfe_u32 v149, v148, 16, 1
	v_add3_u32 v148, v148, v149, s16
	v_cndmask_b32_e64 v149, v169, 0, s[4:5]
	v_bfe_u32 v150, v149, 16, 1
	v_lshrrev_b32_e32 v148, 16, v148
	v_add3_u32 v149, v149, v150, s16
	v_and_or_b32 v148, v149, s17, v148
	v_cndmask_b32_e64 v149, v168, 0, s[4:5]
	v_bfe_u32 v150, v149, 16, 1
	v_add3_u32 v149, v149, v150, s16
	v_cndmask_b32_e64 v150, v170, 0, s[4:5]
	v_bfe_u32 v151, v150, 16, 1
	v_lshrrev_b32_e32 v149, 16, v149
	v_add3_u32 v150, v150, v151, s16
	v_and_or_b32 v149, v150, s17, v149
	v_cndmask_b32_e64 v150, v171, 0, s[4:5]
	v_bfe_u32 v151, v150, 16, 1
	v_add3_u32 v150, v150, v151, s16
	v_cndmask_b32_e64 v151, v164, 0, s[4:5]
	v_bfe_u32 v161, v151, 16, 1
	v_lshrrev_b32_e32 v150, 16, v150
	v_add3_u32 v151, v151, v161, s16
	v_and_or_b32 v150, v151, s17, v150
	v_cndmask_b32_e64 v151, v165, 0, s[4:5]
	v_bfe_u32 v161, v151, 16, 1
	v_add3_u32 v151, v151, v161, s16
	v_cndmask_b32_e64 v161, v172, 0, s[4:5]
	v_bfe_u32 v162, v161, 16, 1
	v_lshrrev_b32_e32 v151, 16, v151
	v_add3_u32 v161, v161, v162, s16
	v_and_or_b32 v151, v161, s17, v151
	global_store_dwordx4 v[136:137], v[148:151], off
	v_mul_f32_e32 v161, 0x3fb8aa3b, v50
	v_exp_f32_e32 v162, v161
	v_mul_f32_e32 v149, 0x3fb8aa3b, v55
	v_mul_f32_e32 v148, 0x3fb8aa3b, v54
	v_exp_f32_e32 v150, v149
	v_mul_f32_e32 v149, 0x3fb8aa3b, v56
	v_exp_f32_e32 v148, v148
	v_exp_f32_e32 v149, v149
	v_mul_f32_e32 v161, 0x3fb8aa3b, v51
	v_exp_f32_e32 v164, v161
	v_mul_f32_e32 v161, 0x3fb8aa3b, v52
	v_pk_add_f32 v[148:149], v[148:149], 1.0 op_sel_hi:[1,0]
	v_exp_f32_e32 v163, v161
	v_rcp_f32_e32 v166, v149
	v_mul_f32_e32 v151, 0x3fb8aa3b, v57
	v_exp_f32_e32 v151, v151
	v_rcp_f32_e32 v169, v148
	v_mul_f32_e32 v161, v144, v166
	v_mul_f32_e32 v166, v146, v169
	v_sub_f32_e32 v148, 1.0, v166
	v_cmp_gt_f32_e64 s[0:1], s14, v148
	v_cndmask_b32_e64 v166, v166, 0, s[4:5]
	s_nop 0
	v_cndmask_b32_e64 v165, 0, 32, s[0:1]
	v_ldexp_f32 v148, v148, v165
	v_log_f32_e32 v167, v148
	v_mul_f32_e32 v148, 0x3fb8aa3b, v53
	v_exp_f32_e32 v165, v148
	v_mul_f32_e32 v148, 0x3f317217, v167
	v_fma_f32 v168, v167, s9, -v148
	v_pk_add_f32 v[148:149], v[150:151], 1.0 op_sel_hi:[1,0]
	v_fmac_f32_e32 v168, 0x3377d1cf, v167
	v_rcp_f32_e32 v151, v149
	v_fmac_f32_e32 v168, 0x3f317217, v167
	v_cmp_lt_f32_e64 vcc, |v167|, s15
	s_nop 1
	v_cndmask_b32_e32 v167, v167, v168, vcc
	v_rcp_f32_e32 v171, v148
	v_mul_f32_e32 v150, v145, v151
	v_mul_f32_e32 v151, v147, v171
	v_sub_f32_e32 v148, 1.0, v151
	v_cmp_gt_f32_e32 vcc, s14, v148
	v_cndmask_b32_e64 v151, v151, 0, s[4:5]
	v_bfe_u32 v176, v151, 16, 1
	v_cndmask_b32_e64 v168, 0, 32, vcc
	v_ldexp_f32 v148, v148, v168
	v_log_f32_e32 v148, v148
	v_cndmask_b32_e64 v168, 0, v131, s[0:1]
	v_sub_f32_e32 v167, v167, v168
	v_sub_f32_e32 v168, 1.0, v161
	v_mul_f32_e32 v149, 0x3f317217, v148
	v_fma_f32 v149, v148, s9, -v149
	v_cmp_gt_f32_e64 s[0:1], s14, v168
	v_fmac_f32_e32 v149, 0x3377d1cf, v148
	v_fmac_f32_e32 v149, 0x3f317217, v148
	v_cndmask_b32_e64 v169, 0, 32, s[0:1]
	v_ldexp_f32 v168, v168, v169
	v_cmp_lt_f32_e64 s[2:3], |v148|, s15
	v_log_f32_e32 v168, v168
	v_cndmask_b32_e64 v161, v161, 0, s[4:5]
	v_cndmask_b32_e64 v148, v148, v149, s[2:3]
	v_cndmask_b32_e32 v149, 0, v131, vcc
	v_sub_f32_e32 v169, v148, v149
	v_sub_f32_e32 v149, 1.0, v150
	v_cmp_gt_f32_e32 vcc, s14, v149
	v_mul_f32_e32 v148, 0x3f317217, v168
	v_fma_f32 v148, v168, s9, -v148
	v_cndmask_b32_e64 v170, 0, 32, vcc
	v_ldexp_f32 v149, v149, v170
	v_log_f32_e32 v149, v149
	v_fmac_f32_e32 v148, 0x3377d1cf, v168
	v_fmac_f32_e32 v148, 0x3f317217, v168
	v_cmp_lt_f32_e64 s[2:3], |v168|, s15
	v_cndmask_b32_e32 v171, 0, v131, vcc
	v_cndmask_b32_e64 v150, v150, 0, s[4:5]
	v_cndmask_b32_e64 v148, v168, v148, s[2:3]
	v_cndmask_b32_e64 v168, 0, v131, s[0:1]
	v_sub_f32_e32 v168, v148, v168
	v_mul_f32_e32 v148, 0x3f317217, v149
	v_fma_f32 v148, v149, s9, -v148
	v_fmac_f32_e32 v148, 0x3377d1cf, v149
	v_fmac_f32_e32 v148, 0x3f317217, v149
	v_cmp_lt_f32_e64 s[0:1], |v149|, s15
	v_add3_u32 v176, v151, v176, s16
	v_bfe_u32 v151, v161, 16, 1
	v_cndmask_b32_e64 v170, v149, v148, s[0:1]
	v_pk_add_f32 v[148:149], v[162:163], 1.0 op_sel_hi:[1,0]
	v_sub_f32_e32 v170, v170, v171
	v_rcp_f32_e32 v163, v149
	v_add3_u32 v151, v161, v151, s16
	v_rcp_f32_e32 v174, v148
	v_mul_f32_e32 v162, v140, v163
	v_mul_f32_e32 v163, v142, v174
	v_sub_f32_e32 v148, 1.0, v163
	v_cmp_gt_f32_e64 s[0:1], s14, v148
	v_cndmask_b32_e64 v163, v163, 0, s[4:5]
	s_nop 0
	v_cndmask_b32_e64 v171, 0, 32, s[0:1]
	v_ldexp_f32 v148, v148, v171
	v_log_f32_e32 v171, v148
	s_nop 0
	v_mul_f32_e32 v148, 0x3f317217, v171
	v_fma_f32 v172, v171, s9, -v148
	v_pk_add_f32 v[148:149], v[164:165], 1.0 op_sel_hi:[1,0]
	v_fmac_f32_e32 v172, 0x3377d1cf, v171
	v_rcp_f32_e32 v165, v149
	v_fmac_f32_e32 v172, 0x3f317217, v171
	v_cmp_lt_f32_e64 vcc, |v171|, s15
	s_nop 1
	v_cndmask_b32_e32 v171, v171, v172, vcc
	v_rcp_f32_e32 v175, v148
	v_mul_f32_e32 v149, v141, v165
	v_mul_f32_e32 v148, v143, v175
	v_sub_f32_e32 v165, 1.0, v148
	v_cmp_gt_f32_e32 vcc, s14, v165
	v_cndmask_b32_e64 v148, v148, 0, s[4:5]
	v_bfe_u32 v175, v150, 16, 1
	v_cndmask_b32_e64 v172, 0, 32, vcc
	v_ldexp_f32 v165, v165, v172
	v_log_f32_e32 v165, v165
	v_cndmask_b32_e64 v172, 0, v131, s[0:1]
	v_sub_f32_e32 v171, v171, v172
	v_sub_f32_e32 v172, 1.0, v162
	v_cmp_gt_f32_e64 s[0:1], s14, v172
	v_mul_f32_e32 v164, 0x3f317217, v165
	v_fma_f32 v164, v165, s9, -v164
	v_cndmask_b32_e64 v173, 0, 32, s[0:1]
	v_ldexp_f32 v172, v172, v173
	v_fmac_f32_e32 v164, 0x3377d1cf, v165
	v_log_f32_e32 v172, v172
	v_fmac_f32_e32 v164, 0x3f317217, v165
	v_cmp_lt_f32_e64 s[2:3], |v165|, s15
	v_sub_f32_e32 v173, 1.0, v149
	v_cndmask_b32_e64 v149, v149, 0, s[4:5]
	v_cndmask_b32_e64 v164, v165, v164, s[2:3]
	v_cndmask_b32_e32 v165, 0, v131, vcc
	v_cmp_gt_f32_e32 vcc, s14, v173
	v_sub_f32_e32 v164, v164, v165
	v_mul_f32_e32 v165, 0x3f317217, v172
	v_cndmask_b32_e64 v174, 0, 32, vcc
	v_ldexp_f32 v173, v173, v174
	v_fma_f32 v165, v172, s9, -v165
	v_log_f32_e32 v173, v173
	v_fmac_f32_e32 v165, 0x3377d1cf, v172
	v_fmac_f32_e32 v165, 0x3f317217, v172
	v_cmp_lt_f32_e64 s[2:3], |v172|, s15
	v_cndmask_b32_e64 v162, v162, 0, s[4:5]
	v_bfe_u32 v174, v148, 16, 1
	v_cndmask_b32_e64 v165, v172, v165, s[2:3]
	v_cndmask_b32_e64 v172, 0, v131, s[0:1]
	v_sub_f32_e32 v165, v165, v172
	v_mul_f32_e32 v172, 0x3f317217, v173
	v_fma_f32 v172, v173, s9, -v172
	v_fmac_f32_e32 v172, 0x3377d1cf, v173
	v_fmac_f32_e32 v172, 0x3f317217, v173
	v_cmp_lt_f32_e64 s[0:1], |v173|, s15
	v_add3_u32 v175, v150, v175, s16
	v_add3_u32 v148, v148, v174, s16
	v_cndmask_b32_e64 v172, v173, v172, s[0:1]
	v_cndmask_b32_e32 v173, 0, v131, vcc
	v_sub_f32_e32 v172, v172, v173
	v_bfe_u32 v173, v149, 16, 1
	v_add3_u32 v149, v149, v173, s16
	v_bfe_u32 v150, v166, 16, 1
	v_bfe_u32 v173, v163, 16, 1
	v_bfe_u32 v174, v162, 16, 1
	v_add3_u32 v162, v162, v174, s16
	v_add3_u32 v163, v163, v173, s16
	v_add3_u32 v150, v166, v150, s16
	v_lshrrev_b32_e32 v161, 16, v150
	v_lshrrev_b32_e32 v166, 16, v151
	v_lshrrev_b32_e32 v150, 16, v163
	v_lshrrev_b32_e32 v151, 16, v162
	v_and_or_b32 v151, v149, s17, v151
	v_and_or_b32 v150, v148, s17, v150
	v_and_or_b32 v149, v175, s17, v166
	v_and_or_b32 v148, v176, s17, v161
	global_store_dwordx4 v[138:139], v[148:151], off offset:256
	v_cndmask_b32_e64 v138, v167, 0, s[4:5]
	v_bfe_u32 v139, v138, 16, 1
	v_add3_u32 v138, v138, v139, s16
	v_cndmask_b32_e64 v139, v169, 0, s[4:5]
	v_bfe_u32 v148, v139, 16, 1
	v_lshrrev_b32_e32 v138, 16, v138
	v_add3_u32 v139, v139, v148, s16
	v_and_or_b32 v148, v139, s17, v138
	v_cndmask_b32_e64 v138, v168, 0, s[4:5]
	v_bfe_u32 v139, v138, 16, 1
	v_add3_u32 v138, v138, v139, s16
	v_cndmask_b32_e64 v139, v170, 0, s[4:5]
	v_bfe_u32 v149, v139, 16, 1
	v_lshrrev_b32_e32 v138, 16, v138
	v_add3_u32 v139, v139, v149, s16
	v_and_or_b32 v149, v139, s17, v138
	v_cndmask_b32_e64 v138, v171, 0, s[4:5]
	v_bfe_u32 v139, v138, 16, 1
	v_add3_u32 v138, v138, v139, s16
	v_cndmask_b32_e64 v139, v164, 0, s[4:5]
	v_bfe_u32 v150, v139, 16, 1
	v_lshrrev_b32_e32 v138, 16, v138
	v_add3_u32 v139, v139, v150, s16
	v_and_or_b32 v150, v139, s17, v138
	v_cndmask_b32_e64 v138, v165, 0, s[4:5]
	v_bfe_u32 v139, v138, 16, 1
	v_add3_u32 v138, v138, v139, s16
	v_cndmask_b32_e64 v139, v172, 0, s[4:5]
	v_bfe_u32 v151, v139, 16, 1
	v_lshrrev_b32_e32 v138, 16, v138
	v_add3_u32 v139, v139, v151, s16
	v_and_or_b32 v151, v139, s17, v138
	global_store_dwordx4 v[136:137], v[148:151], off offset:256
	v_mul_f32_e32 v161, 0x3fb8aa3b, v42
	v_exp_f32_e32 v162, v161
	v_mul_f32_e32 v149, 0x3fb8aa3b, v47
	v_mul_f32_e32 v148, 0x3fb8aa3b, v46
	v_exp_f32_e32 v150, v149
	v_mul_f32_e32 v149, 0x3fb8aa3b, v48
	v_exp_f32_e32 v148, v148
	v_exp_f32_e32 v149, v149
	v_mul_f32_e32 v161, 0x3fb8aa3b, v43
	s_movk_i32 s2, 0x1ff0
	v_exp_f32_e32 v164, v161
	v_pk_add_f32 v[148:149], v[148:149], 1.0 op_sel_hi:[1,0]
	v_mul_f32_e32 v161, 0x3fb8aa3b, v44
	v_div_scale_f32 v165, s[4:5], v149, v149, v157
	v_rcp_f32_e32 v166, v165
	v_cmp_gt_i32_e32 vcc, s2, v130
	v_exp_f32_e32 v163, v161
	v_mul_f32_e32 v151, 0x3fb8aa3b, v49
	v_fma_f32 v161, -v165, v166, 1.0
	v_cndmask_b32_e64 v137, v154, 0, vcc
	v_fmac_f32_e32 v166, v161, v166
	v_div_scale_f32 v161, vcc, v157, v149, v157
	v_mul_f32_e32 v167, v161, v166
	v_fma_f32 v168, -v165, v167, v161
	v_fmac_f32_e32 v167, v168, v166
	v_rcp_f32_e32 v169, v148
	v_fma_f32 v161, -v165, v167, v161
	v_div_fmas_f32 v161, v161, v166, v167
	v_exp_f32_e32 v151, v151
	v_mul_f32_e32 v166, v156, v169
	v_sub_f32_e32 v148, 1.0, v166
	v_cmp_gt_f32_e64 s[4:5], s14, v148
	v_div_fixup_f32 v161, v161, v149, v157
	v_add_u32_e32 v136, 0x90, v130
	v_cndmask_b32_e64 v165, 0, 32, s[4:5]
	v_ldexp_f32 v148, v148, v165
	v_log_f32_e32 v167, v148
	v_mul_f32_e32 v148, 0x3fb8aa3b, v45
	v_exp_f32_e32 v165, v148
	s_movk_i32 s0, 0x4070
	v_mul_f32_e32 v148, 0x3f317217, v167
	v_fma_f32 v168, v167, s9, -v148
	v_pk_add_f32 v[148:149], v[150:151], 1.0 op_sel_hi:[1,0]
	v_fmac_f32_e32 v168, 0x3377d1cf, v167
	v_rcp_f32_e32 v151, v149
	v_fmac_f32_e32 v168, 0x3f317217, v167
	v_cmp_lt_f32_e64 vcc, |v167|, s15
	v_add_u32_e32 v137, v137, v136
	v_cmp_gt_i32_e64 s[0:1], s0, v130
	v_cndmask_b32_e32 v167, v167, v168, vcc
	v_rcp_f32_e32 v171, v148
	v_mul_f32_e32 v150, v158, v151
	v_mul_f32_e32 v151, v155, v171
	v_sub_f32_e32 v148, 1.0, v151
	v_cmp_gt_f32_e32 vcc, s14, v148
	v_cmp_gt_i32_e64 s[2:3], s18, v137
	v_ashrrev_i32_e32 v137, 31, v136
	v_cndmask_b32_e64 v168, 0, 32, vcc
	v_ldexp_f32 v148, v148, v168
	v_log_f32_e32 v148, v148
	v_cndmask_b32_e64 v168, 0, v131, s[4:5]
	v_sub_f32_e32 v167, v167, v168
	v_sub_f32_e32 v168, 1.0, v161
	v_mul_f32_e32 v149, 0x3f317217, v148
	v_fma_f32 v149, v148, s9, -v149
	v_cmp_gt_f32_e64 s[4:5], s14, v168
	v_fmac_f32_e32 v149, 0x3377d1cf, v148
	v_fmac_f32_e32 v149, 0x3f317217, v148
	v_cndmask_b32_e64 v169, 0, 32, s[4:5]
	v_ldexp_f32 v168, v168, v169
	v_cmp_lt_f32_e64 s[6:7], |v148|, s15
	v_log_f32_e32 v168, v168
	v_lshlrev_b64 v[136:137], 10, v[136:137]
	v_cndmask_b32_e64 v148, v148, v149, s[6:7]
	v_cndmask_b32_e32 v149, 0, v131, vcc
	v_sub_f32_e32 v169, v148, v149
	v_sub_f32_e32 v149, 1.0, v150
	v_cmp_gt_f32_e32 vcc, s14, v149
	v_mul_f32_e32 v148, 0x3f317217, v168
	v_fma_f32 v148, v168, s9, -v148
	v_cndmask_b32_e64 v170, 0, 32, vcc
	v_ldexp_f32 v149, v149, v170
	v_log_f32_e32 v149, v149
	v_fmac_f32_e32 v148, 0x3377d1cf, v168
	v_fmac_f32_e32 v148, 0x3f317217, v168
	v_cmp_lt_f32_e64 s[6:7], |v168|, s15
	v_lshl_add_u64 v[138:139], v[132:133], 0, v[136:137]
	v_lshl_add_u64 v[136:137], v[134:135], 0, v[136:137]
	v_cndmask_b32_e64 v148, v168, v148, s[6:7]
	v_cndmask_b32_e64 v168, 0, v131, s[4:5]
	v_sub_f32_e32 v168, v148, v168
	v_mul_f32_e32 v148, 0x3f317217, v149
	v_fma_f32 v148, v149, s9, -v148
	v_fmac_f32_e32 v148, 0x3377d1cf, v149
	v_fmac_f32_e32 v148, 0x3f317217, v149
	v_cmp_lt_f32_e64 s[4:5], |v149|, s15
	s_nop 1
	v_cndmask_b32_e64 v148, v149, v148, s[4:5]
	v_cndmask_b32_e32 v149, 0, v131, vcc
	v_sub_f32_e32 v170, v148, v149
	v_pk_add_f32 v[148:149], v[162:163], 1.0 op_sel_hi:[1,0]
	s_nop 0
	v_rcp_f32_e32 v163, v149
	s_and_b64 s[4:5], s[0:1], s[2:3]
	v_cndmask_b32_e64 v151, v151, 0, s[4:5]
	v_cndmask_b32_e64 v150, v150, 0, s[4:5]
	v_rcp_f32_e32 v174, v148
	v_mul_f32_e32 v162, v152, v163
	v_mul_f32_e32 v163, v159, v174
	v_sub_f32_e32 v148, 1.0, v163
	v_cmp_gt_f32_e64 s[0:1], s14, v148
	v_cndmask_b32_e64 v161, v161, 0, s[4:5]
	v_cndmask_b32_e64 v166, v166, 0, s[4:5]
	v_cndmask_b32_e64 v171, 0, 32, s[0:1]
	v_ldexp_f32 v148, v148, v171
	v_log_f32_e32 v171, v148
	v_cndmask_b32_e64 v163, v163, 0, s[4:5]
	v_bfe_u32 v176, v151, 16, 1
	v_add3_u32 v176, v151, v176, s16
	v_mul_f32_e32 v148, 0x3f317217, v171
	v_fma_f32 v172, v171, s9, -v148
	v_pk_add_f32 v[148:149], v[164:165], 1.0 op_sel_hi:[1,0]
	v_fmac_f32_e32 v172, 0x3377d1cf, v171
	v_rcp_f32_e32 v165, v149
	v_fmac_f32_e32 v172, 0x3f317217, v171
	v_cmp_lt_f32_e64 vcc, |v171|, s15
	v_bfe_u32 v151, v161, 16, 1
	v_add3_u32 v151, v161, v151, s16
	v_cndmask_b32_e32 v171, v171, v172, vcc
	v_rcp_f32_e32 v175, v148
	v_mul_f32_e32 v149, v153, v165
	v_mul_f32_e32 v148, v160, v175
	v_sub_f32_e32 v165, 1.0, v148
	v_cmp_gt_f32_e32 vcc, s14, v165
	v_cndmask_b32_e64 v148, v148, 0, s[4:5]
	v_bfe_u32 v175, v150, 16, 1
	v_cndmask_b32_e64 v172, 0, 32, vcc
	v_ldexp_f32 v165, v165, v172
	v_log_f32_e32 v165, v165
	v_cndmask_b32_e64 v172, 0, v131, s[0:1]
	v_sub_f32_e32 v171, v171, v172
	v_sub_f32_e32 v172, 1.0, v162
	v_cmp_gt_f32_e64 s[0:1], s14, v172
	v_mul_f32_e32 v164, 0x3f317217, v165
	v_fma_f32 v164, v165, s9, -v164
	v_cndmask_b32_e64 v173, 0, 32, s[0:1]
	v_ldexp_f32 v172, v172, v173
	v_fmac_f32_e32 v164, 0x3377d1cf, v165
	v_log_f32_e32 v172, v172
	v_fmac_f32_e32 v164, 0x3f317217, v165
	v_cmp_lt_f32_e64 s[2:3], |v165|, s15
	v_sub_f32_e32 v173, 1.0, v149
	v_cndmask_b32_e64 v149, v149, 0, s[4:5]
	v_cndmask_b32_e64 v164, v165, v164, s[2:3]
	v_cndmask_b32_e32 v165, 0, v131, vcc
	v_cmp_gt_f32_e32 vcc, s14, v173
	v_sub_f32_e32 v164, v164, v165
	v_mul_f32_e32 v165, 0x3f317217, v172
	v_cndmask_b32_e64 v174, 0, 32, vcc
	v_ldexp_f32 v173, v173, v174
	v_fma_f32 v165, v172, s9, -v165
	v_log_f32_e32 v173, v173
	v_fmac_f32_e32 v165, 0x3377d1cf, v172
	v_fmac_f32_e32 v165, 0x3f317217, v172
	v_cmp_lt_f32_e64 s[2:3], |v172|, s15
	v_cndmask_b32_e64 v162, v162, 0, s[4:5]
	v_bfe_u32 v174, v148, 16, 1
	v_cndmask_b32_e64 v165, v172, v165, s[2:3]
	v_cndmask_b32_e64 v172, 0, v131, s[0:1]
	v_sub_f32_e32 v165, v165, v172
	v_mul_f32_e32 v172, 0x3f317217, v173
	v_fma_f32 v172, v173, s9, -v172
	v_fmac_f32_e32 v172, 0x3377d1cf, v173
	v_fmac_f32_e32 v172, 0x3f317217, v173
	v_cmp_lt_f32_e64 s[0:1], |v173|, s15
	v_add3_u32 v175, v150, v175, s16
	v_add3_u32 v148, v148, v174, s16
	v_cndmask_b32_e64 v172, v173, v172, s[0:1]
	v_cndmask_b32_e32 v173, 0, v131, vcc
	v_sub_f32_e32 v172, v172, v173
	v_bfe_u32 v173, v149, 16, 1
	v_add3_u32 v149, v149, v173, s16
	v_bfe_u32 v150, v166, 16, 1
	v_bfe_u32 v173, v163, 16, 1
	v_bfe_u32 v174, v162, 16, 1
	v_add3_u32 v162, v162, v174, s16
	v_add3_u32 v163, v163, v173, s16
	v_add3_u32 v150, v166, v150, s16
	v_lshrrev_b32_e32 v161, 16, v150
	v_lshrrev_b32_e32 v166, 16, v151
	v_lshrrev_b32_e32 v150, 16, v163
	v_lshrrev_b32_e32 v151, 16, v162
	v_and_or_b32 v151, v149, s17, v151
	v_and_or_b32 v150, v148, s17, v150
	v_and_or_b32 v149, v175, s17, v166
	v_and_or_b32 v148, v176, s17, v161
	global_store_dwordx4 v[138:139], v[148:151], off
	s_nop 1
	v_cndmask_b32_e64 v148, v167, 0, s[4:5]
	v_bfe_u32 v149, v148, 16, 1
	v_add3_u32 v148, v148, v149, s16
	v_cndmask_b32_e64 v149, v169, 0, s[4:5]
	v_bfe_u32 v150, v149, 16, 1
	v_lshrrev_b32_e32 v148, 16, v148
	v_add3_u32 v149, v149, v150, s16
	v_and_or_b32 v148, v149, s17, v148
	v_cndmask_b32_e64 v149, v168, 0, s[4:5]
	v_bfe_u32 v150, v149, 16, 1
	v_add3_u32 v149, v149, v150, s16
	v_cndmask_b32_e64 v150, v170, 0, s[4:5]
	v_bfe_u32 v151, v150, 16, 1
	v_lshrrev_b32_e32 v149, 16, v149
	v_add3_u32 v150, v150, v151, s16
	v_and_or_b32 v149, v150, s17, v149
	v_cndmask_b32_e64 v150, v171, 0, s[4:5]
	v_bfe_u32 v151, v150, 16, 1
	v_add3_u32 v150, v150, v151, s16
	v_cndmask_b32_e64 v151, v164, 0, s[4:5]
	v_bfe_u32 v161, v151, 16, 1
	v_lshrrev_b32_e32 v150, 16, v150
	v_add3_u32 v151, v151, v161, s16
	v_and_or_b32 v150, v151, s17, v150
	v_cndmask_b32_e64 v151, v165, 0, s[4:5]
	v_bfe_u32 v161, v151, 16, 1
	v_add3_u32 v151, v151, v161, s16
	v_cndmask_b32_e64 v161, v172, 0, s[4:5]
	v_bfe_u32 v162, v161, 16, 1
	v_lshrrev_b32_e32 v151, 16, v151
	v_add3_u32 v161, v161, v162, s16
	v_and_or_b32 v151, v161, s17, v151
	global_store_dwordx4 v[136:137], v[148:151], off
	v_mul_f32_e32 v161, 0x3fb8aa3b, v34
	v_exp_f32_e32 v162, v161
	v_mul_f32_e32 v149, 0x3fb8aa3b, v39
	v_mul_f32_e32 v148, 0x3fb8aa3b, v38
	v_exp_f32_e32 v150, v149
	v_mul_f32_e32 v149, 0x3fb8aa3b, v40
	v_exp_f32_e32 v148, v148
	v_exp_f32_e32 v149, v149
	v_mul_f32_e32 v161, 0x3fb8aa3b, v35
	v_exp_f32_e32 v164, v161
	v_mul_f32_e32 v161, 0x3fb8aa3b, v36
	v_pk_add_f32 v[148:149], v[148:149], 1.0 op_sel_hi:[1,0]
	v_exp_f32_e32 v163, v161
	v_rcp_f32_e32 v166, v149
	v_mul_f32_e32 v151, 0x3fb8aa3b, v41
	v_exp_f32_e32 v151, v151
	v_rcp_f32_e32 v169, v148
	v_mul_f32_e32 v161, v144, v166
	v_mul_f32_e32 v166, v146, v169
	v_sub_f32_e32 v148, 1.0, v166
	v_cmp_gt_f32_e64 s[0:1], s14, v148
	v_cndmask_b32_e64 v166, v166, 0, s[4:5]
	s_nop 0
	v_cndmask_b32_e64 v165, 0, 32, s[0:1]
	v_ldexp_f32 v148, v148, v165
	v_log_f32_e32 v167, v148
	v_mul_f32_e32 v148, 0x3fb8aa3b, v37
	v_exp_f32_e32 v165, v148
	v_mul_f32_e32 v148, 0x3f317217, v167
	v_fma_f32 v168, v167, s9, -v148
	v_pk_add_f32 v[148:149], v[150:151], 1.0 op_sel_hi:[1,0]
	v_fmac_f32_e32 v168, 0x3377d1cf, v167
	v_rcp_f32_e32 v151, v149
	v_fmac_f32_e32 v168, 0x3f317217, v167
	v_cmp_lt_f32_e64 vcc, |v167|, s15
	s_nop 1
	v_cndmask_b32_e32 v167, v167, v168, vcc
	v_rcp_f32_e32 v171, v148
	v_mul_f32_e32 v150, v145, v151
	v_mul_f32_e32 v151, v147, v171
	v_sub_f32_e32 v148, 1.0, v151
	v_cmp_gt_f32_e32 vcc, s14, v148
	v_cndmask_b32_e64 v151, v151, 0, s[4:5]
	v_bfe_u32 v176, v151, 16, 1
	v_cndmask_b32_e64 v168, 0, 32, vcc
	v_ldexp_f32 v148, v148, v168
	v_log_f32_e32 v148, v148
	v_cndmask_b32_e64 v168, 0, v131, s[0:1]
	v_sub_f32_e32 v167, v167, v168
	v_sub_f32_e32 v168, 1.0, v161
	v_mul_f32_e32 v149, 0x3f317217, v148
	v_fma_f32 v149, v148, s9, -v149
	v_cmp_gt_f32_e64 s[0:1], s14, v168
	v_fmac_f32_e32 v149, 0x3377d1cf, v148
	v_fmac_f32_e32 v149, 0x3f317217, v148
	v_cndmask_b32_e64 v169, 0, 32, s[0:1]
	v_ldexp_f32 v168, v168, v169
	v_cmp_lt_f32_e64 s[2:3], |v148|, s15
	v_log_f32_e32 v168, v168
	v_cndmask_b32_e64 v161, v161, 0, s[4:5]
	v_cndmask_b32_e64 v148, v148, v149, s[2:3]
	v_cndmask_b32_e32 v149, 0, v131, vcc
	v_sub_f32_e32 v169, v148, v149
	v_sub_f32_e32 v149, 1.0, v150
	v_cmp_gt_f32_e32 vcc, s14, v149
	v_mul_f32_e32 v148, 0x3f317217, v168
	v_fma_f32 v148, v168, s9, -v148
	v_cndmask_b32_e64 v170, 0, 32, vcc
	v_ldexp_f32 v149, v149, v170
	v_log_f32_e32 v149, v149
	v_fmac_f32_e32 v148, 0x3377d1cf, v168
	v_fmac_f32_e32 v148, 0x3f317217, v168
	v_cmp_lt_f32_e64 s[2:3], |v168|, s15
	v_cndmask_b32_e32 v171, 0, v131, vcc
	v_cndmask_b32_e64 v150, v150, 0, s[4:5]
	v_cndmask_b32_e64 v148, v168, v148, s[2:3]
	v_cndmask_b32_e64 v168, 0, v131, s[0:1]
	v_sub_f32_e32 v168, v148, v168
	v_mul_f32_e32 v148, 0x3f317217, v149
	v_fma_f32 v148, v149, s9, -v148
	v_fmac_f32_e32 v148, 0x3377d1cf, v149
	v_fmac_f32_e32 v148, 0x3f317217, v149
	v_cmp_lt_f32_e64 s[0:1], |v149|, s15
	v_add3_u32 v176, v151, v176, s16
	v_bfe_u32 v151, v161, 16, 1
	v_cndmask_b32_e64 v170, v149, v148, s[0:1]
	v_pk_add_f32 v[148:149], v[162:163], 1.0 op_sel_hi:[1,0]
	v_sub_f32_e32 v170, v170, v171
	v_rcp_f32_e32 v163, v149
	v_add3_u32 v151, v161, v151, s16
	v_rcp_f32_e32 v174, v148
	v_mul_f32_e32 v162, v140, v163
	v_mul_f32_e32 v163, v142, v174
	v_sub_f32_e32 v148, 1.0, v163
	v_cmp_gt_f32_e64 s[0:1], s14, v148
	v_cndmask_b32_e64 v163, v163, 0, s[4:5]
	s_nop 0
	v_cndmask_b32_e64 v171, 0, 32, s[0:1]
	v_ldexp_f32 v148, v148, v171
	v_log_f32_e32 v171, v148
	s_nop 0
	v_mul_f32_e32 v148, 0x3f317217, v171
	v_fma_f32 v172, v171, s9, -v148
	v_pk_add_f32 v[148:149], v[164:165], 1.0 op_sel_hi:[1,0]
	v_fmac_f32_e32 v172, 0x3377d1cf, v171
	v_rcp_f32_e32 v165, v149
	v_fmac_f32_e32 v172, 0x3f317217, v171
	v_cmp_lt_f32_e64 vcc, |v171|, s15
	s_nop 1
	v_cndmask_b32_e32 v171, v171, v172, vcc
	v_rcp_f32_e32 v175, v148
	v_mul_f32_e32 v149, v141, v165
	v_mul_f32_e32 v148, v143, v175
	v_sub_f32_e32 v165, 1.0, v148
	v_cmp_gt_f32_e32 vcc, s14, v165
	v_cndmask_b32_e64 v148, v148, 0, s[4:5]
	v_bfe_u32 v175, v150, 16, 1
	v_cndmask_b32_e64 v172, 0, 32, vcc
	v_ldexp_f32 v165, v165, v172
	v_log_f32_e32 v165, v165
	v_cndmask_b32_e64 v172, 0, v131, s[0:1]
	v_sub_f32_e32 v171, v171, v172
	v_sub_f32_e32 v172, 1.0, v162
	v_cmp_gt_f32_e64 s[0:1], s14, v172
	v_mul_f32_e32 v164, 0x3f317217, v165
	v_fma_f32 v164, v165, s9, -v164
	v_cndmask_b32_e64 v173, 0, 32, s[0:1]
	v_ldexp_f32 v172, v172, v173
	v_fmac_f32_e32 v164, 0x3377d1cf, v165
	v_log_f32_e32 v172, v172
	v_fmac_f32_e32 v164, 0x3f317217, v165
	v_cmp_lt_f32_e64 s[2:3], |v165|, s15
	v_sub_f32_e32 v173, 1.0, v149
	v_cndmask_b32_e64 v149, v149, 0, s[4:5]
	v_cndmask_b32_e64 v164, v165, v164, s[2:3]
	v_cndmask_b32_e32 v165, 0, v131, vcc
	v_cmp_gt_f32_e32 vcc, s14, v173
	v_sub_f32_e32 v164, v164, v165
	v_mul_f32_e32 v165, 0x3f317217, v172
	v_cndmask_b32_e64 v174, 0, 32, vcc
	v_ldexp_f32 v173, v173, v174
	v_fma_f32 v165, v172, s9, -v165
	v_log_f32_e32 v173, v173
	v_fmac_f32_e32 v165, 0x3377d1cf, v172
	v_fmac_f32_e32 v165, 0x3f317217, v172
	v_cmp_lt_f32_e64 s[2:3], |v172|, s15
	v_cndmask_b32_e64 v162, v162, 0, s[4:5]
	v_bfe_u32 v174, v148, 16, 1
	v_cndmask_b32_e64 v165, v172, v165, s[2:3]
	v_cndmask_b32_e64 v172, 0, v131, s[0:1]
	v_sub_f32_e32 v165, v165, v172
	v_mul_f32_e32 v172, 0x3f317217, v173
	v_fma_f32 v172, v173, s9, -v172
	v_fmac_f32_e32 v172, 0x3377d1cf, v173
	v_fmac_f32_e32 v172, 0x3f317217, v173
	v_cmp_lt_f32_e64 s[0:1], |v173|, s15
	v_add3_u32 v175, v150, v175, s16
	v_add3_u32 v148, v148, v174, s16
	v_cndmask_b32_e64 v172, v173, v172, s[0:1]
	v_cndmask_b32_e32 v173, 0, v131, vcc
	v_sub_f32_e32 v172, v172, v173
	v_bfe_u32 v173, v149, 16, 1
	v_add3_u32 v149, v149, v173, s16
	v_bfe_u32 v150, v166, 16, 1
	v_bfe_u32 v173, v163, 16, 1
	v_bfe_u32 v174, v162, 16, 1
	v_add3_u32 v162, v162, v174, s16
	v_add3_u32 v163, v163, v173, s16
	v_add3_u32 v150, v166, v150, s16
	v_lshrrev_b32_e32 v161, 16, v150
	v_lshrrev_b32_e32 v166, 16, v151
	v_lshrrev_b32_e32 v150, 16, v163
	v_lshrrev_b32_e32 v151, 16, v162
	v_and_or_b32 v151, v149, s17, v151
	v_and_or_b32 v150, v148, s17, v150
	v_and_or_b32 v149, v175, s17, v166
	v_and_or_b32 v148, v176, s17, v161
	global_store_dwordx4 v[138:139], v[148:151], off offset:256
	v_cndmask_b32_e64 v138, v167, 0, s[4:5]
	v_bfe_u32 v139, v138, 16, 1
	v_add3_u32 v138, v138, v139, s16
	v_cndmask_b32_e64 v139, v169, 0, s[4:5]
	v_bfe_u32 v148, v139, 16, 1
	v_lshrrev_b32_e32 v138, 16, v138
	v_add3_u32 v139, v139, v148, s16
	v_and_or_b32 v148, v139, s17, v138
	v_cndmask_b32_e64 v138, v168, 0, s[4:5]
	v_bfe_u32 v139, v138, 16, 1
	v_add3_u32 v138, v138, v139, s16
	v_cndmask_b32_e64 v139, v170, 0, s[4:5]
	v_bfe_u32 v149, v139, 16, 1
	v_lshrrev_b32_e32 v138, 16, v138
	v_add3_u32 v139, v139, v149, s16
	v_and_or_b32 v149, v139, s17, v138
	v_cndmask_b32_e64 v138, v171, 0, s[4:5]
	v_bfe_u32 v139, v138, 16, 1
	v_add3_u32 v138, v138, v139, s16
	v_cndmask_b32_e64 v139, v164, 0, s[4:5]
	v_bfe_u32 v150, v139, 16, 1
	v_lshrrev_b32_e32 v138, 16, v138
	v_add3_u32 v139, v139, v150, s16
	v_and_or_b32 v150, v139, s17, v138
	v_cndmask_b32_e64 v138, v165, 0, s[4:5]
	v_bfe_u32 v139, v138, 16, 1
	v_add3_u32 v138, v138, v139, s16
	v_cndmask_b32_e64 v139, v172, 0, s[4:5]
	v_bfe_u32 v151, v139, 16, 1
	v_lshrrev_b32_e32 v138, 16, v138
	v_add3_u32 v139, v139, v151, s16
	v_and_or_b32 v151, v139, s17, v138
	global_store_dwordx4 v[136:137], v[148:151], off offset:256
	v_mul_f32_e32 v161, 0x3fb8aa3b, v26
	v_exp_f32_e32 v162, v161
	v_mul_f32_e32 v149, 0x3fb8aa3b, v31
	v_mul_f32_e32 v148, 0x3fb8aa3b, v30
	v_exp_f32_e32 v150, v149
	v_mul_f32_e32 v149, 0x3fb8aa3b, v32
	v_exp_f32_e32 v148, v148
	v_exp_f32_e32 v149, v149
	v_mul_f32_e32 v161, 0x3fb8aa3b, v27
	s_movk_i32 s2, 0x1fe0
	v_exp_f32_e32 v164, v161
	v_pk_add_f32 v[148:149], v[148:149], 1.0 op_sel_hi:[1,0]
	v_mul_f32_e32 v161, 0x3fb8aa3b, v28
	v_div_scale_f32 v165, s[4:5], v149, v149, v157
	v_rcp_f32_e32 v166, v165
	v_cmp_gt_i32_e32 vcc, s2, v130
	v_exp_f32_e32 v163, v161
	v_mul_f32_e32 v151, 0x3fb8aa3b, v33
	v_fma_f32 v161, -v165, v166, 1.0
	v_cndmask_b32_e64 v137, v154, 0, vcc
	v_fmac_f32_e32 v166, v161, v166
	v_div_scale_f32 v161, vcc, v157, v149, v157
	v_mul_f32_e32 v167, v161, v166
	v_fma_f32 v168, -v165, v167, v161
	v_fmac_f32_e32 v167, v168, v166
	v_rcp_f32_e32 v169, v148
	v_fma_f32 v161, -v165, v167, v161
	v_div_fmas_f32 v161, v161, v166, v167
	v_exp_f32_e32 v151, v151
	v_mul_f32_e32 v166, v156, v169
	v_sub_f32_e32 v148, 1.0, v166
	v_cmp_gt_f32_e64 s[4:5], s14, v148
	v_div_fixup_f32 v161, v161, v149, v157
	v_add_u32_e32 v136, 0xa0, v130
	v_cndmask_b32_e64 v165, 0, 32, s[4:5]
	v_ldexp_f32 v148, v148, v165
	v_log_f32_e32 v167, v148
	v_mul_f32_e32 v148, 0x3fb8aa3b, v29
	v_exp_f32_e32 v165, v148
	s_movk_i32 s0, 0x4060
	v_mul_f32_e32 v148, 0x3f317217, v167
	v_fma_f32 v168, v167, s9, -v148
	v_pk_add_f32 v[148:149], v[150:151], 1.0 op_sel_hi:[1,0]
	v_fmac_f32_e32 v168, 0x3377d1cf, v167
	v_rcp_f32_e32 v151, v149
	v_fmac_f32_e32 v168, 0x3f317217, v167
	v_cmp_lt_f32_e64 vcc, |v167|, s15
	v_add_u32_e32 v137, v137, v136
	v_cmp_gt_i32_e64 s[0:1], s0, v130
	v_cndmask_b32_e32 v167, v167, v168, vcc
	v_rcp_f32_e32 v171, v148
	v_mul_f32_e32 v150, v158, v151
	v_mul_f32_e32 v151, v155, v171
	v_sub_f32_e32 v148, 1.0, v151
	v_cmp_gt_f32_e32 vcc, s14, v148
	v_cmp_gt_i32_e64 s[2:3], s18, v137
	v_ashrrev_i32_e32 v137, 31, v136
	v_cndmask_b32_e64 v168, 0, 32, vcc
	v_ldexp_f32 v148, v148, v168
	v_log_f32_e32 v148, v148
	v_cndmask_b32_e64 v168, 0, v131, s[4:5]
	v_sub_f32_e32 v167, v167, v168
	v_sub_f32_e32 v168, 1.0, v161
	v_mul_f32_e32 v149, 0x3f317217, v148
	v_fma_f32 v149, v148, s9, -v149
	v_cmp_gt_f32_e64 s[4:5], s14, v168
	v_fmac_f32_e32 v149, 0x3377d1cf, v148
	v_fmac_f32_e32 v149, 0x3f317217, v148
	v_cndmask_b32_e64 v169, 0, 32, s[4:5]
	v_ldexp_f32 v168, v168, v169
	v_cmp_lt_f32_e64 s[6:7], |v148|, s15
	v_log_f32_e32 v168, v168
	v_lshlrev_b64 v[136:137], 10, v[136:137]
	v_cndmask_b32_e64 v148, v148, v149, s[6:7]
	v_cndmask_b32_e32 v149, 0, v131, vcc
	v_sub_f32_e32 v169, v148, v149
	v_sub_f32_e32 v149, 1.0, v150
	v_cmp_gt_f32_e32 vcc, s14, v149
	v_mul_f32_e32 v148, 0x3f317217, v168
	v_fma_f32 v148, v168, s9, -v148
	v_cndmask_b32_e64 v170, 0, 32, vcc
	v_ldexp_f32 v149, v149, v170
	v_log_f32_e32 v149, v149
	v_fmac_f32_e32 v148, 0x3377d1cf, v168
	v_fmac_f32_e32 v148, 0x3f317217, v168
	v_cmp_lt_f32_e64 s[6:7], |v168|, s15
	v_lshl_add_u64 v[138:139], v[132:133], 0, v[136:137]
	v_lshl_add_u64 v[136:137], v[134:135], 0, v[136:137]
	v_cndmask_b32_e64 v148, v168, v148, s[6:7]
	v_cndmask_b32_e64 v168, 0, v131, s[4:5]
	v_sub_f32_e32 v168, v148, v168
	v_mul_f32_e32 v148, 0x3f317217, v149
	v_fma_f32 v148, v149, s9, -v148
	v_fmac_f32_e32 v148, 0x3377d1cf, v149
	v_fmac_f32_e32 v148, 0x3f317217, v149
	v_cmp_lt_f32_e64 s[4:5], |v149|, s15
	s_nop 1
	v_cndmask_b32_e64 v148, v149, v148, s[4:5]
	v_cndmask_b32_e32 v149, 0, v131, vcc
	v_sub_f32_e32 v170, v148, v149
	v_pk_add_f32 v[148:149], v[162:163], 1.0 op_sel_hi:[1,0]
	s_nop 0
	v_rcp_f32_e32 v163, v149
	s_and_b64 s[4:5], s[0:1], s[2:3]
	v_cndmask_b32_e64 v151, v151, 0, s[4:5]
	v_cndmask_b32_e64 v150, v150, 0, s[4:5]
	v_rcp_f32_e32 v174, v148
	v_mul_f32_e32 v162, v152, v163
	v_mul_f32_e32 v163, v159, v174
	v_sub_f32_e32 v148, 1.0, v163
	v_cmp_gt_f32_e64 s[0:1], s14, v148
	v_cndmask_b32_e64 v161, v161, 0, s[4:5]
	v_cndmask_b32_e64 v166, v166, 0, s[4:5]
	v_cndmask_b32_e64 v171, 0, 32, s[0:1]
	v_ldexp_f32 v148, v148, v171
	v_log_f32_e32 v171, v148
	v_cndmask_b32_e64 v163, v163, 0, s[4:5]
	v_bfe_u32 v176, v151, 16, 1
	v_add3_u32 v176, v151, v176, s16
	v_mul_f32_e32 v148, 0x3f317217, v171
	v_fma_f32 v172, v171, s9, -v148
	v_pk_add_f32 v[148:149], v[164:165], 1.0 op_sel_hi:[1,0]
	v_fmac_f32_e32 v172, 0x3377d1cf, v171
	v_rcp_f32_e32 v165, v149
	v_fmac_f32_e32 v172, 0x3f317217, v171
	v_cmp_lt_f32_e64 vcc, |v171|, s15
	v_bfe_u32 v151, v161, 16, 1
	v_add3_u32 v151, v161, v151, s16
	v_cndmask_b32_e32 v171, v171, v172, vcc
	v_rcp_f32_e32 v175, v148
	v_mul_f32_e32 v149, v153, v165
	v_mul_f32_e32 v148, v160, v175
	v_sub_f32_e32 v165, 1.0, v148
	v_cmp_gt_f32_e32 vcc, s14, v165
	v_cndmask_b32_e64 v148, v148, 0, s[4:5]
	v_bfe_u32 v175, v150, 16, 1
	v_cndmask_b32_e64 v172, 0, 32, vcc
	v_ldexp_f32 v165, v165, v172
	v_log_f32_e32 v165, v165
	v_cndmask_b32_e64 v172, 0, v131, s[0:1]
	v_sub_f32_e32 v171, v171, v172
	v_sub_f32_e32 v172, 1.0, v162
	v_cmp_gt_f32_e64 s[0:1], s14, v172
	v_mul_f32_e32 v164, 0x3f317217, v165
	v_fma_f32 v164, v165, s9, -v164
	v_cndmask_b32_e64 v173, 0, 32, s[0:1]
	v_ldexp_f32 v172, v172, v173
	v_fmac_f32_e32 v164, 0x3377d1cf, v165
	v_log_f32_e32 v172, v172
	v_fmac_f32_e32 v164, 0x3f317217, v165
	v_cmp_lt_f32_e64 s[2:3], |v165|, s15
	v_sub_f32_e32 v173, 1.0, v149
	v_cndmask_b32_e64 v149, v149, 0, s[4:5]
	v_cndmask_b32_e64 v164, v165, v164, s[2:3]
	v_cndmask_b32_e32 v165, 0, v131, vcc
	v_cmp_gt_f32_e32 vcc, s14, v173
	v_sub_f32_e32 v164, v164, v165
	v_mul_f32_e32 v165, 0x3f317217, v172
	v_cndmask_b32_e64 v174, 0, 32, vcc
	v_ldexp_f32 v173, v173, v174
	v_fma_f32 v165, v172, s9, -v165
	v_log_f32_e32 v173, v173
	v_fmac_f32_e32 v165, 0x3377d1cf, v172
	v_fmac_f32_e32 v165, 0x3f317217, v172
	v_cmp_lt_f32_e64 s[2:3], |v172|, s15
	v_cndmask_b32_e64 v162, v162, 0, s[4:5]
	v_bfe_u32 v174, v148, 16, 1
	v_cndmask_b32_e64 v165, v172, v165, s[2:3]
	v_cndmask_b32_e64 v172, 0, v131, s[0:1]
	v_sub_f32_e32 v165, v165, v172
	v_mul_f32_e32 v172, 0x3f317217, v173
	v_fma_f32 v172, v173, s9, -v172
	v_fmac_f32_e32 v172, 0x3377d1cf, v173
	v_fmac_f32_e32 v172, 0x3f317217, v173
	v_cmp_lt_f32_e64 s[0:1], |v173|, s15
	v_add3_u32 v175, v150, v175, s16
	v_add3_u32 v148, v148, v174, s16
	v_cndmask_b32_e64 v172, v173, v172, s[0:1]
	v_cndmask_b32_e32 v173, 0, v131, vcc
	v_sub_f32_e32 v172, v172, v173
	v_bfe_u32 v173, v149, 16, 1
	v_add3_u32 v149, v149, v173, s16
	v_bfe_u32 v150, v166, 16, 1
	v_bfe_u32 v173, v163, 16, 1
	v_bfe_u32 v174, v162, 16, 1
	v_add3_u32 v162, v162, v174, s16
	v_add3_u32 v163, v163, v173, s16
	v_add3_u32 v150, v166, v150, s16
	v_lshrrev_b32_e32 v161, 16, v150
	v_lshrrev_b32_e32 v166, 16, v151
	v_lshrrev_b32_e32 v150, 16, v163
	v_lshrrev_b32_e32 v151, 16, v162
	v_and_or_b32 v151, v149, s17, v151
	v_and_or_b32 v150, v148, s17, v150
	v_and_or_b32 v149, v175, s17, v166
	v_and_or_b32 v148, v176, s17, v161
	global_store_dwordx4 v[138:139], v[148:151], off
	s_nop 1
	v_cndmask_b32_e64 v148, v167, 0, s[4:5]
	v_bfe_u32 v149, v148, 16, 1
	v_add3_u32 v148, v148, v149, s16
	v_cndmask_b32_e64 v149, v169, 0, s[4:5]
	v_bfe_u32 v150, v149, 16, 1
	v_lshrrev_b32_e32 v148, 16, v148
	v_add3_u32 v149, v149, v150, s16
	v_and_or_b32 v148, v149, s17, v148
	v_cndmask_b32_e64 v149, v168, 0, s[4:5]
	v_bfe_u32 v150, v149, 16, 1
	v_add3_u32 v149, v149, v150, s16
	v_cndmask_b32_e64 v150, v170, 0, s[4:5]
	v_bfe_u32 v151, v150, 16, 1
	v_lshrrev_b32_e32 v149, 16, v149
	v_add3_u32 v150, v150, v151, s16
	v_and_or_b32 v149, v150, s17, v149
	v_cndmask_b32_e64 v150, v171, 0, s[4:5]
	v_bfe_u32 v151, v150, 16, 1
	v_add3_u32 v150, v150, v151, s16
	v_cndmask_b32_e64 v151, v164, 0, s[4:5]
	v_bfe_u32 v161, v151, 16, 1
	v_lshrrev_b32_e32 v150, 16, v150
	v_add3_u32 v151, v151, v161, s16
	v_and_or_b32 v150, v151, s17, v150
	v_cndmask_b32_e64 v151, v165, 0, s[4:5]
	v_bfe_u32 v161, v151, 16, 1
	v_add3_u32 v151, v151, v161, s16
	v_cndmask_b32_e64 v161, v172, 0, s[4:5]
	v_bfe_u32 v162, v161, 16, 1
	v_lshrrev_b32_e32 v151, 16, v151
	v_add3_u32 v161, v161, v162, s16
	v_and_or_b32 v151, v161, s17, v151
	global_store_dwordx4 v[136:137], v[148:151], off
	v_mul_f32_e32 v161, 0x3fb8aa3b, v18
	v_exp_f32_e32 v162, v161
	v_mul_f32_e32 v149, 0x3fb8aa3b, v23
	v_mul_f32_e32 v148, 0x3fb8aa3b, v22
	v_exp_f32_e32 v150, v149
	v_mul_f32_e32 v149, 0x3fb8aa3b, v24
	v_exp_f32_e32 v148, v148
	v_exp_f32_e32 v149, v149
	v_mul_f32_e32 v161, 0x3fb8aa3b, v19
	v_exp_f32_e32 v164, v161
	v_mul_f32_e32 v161, 0x3fb8aa3b, v20
	v_pk_add_f32 v[148:149], v[148:149], 1.0 op_sel_hi:[1,0]
	v_exp_f32_e32 v163, v161
	v_rcp_f32_e32 v166, v149
	v_mul_f32_e32 v151, 0x3fb8aa3b, v25
	v_exp_f32_e32 v151, v151
	v_rcp_f32_e32 v169, v148
	v_mul_f32_e32 v161, v144, v166
	v_mul_f32_e32 v166, v146, v169
	v_sub_f32_e32 v148, 1.0, v166
	v_cmp_gt_f32_e64 s[0:1], s14, v148
	v_cndmask_b32_e64 v166, v166, 0, s[4:5]
	s_nop 0
	v_cndmask_b32_e64 v165, 0, 32, s[0:1]
	v_ldexp_f32 v148, v148, v165
	v_log_f32_e32 v167, v148
	v_mul_f32_e32 v148, 0x3fb8aa3b, v21
	v_exp_f32_e32 v165, v148
	v_mul_f32_e32 v148, 0x3f317217, v167
	v_fma_f32 v168, v167, s9, -v148
	v_pk_add_f32 v[148:149], v[150:151], 1.0 op_sel_hi:[1,0]
	v_fmac_f32_e32 v168, 0x3377d1cf, v167
	v_rcp_f32_e32 v151, v149
	v_fmac_f32_e32 v168, 0x3f317217, v167
	v_cmp_lt_f32_e64 vcc, |v167|, s15
	s_nop 1
	v_cndmask_b32_e32 v167, v167, v168, vcc
	v_rcp_f32_e32 v171, v148
	v_mul_f32_e32 v150, v145, v151
	v_mul_f32_e32 v151, v147, v171
	v_sub_f32_e32 v148, 1.0, v151
	v_cmp_gt_f32_e32 vcc, s14, v148
	v_cndmask_b32_e64 v151, v151, 0, s[4:5]
	v_bfe_u32 v176, v151, 16, 1
	v_cndmask_b32_e64 v168, 0, 32, vcc
	v_ldexp_f32 v148, v148, v168
	v_log_f32_e32 v148, v148
	v_cndmask_b32_e64 v168, 0, v131, s[0:1]
	v_sub_f32_e32 v167, v167, v168
	v_sub_f32_e32 v168, 1.0, v161
	v_mul_f32_e32 v149, 0x3f317217, v148
	v_fma_f32 v149, v148, s9, -v149
	v_cmp_gt_f32_e64 s[0:1], s14, v168
	v_fmac_f32_e32 v149, 0x3377d1cf, v148
	v_fmac_f32_e32 v149, 0x3f317217, v148
	v_cndmask_b32_e64 v169, 0, 32, s[0:1]
	v_ldexp_f32 v168, v168, v169
	v_cmp_lt_f32_e64 s[2:3], |v148|, s15
	v_log_f32_e32 v168, v168
	v_cndmask_b32_e64 v161, v161, 0, s[4:5]
	v_cndmask_b32_e64 v148, v148, v149, s[2:3]
	v_cndmask_b32_e32 v149, 0, v131, vcc
	v_sub_f32_e32 v169, v148, v149
	v_sub_f32_e32 v149, 1.0, v150
	v_cmp_gt_f32_e32 vcc, s14, v149
	v_mul_f32_e32 v148, 0x3f317217, v168
	v_fma_f32 v148, v168, s9, -v148
	v_cndmask_b32_e64 v170, 0, 32, vcc
	v_ldexp_f32 v149, v149, v170
	v_log_f32_e32 v149, v149
	v_fmac_f32_e32 v148, 0x3377d1cf, v168
	v_fmac_f32_e32 v148, 0x3f317217, v168
	v_cmp_lt_f32_e64 s[2:3], |v168|, s15
	v_cndmask_b32_e32 v171, 0, v131, vcc
	v_cndmask_b32_e64 v150, v150, 0, s[4:5]
	v_cndmask_b32_e64 v148, v168, v148, s[2:3]
	v_cndmask_b32_e64 v168, 0, v131, s[0:1]
	v_sub_f32_e32 v168, v148, v168
	v_mul_f32_e32 v148, 0x3f317217, v149
	v_fma_f32 v148, v149, s9, -v148
	v_fmac_f32_e32 v148, 0x3377d1cf, v149
	v_fmac_f32_e32 v148, 0x3f317217, v149
	v_cmp_lt_f32_e64 s[0:1], |v149|, s15
	v_add3_u32 v176, v151, v176, s16
	v_bfe_u32 v151, v161, 16, 1
	v_cndmask_b32_e64 v170, v149, v148, s[0:1]
	v_pk_add_f32 v[148:149], v[162:163], 1.0 op_sel_hi:[1,0]
	v_sub_f32_e32 v170, v170, v171
	v_rcp_f32_e32 v163, v149
	v_add3_u32 v151, v161, v151, s16
	v_rcp_f32_e32 v174, v148
	v_mul_f32_e32 v162, v140, v163
	v_mul_f32_e32 v163, v142, v174
	v_sub_f32_e32 v148, 1.0, v163
	v_cmp_gt_f32_e64 s[0:1], s14, v148
	v_cndmask_b32_e64 v163, v163, 0, s[4:5]
	s_nop 0
	v_cndmask_b32_e64 v171, 0, 32, s[0:1]
	v_ldexp_f32 v148, v148, v171
	v_log_f32_e32 v171, v148
	s_nop 0
	v_mul_f32_e32 v148, 0x3f317217, v171
	v_fma_f32 v172, v171, s9, -v148
	v_pk_add_f32 v[148:149], v[164:165], 1.0 op_sel_hi:[1,0]
	v_fmac_f32_e32 v172, 0x3377d1cf, v171
	v_rcp_f32_e32 v165, v149
	v_fmac_f32_e32 v172, 0x3f317217, v171
	v_cmp_lt_f32_e64 vcc, |v171|, s15
	s_nop 1
	v_cndmask_b32_e32 v171, v171, v172, vcc
	v_rcp_f32_e32 v175, v148
	v_mul_f32_e32 v149, v141, v165
	v_mul_f32_e32 v148, v143, v175
	v_sub_f32_e32 v165, 1.0, v148
	v_cmp_gt_f32_e32 vcc, s14, v165
	v_cndmask_b32_e64 v148, v148, 0, s[4:5]
	v_bfe_u32 v175, v150, 16, 1
	v_cndmask_b32_e64 v172, 0, 32, vcc
	v_ldexp_f32 v165, v165, v172
	v_log_f32_e32 v165, v165
	v_cndmask_b32_e64 v172, 0, v131, s[0:1]
	v_sub_f32_e32 v171, v171, v172
	v_sub_f32_e32 v172, 1.0, v162
	v_cmp_gt_f32_e64 s[0:1], s14, v172
	v_mul_f32_e32 v164, 0x3f317217, v165
	v_fma_f32 v164, v165, s9, -v164
	v_cndmask_b32_e64 v173, 0, 32, s[0:1]
	v_ldexp_f32 v172, v172, v173
	v_fmac_f32_e32 v164, 0x3377d1cf, v165
	v_log_f32_e32 v172, v172
	v_fmac_f32_e32 v164, 0x3f317217, v165
	v_cmp_lt_f32_e64 s[2:3], |v165|, s15
	v_sub_f32_e32 v173, 1.0, v149
	v_cndmask_b32_e64 v149, v149, 0, s[4:5]
	v_cndmask_b32_e64 v164, v165, v164, s[2:3]
	v_cndmask_b32_e32 v165, 0, v131, vcc
	v_cmp_gt_f32_e32 vcc, s14, v173
	v_sub_f32_e32 v164, v164, v165
	v_mul_f32_e32 v165, 0x3f317217, v172
	v_cndmask_b32_e64 v174, 0, 32, vcc
	v_ldexp_f32 v173, v173, v174
	v_fma_f32 v165, v172, s9, -v165
	v_log_f32_e32 v173, v173
	v_fmac_f32_e32 v165, 0x3377d1cf, v172
	v_fmac_f32_e32 v165, 0x3f317217, v172
	v_cmp_lt_f32_e64 s[2:3], |v172|, s15
	v_cndmask_b32_e64 v162, v162, 0, s[4:5]
	v_bfe_u32 v174, v148, 16, 1
	v_cndmask_b32_e64 v165, v172, v165, s[2:3]
	v_cndmask_b32_e64 v172, 0, v131, s[0:1]
	v_sub_f32_e32 v165, v165, v172
	v_mul_f32_e32 v172, 0x3f317217, v173
	v_fma_f32 v172, v173, s9, -v172
	v_fmac_f32_e32 v172, 0x3377d1cf, v173
	v_fmac_f32_e32 v172, 0x3f317217, v173
	v_cmp_lt_f32_e64 s[0:1], |v173|, s15
	v_add3_u32 v175, v150, v175, s16
	v_add3_u32 v148, v148, v174, s16
	v_cndmask_b32_e64 v172, v173, v172, s[0:1]
	v_cndmask_b32_e32 v173, 0, v131, vcc
	v_sub_f32_e32 v172, v172, v173
	v_bfe_u32 v173, v149, 16, 1
	v_add3_u32 v149, v149, v173, s16
	v_bfe_u32 v150, v166, 16, 1
	v_bfe_u32 v173, v163, 16, 1
	v_bfe_u32 v174, v162, 16, 1
	v_add3_u32 v162, v162, v174, s16
	v_add3_u32 v163, v163, v173, s16
	v_add3_u32 v150, v166, v150, s16
	v_lshrrev_b32_e32 v161, 16, v150
	v_lshrrev_b32_e32 v166, 16, v151
	v_lshrrev_b32_e32 v150, 16, v163
	v_lshrrev_b32_e32 v151, 16, v162
	v_and_or_b32 v151, v149, s17, v151
	v_and_or_b32 v150, v148, s17, v150
	v_and_or_b32 v149, v175, s17, v166
	v_and_or_b32 v148, v176, s17, v161
	global_store_dwordx4 v[138:139], v[148:151], off offset:256
	v_cndmask_b32_e64 v138, v167, 0, s[4:5]
	v_bfe_u32 v139, v138, 16, 1
	v_add3_u32 v138, v138, v139, s16
	v_cndmask_b32_e64 v139, v169, 0, s[4:5]
	v_bfe_u32 v148, v139, 16, 1
	v_lshrrev_b32_e32 v138, 16, v138
	v_add3_u32 v139, v139, v148, s16
	v_and_or_b32 v148, v139, s17, v138
	v_cndmask_b32_e64 v138, v168, 0, s[4:5]
	v_bfe_u32 v139, v138, 16, 1
	v_add3_u32 v138, v138, v139, s16
	v_cndmask_b32_e64 v139, v170, 0, s[4:5]
	v_bfe_u32 v149, v139, 16, 1
	v_lshrrev_b32_e32 v138, 16, v138
	v_add3_u32 v139, v139, v149, s16
	v_and_or_b32 v149, v139, s17, v138
	v_cndmask_b32_e64 v138, v171, 0, s[4:5]
	v_bfe_u32 v139, v138, 16, 1
	v_add3_u32 v138, v138, v139, s16
	v_cndmask_b32_e64 v139, v164, 0, s[4:5]
	v_bfe_u32 v150, v139, 16, 1
	v_lshrrev_b32_e32 v138, 16, v138
	v_add3_u32 v139, v139, v150, s16
	v_and_or_b32 v150, v139, s17, v138
	v_cndmask_b32_e64 v138, v165, 0, s[4:5]
	v_bfe_u32 v139, v138, 16, 1
	v_add3_u32 v138, v138, v139, s16
	v_cndmask_b32_e64 v139, v172, 0, s[4:5]
	v_bfe_u32 v151, v139, 16, 1
	v_lshrrev_b32_e32 v138, 16, v138
	v_add3_u32 v139, v139, v151, s16
	s_movk_i32 s2, 0x1fd0
	v_and_or_b32 v151, v139, s17, v138
	v_cmp_gt_i32_e32 vcc, s2, v130
	global_store_dwordx4 v[136:137], v[148:151], off offset:256
	v_add_u32_e32 v136, 0xb0, v130
	v_cndmask_b32_e64 v137, v154, 0, vcc
	v_add_u32_e32 v137, v137, v136
	v_cmp_gt_i32_e64 s[2:3], s18, v137
	v_ashrrev_i32_e32 v137, 31, v136
	v_lshlrev_b64 v[138:139], 10, v[136:137]
	v_lshl_add_u64 v[136:137], v[132:133], 0, v[138:139]
	v_lshl_add_u64 v[132:133], v[134:135], 0, v[138:139]
	v_mul_f32_e32 v135, 0x3fb8aa3b, v15
	v_mul_f32_e32 v134, 0x3fb8aa3b, v14
	v_exp_f32_e32 v138, v135
	v_mul_f32_e32 v135, 0x3fb8aa3b, v16
	v_exp_f32_e32 v134, v134
	v_exp_f32_e32 v135, v135
	v_mul_f32_e32 v139, 0x3fb8aa3b, v17
	v_exp_f32_e32 v139, v139
	v_mul_f32_e32 v149, 0x3fb8aa3b, v11
	v_pk_add_f32 v[134:135], v[134:135], 1.0 op_sel_hi:[1,0]
	v_mul_f32_e32 v148, 0x3fb8aa3b, v10
	v_rcp_f32_e32 v154, v135
	v_exp_f32_e32 v150, v149
	v_mul_f32_e32 v149, 0x3fb8aa3b, v12
	v_exp_f32_e32 v148, v148
	v_rcp_f32_e32 v164, v134
	v_mul_f32_e32 v154, v157, v154
	v_mul_f32_e32 v156, v156, v164
	v_sub_f32_e32 v134, 1.0, v156
	v_cmp_gt_f32_e64 s[4:5], s14, v134
	v_exp_f32_e32 v149, v149
	s_movk_i32 s0, 0x4050
	v_cndmask_b32_e64 v151, 0, 32, s[4:5]
	v_ldexp_f32 v134, v134, v151
	v_log_f32_e32 v161, v134
	v_mul_f32_e32 v134, 0x3fb8aa3b, v13
	v_exp_f32_e32 v151, v134
	v_cmp_gt_i32_e64 s[0:1], s0, v130
	v_mul_f32_e32 v134, 0x3f317217, v161
	v_fma_f32 v157, v161, s9, -v134
	v_pk_add_f32 v[134:135], v[138:139], 1.0 op_sel_hi:[1,0]
	v_fmac_f32_e32 v157, 0x3377d1cf, v161
	v_rcp_f32_e32 v139, v135
	v_fmac_f32_e32 v157, 0x3f317217, v161
	v_cmp_lt_f32_e64 vcc, |v161|, s15
	s_nop 1
	v_cndmask_b32_e32 v157, v161, v157, vcc
	v_rcp_f32_e32 v164, v134
	v_mul_f32_e32 v138, v158, v139
	v_mul_f32_e32 v139, v155, v164
	v_sub_f32_e32 v134, 1.0, v139
	v_cmp_gt_f32_e32 vcc, s14, v134
	s_nop 1
	v_cndmask_b32_e64 v155, 0, 32, vcc
	v_ldexp_f32 v134, v134, v155
	v_log_f32_e32 v134, v134
	v_cndmask_b32_e64 v155, 0, v131, s[4:5]
	v_sub_f32_e32 v155, v157, v155
	v_sub_f32_e32 v157, 1.0, v154
	v_mul_f32_e32 v135, 0x3f317217, v134
	v_fma_f32 v135, v134, s9, -v135
	v_cmp_gt_f32_e64 s[4:5], s14, v157
	v_fmac_f32_e32 v135, 0x3377d1cf, v134
	v_fmac_f32_e32 v135, 0x3f317217, v134
	v_cndmask_b32_e64 v158, 0, 32, s[4:5]
	v_ldexp_f32 v157, v157, v158
	v_cmp_lt_f32_e64 s[6:7], |v134|, s15
	v_log_f32_e32 v157, v157
	s_nop 0
	v_cndmask_b32_e64 v134, v134, v135, s[6:7]
	v_cndmask_b32_e32 v135, 0, v131, vcc
	v_sub_f32_e32 v158, v134, v135
	v_sub_f32_e32 v135, 1.0, v138
	v_cmp_gt_f32_e32 vcc, s14, v135
	v_mul_f32_e32 v134, 0x3f317217, v157
	v_fma_f32 v134, v157, s9, -v134
	v_cndmask_b32_e64 v161, 0, 32, vcc
	v_ldexp_f32 v135, v135, v161
	v_log_f32_e32 v135, v135
	v_fmac_f32_e32 v134, 0x3377d1cf, v157
	v_fmac_f32_e32 v134, 0x3f317217, v157
	v_cmp_lt_f32_e64 s[6:7], |v157|, s15
	s_nop 1
	v_cndmask_b32_e64 v134, v157, v134, s[6:7]
	v_cndmask_b32_e64 v157, 0, v131, s[4:5]
	v_sub_f32_e32 v157, v134, v157
	v_mul_f32_e32 v134, 0x3f317217, v135
	v_fma_f32 v134, v135, s9, -v134
	v_fmac_f32_e32 v134, 0x3377d1cf, v135
	v_fmac_f32_e32 v134, 0x3f317217, v135
	v_cmp_lt_f32_e64 s[4:5], |v135|, s15
	s_nop 1
	v_cndmask_b32_e64 v134, v135, v134, s[4:5]
	v_cndmask_b32_e32 v135, 0, v131, vcc
	v_sub_f32_e32 v161, v134, v135
	v_pk_add_f32 v[134:135], v[148:149], 1.0 op_sel_hi:[1,0]
	s_nop 0
	v_rcp_f32_e32 v149, v135
	s_and_b64 s[4:5], s[0:1], s[2:3]
	v_cndmask_b32_e64 v138, v138, 0, s[4:5]
	v_cndmask_b32_e64 v139, v139, 0, s[4:5]
	v_rcp_f32_e32 v165, v134
	v_mul_f32_e32 v148, v152, v149
	v_mul_f32_e32 v149, v159, v165
	v_sub_f32_e32 v134, 1.0, v149
	v_cmp_gt_f32_e64 s[0:1], s14, v134
	v_cndmask_b32_e64 v149, v149, 0, s[4:5]
	v_cndmask_b32_e64 v156, v156, 0, s[4:5]
	v_cndmask_b32_e64 v159, 0, 32, s[0:1]
	v_ldexp_f32 v134, v134, v159
	v_log_f32_e32 v159, v134
	v_cndmask_b32_e64 v154, v154, 0, s[4:5]
	v_mul_f32_e32 v134, 0x3f317217, v159
	v_fma_f32 v152, v159, s9, -v134
	v_pk_add_f32 v[134:135], v[150:151], 1.0 op_sel_hi:[1,0]
	v_fmac_f32_e32 v152, 0x3377d1cf, v159
	v_rcp_f32_e32 v151, v135
	v_fmac_f32_e32 v152, 0x3f317217, v159
	v_cmp_lt_f32_e64 vcc, |v159|, s15
	s_nop 1
	v_cndmask_b32_e32 v152, v159, v152, vcc
	v_rcp_f32_e32 v164, v134
	v_mul_f32_e32 v135, v153, v151
	v_mul_f32_e32 v134, v160, v164
	v_sub_f32_e32 v151, 1.0, v134
	v_cmp_gt_f32_e32 vcc, s14, v151
	v_sub_f32_e32 v153, 1.0, v148
	v_bfe_u32 v162, v138, 16, 1
	v_cndmask_b32_e64 v159, 0, 32, vcc
	v_ldexp_f32 v151, v151, v159
	v_log_f32_e32 v151, v151
	v_cndmask_b32_e64 v159, 0, v131, s[0:1]
	v_cmp_gt_f32_e64 s[0:1], s14, v153
	v_sub_f32_e32 v152, v152, v159
	v_mul_f32_e32 v150, 0x3f317217, v151
	v_fma_f32 v150, v151, s9, -v150
	v_fmac_f32_e32 v150, 0x3377d1cf, v151
	v_cndmask_b32_e64 v159, 0, 32, s[0:1]
	v_fmac_f32_e32 v150, 0x3f317217, v151
	v_ldexp_f32 v153, v153, v159
	v_cmp_lt_f32_e64 s[2:3], |v151|, s15
	v_log_f32_e32 v153, v153
	v_cndmask_b32_e64 v148, v148, 0, s[4:5]
	v_cndmask_b32_e64 v150, v151, v150, s[2:3]
	v_cndmask_b32_e32 v151, 0, v131, vcc
	v_sub_f32_e32 v159, v150, v151
	v_sub_f32_e32 v151, 1.0, v135
	v_cmp_gt_f32_e32 vcc, s14, v151
	v_mul_f32_e32 v150, 0x3f317217, v153
	v_fma_f32 v150, v153, s9, -v150
	v_cndmask_b32_e64 v160, 0, 32, vcc
	v_ldexp_f32 v151, v151, v160
	v_log_f32_e32 v151, v151
	v_fmac_f32_e32 v150, 0x3377d1cf, v153
	v_fmac_f32_e32 v150, 0x3f317217, v153
	v_cmp_lt_f32_e64 s[2:3], |v153|, s15
	v_cndmask_b32_e64 v135, v135, 0, s[4:5]
	v_cndmask_b32_e64 v134, v134, 0, s[4:5]
	v_cndmask_b32_e64 v150, v153, v150, s[2:3]
	v_cndmask_b32_e64 v153, 0, v131, s[0:1]
	v_sub_f32_e32 v153, v150, v153
	v_mul_f32_e32 v150, 0x3f317217, v151
	v_fma_f32 v150, v151, s9, -v150
	v_fmac_f32_e32 v150, 0x3377d1cf, v151
	v_fmac_f32_e32 v150, 0x3f317217, v151
	v_cmp_lt_f32_e64 s[0:1], |v151|, s15
	v_bfe_u32 v163, v139, 16, 1
	v_add3_u32 v138, v138, v162, s16
	v_cndmask_b32_e64 v150, v151, v150, s[0:1]
	v_cndmask_b32_e32 v151, 0, v131, vcc
	v_sub_f32_e32 v160, v150, v151
	v_bfe_u32 v150, v135, 16, 1
	v_bfe_u32 v162, v149, 16, 1
	v_bfe_u32 v151, v134, 16, 1
	v_add3_u32 v139, v139, v163, s16
	v_add3_u32 v135, v135, v150, s16
	v_bfe_u32 v150, v156, 16, 1
	v_bfe_u32 v163, v148, 16, 1
	v_add3_u32 v149, v149, v162, s16
	v_add3_u32 v134, v134, v151, s16
	v_bfe_u32 v151, v154, 16, 1
	v_add3_u32 v148, v148, v163, s16
	v_add3_u32 v150, v156, v150, s16
	v_lshrrev_b32_e32 v149, 16, v149
	v_add3_u32 v151, v154, v151, s16
	v_lshrrev_b32_e32 v154, 16, v150
	v_lshrrev_b32_e32 v148, 16, v148
	v_and_or_b32 v150, v134, s17, v149
	v_cndmask_b32_e64 v134, v155, 0, s[4:5]
	v_lshrrev_b32_e32 v156, 16, v151
	v_and_or_b32 v151, v135, s17, v148
	v_bfe_u32 v135, v134, 16, 1
	v_add3_u32 v134, v134, v135, s16
	v_cndmask_b32_e64 v135, v158, 0, s[4:5]
	v_and_or_b32 v149, v138, s17, v156
	v_bfe_u32 v138, v135, 16, 1
	v_and_or_b32 v148, v139, s17, v154
	v_lshrrev_b32_e32 v134, 16, v134
	v_add3_u32 v135, v135, v138, s16
	global_store_dwordx4 v[136:137], v[148:151], off
	v_mul_f32_e32 v139, 0x3fb8aa3b, v9
	v_exp_f32_e32 v139, v139
	v_and_or_b32 v148, v135, s17, v134
	v_cndmask_b32_e64 v134, v157, 0, s[4:5]
	v_bfe_u32 v135, v134, 16, 1
	v_add3_u32 v134, v134, v135, s16
	v_cndmask_b32_e64 v135, v161, 0, s[4:5]
	v_bfe_u32 v138, v135, 16, 1
	v_lshrrev_b32_e32 v134, 16, v134
	v_add3_u32 v135, v135, v138, s16
	v_and_or_b32 v149, v135, s17, v134
	v_cndmask_b32_e64 v134, v152, 0, s[4:5]
	v_bfe_u32 v135, v134, 16, 1
	v_add3_u32 v134, v134, v135, s16
	v_cndmask_b32_e64 v135, v159, 0, s[4:5]
	v_bfe_u32 v138, v135, 16, 1
	v_lshrrev_b32_e32 v134, 16, v134
	v_add3_u32 v135, v135, v138, s16
	v_and_or_b32 v150, v135, s17, v134
	v_cndmask_b32_e64 v134, v153, 0, s[4:5]
	v_bfe_u32 v135, v134, 16, 1
	v_add3_u32 v134, v134, v135, s16
	v_cndmask_b32_e64 v135, v160, 0, s[4:5]
	v_bfe_u32 v138, v135, 16, 1
	v_lshrrev_b32_e32 v134, 16, v134
	v_add3_u32 v135, v135, v138, s16
	v_and_or_b32 v151, v135, s17, v134
	v_mul_f32_e32 v135, 0x3fb8aa3b, v7
	v_mul_f32_e32 v134, 0x3fb8aa3b, v6
	v_exp_f32_e32 v138, v135
	v_mul_f32_e32 v135, 0x3fb8aa3b, v8
	v_exp_f32_e32 v134, v134
	v_exp_f32_e32 v135, v135
	global_store_dwordx4 v[132:133], v[148:151], off
	v_pk_add_f32 v[134:135], v[134:135], 1.0 op_sel_hi:[1,0]
	s_nop 0
	v_rcp_f32_e32 v152, v135
	v_mul_f32_e32 v149, 0x3fb8aa3b, v3
	v_mul_f32_e32 v148, 0x3fb8aa3b, v2
	v_exp_f32_e32 v150, v149
	v_rcp_f32_e32 v156, v134
	v_mul_f32_e32 v144, v144, v152
	v_mul_f32_e32 v146, v146, v156
	v_sub_f32_e32 v134, 1.0, v146
	v_cmp_gt_f32_e64 s[0:1], s14, v134
	v_mul_f32_e32 v149, 0x3fb8aa3b, v4
	v_exp_f32_e32 v148, v148
	v_cndmask_b32_e64 v151, 0, 32, s[0:1]
	v_ldexp_f32 v134, v134, v151
	v_log_f32_e32 v153, v134
	v_mul_f32_e32 v134, 0x3fb8aa3b, v5
	v_exp_f32_e32 v151, v134
	v_exp_f32_e32 v149, v149
	v_mul_f32_e32 v134, 0x3f317217, v153
	v_fma_f32 v152, v153, s9, -v134
	v_pk_add_f32 v[134:135], v[138:139], 1.0 op_sel_hi:[1,0]
	v_fmac_f32_e32 v152, 0x3377d1cf, v153
	v_rcp_f32_e32 v139, v135
	v_fmac_f32_e32 v152, 0x3f317217, v153
	v_cmp_lt_f32_e64 vcc, |v153|, s15
	v_cndmask_b32_e64 v146, v146, 0, s[4:5]
	s_nop 0
	v_cndmask_b32_e32 v152, v153, v152, vcc
	v_rcp_f32_e32 v156, v134
	v_mul_f32_e32 v138, v145, v139
	v_mul_f32_e32 v139, v147, v156
	v_sub_f32_e32 v134, 1.0, v139
	v_cmp_gt_f32_e32 vcc, s14, v134
	v_sub_f32_e32 v145, 1.0, v144
	v_cndmask_b32_e64 v139, v139, 0, s[4:5]
	v_cndmask_b32_e64 v147, 0, 32, vcc
	v_ldexp_f32 v134, v134, v147
	v_log_f32_e32 v134, v134
	v_cndmask_b32_e64 v147, 0, v131, s[0:1]
	v_cmp_gt_f32_e64 s[0:1], s14, v145
	v_sub_f32_e32 v147, v152, v147
	v_mul_f32_e32 v135, 0x3f317217, v134
	v_fma_f32 v135, v134, s9, -v135
	v_fmac_f32_e32 v135, 0x3377d1cf, v134
	v_cndmask_b32_e64 v152, 0, 32, s[0:1]
	v_fmac_f32_e32 v135, 0x3f317217, v134
	v_ldexp_f32 v145, v145, v152
	v_cmp_lt_f32_e64 s[2:3], |v134|, s15
	v_log_f32_e32 v145, v145
	v_cndmask_b32_e64 v144, v144, 0, s[4:5]
	v_cndmask_b32_e64 v134, v134, v135, s[2:3]
	v_cndmask_b32_e32 v135, 0, v131, vcc
	v_sub_f32_e32 v152, v134, v135
	v_sub_f32_e32 v135, 1.0, v138
	v_cmp_gt_f32_e32 vcc, s14, v135
	v_mul_f32_e32 v134, 0x3f317217, v145
	v_fma_f32 v134, v145, s9, -v134
	v_cndmask_b32_e64 v153, 0, 32, vcc
	v_ldexp_f32 v135, v135, v153
	v_log_f32_e32 v135, v135
	v_fmac_f32_e32 v134, 0x3377d1cf, v145
	v_fmac_f32_e32 v134, 0x3f317217, v145
	v_cmp_lt_f32_e64 s[2:3], |v145|, s15
	v_cndmask_b32_e32 v154, 0, v131, vcc
	v_cndmask_b32_e64 v138, v138, 0, s[4:5]
	v_cndmask_b32_e64 v134, v145, v134, s[2:3]
	v_cndmask_b32_e64 v145, 0, v131, s[0:1]
	v_sub_f32_e32 v145, v134, v145
	v_mul_f32_e32 v134, 0x3f317217, v135
	v_fma_f32 v134, v135, s9, -v134
	v_fmac_f32_e32 v134, 0x3377d1cf, v135
	v_fmac_f32_e32 v134, 0x3f317217, v135
	v_cmp_lt_f32_e64 s[0:1], |v135|, s15
	s_nop 1
	v_cndmask_b32_e64 v153, v135, v134, s[0:1]
	v_pk_add_f32 v[134:135], v[148:149], 1.0 op_sel_hi:[1,0]
	v_sub_f32_e32 v153, v153, v154
	v_rcp_f32_e32 v149, v135
	s_nop 0
	v_rcp_f32_e32 v157, v134
	v_mul_f32_e32 v140, v140, v149
	v_mul_f32_e32 v142, v142, v157
	v_sub_f32_e32 v134, 1.0, v142
	v_cmp_gt_f32_e64 s[0:1], s14, v134
	s_nop 1
	v_cndmask_b32_e64 v149, 0, 32, s[0:1]
	v_ldexp_f32 v134, v134, v149
	v_log_f32_e32 v149, v134
	s_nop 0
	v_mul_f32_e32 v134, 0x3f317217, v149
	v_fma_f32 v148, v149, s9, -v134
	v_pk_add_f32 v[134:135], v[150:151], 1.0 op_sel_hi:[1,0]
	v_fmac_f32_e32 v148, 0x3377d1cf, v149
	v_rcp_f32_e32 v151, v135
	v_fmac_f32_e32 v148, 0x3f317217, v149
	v_cmp_lt_f32_e64 vcc, |v149|, s15
	s_nop 1
	v_cndmask_b32_e32 v148, v149, v148, vcc
	v_rcp_f32_e32 v156, v134
	v_mul_f32_e32 v135, v141, v151
	v_mul_f32_e32 v134, v143, v156
	v_sub_f32_e32 v143, 1.0, v134
	v_cmp_gt_f32_e32 vcc, s14, v143
	v_sub_f32_e32 v149, 1.0, v140
	v_cndmask_b32_e64 v134, v134, 0, s[4:5]
	v_cndmask_b32_e64 v150, 0, 32, vcc
	v_ldexp_f32 v143, v143, v150
	v_log_f32_e32 v143, v143
	v_cndmask_b32_e64 v150, 0, v131, s[0:1]
	v_cmp_gt_f32_e64 s[0:1], s14, v149
	v_sub_f32_e32 v148, v148, v150
	v_mul_f32_e32 v141, 0x3f317217, v143
	v_cndmask_b32_e64 v150, 0, 32, s[0:1]
	v_fma_f32 v141, v143, s9, -v141
	v_ldexp_f32 v149, v149, v150
	v_fmac_f32_e32 v141, 0x3377d1cf, v143
	v_log_f32_e32 v149, v149
	v_fmac_f32_e32 v141, 0x3f317217, v143
	v_cmp_lt_f32_e64 s[2:3], |v143|, s15
	v_sub_f32_e32 v150, 1.0, v135
	v_cndmask_b32_e64 v135, v135, 0, s[4:5]
	v_cndmask_b32_e64 v141, v143, v141, s[2:3]
	v_cndmask_b32_e32 v143, 0, v131, vcc
	v_cmp_gt_f32_e32 vcc, s14, v150
	v_sub_f32_e32 v143, v141, v143
	v_mul_f32_e32 v141, 0x3f317217, v149
	v_cndmask_b32_e64 v151, 0, 32, vcc
	v_ldexp_f32 v150, v150, v151
	v_fma_f32 v141, v149, s9, -v141
	v_log_f32_e32 v150, v150
	v_fmac_f32_e32 v141, 0x3377d1cf, v149
	v_fmac_f32_e32 v141, 0x3f317217, v149
	v_cmp_lt_f32_e64 s[2:3], |v149|, s15
	v_cndmask_b32_e64 v140, v140, 0, s[4:5]
	v_bfe_u32 v151, v138, 16, 1
	v_cndmask_b32_e64 v141, v149, v141, s[2:3]
	v_cndmask_b32_e64 v149, 0, v131, s[0:1]
	v_sub_f32_e32 v149, v141, v149
	v_mul_f32_e32 v141, 0x3f317217, v150
	v_fma_f32 v141, v150, s9, -v141
	v_fmac_f32_e32 v141, 0x3377d1cf, v150
	v_fmac_f32_e32 v141, 0x3f317217, v150
	v_cmp_lt_f32_e64 s[0:1], |v150|, s15
	v_cndmask_b32_e32 v131, 0, v131, vcc
	v_bfe_u32 v154, v139, 16, 1
	v_cndmask_b32_e64 v141, v150, v141, s[0:1]
	v_sub_f32_e32 v131, v141, v131
	v_cndmask_b32_e64 v141, v142, 0, s[4:5]
	v_bfe_u32 v142, v135, 16, 1
	v_bfe_u32 v150, v134, 16, 1
	v_add3_u32 v154, v139, v154, s16
	v_add3_u32 v138, v138, v151, s16
	v_add3_u32 v134, v134, v150, s16
	v_add3_u32 v135, v135, v142, s16
	v_bfe_u32 v139, v146, 16, 1
	v_bfe_u32 v142, v144, 16, 1
	v_bfe_u32 v150, v141, 16, 1
	v_bfe_u32 v151, v140, 16, 1
	v_add3_u32 v140, v140, v151, s16
	v_add3_u32 v141, v141, v150, s16
	v_add3_u32 v142, v144, v142, s16
	v_add3_u32 v139, v146, v139, s16
	v_lshrrev_b32_e32 v144, 16, v139
	v_lshrrev_b32_e32 v139, 16, v142
	v_lshrrev_b32_e32 v142, 16, v141
	v_lshrrev_b32_e32 v140, 16, v140
	v_and_or_b32 v141, v135, s17, v140
	v_and_or_b32 v140, v134, s17, v142
	v_cndmask_b32_e64 v134, v147, 0, s[4:5]
	v_bfe_u32 v135, v134, 16, 1
	v_and_or_b32 v139, v138, s17, v139
	v_and_or_b32 v138, v154, s17, v144
	v_add3_u32 v134, v134, v135, s16
	v_cndmask_b32_e64 v135, v152, 0, s[4:5]
	global_store_dwordx4 v[136:137], v[138:141], off offset:256
	v_bfe_u32 v136, v135, 16, 1
	v_lshrrev_b32_e32 v134, 16, v134
	v_add3_u32 v135, v135, v136, s16
	v_and_or_b32 v134, v135, s17, v134
	v_cndmask_b32_e64 v135, v145, 0, s[4:5]
	v_bfe_u32 v136, v135, 16, 1
	v_add3_u32 v135, v135, v136, s16
	v_cndmask_b32_e64 v136, v153, 0, s[4:5]
	v_bfe_u32 v137, v136, 16, 1
	v_lshrrev_b32_e32 v135, 16, v135
	v_add3_u32 v136, v136, v137, s16
	v_and_or_b32 v135, v136, s17, v135
	v_cndmask_b32_e64 v136, v148, 0, s[4:5]
	v_bfe_u32 v137, v136, 16, 1
	v_add3_u32 v136, v136, v137, s16
	v_cndmask_b32_e64 v137, v143, 0, s[4:5]
	v_bfe_u32 v138, v137, 16, 1
	v_lshrrev_b32_e32 v136, 16, v136
	v_add3_u32 v137, v137, v138, s16
	v_and_or_b32 v136, v137, s17, v136
	v_cndmask_b32_e64 v137, v149, 0, s[4:5]
	v_bfe_u32 v138, v137, 16, 1
	v_cndmask_b32_e64 v131, v131, 0, s[4:5]
	v_add3_u32 v137, v137, v138, s16
	v_bfe_u32 v138, v131, 16, 1
	v_lshrrev_b32_e32 v137, 16, v137
	v_add3_u32 v131, v131, v138, s16
	v_and_or_b32 v137, v131, s17, v137
	global_store_dwordx4 v[132:133], v[134:137], off offset:256

.LBB0_1105:
	s_lshl_b32 s4, s12, 14
	s_add_i32 s4, s4, 0
	v_lshlrev_b32_e32 v140, 2, v139
	v_lshlrev_b32_e32 v141, 2, v138
	v_add3_u32 v241, s4, v140, v141
	s_add_i32 s4, 0, 0x10000
	v_add3_u32 v242, s4, v140, v141
	v_and_b32_e32 v140, 1, v135
	v_and_b32_e32 v135, 2, v135
	v_cmp_eq_u32_e64 s[6:7], 0, v135
	v_or_b32_e32 v135, v139, v138
	v_mov_b32_e32 v226, 0
	v_lshlrev_b32_e32 v138, 2, v135
	v_mov_b32_e32 v139, v226
	v_lshl_add_u64 v[138:139], s[72:73], 0, v[138:139]
	s_mov_b64 s[12:13], 0xde00000
	v_lshl_add_u64 v[228:229], v[138:139], 0, s[12:13]
	s_mov_b64 s[12:13], 0xdd00000
	v_lshl_add_u64 v[230:231], v[138:139], 0, s[12:13]
	s_add_u32 s12, s72, 0xf100
	s_addc_u32 s13, s73, 0
	v_lshl_add_u64 v[232:233], v[132:133], 1, s[14:15]
	s_add_u32 s14, s72, 0x4200
	s_addc_u32 s15, s73, 0
	v_lshl_add_u64 v[234:235], v[130:131], 2, s[16:17]
	s_add_u32 s16, s72, 0x4400
	s_addc_u32 s17, s73, 0
	s_add_u32 s18, s72, 0x4500
	s_addc_u32 s19, s73, 0
	s_add_u32 s20, s72, 0x4600
	s_addc_u32 s21, s73, 0
	s_add_u32 s22, s72, 0x4700
	s_addc_u32 s23, s73, 0
	s_add_u32 s24, s72, 0x4800
	s_addc_u32 s25, s73, 0
	s_add_u32 s26, s72, 0x4900
	s_addc_u32 s27, s73, 0
	s_add_u32 s28, s72, 0x4a00
	s_addc_u32 s29, s73, 0
	s_add_u32 s30, s72, 0x4b00
	s_addc_u32 s31, s73, 0
	s_add_u32 s34, s72, 0x4c00
	s_addc_u32 s35, s73, 0
	s_add_u32 s36, s72, 0x4d00
	s_addc_u32 s37, s73, 0
	s_add_u32 s40, s72, 0x4e00
	s_addc_u32 s41, s73, 0
	s_add_u32 s42, s72, 0x4f00
	s_addc_u32 s43, s73, 0
	s_add_u32 s44, s72, 0x5000
	s_addc_u32 s45, s73, 0
	s_add_u32 s46, s72, 0x5100
	s_addc_u32 s47, s73, 0
	s_add_u32 s48, s72, 0x5200
	s_addc_u32 s49, s73, 0
	s_add_u32 s52, s72, 0x5300
	s_addc_u32 s53, s73, 0
	s_add_u32 s66, s72, 0x7400
	v_lshlrev_b32_e32 v131, 2, v134
	s_addc_u32 s67, s73, 0
	v_lshl_or_b32 v130, v130, 10, v131
	v_mov_b32_e32 v131, v226
	s_add_u32 s70, s72, 0x7500
	v_lshl_add_u64 v[130:131], s[72:73], 0, v[130:131]
	s_mov_b64 s[38:39], 0xdf00000
	s_mov_b32 s50, 0
	s_mov_b32 s33, 4
	v_cmp_eq_u32_e64 s[4:5], 0, v140
	v_cmp_gt_u32_e64 s[8:9], 4, v137
	s_addc_u32 s71, s73, 0
	v_or_b32_e32 v243, 0x1000, v136
	v_lshl_add_u64 v[236:237], v[130:131], 0, s[38:39]
	v_mov_b32_e32 v248, 0xf149f2ca
	s_add_i32 s92, 0, 0x23fc0
	s_add_i32 s93, 0, 0x23fc4
	v_mov_b32_e32 v244, 0x2000
	v_mov_b32_e32 v245, 0x800
	s_branch .LBB0_1108
	s_nop 0
	s_nop 0
	s_nop 0
	s_nop 0
	s_nop 0
	s_nop 0

.LBB0_1183:
	s_and_b32 s55, s54, 0xff
	s_mov_b64 s[86:87], -1
	s_cmp_lg_u32 s55, 0
	s_mov_b64 s[90:91], -1
	s_sleep 2
	s_cbranch_scc1 .LBB0_1186
	global_load_dword v130, v226, s[14:15] sc1
	s_waitcnt vmcnt(0)
	v_cmp_eq_u32_e32 vcc, 0, v130
	s_cbranch_vccnz .LBB0_1188
	s_mov_b64 s[90:91], 0
	s_mov_b64 s[88:89], -1

.LBB0_1200:
	s_and_b32 s55, s54, 0xff
	s_mov_b64 s[84:85], -1
	s_cmp_lg_u32 s55, 0
	s_mov_b64 s[88:89], -1
	s_sleep 2
	s_cbranch_scc1 .LBB0_1203
	global_load_dword v130, v226, s[14:15] sc1
	s_waitcnt vmcnt(0)
	v_cmp_eq_u32_e32 vcc, 0, v130
	s_cbranch_vccnz .LBB0_1205
	s_mov_b64 s[88:89], 0
	s_mov_b64 s[86:87], -1
